# v60 + K-loop LOAD-segment trimming: ds_read_b128 issued first in each LOAD segment, vmcnt+lgkmcnt waits merged into one instruction, M0 wait state supplied by the address VALU op instead of s_nop
# baseline (speedup 1.0000x reference)
.LBB0_297:
	ds_read_b128 v[150:153], v146
	ds_read_b128 v[154:157], v146 offset:1024
	ds_read_b128 v[158:161], v146 offset:2048
	ds_read_b128 v[162:165], v146 offset:3072
	ds_read_b128 v[166:169], v147
	ds_read_b128 v[170:173], v147 offset:1024
	ds_read_b128 v[174:177], v147 offset:2048
	ds_read_b128 v[178:181], v147 offset:3072
	ds_read_b128 v[182:185], v148
	ds_read_b128 v[186:189], v148 offset:1024
	ds_read_b128 v[190:193], v148 offset:2048
	ds_read_b128 v[194:197], v148 offset:3072
	ds_read_b128 v[198:201], v148 offset:4096
	ds_read_b128 v[206:209], v148 offset:5120
	ds_read_b128 v[210:213], v148 offset:6144
	ds_read_b128 v[214:217], v148 offset:7168
	s_add_u32 s47, s38, s46
	s_addc_u32 s66, s39, 0
	s_add_u32 s64, s47, 0x100
	s_addc_u32 s65, s66, 0
	s_and_b64 s[48:49], s[44:45], exec
	s_cselect_b32 s49, s70, s65
	s_cselect_b32 s48, s71, s64
	s_add_u32 s46, s36, s46
	s_addc_u32 s64, s37, 0
	s_add_u32 s46, s46, 0x100
	s_addc_u32 s64, s64, 0
	s_and_b64 s[44:45], s[44:45], exec
	s_cselect_b32 s65, s72, s64
	s_cselect_b32 s64, s73, s46
	s_add_u32 s68, s47, 0x10080
	s_addc_u32 s69, s66, 0
	s_add_i32 s83, s30, s2
	s_add_i32 m0, s16, 0xc000
	s_add_i32 s84, s16, 0xe000
	s_add_i32 s80, s83, 0x2000
	s_add_u32 s66, s64, 0x40000
	s_addc_u32 s67, s65, 0
	s_add_i32 s82, s31, s2
	s_add_i32 s81, s82, 0x2000
	s_add_i32 s79, 0, 0x18000
	s_add_i32 s78, 0, 0x1c000
	s_add_u32 s46, s48, 0x10000
	s_addc_u32 s47, s49, 0
	s_add_i32 s77, s79, s2
	s_add_i32 s75, s77, 0x2000
	s_add_u32 s44, s64, 0x40080
	s_addc_u32 s45, s65, 0
	s_add_i32 s76, s78, s2
	s_add_i32 s74, s76, 0x2000
	v_lshl_add_u64 v[202:203], s[68:69], 0, v[130:131]
	global_load_lds_dwordx4 v[202:203], off
	s_mov_b32 m0, s84
	v_lshl_add_u64 v[202:203], s[68:69], 0, v[132:133]
	global_load_lds_dwordx4 v[202:203], off
	s_waitcnt vmcnt(8) lgkmcnt(0)
	s_setprio 1
	s_barrier
	v_mfma_f32_16x16x32_bf16 v[126:129], v[150:153], v[182:185], v[126:129]
	v_mfma_f32_16x16x32_bf16 v[122:125], v[158:161], v[182:185], v[122:125]
	v_mfma_f32_16x16x32_bf16 v[118:121], v[150:153], v[190:193], v[118:121]
	v_mfma_f32_16x16x32_bf16 v[114:117], v[158:161], v[190:193], v[114:117]
	v_mfma_f32_16x16x32_bf16 v[102:105], v[150:153], v[198:201], v[102:105]
	v_mfma_f32_16x16x32_bf16 v[98:101], v[158:161], v[198:201], v[98:101]
	v_mfma_f32_16x16x32_bf16 v[86:89], v[150:153], v[210:213], v[86:89]
	v_mfma_f32_16x16x32_bf16 v[82:85], v[158:161], v[210:213], v[82:85]
	v_mfma_f32_16x16x32_bf16 v[126:129], v[154:157], v[186:189], v[126:129]
	v_mfma_f32_16x16x32_bf16 v[122:125], v[162:165], v[186:189], v[122:125]
	v_mfma_f32_16x16x32_bf16 v[118:121], v[154:157], v[194:197], v[118:121]
	v_mfma_f32_16x16x32_bf16 v[114:117], v[162:165], v[194:197], v[114:117]
	v_mfma_f32_16x16x32_bf16 v[102:105], v[154:157], v[206:209], v[102:105]
	v_mfma_f32_16x16x32_bf16 v[98:101], v[162:165], v[206:209], v[98:101]
	v_mfma_f32_16x16x32_bf16 v[86:89], v[154:157], v[214:217], v[86:89]
	v_mfma_f32_16x16x32_bf16 v[82:85], v[162:165], v[214:217], v[82:85]
	v_mfma_f32_16x16x32_bf16 v[110:113], v[166:169], v[182:185], v[110:113]
	v_mfma_f32_16x16x32_bf16 v[106:109], v[174:177], v[182:185], v[106:109]
	v_mfma_f32_16x16x32_bf16 v[94:97], v[166:169], v[190:193], v[94:97]
	v_mfma_f32_16x16x32_bf16 v[90:93], v[174:177], v[190:193], v[90:93]
	v_mfma_f32_16x16x32_bf16 v[78:81], v[166:169], v[198:201], v[78:81]
	v_mfma_f32_16x16x32_bf16 v[74:77], v[174:177], v[198:201], v[74:77]
	v_mfma_f32_16x16x32_bf16 v[70:73], v[166:169], v[210:213], v[70:73]
	v_mfma_f32_16x16x32_bf16 v[66:69], v[174:177], v[210:213], v[66:69]
	v_mfma_f32_16x16x32_bf16 v[110:113], v[170:173], v[186:189], v[110:113]
	v_mfma_f32_16x16x32_bf16 v[106:109], v[178:181], v[186:189], v[106:109]
	v_mfma_f32_16x16x32_bf16 v[94:97], v[170:173], v[194:197], v[94:97]
	v_mfma_f32_16x16x32_bf16 v[90:93], v[178:181], v[194:197], v[90:93]
	v_mfma_f32_16x16x32_bf16 v[78:81], v[170:173], v[206:209], v[78:81]
	v_mfma_f32_16x16x32_bf16 v[74:77], v[178:181], v[206:209], v[74:77]
	v_mfma_f32_16x16x32_bf16 v[70:73], v[170:173], v[214:217], v[70:73]
	v_mfma_f32_16x16x32_bf16 v[66:69], v[178:181], v[214:217], v[66:69]
	s_setprio 0
	s_barrier
	ds_read_b128 v[182:185], v148 offset:16384
	ds_read_b128 v[186:189], v148 offset:17408
	ds_read_b128 v[190:193], v148 offset:18432
	ds_read_b128 v[194:197], v148 offset:19456
	ds_read_b128 v[198:201], v148 offset:20480
	ds_read_b128 v[206:209], v148 offset:21504
	ds_read_b128 v[210:213], v148 offset:22528
	ds_read_b128 v[214:217], v148 offset:23552
	s_mov_b32 m0, s83
	v_lshl_add_u64 v[202:203], s[64:65], 0, v[136:137]
	global_load_lds_dwordx4 v[202:203], off
	v_lshl_add_u64 v[218:219], s[64:65], 0, v[134:135]
	s_mov_b32 m0, s80
	v_lshl_add_u64 v[220:221], s[66:67], 0, v[136:137]
	global_load_lds_dwordx4 v[218:219], off
	s_mov_b32 m0, s82
	v_lshl_add_u64 v[222:223], s[48:49], 0, v[132:133]
	global_load_lds_dwordx4 v[220:221], off
	s_mov_b32 m0, s81
	v_lshl_add_u64 v[220:221], s[66:67], 0, v[134:135]
	global_load_lds_dwordx4 v[220:221], off
	s_mov_b32 m0, s16
	v_lshl_add_u64 v[220:221], s[48:49], 0, v[130:131]
	global_load_lds_dwordx4 v[220:221], off
	s_mov_b32 m0, s17
	s_nop 0
	global_load_lds_dwordx4 v[222:223], off
	s_waitcnt vmcnt(8) lgkmcnt(0)
	s_setprio 1
	s_barrier
	v_mfma_f32_16x16x32_bf16 v[62:65], v[150:153], v[182:185], v[62:65]
	v_mfma_f32_16x16x32_bf16 v[58:61], v[158:161], v[182:185], v[58:61]
	v_mfma_f32_16x16x32_bf16 v[54:57], v[150:153], v[190:193], v[54:57]
	v_mfma_f32_16x16x32_bf16 v[50:53], v[158:161], v[190:193], v[50:53]
	v_mfma_f32_16x16x32_bf16 v[38:41], v[150:153], v[198:201], v[38:41]
	v_mfma_f32_16x16x32_bf16 v[34:37], v[158:161], v[198:201], v[34:37]
	v_mfma_f32_16x16x32_bf16 v[22:25], v[150:153], v[210:213], v[22:25]
	v_mfma_f32_16x16x32_bf16 v[18:21], v[158:161], v[210:213], v[18:21]
	v_mfma_f32_16x16x32_bf16 v[62:65], v[154:157], v[186:189], v[62:65]
	v_mfma_f32_16x16x32_bf16 v[58:61], v[162:165], v[186:189], v[58:61]
	v_mfma_f32_16x16x32_bf16 v[54:57], v[154:157], v[194:197], v[54:57]
	v_mfma_f32_16x16x32_bf16 v[50:53], v[162:165], v[194:197], v[50:53]
	v_mfma_f32_16x16x32_bf16 v[38:41], v[154:157], v[206:209], v[38:41]
	v_mfma_f32_16x16x32_bf16 v[34:37], v[162:165], v[206:209], v[34:37]
	v_mfma_f32_16x16x32_bf16 v[22:25], v[154:157], v[214:217], v[22:25]
	v_mfma_f32_16x16x32_bf16 v[18:21], v[162:165], v[214:217], v[18:21]
	v_mfma_f32_16x16x32_bf16 v[46:49], v[166:169], v[182:185], v[46:49]
	v_mfma_f32_16x16x32_bf16 v[42:45], v[174:177], v[182:185], v[42:45]
	v_mfma_f32_16x16x32_bf16 v[30:33], v[166:169], v[190:193], v[30:33]
	v_mfma_f32_16x16x32_bf16 v[26:29], v[174:177], v[190:193], v[26:29]
	v_mfma_f32_16x16x32_bf16 v[14:17], v[166:169], v[198:201], v[14:17]
	v_mfma_f32_16x16x32_bf16 v[10:13], v[174:177], v[198:201], v[10:13]
	v_mfma_f32_16x16x32_bf16 v[6:9], v[166:169], v[210:213], v[6:9]
	v_mfma_f32_16x16x32_bf16 v[2:5], v[174:177], v[210:213], v[2:5]
	v_mfma_f32_16x16x32_bf16 v[46:49], v[170:173], v[186:189], v[46:49]
	v_mfma_f32_16x16x32_bf16 v[42:45], v[178:181], v[186:189], v[42:45]
	v_mfma_f32_16x16x32_bf16 v[30:33], v[170:173], v[194:197], v[30:33]
	v_mfma_f32_16x16x32_bf16 v[26:29], v[178:181], v[194:197], v[26:29]
	v_mfma_f32_16x16x32_bf16 v[14:17], v[170:173], v[206:209], v[14:17]
	v_mfma_f32_16x16x32_bf16 v[10:13], v[178:181], v[206:209], v[10:13]
	v_mfma_f32_16x16x32_bf16 v[6:9], v[170:173], v[214:217], v[6:9]
	v_mfma_f32_16x16x32_bf16 v[2:5], v[178:181], v[214:217], v[2:5]
	s_setprio 0
	s_barrier
	v_add_u32_e32 v149, s79, v145
	ds_read_b128 v[150:153], v149
	ds_read_b128 v[154:157], v149 offset:1024
	ds_read_b128 v[158:161], v149 offset:2048
	ds_read_b128 v[162:165], v149 offset:3072
	v_add_u32_e32 v149, s78, v145
	ds_read_b128 v[166:169], v149
	ds_read_b128 v[170:173], v149 offset:1024
	ds_read_b128 v[174:177], v149 offset:2048
	ds_read_b128 v[178:181], v149 offset:3072
	s_mov_b32 m0, s18
	v_lshl_add_u64 v[224:225], s[46:47], 0, v[130:131]
	ds_read_b128 v[182:185], v148 offset:32768
	ds_read_b128 v[186:189], v148 offset:33792
	ds_read_b128 v[190:193], v148 offset:34816
	ds_read_b128 v[194:197], v148 offset:35840
	ds_read_b128 v[198:201], v148 offset:36864
	ds_read_b128 v[206:209], v148 offset:37888
	ds_read_b128 v[210:213], v148 offset:38912
	ds_read_b128 v[214:217], v148 offset:39936
	global_load_lds_dwordx4 v[224:225], off
	s_mov_b32 m0, s19
	v_lshl_add_u64 v[224:225], s[46:47], 0, v[132:133]
	global_load_lds_dwordx4 v[224:225], off
	s_waitcnt vmcnt(8) lgkmcnt(0)
	s_setprio 1
	s_barrier
	v_mfma_f32_16x16x32_bf16 v[126:129], v[150:153], v[182:185], v[126:129]
	v_mfma_f32_16x16x32_bf16 v[122:125], v[158:161], v[182:185], v[122:125]
	v_mfma_f32_16x16x32_bf16 v[118:121], v[150:153], v[190:193], v[118:121]
	v_mfma_f32_16x16x32_bf16 v[114:117], v[158:161], v[190:193], v[114:117]
	v_mfma_f32_16x16x32_bf16 v[102:105], v[150:153], v[198:201], v[102:105]
	v_mfma_f32_16x16x32_bf16 v[98:101], v[158:161], v[198:201], v[98:101]
	v_mfma_f32_16x16x32_bf16 v[86:89], v[150:153], v[210:213], v[86:89]
	v_mfma_f32_16x16x32_bf16 v[82:85], v[158:161], v[210:213], v[82:85]
	v_mfma_f32_16x16x32_bf16 v[126:129], v[154:157], v[186:189], v[126:129]
	v_mfma_f32_16x16x32_bf16 v[122:125], v[162:165], v[186:189], v[122:125]
	v_mfma_f32_16x16x32_bf16 v[118:121], v[154:157], v[194:197], v[118:121]
	v_mfma_f32_16x16x32_bf16 v[114:117], v[162:165], v[194:197], v[114:117]
	v_mfma_f32_16x16x32_bf16 v[102:105], v[154:157], v[206:209], v[102:105]
	v_mfma_f32_16x16x32_bf16 v[98:101], v[162:165], v[206:209], v[98:101]
	v_mfma_f32_16x16x32_bf16 v[86:89], v[154:157], v[214:217], v[86:89]
	v_mfma_f32_16x16x32_bf16 v[82:85], v[162:165], v[214:217], v[82:85]
	v_mfma_f32_16x16x32_bf16 v[110:113], v[166:169], v[182:185], v[110:113]
	v_mfma_f32_16x16x32_bf16 v[106:109], v[174:177], v[182:185], v[106:109]
	v_mfma_f32_16x16x32_bf16 v[94:97], v[166:169], v[190:193], v[94:97]
	v_mfma_f32_16x16x32_bf16 v[90:93], v[174:177], v[190:193], v[90:93]
	v_mfma_f32_16x16x32_bf16 v[78:81], v[166:169], v[198:201], v[78:81]
	v_mfma_f32_16x16x32_bf16 v[74:77], v[174:177], v[198:201], v[74:77]
	v_mfma_f32_16x16x32_bf16 v[70:73], v[166:169], v[210:213], v[70:73]
	v_mfma_f32_16x16x32_bf16 v[66:69], v[174:177], v[210:213], v[66:69]
	v_mfma_f32_16x16x32_bf16 v[110:113], v[170:173], v[186:189], v[110:113]
	v_mfma_f32_16x16x32_bf16 v[106:109], v[178:181], v[186:189], v[106:109]
	v_mfma_f32_16x16x32_bf16 v[94:97], v[170:173], v[194:197], v[94:97]
	v_mfma_f32_16x16x32_bf16 v[90:93], v[178:181], v[194:197], v[90:93]
	v_mfma_f32_16x16x32_bf16 v[78:81], v[170:173], v[206:209], v[78:81]
	v_mfma_f32_16x16x32_bf16 v[74:77], v[178:181], v[206:209], v[74:77]
	v_mfma_f32_16x16x32_bf16 v[70:73], v[170:173], v[214:217], v[70:73]
	v_mfma_f32_16x16x32_bf16 v[66:69], v[178:181], v[214:217], v[66:69]
	s_setprio 0
	s_barrier
	ds_read_b128 v[182:185], v148 offset:49152
	ds_read_b128 v[186:189], v148 offset:50176
	ds_read_b128 v[190:193], v148 offset:51200
	ds_read_b128 v[194:197], v148 offset:52224
	ds_read_b128 v[198:201], v148 offset:53248
	ds_read_b128 v[206:209], v148 offset:54272
	ds_read_b128 v[210:213], v148 offset:55296
	ds_read_b128 v[214:217], v148 offset:56320
	s_mov_b32 m0, s77
	v_lshl_add_u64 v[202:203], v[202:203], 0, s[8:9]
	global_load_lds_dwordx4 v[202:203], off
	s_mov_b32 m0, s75
	v_lshl_add_u64 v[202:203], v[218:219], 0, s[8:9]
	global_load_lds_dwordx4 v[202:203], off
	s_mov_b32 m0, s76
	v_lshl_add_u64 v[202:203], s[44:45], 0, v[136:137]
	global_load_lds_dwordx4 v[202:203], off
	s_mov_b32 m0, s74
	v_lshl_add_u64 v[202:203], s[44:45], 0, v[134:135]
	global_load_lds_dwordx4 v[202:203], off
	s_mov_b32 m0, s28
	v_lshl_add_u64 v[202:203], v[220:221], 0, s[8:9]
	global_load_lds_dwordx4 v[202:203], off
	s_mov_b32 m0, s29
	v_lshl_add_u64 v[202:203], v[222:223], 0, s[8:9]
	global_load_lds_dwordx4 v[202:203], off
	s_waitcnt vmcnt(8) lgkmcnt(0)
	s_setprio 1
	s_barrier
	v_mfma_f32_16x16x32_bf16 v[62:65], v[150:153], v[182:185], v[62:65]
	v_mfma_f32_16x16x32_bf16 v[58:61], v[158:161], v[182:185], v[58:61]
	v_mfma_f32_16x16x32_bf16 v[54:57], v[150:153], v[190:193], v[54:57]
	v_mfma_f32_16x16x32_bf16 v[50:53], v[158:161], v[190:193], v[50:53]
	v_mfma_f32_16x16x32_bf16 v[38:41], v[150:153], v[198:201], v[38:41]
	v_mfma_f32_16x16x32_bf16 v[34:37], v[158:161], v[198:201], v[34:37]
	v_mfma_f32_16x16x32_bf16 v[22:25], v[150:153], v[210:213], v[22:25]
	v_mfma_f32_16x16x32_bf16 v[18:21], v[158:161], v[210:213], v[18:21]
	v_mfma_f32_16x16x32_bf16 v[62:65], v[154:157], v[186:189], v[62:65]
	v_mfma_f32_16x16x32_bf16 v[58:61], v[162:165], v[186:189], v[58:61]
	v_mfma_f32_16x16x32_bf16 v[54:57], v[154:157], v[194:197], v[54:57]
	v_mfma_f32_16x16x32_bf16 v[50:53], v[162:165], v[194:197], v[50:53]
	v_mfma_f32_16x16x32_bf16 v[38:41], v[154:157], v[206:209], v[38:41]
	v_mfma_f32_16x16x32_bf16 v[34:37], v[162:165], v[206:209], v[34:37]
	v_mfma_f32_16x16x32_bf16 v[22:25], v[154:157], v[214:217], v[22:25]
	v_mfma_f32_16x16x32_bf16 v[18:21], v[162:165], v[214:217], v[18:21]
	v_mfma_f32_16x16x32_bf16 v[46:49], v[166:169], v[182:185], v[46:49]
	v_mfma_f32_16x16x32_bf16 v[42:45], v[174:177], v[182:185], v[42:45]
	v_mfma_f32_16x16x32_bf16 v[30:33], v[166:169], v[190:193], v[30:33]
	v_mfma_f32_16x16x32_bf16 v[26:29], v[174:177], v[190:193], v[26:29]
	v_mfma_f32_16x16x32_bf16 v[14:17], v[166:169], v[198:201], v[14:17]
	v_mfma_f32_16x16x32_bf16 v[10:13], v[174:177], v[198:201], v[10:13]
	v_mfma_f32_16x16x32_bf16 v[6:9], v[166:169], v[210:213], v[6:9]
	v_mfma_f32_16x16x32_bf16 v[2:5], v[174:177], v[210:213], v[2:5]
	v_mfma_f32_16x16x32_bf16 v[46:49], v[170:173], v[186:189], v[46:49]
	v_mfma_f32_16x16x32_bf16 v[42:45], v[178:181], v[186:189], v[42:45]
	v_mfma_f32_16x16x32_bf16 v[30:33], v[170:173], v[194:197], v[30:33]
	v_mfma_f32_16x16x32_bf16 v[26:29], v[178:181], v[194:197], v[26:29]
	v_mfma_f32_16x16x32_bf16 v[14:17], v[170:173], v[206:209], v[14:17]
	v_mfma_f32_16x16x32_bf16 v[10:13], v[178:181], v[206:209], v[10:13]
	v_mfma_f32_16x16x32_bf16 v[6:9], v[170:173], v[214:217], v[6:9]
	v_mfma_f32_16x16x32_bf16 v[2:5], v[178:181], v[214:217], v[2:5]
	s_setprio 0
	s_barrier
	s_movk_i32 s46, 0x100
	s_andn2_b64 vcc, exec, s[42:43]
	s_mov_b64 s[44:45], -1
	s_mov_b64 s[42:43], 0
	s_cbranch_vccz .LBB0_297
	s_and_b64 vcc, exec, s[10:11]
	s_cbranch_vccz .LBB0_300
	s_barrier

.LBB0_313:
	ds_read_b128 v[144:147], v140
	ds_read_b128 v[148:151], v140 offset:1024
	ds_read_b128 v[152:155], v140 offset:2048
	ds_read_b128 v[156:159], v140 offset:3072
	ds_read_b128 v[160:163], v141
	ds_read_b128 v[164:167], v141 offset:1024
	ds_read_b128 v[168:171], v141 offset:2048
	ds_read_b128 v[172:175], v141 offset:3072
	ds_read_b128 v[176:179], v142
	ds_read_b128 v[180:183], v142 offset:1024
	ds_read_b128 v[184:187], v142 offset:2048
	ds_read_b128 v[188:191], v142 offset:3072
	ds_read_b128 v[192:195], v142 offset:4096
	ds_read_b128 v[196:199], v142 offset:5120
	ds_read_b128 v[200:203], v142 offset:6144
	ds_read_b128 v[206:209], v142 offset:7168
	s_add_u32 s49, s38, s48
	s_addc_u32 s68, s39, 0
	s_add_u32 s66, s49, 0x100
	s_addc_u32 s67, s68, 0
	s_and_b64 s[64:65], s[46:47], exec
	s_cselect_b32 s65, s43, s67
	s_cselect_b32 s64, s75, s66
	s_add_u32 s48, s36, s48
	s_addc_u32 s66, s37, 0
	s_add_u32 s48, s48, 0x100
	s_addc_u32 s66, s66, 0
	s_and_b64 s[46:47], s[46:47], exec
	s_cselect_b32 s67, s76, s66
	s_cselect_b32 s66, s77, s48
	s_add_u32 s70, s49, 0x10080
	s_addc_u32 s71, s68, 0
	s_add_i32 s87, s33, s2
	s_add_i32 m0, s16, 0xc000
	s_add_i32 s88, s16, 0xe000
	s_add_i32 s84, s87, 0x2000
	s_add_u32 s68, s66, 0x1000
	s_addc_u32 s69, s67, 0
	s_add_i32 s86, s34, s2
	s_add_i32 s85, s86, 0x2000
	s_add_i32 s83, 0, 0x18000
	s_add_i32 s82, 0, 0x1c000
	s_add_u32 s48, s64, 0x10000
	s_addc_u32 s49, s65, 0
	s_add_i32 s81, s83, s2
	s_add_i32 s79, s81, 0x2000
	s_add_u32 s46, s66, 0x1080
	s_addc_u32 s47, s67, 0
	s_add_i32 s80, s82, s2
	s_add_i32 s78, s80, 0x2000
	v_lshl_add_u64 v[210:211], s[70:71], 0, v[130:131]
	global_load_lds_dwordx4 v[210:211], off
	s_mov_b32 m0, s88
	v_lshl_add_u64 v[210:211], s[70:71], 0, v[132:133]
	global_load_lds_dwordx4 v[210:211], off
	s_waitcnt vmcnt(8) lgkmcnt(0)
	s_setprio 1
	s_barrier
	v_mfma_f32_16x16x32_bf16 v[126:129], v[144:147], v[176:179], v[126:129]
	v_mfma_f32_16x16x32_bf16 v[122:125], v[152:155], v[176:179], v[122:125]
	v_mfma_f32_16x16x32_bf16 v[118:121], v[144:147], v[184:187], v[118:121]
	v_mfma_f32_16x16x32_bf16 v[114:117], v[152:155], v[184:187], v[114:117]
	v_mfma_f32_16x16x32_bf16 v[102:105], v[144:147], v[192:195], v[102:105]
	v_mfma_f32_16x16x32_bf16 v[98:101], v[152:155], v[192:195], v[98:101]
	v_mfma_f32_16x16x32_bf16 v[86:89], v[144:147], v[200:203], v[86:89]
	v_mfma_f32_16x16x32_bf16 v[82:85], v[152:155], v[200:203], v[82:85]
	v_mfma_f32_16x16x32_bf16 v[126:129], v[148:151], v[180:183], v[126:129]
	v_mfma_f32_16x16x32_bf16 v[122:125], v[156:159], v[180:183], v[122:125]
	v_mfma_f32_16x16x32_bf16 v[118:121], v[148:151], v[188:191], v[118:121]
	v_mfma_f32_16x16x32_bf16 v[114:117], v[156:159], v[188:191], v[114:117]
	v_mfma_f32_16x16x32_bf16 v[102:105], v[148:151], v[196:199], v[102:105]
	v_mfma_f32_16x16x32_bf16 v[98:101], v[156:159], v[196:199], v[98:101]
	v_mfma_f32_16x16x32_bf16 v[86:89], v[148:151], v[206:209], v[86:89]
	v_mfma_f32_16x16x32_bf16 v[82:85], v[156:159], v[206:209], v[82:85]
	v_mfma_f32_16x16x32_bf16 v[110:113], v[160:163], v[176:179], v[110:113]
	v_mfma_f32_16x16x32_bf16 v[106:109], v[168:171], v[176:179], v[106:109]
	v_mfma_f32_16x16x32_bf16 v[94:97], v[160:163], v[184:187], v[94:97]
	v_mfma_f32_16x16x32_bf16 v[90:93], v[168:171], v[184:187], v[90:93]
	v_mfma_f32_16x16x32_bf16 v[78:81], v[160:163], v[192:195], v[78:81]
	v_mfma_f32_16x16x32_bf16 v[74:77], v[168:171], v[192:195], v[74:77]
	v_mfma_f32_16x16x32_bf16 v[70:73], v[160:163], v[200:203], v[70:73]
	v_mfma_f32_16x16x32_bf16 v[66:69], v[168:171], v[200:203], v[66:69]
	v_mfma_f32_16x16x32_bf16 v[110:113], v[164:167], v[180:183], v[110:113]
	v_mfma_f32_16x16x32_bf16 v[106:109], v[172:175], v[180:183], v[106:109]
	v_mfma_f32_16x16x32_bf16 v[94:97], v[164:167], v[188:191], v[94:97]
	v_mfma_f32_16x16x32_bf16 v[90:93], v[172:175], v[188:191], v[90:93]
	v_mfma_f32_16x16x32_bf16 v[78:81], v[164:167], v[196:199], v[78:81]
	v_mfma_f32_16x16x32_bf16 v[74:77], v[172:175], v[196:199], v[74:77]
	v_mfma_f32_16x16x32_bf16 v[70:73], v[164:167], v[206:209], v[70:73]
	v_mfma_f32_16x16x32_bf16 v[66:69], v[172:175], v[206:209], v[66:69]
	s_setprio 0
	s_barrier
	ds_read_b128 v[176:179], v142 offset:16384
	ds_read_b128 v[180:183], v142 offset:17408
	ds_read_b128 v[184:187], v142 offset:18432
	ds_read_b128 v[188:191], v142 offset:19456
	ds_read_b128 v[192:195], v142 offset:20480
	ds_read_b128 v[196:199], v142 offset:21504
	ds_read_b128 v[200:203], v142 offset:22528
	ds_read_b128 v[206:209], v142 offset:23552
	s_mov_b32 m0, s87
	v_lshl_add_u64 v[210:211], s[66:67], 0, v[136:137]
	global_load_lds_dwordx4 v[210:211], off
	v_lshl_add_u64 v[212:213], s[66:67], 0, v[134:135]
	s_mov_b32 m0, s84
	v_lshl_add_u64 v[214:215], s[68:69], 0, v[136:137]
	global_load_lds_dwordx4 v[212:213], off
	s_mov_b32 m0, s86
	v_lshl_add_u64 v[216:217], s[64:65], 0, v[132:133]
	global_load_lds_dwordx4 v[214:215], off
	s_mov_b32 m0, s85
	v_lshl_add_u64 v[214:215], s[68:69], 0, v[134:135]
	global_load_lds_dwordx4 v[214:215], off
	s_mov_b32 m0, s16
	v_lshl_add_u64 v[214:215], s[64:65], 0, v[130:131]
	global_load_lds_dwordx4 v[214:215], off
	s_mov_b32 m0, s17
	s_nop 0
	global_load_lds_dwordx4 v[216:217], off
	s_waitcnt vmcnt(8) lgkmcnt(0)
	s_setprio 1
	s_barrier
	v_mfma_f32_16x16x32_bf16 v[62:65], v[144:147], v[176:179], v[62:65]
	v_mfma_f32_16x16x32_bf16 v[58:61], v[152:155], v[176:179], v[58:61]
	v_mfma_f32_16x16x32_bf16 v[54:57], v[144:147], v[184:187], v[54:57]
	v_mfma_f32_16x16x32_bf16 v[50:53], v[152:155], v[184:187], v[50:53]
	v_mfma_f32_16x16x32_bf16 v[38:41], v[144:147], v[192:195], v[38:41]
	v_mfma_f32_16x16x32_bf16 v[34:37], v[152:155], v[192:195], v[34:37]
	v_mfma_f32_16x16x32_bf16 v[22:25], v[144:147], v[200:203], v[22:25]
	v_mfma_f32_16x16x32_bf16 v[18:21], v[152:155], v[200:203], v[18:21]
	v_mfma_f32_16x16x32_bf16 v[62:65], v[148:151], v[180:183], v[62:65]
	v_mfma_f32_16x16x32_bf16 v[58:61], v[156:159], v[180:183], v[58:61]
	v_mfma_f32_16x16x32_bf16 v[54:57], v[148:151], v[188:191], v[54:57]
	v_mfma_f32_16x16x32_bf16 v[50:53], v[156:159], v[188:191], v[50:53]
	v_mfma_f32_16x16x32_bf16 v[38:41], v[148:151], v[196:199], v[38:41]
	v_mfma_f32_16x16x32_bf16 v[34:37], v[156:159], v[196:199], v[34:37]
	v_mfma_f32_16x16x32_bf16 v[22:25], v[148:151], v[206:209], v[22:25]
	v_mfma_f32_16x16x32_bf16 v[18:21], v[156:159], v[206:209], v[18:21]
	v_mfma_f32_16x16x32_bf16 v[46:49], v[160:163], v[176:179], v[46:49]
	v_mfma_f32_16x16x32_bf16 v[42:45], v[168:171], v[176:179], v[42:45]
	v_mfma_f32_16x16x32_bf16 v[30:33], v[160:163], v[184:187], v[30:33]
	v_mfma_f32_16x16x32_bf16 v[26:29], v[168:171], v[184:187], v[26:29]
	v_mfma_f32_16x16x32_bf16 v[14:17], v[160:163], v[192:195], v[14:17]
	v_mfma_f32_16x16x32_bf16 v[10:13], v[168:171], v[192:195], v[10:13]
	v_mfma_f32_16x16x32_bf16 v[6:9], v[160:163], v[200:203], v[6:9]
	v_mfma_f32_16x16x32_bf16 v[2:5], v[168:171], v[200:203], v[2:5]
	v_mfma_f32_16x16x32_bf16 v[46:49], v[164:167], v[180:183], v[46:49]
	v_mfma_f32_16x16x32_bf16 v[42:45], v[172:175], v[180:183], v[42:45]
	v_mfma_f32_16x16x32_bf16 v[30:33], v[164:167], v[188:191], v[30:33]
	v_mfma_f32_16x16x32_bf16 v[26:29], v[172:175], v[188:191], v[26:29]
	v_mfma_f32_16x16x32_bf16 v[14:17], v[164:167], v[196:199], v[14:17]
	v_mfma_f32_16x16x32_bf16 v[10:13], v[172:175], v[196:199], v[10:13]
	v_mfma_f32_16x16x32_bf16 v[6:9], v[164:167], v[206:209], v[6:9]
	v_mfma_f32_16x16x32_bf16 v[2:5], v[172:175], v[206:209], v[2:5]
	s_setprio 0
	s_barrier
	v_add_u32_e32 v143, s83, v139
	ds_read_b128 v[144:147], v143
	ds_read_b128 v[148:151], v143 offset:1024
	ds_read_b128 v[152:155], v143 offset:2048
	ds_read_b128 v[156:159], v143 offset:3072
	v_add_u32_e32 v143, s82, v139
	ds_read_b128 v[160:163], v143
	ds_read_b128 v[164:167], v143 offset:1024
	ds_read_b128 v[168:171], v143 offset:2048
	ds_read_b128 v[172:175], v143 offset:3072
	s_mov_b32 m0, s18
	v_lshl_add_u64 v[218:219], s[48:49], 0, v[130:131]
	ds_read_b128 v[176:179], v142 offset:32768
	ds_read_b128 v[180:183], v142 offset:33792
	ds_read_b128 v[184:187], v142 offset:34816
	ds_read_b128 v[188:191], v142 offset:35840
	ds_read_b128 v[192:195], v142 offset:36864
	ds_read_b128 v[196:199], v142 offset:37888
	ds_read_b128 v[200:203], v142 offset:38912
	ds_read_b128 v[206:209], v142 offset:39936
	global_load_lds_dwordx4 v[218:219], off
	s_mov_b32 m0, s19
	v_lshl_add_u64 v[218:219], s[48:49], 0, v[132:133]
	global_load_lds_dwordx4 v[218:219], off
	s_waitcnt vmcnt(8) lgkmcnt(0)
	s_setprio 1
	s_barrier
	v_mfma_f32_16x16x32_bf16 v[126:129], v[144:147], v[176:179], v[126:129]
	v_mfma_f32_16x16x32_bf16 v[122:125], v[152:155], v[176:179], v[122:125]
	v_mfma_f32_16x16x32_bf16 v[118:121], v[144:147], v[184:187], v[118:121]
	v_mfma_f32_16x16x32_bf16 v[114:117], v[152:155], v[184:187], v[114:117]
	v_mfma_f32_16x16x32_bf16 v[102:105], v[144:147], v[192:195], v[102:105]
	v_mfma_f32_16x16x32_bf16 v[98:101], v[152:155], v[192:195], v[98:101]
	v_mfma_f32_16x16x32_bf16 v[86:89], v[144:147], v[200:203], v[86:89]
	v_mfma_f32_16x16x32_bf16 v[82:85], v[152:155], v[200:203], v[82:85]
	v_mfma_f32_16x16x32_bf16 v[126:129], v[148:151], v[180:183], v[126:129]
	v_mfma_f32_16x16x32_bf16 v[122:125], v[156:159], v[180:183], v[122:125]
	v_mfma_f32_16x16x32_bf16 v[118:121], v[148:151], v[188:191], v[118:121]
	v_mfma_f32_16x16x32_bf16 v[114:117], v[156:159], v[188:191], v[114:117]
	v_mfma_f32_16x16x32_bf16 v[102:105], v[148:151], v[196:199], v[102:105]
	v_mfma_f32_16x16x32_bf16 v[98:101], v[156:159], v[196:199], v[98:101]
	v_mfma_f32_16x16x32_bf16 v[86:89], v[148:151], v[206:209], v[86:89]
	v_mfma_f32_16x16x32_bf16 v[82:85], v[156:159], v[206:209], v[82:85]
	v_mfma_f32_16x16x32_bf16 v[110:113], v[160:163], v[176:179], v[110:113]
	v_mfma_f32_16x16x32_bf16 v[106:109], v[168:171], v[176:179], v[106:109]
	v_mfma_f32_16x16x32_bf16 v[94:97], v[160:163], v[184:187], v[94:97]
	v_mfma_f32_16x16x32_bf16 v[90:93], v[168:171], v[184:187], v[90:93]
	v_mfma_f32_16x16x32_bf16 v[78:81], v[160:163], v[192:195], v[78:81]
	v_mfma_f32_16x16x32_bf16 v[74:77], v[168:171], v[192:195], v[74:77]
	v_mfma_f32_16x16x32_bf16 v[70:73], v[160:163], v[200:203], v[70:73]
	v_mfma_f32_16x16x32_bf16 v[66:69], v[168:171], v[200:203], v[66:69]
	v_mfma_f32_16x16x32_bf16 v[110:113], v[164:167], v[180:183], v[110:113]
	v_mfma_f32_16x16x32_bf16 v[106:109], v[172:175], v[180:183], v[106:109]
	v_mfma_f32_16x16x32_bf16 v[94:97], v[164:167], v[188:191], v[94:97]
	v_mfma_f32_16x16x32_bf16 v[90:93], v[172:175], v[188:191], v[90:93]
	v_mfma_f32_16x16x32_bf16 v[78:81], v[164:167], v[196:199], v[78:81]
	v_mfma_f32_16x16x32_bf16 v[74:77], v[172:175], v[196:199], v[74:77]
	v_mfma_f32_16x16x32_bf16 v[70:73], v[164:167], v[206:209], v[70:73]
	v_mfma_f32_16x16x32_bf16 v[66:69], v[172:175], v[206:209], v[66:69]
	s_setprio 0
	s_barrier
	ds_read_b128 v[176:179], v142 offset:49152
	ds_read_b128 v[180:183], v142 offset:50176
	ds_read_b128 v[184:187], v142 offset:51200
	ds_read_b128 v[188:191], v142 offset:52224
	ds_read_b128 v[192:195], v142 offset:53248
	ds_read_b128 v[196:199], v142 offset:54272
	ds_read_b128 v[200:203], v142 offset:55296
	ds_read_b128 v[206:209], v142 offset:56320
	s_mov_b32 m0, s81
	v_lshl_add_u64 v[210:211], v[210:211], 0, s[8:9]
	global_load_lds_dwordx4 v[210:211], off
	s_mov_b32 m0, s79
	v_lshl_add_u64 v[210:211], v[212:213], 0, s[8:9]
	global_load_lds_dwordx4 v[210:211], off
	s_mov_b32 m0, s80
	v_lshl_add_u64 v[210:211], s[46:47], 0, v[136:137]
	global_load_lds_dwordx4 v[210:211], off
	s_mov_b32 m0, s78
	v_lshl_add_u64 v[210:211], s[46:47], 0, v[134:135]
	global_load_lds_dwordx4 v[210:211], off
	s_mov_b32 m0, s30
	v_lshl_add_u64 v[210:211], v[214:215], 0, s[8:9]
	global_load_lds_dwordx4 v[210:211], off
	s_mov_b32 m0, s31
	v_lshl_add_u64 v[210:211], v[216:217], 0, s[8:9]
	global_load_lds_dwordx4 v[210:211], off
	s_waitcnt vmcnt(8) lgkmcnt(0)
	s_setprio 1
	s_barrier
	v_mfma_f32_16x16x32_bf16 v[62:65], v[144:147], v[176:179], v[62:65]
	v_mfma_f32_16x16x32_bf16 v[58:61], v[152:155], v[176:179], v[58:61]
	v_mfma_f32_16x16x32_bf16 v[54:57], v[144:147], v[184:187], v[54:57]
	v_mfma_f32_16x16x32_bf16 v[50:53], v[152:155], v[184:187], v[50:53]
	v_mfma_f32_16x16x32_bf16 v[38:41], v[144:147], v[192:195], v[38:41]
	v_mfma_f32_16x16x32_bf16 v[34:37], v[152:155], v[192:195], v[34:37]
	v_mfma_f32_16x16x32_bf16 v[22:25], v[144:147], v[200:203], v[22:25]
	v_mfma_f32_16x16x32_bf16 v[18:21], v[152:155], v[200:203], v[18:21]
	v_mfma_f32_16x16x32_bf16 v[62:65], v[148:151], v[180:183], v[62:65]
	v_mfma_f32_16x16x32_bf16 v[58:61], v[156:159], v[180:183], v[58:61]
	v_mfma_f32_16x16x32_bf16 v[54:57], v[148:151], v[188:191], v[54:57]
	v_mfma_f32_16x16x32_bf16 v[50:53], v[156:159], v[188:191], v[50:53]
	v_mfma_f32_16x16x32_bf16 v[38:41], v[148:151], v[196:199], v[38:41]
	v_mfma_f32_16x16x32_bf16 v[34:37], v[156:159], v[196:199], v[34:37]
	v_mfma_f32_16x16x32_bf16 v[22:25], v[148:151], v[206:209], v[22:25]
	v_mfma_f32_16x16x32_bf16 v[18:21], v[156:159], v[206:209], v[18:21]
	v_mfma_f32_16x16x32_bf16 v[46:49], v[160:163], v[176:179], v[46:49]
	v_mfma_f32_16x16x32_bf16 v[42:45], v[168:171], v[176:179], v[42:45]
	v_mfma_f32_16x16x32_bf16 v[30:33], v[160:163], v[184:187], v[30:33]
	v_mfma_f32_16x16x32_bf16 v[26:29], v[168:171], v[184:187], v[26:29]
	v_mfma_f32_16x16x32_bf16 v[14:17], v[160:163], v[192:195], v[14:17]
	v_mfma_f32_16x16x32_bf16 v[10:13], v[168:171], v[192:195], v[10:13]
	v_mfma_f32_16x16x32_bf16 v[6:9], v[160:163], v[200:203], v[6:9]
	v_mfma_f32_16x16x32_bf16 v[2:5], v[168:171], v[200:203], v[2:5]
	v_mfma_f32_16x16x32_bf16 v[46:49], v[164:167], v[180:183], v[46:49]
	v_mfma_f32_16x16x32_bf16 v[42:45], v[172:175], v[180:183], v[42:45]
	v_mfma_f32_16x16x32_bf16 v[30:33], v[164:167], v[188:191], v[30:33]
	v_mfma_f32_16x16x32_bf16 v[26:29], v[172:175], v[188:191], v[26:29]
	v_mfma_f32_16x16x32_bf16 v[14:17], v[164:167], v[196:199], v[14:17]
	v_mfma_f32_16x16x32_bf16 v[10:13], v[172:175], v[196:199], v[10:13]
	v_mfma_f32_16x16x32_bf16 v[6:9], v[164:167], v[206:209], v[6:9]
	v_mfma_f32_16x16x32_bf16 v[2:5], v[172:175], v[206:209], v[2:5]
	s_setprio 0
	s_barrier
	s_movk_i32 s48, 0x100
	s_andn2_b64 vcc, exec, s[44:45]
	s_mov_b64 s[46:47], -1
	s_mov_b64 s[44:45], 0
	s_cbranch_vccz .LBB0_313
	s_and_b64 vcc, exec, s[10:11]
	s_cbranch_vccz .LBB0_316
	s_barrier

.LBB0_383:
	s_add_u32 s26, s0, s22
	s_addc_u32 s27, s1, s23
	s_and_b64 s[44:45], s[36:37], exec
	s_cselect_b32 s15, s27, s43
	s_cselect_b32 s39, s26, s42
	s_add_u32 s66, s42, 0x100
	s_addc_u32 s67, s43, 0
	s_mov_b32 s68, -2
	s_mov_b64 s[42:43], 0
	ds_read_b128 v[152:155], v146
	ds_read_b128 v[156:159], v146 offset:1024
	ds_read_b128 v[160:163], v146 offset:2048
	ds_read_b128 v[164:167], v146 offset:3072
	ds_read_b128 v[168:171], v147
	ds_read_b128 v[172:175], v147 offset:1024
	ds_read_b128 v[176:179], v147 offset:2048
	ds_read_b128 v[180:183], v147 offset:3072
	ds_read_b128 v[184:187], v148
	ds_read_b128 v[188:191], v148 offset:1024
	ds_read_b128 v[192:195], v148 offset:2048
	ds_read_b128 v[196:199], v148 offset:3072
	ds_read_b128 v[200:203], v148 offset:4096
	ds_read_b128 v[206:209], v148 offset:5120
	ds_read_b128 v[210:213], v148 offset:6144
	ds_read_b128 v[214:217], v148 offset:7168
	s_add_u32 s44, s42, 0x100
	s_addc_u32 s45, s43, 0
	s_add_u32 s46, s66, s42
	s_addc_u32 s47, s67, s43
	s_cmp_eq_u32 s68, 4
	s_cselect_b32 s48, 0, s44
	s_cselect_b32 s49, 0, s45
	s_cselect_b32 s46, s39, s46
	s_cselect_b32 s47, s15, s47
	s_add_u32 s48, s6, s48
	s_addc_u32 s49, s7, s49
	s_mov_b32 m0, s29
	v_lshl_add_u64 v[218:219], v[138:139], 0, s[42:43]
	global_load_lds_dwordx4 v[218:219], off
	s_mov_b32 m0, s30
	v_lshl_add_u64 v[218:219], v[140:141], 0, s[42:43]
	global_load_lds_dwordx4 v[218:219], off
	s_waitcnt vmcnt(8) lgkmcnt(0)
	s_setprio 1
	s_barrier
	v_mfma_f32_16x16x32_bf16 v[126:129], v[152:155], v[184:187], 0
	v_mfma_f32_16x16x32_bf16 v[122:125], v[160:163], v[184:187], 0
	v_mfma_f32_16x16x32_bf16 v[118:121], v[152:155], v[192:195], 0
	v_mfma_f32_16x16x32_bf16 v[114:117], v[160:163], v[192:195], 0
	v_mfma_f32_16x16x32_bf16 v[102:105], v[152:155], v[200:203], 0
	v_mfma_f32_16x16x32_bf16 v[98:101], v[160:163], v[200:203], 0
	v_mfma_f32_16x16x32_bf16 v[86:89], v[152:155], v[210:213], 0
	v_mfma_f32_16x16x32_bf16 v[82:85], v[160:163], v[210:213], 0
	v_mfma_f32_16x16x32_bf16 v[126:129], v[156:159], v[188:191], v[126:129]
	v_mfma_f32_16x16x32_bf16 v[122:125], v[164:167], v[188:191], v[122:125]
	v_mfma_f32_16x16x32_bf16 v[118:121], v[156:159], v[196:199], v[118:121]
	v_mfma_f32_16x16x32_bf16 v[114:117], v[164:167], v[196:199], v[114:117]
	v_mfma_f32_16x16x32_bf16 v[102:105], v[156:159], v[206:209], v[102:105]
	v_mfma_f32_16x16x32_bf16 v[98:101], v[164:167], v[206:209], v[98:101]
	v_mfma_f32_16x16x32_bf16 v[86:89], v[156:159], v[214:217], v[86:89]
	v_mfma_f32_16x16x32_bf16 v[82:85], v[164:167], v[214:217], v[82:85]
	v_mfma_f32_16x16x32_bf16 v[110:113], v[168:171], v[184:187], 0
	v_mfma_f32_16x16x32_bf16 v[106:109], v[176:179], v[184:187], 0
	v_mfma_f32_16x16x32_bf16 v[94:97], v[168:171], v[192:195], 0
	v_mfma_f32_16x16x32_bf16 v[90:93], v[176:179], v[192:195], 0
	v_mfma_f32_16x16x32_bf16 v[78:81], v[168:171], v[200:203], 0
	v_mfma_f32_16x16x32_bf16 v[74:77], v[176:179], v[200:203], 0
	v_mfma_f32_16x16x32_bf16 v[70:73], v[168:171], v[210:213], 0
	v_mfma_f32_16x16x32_bf16 v[66:69], v[176:179], v[210:213], 0
	v_mfma_f32_16x16x32_bf16 v[110:113], v[172:175], v[188:191], v[110:113]
	v_mfma_f32_16x16x32_bf16 v[106:109], v[180:183], v[188:191], v[106:109]
	v_mfma_f32_16x16x32_bf16 v[94:97], v[172:175], v[196:199], v[94:97]
	v_mfma_f32_16x16x32_bf16 v[90:93], v[180:183], v[196:199], v[90:93]
	v_mfma_f32_16x16x32_bf16 v[78:81], v[172:175], v[206:209], v[78:81]
	v_mfma_f32_16x16x32_bf16 v[74:77], v[180:183], v[206:209], v[74:77]
	v_mfma_f32_16x16x32_bf16 v[70:73], v[172:175], v[214:217], v[70:73]
	v_mfma_f32_16x16x32_bf16 v[66:69], v[180:183], v[214:217], v[66:69]
	s_setprio 0
	s_barrier
	ds_read_b128 v[184:187], v148 offset:16384
	ds_read_b128 v[188:191], v148 offset:17408
	ds_read_b128 v[192:195], v148 offset:18432
	ds_read_b128 v[196:199], v148 offset:19456
	ds_read_b128 v[200:203], v148 offset:20480
	ds_read_b128 v[206:209], v148 offset:21504
	ds_read_b128 v[210:213], v148 offset:22528
	ds_read_b128 v[214:217], v148 offset:23552
	s_mov_b32 m0, s31
	v_lshl_add_u64 v[218:219], s[46:47], 0, v[134:135]
	s_add_u32 s42, s46, 0x20000
	global_load_lds_dwordx4 v[218:219], off
	v_lshl_add_u64 v[220:221], s[46:47], 0, v[130:131]
	s_mov_b32 m0, s33
	s_addc_u32 s43, s47, 0
	global_load_lds_dwordx4 v[220:221], off
	v_lshl_add_u64 v[222:223], s[42:43], 0, v[134:135]
	s_mov_b32 m0, s34
	v_lshl_add_u64 v[224:225], s[48:49], 0, v[132:133]
	global_load_lds_dwordx4 v[222:223], off
	s_mov_b32 m0, s35
	v_lshl_add_u64 v[222:223], s[42:43], 0, v[130:131]
	global_load_lds_dwordx4 v[222:223], off
	s_mov_b32 m0, s2
	v_lshl_add_u64 v[222:223], s[48:49], 0, v[136:137]
	global_load_lds_dwordx4 v[222:223], off
	s_mov_b32 m0, s3
	s_nop 0
	global_load_lds_dwordx4 v[224:225], off
	s_waitcnt vmcnt(8) lgkmcnt(0)
	s_setprio 1
	s_barrier
	v_mfma_f32_16x16x32_bf16 v[62:65], v[152:155], v[184:187], 0
	v_mfma_f32_16x16x32_bf16 v[58:61], v[160:163], v[184:187], 0
	v_mfma_f32_16x16x32_bf16 v[54:57], v[152:155], v[192:195], 0
	v_mfma_f32_16x16x32_bf16 v[50:53], v[160:163], v[192:195], 0
	v_mfma_f32_16x16x32_bf16 v[38:41], v[152:155], v[200:203], 0
	v_mfma_f32_16x16x32_bf16 v[34:37], v[160:163], v[200:203], 0
	v_mfma_f32_16x16x32_bf16 v[22:25], v[152:155], v[210:213], 0
	v_mfma_f32_16x16x32_bf16 v[18:21], v[160:163], v[210:213], 0
	v_mfma_f32_16x16x32_bf16 v[62:65], v[156:159], v[188:191], v[62:65]
	v_mfma_f32_16x16x32_bf16 v[58:61], v[164:167], v[188:191], v[58:61]
	v_mfma_f32_16x16x32_bf16 v[54:57], v[156:159], v[196:199], v[54:57]
	v_mfma_f32_16x16x32_bf16 v[50:53], v[164:167], v[196:199], v[50:53]
	v_mfma_f32_16x16x32_bf16 v[38:41], v[156:159], v[206:209], v[38:41]
	v_mfma_f32_16x16x32_bf16 v[34:37], v[164:167], v[206:209], v[34:37]
	v_mfma_f32_16x16x32_bf16 v[22:25], v[156:159], v[214:217], v[22:25]
	v_mfma_f32_16x16x32_bf16 v[18:21], v[164:167], v[214:217], v[18:21]
	v_mfma_f32_16x16x32_bf16 v[46:49], v[168:171], v[184:187], 0
	v_mfma_f32_16x16x32_bf16 v[42:45], v[176:179], v[184:187], 0
	v_mfma_f32_16x16x32_bf16 v[30:33], v[168:171], v[192:195], 0
	v_mfma_f32_16x16x32_bf16 v[26:29], v[176:179], v[192:195], 0
	v_mfma_f32_16x16x32_bf16 v[14:17], v[168:171], v[200:203], 0
	v_mfma_f32_16x16x32_bf16 v[10:13], v[176:179], v[200:203], 0
	v_mfma_f32_16x16x32_bf16 v[6:9], v[168:171], v[210:213], 0
	v_mfma_f32_16x16x32_bf16 v[2:5], v[176:179], v[210:213], 0
	v_mfma_f32_16x16x32_bf16 v[46:49], v[172:175], v[188:191], v[46:49]
	v_mfma_f32_16x16x32_bf16 v[42:45], v[180:183], v[188:191], v[42:45]
	v_mfma_f32_16x16x32_bf16 v[30:33], v[172:175], v[196:199], v[30:33]
	v_mfma_f32_16x16x32_bf16 v[26:29], v[180:183], v[196:199], v[26:29]
	v_mfma_f32_16x16x32_bf16 v[14:17], v[172:175], v[206:209], v[14:17]
	v_mfma_f32_16x16x32_bf16 v[10:13], v[180:183], v[206:209], v[10:13]
	v_mfma_f32_16x16x32_bf16 v[6:9], v[172:175], v[214:217], v[6:9]
	v_mfma_f32_16x16x32_bf16 v[2:5], v[180:183], v[214:217], v[2:5]
	s_setprio 0
	s_barrier
	ds_read_b128 v[152:155], v149
	ds_read_b128 v[156:159], v149 offset:1024
	ds_read_b128 v[160:163], v149 offset:2048
	ds_read_b128 v[164:167], v149 offset:3072
	ds_read_b128 v[168:171], v150
	ds_read_b128 v[172:175], v150 offset:1024
	ds_read_b128 v[176:179], v150 offset:2048
	ds_read_b128 v[180:183], v150 offset:3072
	ds_read_b128 v[184:187], v148 offset:32768
	ds_read_b128 v[188:191], v148 offset:33792
	ds_read_b128 v[192:195], v148 offset:34816
	ds_read_b128 v[196:199], v148 offset:35840
	ds_read_b128 v[200:203], v148 offset:36864
	ds_read_b128 v[206:209], v148 offset:37888
	ds_read_b128 v[210:213], v148 offset:38912
	ds_read_b128 v[214:217], v148 offset:39936
	s_add_u32 s42, s48, 0x20000
	s_addc_u32 s43, s49, 0
	s_mov_b32 m0, s16
	v_lshl_add_u64 v[226:227], s[42:43], 0, v[136:137]
	global_load_lds_dwordx4 v[226:227], off
	s_mov_b32 m0, s17
	v_lshl_add_u64 v[226:227], s[42:43], 0, v[132:133]
	global_load_lds_dwordx4 v[226:227], off
	s_waitcnt vmcnt(8) lgkmcnt(0)
	s_setprio 1
	s_barrier
	v_mfma_f32_16x16x32_bf16 v[126:129], v[152:155], v[184:187], v[126:129]
	v_mfma_f32_16x16x32_bf16 v[122:125], v[160:163], v[184:187], v[122:125]
	v_mfma_f32_16x16x32_bf16 v[118:121], v[152:155], v[192:195], v[118:121]
	v_mfma_f32_16x16x32_bf16 v[114:117], v[160:163], v[192:195], v[114:117]
	v_mfma_f32_16x16x32_bf16 v[102:105], v[152:155], v[200:203], v[102:105]
	v_mfma_f32_16x16x32_bf16 v[98:101], v[160:163], v[200:203], v[98:101]
	v_mfma_f32_16x16x32_bf16 v[86:89], v[152:155], v[210:213], v[86:89]
	v_mfma_f32_16x16x32_bf16 v[82:85], v[160:163], v[210:213], v[82:85]
	v_mfma_f32_16x16x32_bf16 v[126:129], v[156:159], v[188:191], v[126:129]
	v_mfma_f32_16x16x32_bf16 v[122:125], v[164:167], v[188:191], v[122:125]
	v_mfma_f32_16x16x32_bf16 v[118:121], v[156:159], v[196:199], v[118:121]
	v_mfma_f32_16x16x32_bf16 v[114:117], v[164:167], v[196:199], v[114:117]
	v_mfma_f32_16x16x32_bf16 v[102:105], v[156:159], v[206:209], v[102:105]
	v_mfma_f32_16x16x32_bf16 v[98:101], v[164:167], v[206:209], v[98:101]
	v_mfma_f32_16x16x32_bf16 v[86:89], v[156:159], v[214:217], v[86:89]
	v_mfma_f32_16x16x32_bf16 v[82:85], v[164:167], v[214:217], v[82:85]
	v_mfma_f32_16x16x32_bf16 v[110:113], v[168:171], v[184:187], v[110:113]
	v_mfma_f32_16x16x32_bf16 v[106:109], v[176:179], v[184:187], v[106:109]
	v_mfma_f32_16x16x32_bf16 v[94:97], v[168:171], v[192:195], v[94:97]
	v_mfma_f32_16x16x32_bf16 v[90:93], v[176:179], v[192:195], v[90:93]
	v_mfma_f32_16x16x32_bf16 v[78:81], v[168:171], v[200:203], v[78:81]
	v_mfma_f32_16x16x32_bf16 v[74:77], v[176:179], v[200:203], v[74:77]
	v_mfma_f32_16x16x32_bf16 v[70:73], v[168:171], v[210:213], v[70:73]
	v_mfma_f32_16x16x32_bf16 v[66:69], v[176:179], v[210:213], v[66:69]
	v_mfma_f32_16x16x32_bf16 v[110:113], v[172:175], v[188:191], v[110:113]
	v_mfma_f32_16x16x32_bf16 v[106:109], v[180:183], v[188:191], v[106:109]
	v_mfma_f32_16x16x32_bf16 v[94:97], v[172:175], v[196:199], v[94:97]
	v_mfma_f32_16x16x32_bf16 v[90:93], v[180:183], v[196:199], v[90:93]
	v_mfma_f32_16x16x32_bf16 v[78:81], v[172:175], v[206:209], v[78:81]
	v_mfma_f32_16x16x32_bf16 v[74:77], v[180:183], v[206:209], v[74:77]
	v_mfma_f32_16x16x32_bf16 v[70:73], v[172:175], v[214:217], v[70:73]
	v_mfma_f32_16x16x32_bf16 v[66:69], v[180:183], v[214:217], v[66:69]
	s_setprio 0
	s_barrier
	ds_read_b128 v[184:187], v148 offset:49152
	ds_read_b128 v[188:191], v148 offset:50176
	ds_read_b128 v[192:195], v148 offset:51200
	ds_read_b128 v[196:199], v148 offset:52224
	ds_read_b128 v[200:203], v148 offset:53248
	ds_read_b128 v[206:209], v148 offset:54272
	ds_read_b128 v[210:213], v148 offset:55296
	ds_read_b128 v[214:217], v148 offset:56320
	s_mov_b32 m0, s62
	v_lshl_add_u64 v[218:219], v[218:219], 0, s[10:11]
	s_add_u32 s42, s46, 0x20080
	global_load_lds_dwordx4 v[218:219], off
	v_lshl_add_u64 v[218:219], v[220:221], 0, s[10:11]
	s_mov_b32 m0, s63
	s_addc_u32 s43, s47, 0
	global_load_lds_dwordx4 v[218:219], off
	s_mov_b32 m0, s64
	v_lshl_add_u64 v[218:219], s[42:43], 0, v[134:135]
	global_load_lds_dwordx4 v[218:219], off
	s_mov_b32 m0, s65
	v_lshl_add_u64 v[218:219], s[42:43], 0, v[130:131]
	global_load_lds_dwordx4 v[218:219], off
	s_mov_b32 m0, s25
	v_lshl_add_u64 v[218:219], v[222:223], 0, s[10:11]
	global_load_lds_dwordx4 v[218:219], off
	s_mov_b32 m0, s28
	v_lshl_add_u64 v[218:219], v[224:225], 0, s[10:11]
	global_load_lds_dwordx4 v[218:219], off
	s_waitcnt vmcnt(8) lgkmcnt(0)
	s_setprio 1
	s_barrier
	v_mfma_f32_16x16x32_bf16 v[62:65], v[152:155], v[184:187], v[62:65]
	v_mfma_f32_16x16x32_bf16 v[58:61], v[160:163], v[184:187], v[58:61]
	v_mfma_f32_16x16x32_bf16 v[54:57], v[152:155], v[192:195], v[54:57]
	v_mfma_f32_16x16x32_bf16 v[50:53], v[160:163], v[192:195], v[50:53]
	v_mfma_f32_16x16x32_bf16 v[38:41], v[152:155], v[200:203], v[38:41]
	v_mfma_f32_16x16x32_bf16 v[34:37], v[160:163], v[200:203], v[34:37]
	v_mfma_f32_16x16x32_bf16 v[22:25], v[152:155], v[210:213], v[22:25]
	v_mfma_f32_16x16x32_bf16 v[18:21], v[160:163], v[210:213], v[18:21]
	v_mfma_f32_16x16x32_bf16 v[62:65], v[156:159], v[188:191], v[62:65]
	v_mfma_f32_16x16x32_bf16 v[58:61], v[164:167], v[188:191], v[58:61]
	v_mfma_f32_16x16x32_bf16 v[54:57], v[156:159], v[196:199], v[54:57]
	v_mfma_f32_16x16x32_bf16 v[50:53], v[164:167], v[196:199], v[50:53]
	v_mfma_f32_16x16x32_bf16 v[38:41], v[156:159], v[206:209], v[38:41]
	v_mfma_f32_16x16x32_bf16 v[34:37], v[164:167], v[206:209], v[34:37]
	v_mfma_f32_16x16x32_bf16 v[22:25], v[156:159], v[214:217], v[22:25]
	v_mfma_f32_16x16x32_bf16 v[18:21], v[164:167], v[214:217], v[18:21]
	v_mfma_f32_16x16x32_bf16 v[46:49], v[168:171], v[184:187], v[46:49]
	v_mfma_f32_16x16x32_bf16 v[42:45], v[176:179], v[184:187], v[42:45]
	v_mfma_f32_16x16x32_bf16 v[30:33], v[168:171], v[192:195], v[30:33]
	v_mfma_f32_16x16x32_bf16 v[26:29], v[176:179], v[192:195], v[26:29]
	v_mfma_f32_16x16x32_bf16 v[14:17], v[168:171], v[200:203], v[14:17]
	v_mfma_f32_16x16x32_bf16 v[10:13], v[176:179], v[200:203], v[10:13]
	v_mfma_f32_16x16x32_bf16 v[6:9], v[168:171], v[210:213], v[6:9]
	v_mfma_f32_16x16x32_bf16 v[2:5], v[176:179], v[210:213], v[2:5]
	v_mfma_f32_16x16x32_bf16 v[46:49], v[172:175], v[188:191], v[46:49]
	v_mfma_f32_16x16x32_bf16 v[42:45], v[180:183], v[188:191], v[42:45]
	v_mfma_f32_16x16x32_bf16 v[30:33], v[172:175], v[196:199], v[30:33]
	v_mfma_f32_16x16x32_bf16 v[26:29], v[180:183], v[196:199], v[26:29]
	v_mfma_f32_16x16x32_bf16 v[14:17], v[172:175], v[206:209], v[14:17]
	v_mfma_f32_16x16x32_bf16 v[10:13], v[180:183], v[206:209], v[10:13]
	v_mfma_f32_16x16x32_bf16 v[6:9], v[172:175], v[214:217], v[6:9]
	v_mfma_f32_16x16x32_bf16 v[2:5], v[180:183], v[214:217], v[2:5]
	s_setprio 0
	s_barrier
	s_add_i32 s68, s68, 2
	s_cmp_gt_u32 s68, 5
	s_mov_b64 s[42:43], s[44:45]
.LBB0_384:
	ds_read_b128 v[152:155], v146
	ds_read_b128 v[156:159], v146 offset:1024
	ds_read_b128 v[160:163], v146 offset:2048
	ds_read_b128 v[164:167], v146 offset:3072
	ds_read_b128 v[168:171], v147
	ds_read_b128 v[172:175], v147 offset:1024
	ds_read_b128 v[176:179], v147 offset:2048
	ds_read_b128 v[180:183], v147 offset:3072
	ds_read_b128 v[184:187], v148
	ds_read_b128 v[188:191], v148 offset:1024
	ds_read_b128 v[192:195], v148 offset:2048
	ds_read_b128 v[196:199], v148 offset:3072
	ds_read_b128 v[200:203], v148 offset:4096
	ds_read_b128 v[206:209], v148 offset:5120
	ds_read_b128 v[210:213], v148 offset:6144
	ds_read_b128 v[214:217], v148 offset:7168
	s_add_u32 s44, s42, 0x100
	s_addc_u32 s45, s43, 0
	s_add_u32 s46, s66, s42
	s_addc_u32 s47, s67, s43
	s_cmp_eq_u32 s68, 4
	s_cselect_b32 s48, 0, s44
	s_cselect_b32 s49, 0, s45
	s_cselect_b32 s46, s39, s46
	s_cselect_b32 s47, s15, s47
	s_add_u32 s48, s6, s48
	s_addc_u32 s49, s7, s49
	s_mov_b32 m0, s29
	v_lshl_add_u64 v[218:219], v[138:139], 0, s[42:43]
	global_load_lds_dwordx4 v[218:219], off
	s_mov_b32 m0, s30
	v_lshl_add_u64 v[218:219], v[140:141], 0, s[42:43]
	global_load_lds_dwordx4 v[218:219], off
	s_waitcnt vmcnt(8) lgkmcnt(0)
	s_setprio 1
	s_barrier
	v_mfma_f32_16x16x32_bf16 v[126:129], v[152:155], v[184:187], v[126:129]
	v_mfma_f32_16x16x32_bf16 v[122:125], v[160:163], v[184:187], v[122:125]
	v_mfma_f32_16x16x32_bf16 v[118:121], v[152:155], v[192:195], v[118:121]
	v_mfma_f32_16x16x32_bf16 v[114:117], v[160:163], v[192:195], v[114:117]
	v_mfma_f32_16x16x32_bf16 v[102:105], v[152:155], v[200:203], v[102:105]
	v_mfma_f32_16x16x32_bf16 v[98:101], v[160:163], v[200:203], v[98:101]
	v_mfma_f32_16x16x32_bf16 v[86:89], v[152:155], v[210:213], v[86:89]
	v_mfma_f32_16x16x32_bf16 v[82:85], v[160:163], v[210:213], v[82:85]
	v_mfma_f32_16x16x32_bf16 v[126:129], v[156:159], v[188:191], v[126:129]
	v_mfma_f32_16x16x32_bf16 v[122:125], v[164:167], v[188:191], v[122:125]
	v_mfma_f32_16x16x32_bf16 v[118:121], v[156:159], v[196:199], v[118:121]
	v_mfma_f32_16x16x32_bf16 v[114:117], v[164:167], v[196:199], v[114:117]
	v_mfma_f32_16x16x32_bf16 v[102:105], v[156:159], v[206:209], v[102:105]
	v_mfma_f32_16x16x32_bf16 v[98:101], v[164:167], v[206:209], v[98:101]
	v_mfma_f32_16x16x32_bf16 v[86:89], v[156:159], v[214:217], v[86:89]
	v_mfma_f32_16x16x32_bf16 v[82:85], v[164:167], v[214:217], v[82:85]
	v_mfma_f32_16x16x32_bf16 v[110:113], v[168:171], v[184:187], v[110:113]
	v_mfma_f32_16x16x32_bf16 v[106:109], v[176:179], v[184:187], v[106:109]
	v_mfma_f32_16x16x32_bf16 v[94:97], v[168:171], v[192:195], v[94:97]
	v_mfma_f32_16x16x32_bf16 v[90:93], v[176:179], v[192:195], v[90:93]
	v_mfma_f32_16x16x32_bf16 v[78:81], v[168:171], v[200:203], v[78:81]
	v_mfma_f32_16x16x32_bf16 v[74:77], v[176:179], v[200:203], v[74:77]
	v_mfma_f32_16x16x32_bf16 v[70:73], v[168:171], v[210:213], v[70:73]
	v_mfma_f32_16x16x32_bf16 v[66:69], v[176:179], v[210:213], v[66:69]
	v_mfma_f32_16x16x32_bf16 v[110:113], v[172:175], v[188:191], v[110:113]
	v_mfma_f32_16x16x32_bf16 v[106:109], v[180:183], v[188:191], v[106:109]
	v_mfma_f32_16x16x32_bf16 v[94:97], v[172:175], v[196:199], v[94:97]
	v_mfma_f32_16x16x32_bf16 v[90:93], v[180:183], v[196:199], v[90:93]
	v_mfma_f32_16x16x32_bf16 v[78:81], v[172:175], v[206:209], v[78:81]
	v_mfma_f32_16x16x32_bf16 v[74:77], v[180:183], v[206:209], v[74:77]
	v_mfma_f32_16x16x32_bf16 v[70:73], v[172:175], v[214:217], v[70:73]
	v_mfma_f32_16x16x32_bf16 v[66:69], v[180:183], v[214:217], v[66:69]
	s_setprio 0
	s_barrier
	ds_read_b128 v[184:187], v148 offset:16384
	ds_read_b128 v[188:191], v148 offset:17408
	ds_read_b128 v[192:195], v148 offset:18432
	ds_read_b128 v[196:199], v148 offset:19456
	ds_read_b128 v[200:203], v148 offset:20480
	ds_read_b128 v[206:209], v148 offset:21504
	ds_read_b128 v[210:213], v148 offset:22528
	ds_read_b128 v[214:217], v148 offset:23552
	s_mov_b32 m0, s31
	v_lshl_add_u64 v[218:219], s[46:47], 0, v[134:135]
	s_add_u32 s42, s46, 0x20000
	global_load_lds_dwordx4 v[218:219], off
	v_lshl_add_u64 v[220:221], s[46:47], 0, v[130:131]
	s_mov_b32 m0, s33
	s_addc_u32 s43, s47, 0
	global_load_lds_dwordx4 v[220:221], off
	v_lshl_add_u64 v[222:223], s[42:43], 0, v[134:135]
	s_mov_b32 m0, s34
	v_lshl_add_u64 v[224:225], s[48:49], 0, v[132:133]
	global_load_lds_dwordx4 v[222:223], off
	s_mov_b32 m0, s35
	v_lshl_add_u64 v[222:223], s[42:43], 0, v[130:131]
	global_load_lds_dwordx4 v[222:223], off
	s_mov_b32 m0, s2
	v_lshl_add_u64 v[222:223], s[48:49], 0, v[136:137]
	global_load_lds_dwordx4 v[222:223], off
	s_mov_b32 m0, s3
	s_nop 0
	global_load_lds_dwordx4 v[224:225], off
	s_waitcnt vmcnt(8) lgkmcnt(0)
	s_setprio 1
	s_barrier
	v_mfma_f32_16x16x32_bf16 v[62:65], v[152:155], v[184:187], v[62:65]
	v_mfma_f32_16x16x32_bf16 v[58:61], v[160:163], v[184:187], v[58:61]
	v_mfma_f32_16x16x32_bf16 v[54:57], v[152:155], v[192:195], v[54:57]
	v_mfma_f32_16x16x32_bf16 v[50:53], v[160:163], v[192:195], v[50:53]
	v_mfma_f32_16x16x32_bf16 v[38:41], v[152:155], v[200:203], v[38:41]
	v_mfma_f32_16x16x32_bf16 v[34:37], v[160:163], v[200:203], v[34:37]
	v_mfma_f32_16x16x32_bf16 v[22:25], v[152:155], v[210:213], v[22:25]
	v_mfma_f32_16x16x32_bf16 v[18:21], v[160:163], v[210:213], v[18:21]
	v_mfma_f32_16x16x32_bf16 v[62:65], v[156:159], v[188:191], v[62:65]
	v_mfma_f32_16x16x32_bf16 v[58:61], v[164:167], v[188:191], v[58:61]
	v_mfma_f32_16x16x32_bf16 v[54:57], v[156:159], v[196:199], v[54:57]
	v_mfma_f32_16x16x32_bf16 v[50:53], v[164:167], v[196:199], v[50:53]
	v_mfma_f32_16x16x32_bf16 v[38:41], v[156:159], v[206:209], v[38:41]
	v_mfma_f32_16x16x32_bf16 v[34:37], v[164:167], v[206:209], v[34:37]
	v_mfma_f32_16x16x32_bf16 v[22:25], v[156:159], v[214:217], v[22:25]
	v_mfma_f32_16x16x32_bf16 v[18:21], v[164:167], v[214:217], v[18:21]
	v_mfma_f32_16x16x32_bf16 v[46:49], v[168:171], v[184:187], v[46:49]
	v_mfma_f32_16x16x32_bf16 v[42:45], v[176:179], v[184:187], v[42:45]
	v_mfma_f32_16x16x32_bf16 v[30:33], v[168:171], v[192:195], v[30:33]
	v_mfma_f32_16x16x32_bf16 v[26:29], v[176:179], v[192:195], v[26:29]
	v_mfma_f32_16x16x32_bf16 v[14:17], v[168:171], v[200:203], v[14:17]
	v_mfma_f32_16x16x32_bf16 v[10:13], v[176:179], v[200:203], v[10:13]
	v_mfma_f32_16x16x32_bf16 v[6:9], v[168:171], v[210:213], v[6:9]
	v_mfma_f32_16x16x32_bf16 v[2:5], v[176:179], v[210:213], v[2:5]
	v_mfma_f32_16x16x32_bf16 v[46:49], v[172:175], v[188:191], v[46:49]
	v_mfma_f32_16x16x32_bf16 v[42:45], v[180:183], v[188:191], v[42:45]
	v_mfma_f32_16x16x32_bf16 v[30:33], v[172:175], v[196:199], v[30:33]
	v_mfma_f32_16x16x32_bf16 v[26:29], v[180:183], v[196:199], v[26:29]
	v_mfma_f32_16x16x32_bf16 v[14:17], v[172:175], v[206:209], v[14:17]
	v_mfma_f32_16x16x32_bf16 v[10:13], v[180:183], v[206:209], v[10:13]
	v_mfma_f32_16x16x32_bf16 v[6:9], v[172:175], v[214:217], v[6:9]
	v_mfma_f32_16x16x32_bf16 v[2:5], v[180:183], v[214:217], v[2:5]
	s_setprio 0
	s_barrier
	ds_read_b128 v[152:155], v149
	ds_read_b128 v[156:159], v149 offset:1024
	ds_read_b128 v[160:163], v149 offset:2048
	ds_read_b128 v[164:167], v149 offset:3072
	ds_read_b128 v[168:171], v150
	ds_read_b128 v[172:175], v150 offset:1024
	ds_read_b128 v[176:179], v150 offset:2048
	ds_read_b128 v[180:183], v150 offset:3072
	ds_read_b128 v[184:187], v148 offset:32768
	ds_read_b128 v[188:191], v148 offset:33792
	ds_read_b128 v[192:195], v148 offset:34816
	ds_read_b128 v[196:199], v148 offset:35840
	ds_read_b128 v[200:203], v148 offset:36864
	ds_read_b128 v[206:209], v148 offset:37888
	ds_read_b128 v[210:213], v148 offset:38912
	ds_read_b128 v[214:217], v148 offset:39936
	s_add_u32 s42, s48, 0x20000
	s_addc_u32 s43, s49, 0
	s_mov_b32 m0, s16
	v_lshl_add_u64 v[226:227], s[42:43], 0, v[136:137]
	global_load_lds_dwordx4 v[226:227], off
	s_mov_b32 m0, s17
	v_lshl_add_u64 v[226:227], s[42:43], 0, v[132:133]
	global_load_lds_dwordx4 v[226:227], off
	s_waitcnt vmcnt(8) lgkmcnt(0)
	s_setprio 1
	s_barrier
	v_mfma_f32_16x16x32_bf16 v[126:129], v[152:155], v[184:187], v[126:129]
	v_mfma_f32_16x16x32_bf16 v[122:125], v[160:163], v[184:187], v[122:125]
	v_mfma_f32_16x16x32_bf16 v[118:121], v[152:155], v[192:195], v[118:121]
	v_mfma_f32_16x16x32_bf16 v[114:117], v[160:163], v[192:195], v[114:117]
	v_mfma_f32_16x16x32_bf16 v[102:105], v[152:155], v[200:203], v[102:105]
	v_mfma_f32_16x16x32_bf16 v[98:101], v[160:163], v[200:203], v[98:101]
	v_mfma_f32_16x16x32_bf16 v[86:89], v[152:155], v[210:213], v[86:89]
	v_mfma_f32_16x16x32_bf16 v[82:85], v[160:163], v[210:213], v[82:85]
	v_mfma_f32_16x16x32_bf16 v[126:129], v[156:159], v[188:191], v[126:129]
	v_mfma_f32_16x16x32_bf16 v[122:125], v[164:167], v[188:191], v[122:125]
	v_mfma_f32_16x16x32_bf16 v[118:121], v[156:159], v[196:199], v[118:121]
	v_mfma_f32_16x16x32_bf16 v[114:117], v[164:167], v[196:199], v[114:117]
	v_mfma_f32_16x16x32_bf16 v[102:105], v[156:159], v[206:209], v[102:105]
	v_mfma_f32_16x16x32_bf16 v[98:101], v[164:167], v[206:209], v[98:101]
	v_mfma_f32_16x16x32_bf16 v[86:89], v[156:159], v[214:217], v[86:89]
	v_mfma_f32_16x16x32_bf16 v[82:85], v[164:167], v[214:217], v[82:85]
	v_mfma_f32_16x16x32_bf16 v[110:113], v[168:171], v[184:187], v[110:113]
	v_mfma_f32_16x16x32_bf16 v[106:109], v[176:179], v[184:187], v[106:109]
	v_mfma_f32_16x16x32_bf16 v[94:97], v[168:171], v[192:195], v[94:97]
	v_mfma_f32_16x16x32_bf16 v[90:93], v[176:179], v[192:195], v[90:93]
	v_mfma_f32_16x16x32_bf16 v[78:81], v[168:171], v[200:203], v[78:81]
	v_mfma_f32_16x16x32_bf16 v[74:77], v[176:179], v[200:203], v[74:77]
	v_mfma_f32_16x16x32_bf16 v[70:73], v[168:171], v[210:213], v[70:73]
	v_mfma_f32_16x16x32_bf16 v[66:69], v[176:179], v[210:213], v[66:69]
	v_mfma_f32_16x16x32_bf16 v[110:113], v[172:175], v[188:191], v[110:113]
	v_mfma_f32_16x16x32_bf16 v[106:109], v[180:183], v[188:191], v[106:109]
	v_mfma_f32_16x16x32_bf16 v[94:97], v[172:175], v[196:199], v[94:97]
	v_mfma_f32_16x16x32_bf16 v[90:93], v[180:183], v[196:199], v[90:93]
	v_mfma_f32_16x16x32_bf16 v[78:81], v[172:175], v[206:209], v[78:81]
	v_mfma_f32_16x16x32_bf16 v[74:77], v[180:183], v[206:209], v[74:77]
	v_mfma_f32_16x16x32_bf16 v[70:73], v[172:175], v[214:217], v[70:73]
	v_mfma_f32_16x16x32_bf16 v[66:69], v[180:183], v[214:217], v[66:69]
	s_setprio 0
	s_barrier
	ds_read_b128 v[184:187], v148 offset:49152
	ds_read_b128 v[188:191], v148 offset:50176
	ds_read_b128 v[192:195], v148 offset:51200
	ds_read_b128 v[196:199], v148 offset:52224
	ds_read_b128 v[200:203], v148 offset:53248
	ds_read_b128 v[206:209], v148 offset:54272
	ds_read_b128 v[210:213], v148 offset:55296
	ds_read_b128 v[214:217], v148 offset:56320
	s_mov_b32 m0, s62
	v_lshl_add_u64 v[218:219], v[218:219], 0, s[10:11]
	s_add_u32 s42, s46, 0x20080
	global_load_lds_dwordx4 v[218:219], off
	v_lshl_add_u64 v[218:219], v[220:221], 0, s[10:11]
	s_mov_b32 m0, s63
	s_addc_u32 s43, s47, 0
	global_load_lds_dwordx4 v[218:219], off
	s_mov_b32 m0, s64
	v_lshl_add_u64 v[218:219], s[42:43], 0, v[134:135]
	global_load_lds_dwordx4 v[218:219], off
	s_mov_b32 m0, s65
	v_lshl_add_u64 v[218:219], s[42:43], 0, v[130:131]
	global_load_lds_dwordx4 v[218:219], off
	s_mov_b32 m0, s25
	v_lshl_add_u64 v[218:219], v[222:223], 0, s[10:11]
	global_load_lds_dwordx4 v[218:219], off
	s_mov_b32 m0, s28
	v_lshl_add_u64 v[218:219], v[224:225], 0, s[10:11]
	global_load_lds_dwordx4 v[218:219], off
	s_waitcnt vmcnt(8) lgkmcnt(0)
	s_setprio 1
	s_barrier
	v_mfma_f32_16x16x32_bf16 v[62:65], v[152:155], v[184:187], v[62:65]
	v_mfma_f32_16x16x32_bf16 v[58:61], v[160:163], v[184:187], v[58:61]
	v_mfma_f32_16x16x32_bf16 v[54:57], v[152:155], v[192:195], v[54:57]
	v_mfma_f32_16x16x32_bf16 v[50:53], v[160:163], v[192:195], v[50:53]
	v_mfma_f32_16x16x32_bf16 v[38:41], v[152:155], v[200:203], v[38:41]
	v_mfma_f32_16x16x32_bf16 v[34:37], v[160:163], v[200:203], v[34:37]
	v_mfma_f32_16x16x32_bf16 v[22:25], v[152:155], v[210:213], v[22:25]
	v_mfma_f32_16x16x32_bf16 v[18:21], v[160:163], v[210:213], v[18:21]
	v_mfma_f32_16x16x32_bf16 v[62:65], v[156:159], v[188:191], v[62:65]
	v_mfma_f32_16x16x32_bf16 v[58:61], v[164:167], v[188:191], v[58:61]
	v_mfma_f32_16x16x32_bf16 v[54:57], v[156:159], v[196:199], v[54:57]
	v_mfma_f32_16x16x32_bf16 v[50:53], v[164:167], v[196:199], v[50:53]
	v_mfma_f32_16x16x32_bf16 v[38:41], v[156:159], v[206:209], v[38:41]
	v_mfma_f32_16x16x32_bf16 v[34:37], v[164:167], v[206:209], v[34:37]
	v_mfma_f32_16x16x32_bf16 v[22:25], v[156:159], v[214:217], v[22:25]
	v_mfma_f32_16x16x32_bf16 v[18:21], v[164:167], v[214:217], v[18:21]
	v_mfma_f32_16x16x32_bf16 v[46:49], v[168:171], v[184:187], v[46:49]
	v_mfma_f32_16x16x32_bf16 v[42:45], v[176:179], v[184:187], v[42:45]
	v_mfma_f32_16x16x32_bf16 v[30:33], v[168:171], v[192:195], v[30:33]
	v_mfma_f32_16x16x32_bf16 v[26:29], v[176:179], v[192:195], v[26:29]
	v_mfma_f32_16x16x32_bf16 v[14:17], v[168:171], v[200:203], v[14:17]
	v_mfma_f32_16x16x32_bf16 v[10:13], v[176:179], v[200:203], v[10:13]
	v_mfma_f32_16x16x32_bf16 v[6:9], v[168:171], v[210:213], v[6:9]
	v_mfma_f32_16x16x32_bf16 v[2:5], v[176:179], v[210:213], v[2:5]
	v_mfma_f32_16x16x32_bf16 v[46:49], v[172:175], v[188:191], v[46:49]
	v_mfma_f32_16x16x32_bf16 v[42:45], v[180:183], v[188:191], v[42:45]
	v_mfma_f32_16x16x32_bf16 v[30:33], v[172:175], v[196:199], v[30:33]
	v_mfma_f32_16x16x32_bf16 v[26:29], v[180:183], v[196:199], v[26:29]
	v_mfma_f32_16x16x32_bf16 v[14:17], v[172:175], v[206:209], v[14:17]
	v_mfma_f32_16x16x32_bf16 v[10:13], v[180:183], v[206:209], v[10:13]
	v_mfma_f32_16x16x32_bf16 v[6:9], v[172:175], v[214:217], v[6:9]
	v_mfma_f32_16x16x32_bf16 v[2:5], v[180:183], v[214:217], v[2:5]
	s_setprio 0
	s_barrier
	s_add_i32 s68, s68, 2
	s_cmp_gt_u32 s68, 5
	s_mov_b64 s[42:43], s[44:45]
	s_cbranch_scc0 .LBB0_384
	s_and_b64 vcc, exec, s[12:13]
	s_cbranch_vccz .LBB0_387
	s_barrier

.LBB0_406:
	ds_read_b128 v[146:149], v141
	ds_read_b128 v[150:153], v141 offset:1024
	ds_read_b128 v[154:157], v141 offset:2048
	ds_read_b128 v[158:161], v141 offset:3072
	ds_read_b128 v[162:165], v143
	ds_read_b128 v[166:169], v143 offset:1024
	ds_read_b128 v[170:173], v143 offset:2048
	ds_read_b128 v[174:177], v143 offset:3072
	ds_read_b128 v[178:181], v144
	ds_read_b128 v[182:185], v144 offset:1024
	ds_read_b128 v[186:189], v144 offset:2048
	ds_read_b128 v[190:193], v144 offset:3072
	ds_read_b128 v[194:197], v144 offset:4096
	ds_read_b128 v[198:201], v144 offset:5120
	ds_read_b128 v[206:209], v144 offset:6144
	ds_read_b128 v[210:213], v144 offset:7168
	s_lshl_b32 s74, s12, 7
	s_add_i32 s12, s12, 2
	v_cndmask_b32_e64 v138, 0, 1, s[66:67]
	s_lshl_b64 s[66:67], s[12:13], 7
	s_and_b64 s[68:69], s[64:65], exec
	s_cselect_b32 s66, 0, s66
	s_cselect_b32 s67, 0, s67
	s_add_u32 s70, s8, s66
	s_addc_u32 s71, s9, s67
	s_lshl_b64 s[66:67], s[12:13], 12
	s_add_u32 s12, s48, s66
	s_addc_u32 s66, s49, s67
	s_and_b64 s[64:65], s[64:65], exec
	s_cselect_b32 s73, s14, s66
	s_cselect_b32 s72, s15, s12
	s_add_u32 s76, s10, s74
	s_addc_u32 s77, s11, 0
	s_add_i32 s91, s62, s16
	s_add_i32 m0, s17, 0xc000
	s_add_i32 s92, s17, 0xe000
	s_add_i32 s88, s91, 0x2000
	s_add_u32 s74, s72, 0x10000
	s_addc_u32 s75, s73, 0
	s_add_i32 s90, s63, s16
	s_add_i32 s89, s90, 0x2000
	s_add_i32 s87, 0, 0x18000
	s_add_i32 s86, 0, 0x1c000
	s_add_u32 s68, s70, 0x10000
	s_addc_u32 s69, s71, 0
	s_add_u32 s64, s72, 0x1000
	s_addc_u32 s65, s73, 0
	s_add_i32 s85, s87, s16
	s_add_i32 s83, s85, 0x2000
	s_add_u32 s66, s72, 0x11000
	s_addc_u32 s67, s73, 0
	s_add_i32 s84, s86, s16
	s_add_i32 s12, s84, 0x2000
	v_cmp_ne_u32_e32 vcc, 1, v138
	v_lshl_add_u64 v[202:203], s[76:77], 0, v[136:137]
	v_lshl_add_u64 v[202:203], v[202:203], 0, s[36:37]
	global_load_lds_dwordx4 v[202:203], off
	v_lshl_add_u64 v[202:203], s[76:77], 0, v[132:133]
	s_mov_b32 m0, s92
	v_lshl_add_u64 v[202:203], v[202:203], 0, s[36:37]
	global_load_lds_dwordx4 v[202:203], off
	s_waitcnt vmcnt(8) lgkmcnt(0)
	s_setprio 1
	s_barrier
	v_mfma_f32_16x16x32_bf16 v[126:129], v[146:149], v[178:181], v[126:129]
	v_mfma_f32_16x16x32_bf16 v[122:125], v[154:157], v[178:181], v[122:125]
	v_mfma_f32_16x16x32_bf16 v[118:121], v[146:149], v[186:189], v[118:121]
	v_mfma_f32_16x16x32_bf16 v[110:113], v[154:157], v[186:189], v[110:113]
	v_mfma_f32_16x16x32_bf16 v[102:105], v[146:149], v[194:197], v[102:105]
	v_mfma_f32_16x16x32_bf16 v[98:101], v[154:157], v[194:197], v[98:101]
	v_mfma_f32_16x16x32_bf16 v[86:89], v[146:149], v[206:209], v[86:89]
	v_mfma_f32_16x16x32_bf16 v[82:85], v[154:157], v[206:209], v[82:85]
	v_mfma_f32_16x16x32_bf16 v[126:129], v[150:153], v[182:185], v[126:129]
	v_mfma_f32_16x16x32_bf16 v[122:125], v[158:161], v[182:185], v[122:125]
	v_mfma_f32_16x16x32_bf16 v[118:121], v[150:153], v[190:193], v[118:121]
	v_mfma_f32_16x16x32_bf16 v[110:113], v[158:161], v[190:193], v[110:113]
	v_mfma_f32_16x16x32_bf16 v[102:105], v[150:153], v[198:201], v[102:105]
	v_mfma_f32_16x16x32_bf16 v[98:101], v[158:161], v[198:201], v[98:101]
	v_mfma_f32_16x16x32_bf16 v[86:89], v[150:153], v[210:213], v[86:89]
	v_mfma_f32_16x16x32_bf16 v[82:85], v[158:161], v[210:213], v[82:85]
	v_mfma_f32_16x16x32_bf16 v[114:117], v[162:165], v[178:181], v[114:117]
	v_mfma_f32_16x16x32_bf16 v[106:109], v[170:173], v[178:181], v[106:109]
	v_mfma_f32_16x16x32_bf16 v[94:97], v[162:165], v[186:189], v[94:97]
	v_mfma_f32_16x16x32_bf16 v[90:93], v[170:173], v[186:189], v[90:93]
	v_mfma_f32_16x16x32_bf16 v[78:81], v[162:165], v[194:197], v[78:81]
	v_mfma_f32_16x16x32_bf16 v[74:77], v[170:173], v[194:197], v[74:77]
	v_mfma_f32_16x16x32_bf16 v[70:73], v[162:165], v[206:209], v[70:73]
	v_mfma_f32_16x16x32_bf16 v[66:69], v[170:173], v[206:209], v[66:69]
	v_mfma_f32_16x16x32_bf16 v[114:117], v[166:169], v[182:185], v[114:117]
	v_mfma_f32_16x16x32_bf16 v[106:109], v[174:177], v[182:185], v[106:109]
	v_mfma_f32_16x16x32_bf16 v[94:97], v[166:169], v[190:193], v[94:97]
	v_mfma_f32_16x16x32_bf16 v[90:93], v[174:177], v[190:193], v[90:93]
	v_mfma_f32_16x16x32_bf16 v[78:81], v[166:169], v[198:201], v[78:81]
	v_mfma_f32_16x16x32_bf16 v[74:77], v[174:177], v[198:201], v[74:77]
	v_mfma_f32_16x16x32_bf16 v[70:73], v[166:169], v[210:213], v[70:73]
	v_mfma_f32_16x16x32_bf16 v[66:69], v[174:177], v[210:213], v[66:69]
	s_setprio 0
	s_barrier
	ds_read_b128 v[178:181], v144 offset:16384
	ds_read_b128 v[182:185], v144 offset:17408
	ds_read_b128 v[186:189], v144 offset:18432
	ds_read_b128 v[190:193], v144 offset:19456
	ds_read_b128 v[194:197], v144 offset:20480
	ds_read_b128 v[198:201], v144 offset:21504
	ds_read_b128 v[206:209], v144 offset:22528
	ds_read_b128 v[210:213], v144 offset:23552
	s_mov_b32 m0, s91
	v_lshl_add_u64 v[202:203], s[72:73], 0, v[134:135]
	global_load_lds_dwordx4 v[202:203], off
	v_lshl_add_u64 v[202:203], s[72:73], 0, v[130:131]
	s_mov_b32 m0, s88
	v_lshl_add_u64 v[214:215], s[70:71], 0, v[132:133]
	global_load_lds_dwordx4 v[202:203], off
	s_mov_b32 m0, s90
	v_lshl_add_u64 v[202:203], s[74:75], 0, v[134:135]
	global_load_lds_dwordx4 v[202:203], off
	s_mov_b32 m0, s89
	v_lshl_add_u64 v[202:203], s[74:75], 0, v[130:131]
	global_load_lds_dwordx4 v[202:203], off
	s_mov_b32 m0, s17
	v_lshl_add_u64 v[202:203], s[70:71], 0, v[136:137]
	global_load_lds_dwordx4 v[202:203], off
	s_mov_b32 m0, s18
	s_nop 0
	global_load_lds_dwordx4 v[214:215], off
	s_waitcnt vmcnt(8) lgkmcnt(0)
	s_setprio 1
	s_barrier
	v_mfma_f32_16x16x32_bf16 v[62:65], v[146:149], v[178:181], v[62:65]
	v_mfma_f32_16x16x32_bf16 v[58:61], v[154:157], v[178:181], v[58:61]
	v_mfma_f32_16x16x32_bf16 v[54:57], v[146:149], v[186:189], v[54:57]
	v_mfma_f32_16x16x32_bf16 v[50:53], v[154:157], v[186:189], v[50:53]
	v_mfma_f32_16x16x32_bf16 v[38:41], v[146:149], v[194:197], v[38:41]
	v_mfma_f32_16x16x32_bf16 v[34:37], v[154:157], v[194:197], v[34:37]
	v_mfma_f32_16x16x32_bf16 v[22:25], v[146:149], v[206:209], v[22:25]
	v_mfma_f32_16x16x32_bf16 v[18:21], v[154:157], v[206:209], v[18:21]
	v_mfma_f32_16x16x32_bf16 v[62:65], v[150:153], v[182:185], v[62:65]
	v_mfma_f32_16x16x32_bf16 v[58:61], v[158:161], v[182:185], v[58:61]
	v_mfma_f32_16x16x32_bf16 v[54:57], v[150:153], v[190:193], v[54:57]
	v_mfma_f32_16x16x32_bf16 v[50:53], v[158:161], v[190:193], v[50:53]
	v_mfma_f32_16x16x32_bf16 v[38:41], v[150:153], v[198:201], v[38:41]
	v_mfma_f32_16x16x32_bf16 v[34:37], v[158:161], v[198:201], v[34:37]
	v_mfma_f32_16x16x32_bf16 v[22:25], v[150:153], v[210:213], v[22:25]
	v_mfma_f32_16x16x32_bf16 v[18:21], v[158:161], v[210:213], v[18:21]
	v_mfma_f32_16x16x32_bf16 v[46:49], v[162:165], v[178:181], v[46:49]
	v_mfma_f32_16x16x32_bf16 v[42:45], v[170:173], v[178:181], v[42:45]
	v_mfma_f32_16x16x32_bf16 v[30:33], v[162:165], v[186:189], v[30:33]
	v_mfma_f32_16x16x32_bf16 v[26:29], v[170:173], v[186:189], v[26:29]
	v_mfma_f32_16x16x32_bf16 v[14:17], v[162:165], v[194:197], v[14:17]
	v_mfma_f32_16x16x32_bf16 v[10:13], v[170:173], v[194:197], v[10:13]
	v_mfma_f32_16x16x32_bf16 v[6:9], v[162:165], v[206:209], v[6:9]
	v_mfma_f32_16x16x32_bf16 v[2:5], v[170:173], v[206:209], v[2:5]
	v_mfma_f32_16x16x32_bf16 v[46:49], v[166:169], v[182:185], v[46:49]
	v_mfma_f32_16x16x32_bf16 v[42:45], v[174:177], v[182:185], v[42:45]
	v_mfma_f32_16x16x32_bf16 v[30:33], v[166:169], v[190:193], v[30:33]
	v_mfma_f32_16x16x32_bf16 v[26:29], v[174:177], v[190:193], v[26:29]
	v_mfma_f32_16x16x32_bf16 v[14:17], v[166:169], v[198:201], v[14:17]
	v_mfma_f32_16x16x32_bf16 v[10:13], v[174:177], v[198:201], v[10:13]
	v_mfma_f32_16x16x32_bf16 v[6:9], v[166:169], v[210:213], v[6:9]
	v_mfma_f32_16x16x32_bf16 v[2:5], v[174:177], v[210:213], v[2:5]
	s_setprio 0
	s_barrier
	v_add_u32_e32 v138, s87, v140
	ds_read_b128 v[146:149], v138
	ds_read_b128 v[150:153], v138 offset:1024
	ds_read_b128 v[154:157], v138 offset:2048
	ds_read_b128 v[158:161], v138 offset:3072
	v_add_u32_e32 v138, s86, v140
	ds_read_b128 v[162:165], v138
	ds_read_b128 v[166:169], v138 offset:1024
	ds_read_b128 v[170:173], v138 offset:2048
	ds_read_b128 v[174:177], v138 offset:3072
	s_mov_b32 m0, s19
	v_lshl_add_u64 v[216:217], s[68:69], 0, v[136:137]
	ds_read_b128 v[178:181], v144 offset:32768
	ds_read_b128 v[182:185], v144 offset:33792
	ds_read_b128 v[186:189], v144 offset:34816
	ds_read_b128 v[190:193], v144 offset:35840
	ds_read_b128 v[194:197], v144 offset:36864
	ds_read_b128 v[198:201], v144 offset:37888
	ds_read_b128 v[206:209], v144 offset:38912
	ds_read_b128 v[210:213], v144 offset:39936
	global_load_lds_dwordx4 v[216:217], off
	s_mov_b32 m0, s24
	v_lshl_add_u64 v[216:217], s[68:69], 0, v[132:133]
	global_load_lds_dwordx4 v[216:217], off
	s_waitcnt vmcnt(8) lgkmcnt(0)
	s_setprio 1
	s_barrier
	v_mfma_f32_16x16x32_bf16 v[126:129], v[146:149], v[178:181], v[126:129]
	v_mfma_f32_16x16x32_bf16 v[122:125], v[154:157], v[178:181], v[122:125]
	v_mfma_f32_16x16x32_bf16 v[118:121], v[146:149], v[186:189], v[118:121]
	v_mfma_f32_16x16x32_bf16 v[110:113], v[154:157], v[186:189], v[110:113]
	v_mfma_f32_16x16x32_bf16 v[102:105], v[146:149], v[194:197], v[102:105]
	v_mfma_f32_16x16x32_bf16 v[98:101], v[154:157], v[194:197], v[98:101]
	v_mfma_f32_16x16x32_bf16 v[86:89], v[146:149], v[206:209], v[86:89]
	v_mfma_f32_16x16x32_bf16 v[82:85], v[154:157], v[206:209], v[82:85]
	v_mfma_f32_16x16x32_bf16 v[126:129], v[150:153], v[182:185], v[126:129]
	v_mfma_f32_16x16x32_bf16 v[122:125], v[158:161], v[182:185], v[122:125]
	v_mfma_f32_16x16x32_bf16 v[118:121], v[150:153], v[190:193], v[118:121]
	v_mfma_f32_16x16x32_bf16 v[110:113], v[158:161], v[190:193], v[110:113]
	v_mfma_f32_16x16x32_bf16 v[102:105], v[150:153], v[198:201], v[102:105]
	v_mfma_f32_16x16x32_bf16 v[98:101], v[158:161], v[198:201], v[98:101]
	v_mfma_f32_16x16x32_bf16 v[86:89], v[150:153], v[210:213], v[86:89]
	v_mfma_f32_16x16x32_bf16 v[82:85], v[158:161], v[210:213], v[82:85]
	v_mfma_f32_16x16x32_bf16 v[114:117], v[162:165], v[178:181], v[114:117]
	v_mfma_f32_16x16x32_bf16 v[106:109], v[170:173], v[178:181], v[106:109]
	v_mfma_f32_16x16x32_bf16 v[94:97], v[162:165], v[186:189], v[94:97]
	v_mfma_f32_16x16x32_bf16 v[90:93], v[170:173], v[186:189], v[90:93]
	v_mfma_f32_16x16x32_bf16 v[78:81], v[162:165], v[194:197], v[78:81]
	v_mfma_f32_16x16x32_bf16 v[74:77], v[170:173], v[194:197], v[74:77]
	v_mfma_f32_16x16x32_bf16 v[70:73], v[162:165], v[206:209], v[70:73]
	v_mfma_f32_16x16x32_bf16 v[66:69], v[170:173], v[206:209], v[66:69]
	v_mfma_f32_16x16x32_bf16 v[114:117], v[166:169], v[182:185], v[114:117]
	v_mfma_f32_16x16x32_bf16 v[106:109], v[174:177], v[182:185], v[106:109]
	v_mfma_f32_16x16x32_bf16 v[94:97], v[166:169], v[190:193], v[94:97]
	v_mfma_f32_16x16x32_bf16 v[90:93], v[174:177], v[190:193], v[90:93]
	v_mfma_f32_16x16x32_bf16 v[78:81], v[166:169], v[198:201], v[78:81]
	v_mfma_f32_16x16x32_bf16 v[74:77], v[174:177], v[198:201], v[74:77]
	v_mfma_f32_16x16x32_bf16 v[70:73], v[166:169], v[210:213], v[70:73]
	v_mfma_f32_16x16x32_bf16 v[66:69], v[174:177], v[210:213], v[66:69]
	s_setprio 0
	s_barrier
	ds_read_b128 v[178:181], v144 offset:49152
	ds_read_b128 v[182:185], v144 offset:50176
	ds_read_b128 v[186:189], v144 offset:51200
	ds_read_b128 v[190:193], v144 offset:52224
	ds_read_b128 v[194:197], v144 offset:53248
	ds_read_b128 v[198:201], v144 offset:54272
	ds_read_b128 v[206:209], v144 offset:55296
	ds_read_b128 v[210:213], v144 offset:56320
	s_mov_b32 m0, s85
	v_lshl_add_u64 v[216:217], s[64:65], 0, v[134:135]
	global_load_lds_dwordx4 v[216:217], off
	v_lshl_add_u64 v[216:217], s[64:65], 0, v[130:131]
	s_mov_b32 m0, s83
	v_lshl_add_u64 v[202:203], v[202:203], 0, s[36:37]
	global_load_lds_dwordx4 v[216:217], off
	s_mov_b32 m0, s84
	v_lshl_add_u64 v[216:217], s[66:67], 0, v[134:135]
	global_load_lds_dwordx4 v[216:217], off
	s_mov_b32 m0, s12
	v_lshl_add_u64 v[216:217], s[66:67], 0, v[130:131]
	global_load_lds_dwordx4 v[216:217], off
	s_mov_b32 m0, s31
	s_nop 0
	global_load_lds_dwordx4 v[202:203], off
	s_mov_b32 m0, s33
	v_lshl_add_u64 v[202:203], v[214:215], 0, s[36:37]
	global_load_lds_dwordx4 v[202:203], off
	s_waitcnt vmcnt(8) lgkmcnt(0)
	s_setprio 1
	s_barrier
	v_mfma_f32_16x16x32_bf16 v[62:65], v[146:149], v[178:181], v[62:65]
	v_mfma_f32_16x16x32_bf16 v[58:61], v[154:157], v[178:181], v[58:61]
	v_mfma_f32_16x16x32_bf16 v[54:57], v[146:149], v[186:189], v[54:57]
	v_mfma_f32_16x16x32_bf16 v[50:53], v[154:157], v[186:189], v[50:53]
	v_mfma_f32_16x16x32_bf16 v[38:41], v[146:149], v[194:197], v[38:41]
	v_mfma_f32_16x16x32_bf16 v[34:37], v[154:157], v[194:197], v[34:37]
	v_mfma_f32_16x16x32_bf16 v[22:25], v[146:149], v[206:209], v[22:25]
	v_mfma_f32_16x16x32_bf16 v[18:21], v[154:157], v[206:209], v[18:21]
	v_mfma_f32_16x16x32_bf16 v[62:65], v[150:153], v[182:185], v[62:65]
	v_mfma_f32_16x16x32_bf16 v[58:61], v[158:161], v[182:185], v[58:61]
	v_mfma_f32_16x16x32_bf16 v[54:57], v[150:153], v[190:193], v[54:57]
	v_mfma_f32_16x16x32_bf16 v[50:53], v[158:161], v[190:193], v[50:53]
	v_mfma_f32_16x16x32_bf16 v[38:41], v[150:153], v[198:201], v[38:41]
	v_mfma_f32_16x16x32_bf16 v[34:37], v[158:161], v[198:201], v[34:37]
	v_mfma_f32_16x16x32_bf16 v[22:25], v[150:153], v[210:213], v[22:25]
	v_mfma_f32_16x16x32_bf16 v[18:21], v[158:161], v[210:213], v[18:21]
	v_mfma_f32_16x16x32_bf16 v[46:49], v[162:165], v[178:181], v[46:49]
	v_mfma_f32_16x16x32_bf16 v[42:45], v[170:173], v[178:181], v[42:45]
	v_mfma_f32_16x16x32_bf16 v[30:33], v[162:165], v[186:189], v[30:33]
	v_mfma_f32_16x16x32_bf16 v[26:29], v[170:173], v[186:189], v[26:29]
	v_mfma_f32_16x16x32_bf16 v[14:17], v[162:165], v[194:197], v[14:17]
	v_mfma_f32_16x16x32_bf16 v[10:13], v[170:173], v[194:197], v[10:13]
	v_mfma_f32_16x16x32_bf16 v[6:9], v[162:165], v[206:209], v[6:9]
	v_mfma_f32_16x16x32_bf16 v[2:5], v[170:173], v[206:209], v[2:5]
	v_mfma_f32_16x16x32_bf16 v[46:49], v[166:169], v[182:185], v[46:49]
	v_mfma_f32_16x16x32_bf16 v[42:45], v[174:177], v[182:185], v[42:45]
	v_mfma_f32_16x16x32_bf16 v[30:33], v[166:169], v[190:193], v[30:33]
	v_mfma_f32_16x16x32_bf16 v[26:29], v[174:177], v[190:193], v[26:29]
	v_mfma_f32_16x16x32_bf16 v[14:17], v[166:169], v[198:201], v[14:17]
	v_mfma_f32_16x16x32_bf16 v[10:13], v[174:177], v[198:201], v[10:13]
	v_mfma_f32_16x16x32_bf16 v[6:9], v[166:169], v[210:213], v[6:9]
	v_mfma_f32_16x16x32_bf16 v[2:5], v[174:177], v[210:213], v[2:5]
	s_setprio 0
	s_barrier
	s_mov_b64 s[66:67], 0
	s_mov_b64 s[64:65], -1
	s_mov_b32 s12, 2
	s_cbranch_vccz .LBB0_406
	s_and_b64 vcc, exec, s[22:23]
	s_cbranch_vccz .LBB0_409
	s_barrier

.LBB0_476:
	s_add_u32 s22, s2, s49
	s_addc_u32 s23, s3, s29
	s_and_b64 s[26:27], s[20:21], exec
	s_cselect_b32 s63, s23, s37
	s_cselect_b32 s64, s22, s36
	s_add_u32 s26, s16, s12
	s_addc_u32 s27, s17, s13
	s_and_b64 s[42:43], s[20:21], exec
	s_cselect_b32 s65, s27, s39
	s_cselect_b32 s66, s26, s38
	s_add_u32 s36, s36, 0x20080
	s_addc_u32 s37, s37, 0
	s_add_u32 s67, s38, 0x100
	s_addc_u32 s68, s39, 0
	s_mov_b32 s69, -2
	ds_read_b128 v[148:151], v144
	ds_read_b128 v[152:155], v144 offset:1024
	ds_read_b128 v[156:159], v144 offset:2048
	ds_read_b128 v[160:163], v144 offset:3072
	ds_read_b128 v[164:167], v145
	ds_read_b128 v[168:171], v145 offset:1024
	ds_read_b128 v[172:175], v145 offset:2048
	ds_read_b128 v[176:179], v145 offset:3072
	ds_read_b128 v[180:183], v146
	ds_read_b128 v[184:187], v146 offset:1024
	ds_read_b128 v[188:191], v146 offset:2048
	ds_read_b128 v[192:195], v146 offset:3072
	ds_read_b128 v[196:199], v146 offset:4096
	ds_read_b128 v[200:203], v146 offset:5120
	ds_read_b128 v[206:209], v146 offset:6144
	ds_read_b128 v[210:213], v146 offset:7168
	s_add_u32 s38, s36, 0xfffe0080
	s_addc_u32 s39, s37, -1
	s_cmp_eq_u32 s69, 4
	s_cselect_b32 s43, s63, s39
	s_cselect_b32 s42, s64, s38
	s_cselect_b32 s39, s65, s68
	s_cselect_b32 s38, s66, s67
	s_add_i32 m0, s19, 0xc000
	v_lshl_add_u64 v[214:215], s[36:37], 0, v[138:139]
	global_load_lds_dwordx4 v[214:215], off
	s_add_i32 m0, s19, 0xe000
	v_lshl_add_u64 v[214:215], s[36:37], 0, v[140:141]
	global_load_lds_dwordx4 v[214:215], off
	s_waitcnt vmcnt(8) lgkmcnt(0)
	s_setprio 1
	s_barrier
	v_mfma_f32_16x16x32_bf16 v[126:129], v[148:151], v[180:183], 0
	v_mfma_f32_16x16x32_bf16 v[122:125], v[156:159], v[180:183], 0
	v_mfma_f32_16x16x32_bf16 v[118:121], v[148:151], v[188:191], 0
	v_mfma_f32_16x16x32_bf16 v[114:117], v[156:159], v[188:191], 0
	v_mfma_f32_16x16x32_bf16 v[102:105], v[148:151], v[196:199], 0
	v_mfma_f32_16x16x32_bf16 v[98:101], v[156:159], v[196:199], 0
	v_mfma_f32_16x16x32_bf16 v[86:89], v[148:151], v[206:209], 0
	v_mfma_f32_16x16x32_bf16 v[82:85], v[156:159], v[206:209], 0
	v_mfma_f32_16x16x32_bf16 v[126:129], v[152:155], v[184:187], v[126:129]
	v_mfma_f32_16x16x32_bf16 v[122:125], v[160:163], v[184:187], v[122:125]
	v_mfma_f32_16x16x32_bf16 v[118:121], v[152:155], v[192:195], v[118:121]
	v_mfma_f32_16x16x32_bf16 v[114:117], v[160:163], v[192:195], v[114:117]
	v_mfma_f32_16x16x32_bf16 v[102:105], v[152:155], v[200:203], v[102:105]
	v_mfma_f32_16x16x32_bf16 v[98:101], v[160:163], v[200:203], v[98:101]
	v_mfma_f32_16x16x32_bf16 v[86:89], v[152:155], v[210:213], v[86:89]
	v_mfma_f32_16x16x32_bf16 v[82:85], v[160:163], v[210:213], v[82:85]
	v_mfma_f32_16x16x32_bf16 v[110:113], v[164:167], v[180:183], 0
	v_mfma_f32_16x16x32_bf16 v[106:109], v[172:175], v[180:183], 0
	v_mfma_f32_16x16x32_bf16 v[94:97], v[164:167], v[188:191], 0
	v_mfma_f32_16x16x32_bf16 v[90:93], v[172:175], v[188:191], 0
	v_mfma_f32_16x16x32_bf16 v[78:81], v[164:167], v[196:199], 0
	v_mfma_f32_16x16x32_bf16 v[74:77], v[172:175], v[196:199], 0
	v_mfma_f32_16x16x32_bf16 v[70:73], v[164:167], v[206:209], 0
	v_mfma_f32_16x16x32_bf16 v[66:69], v[172:175], v[206:209], 0
	v_mfma_f32_16x16x32_bf16 v[110:113], v[168:171], v[184:187], v[110:113]
	v_mfma_f32_16x16x32_bf16 v[106:109], v[176:179], v[184:187], v[106:109]
	v_mfma_f32_16x16x32_bf16 v[94:97], v[168:171], v[192:195], v[94:97]
	v_mfma_f32_16x16x32_bf16 v[90:93], v[176:179], v[192:195], v[90:93]
	v_mfma_f32_16x16x32_bf16 v[78:81], v[168:171], v[200:203], v[78:81]
	v_mfma_f32_16x16x32_bf16 v[74:77], v[176:179], v[200:203], v[74:77]
	v_mfma_f32_16x16x32_bf16 v[70:73], v[168:171], v[210:213], v[70:73]
	v_mfma_f32_16x16x32_bf16 v[66:69], v[176:179], v[210:213], v[66:69]
	s_setprio 0
	s_barrier
	ds_read_b128 v[180:183], v146 offset:16384
	ds_read_b128 v[184:187], v146 offset:17408
	ds_read_b128 v[188:191], v146 offset:18432
	ds_read_b128 v[192:195], v146 offset:19456
	ds_read_b128 v[196:199], v146 offset:20480
	ds_read_b128 v[200:203], v146 offset:21504
	ds_read_b128 v[206:209], v146 offset:22528
	ds_read_b128 v[210:213], v146 offset:23552
	s_add_i32 s70, s35, s18
	s_mov_b32 m0, s70
	v_lshl_add_u64 v[214:215], s[38:39], 0, v[134:135]
	global_load_lds_dwordx4 v[214:215], off
	s_add_i32 m0, s70, 0x2000
	s_add_u32 s70, s38, 0x200000
	v_lshl_add_u64 v[216:217], s[38:39], 0, v[130:131]
	s_addc_u32 s71, s39, 0
	s_add_i32 s72, s44, s18
	global_load_lds_dwordx4 v[216:217], off
	v_lshl_add_u64 v[218:219], s[70:71], 0, v[134:135]
	s_mov_b32 m0, s72
	v_lshl_add_u64 v[220:221], s[42:43], 0, v[132:133]
	global_load_lds_dwordx4 v[218:219], off
	s_add_i32 m0, s72, 0x2000
	v_lshl_add_u64 v[218:219], s[70:71], 0, v[130:131]
	global_load_lds_dwordx4 v[218:219], off
	s_mov_b32 m0, s19
	v_lshl_add_u64 v[218:219], s[42:43], 0, v[136:137]
	global_load_lds_dwordx4 v[218:219], off
	s_mov_b32 m0, s24
	s_nop 0
	global_load_lds_dwordx4 v[220:221], off
	s_waitcnt vmcnt(8) lgkmcnt(0)
	s_setprio 1
	s_barrier
	v_mfma_f32_16x16x32_bf16 v[62:65], v[148:151], v[180:183], 0
	v_mfma_f32_16x16x32_bf16 v[58:61], v[156:159], v[180:183], 0
	v_mfma_f32_16x16x32_bf16 v[54:57], v[148:151], v[188:191], 0
	v_mfma_f32_16x16x32_bf16 v[50:53], v[156:159], v[188:191], 0
	v_mfma_f32_16x16x32_bf16 v[38:41], v[148:151], v[196:199], 0
	v_mfma_f32_16x16x32_bf16 v[34:37], v[156:159], v[196:199], 0
	v_mfma_f32_16x16x32_bf16 v[22:25], v[148:151], v[206:209], 0
	v_mfma_f32_16x16x32_bf16 v[18:21], v[156:159], v[206:209], 0
	v_mfma_f32_16x16x32_bf16 v[62:65], v[152:155], v[184:187], v[62:65]
	v_mfma_f32_16x16x32_bf16 v[58:61], v[160:163], v[184:187], v[58:61]
	v_mfma_f32_16x16x32_bf16 v[54:57], v[152:155], v[192:195], v[54:57]
	v_mfma_f32_16x16x32_bf16 v[50:53], v[160:163], v[192:195], v[50:53]
	v_mfma_f32_16x16x32_bf16 v[38:41], v[152:155], v[200:203], v[38:41]
	v_mfma_f32_16x16x32_bf16 v[34:37], v[160:163], v[200:203], v[34:37]
	v_mfma_f32_16x16x32_bf16 v[22:25], v[152:155], v[210:213], v[22:25]
	v_mfma_f32_16x16x32_bf16 v[18:21], v[160:163], v[210:213], v[18:21]
	v_mfma_f32_16x16x32_bf16 v[46:49], v[164:167], v[180:183], 0
	v_mfma_f32_16x16x32_bf16 v[42:45], v[172:175], v[180:183], 0
	v_mfma_f32_16x16x32_bf16 v[30:33], v[164:167], v[188:191], 0
	v_mfma_f32_16x16x32_bf16 v[26:29], v[172:175], v[188:191], 0
	v_mfma_f32_16x16x32_bf16 v[14:17], v[164:167], v[196:199], 0
	v_mfma_f32_16x16x32_bf16 v[10:13], v[172:175], v[196:199], 0
	v_mfma_f32_16x16x32_bf16 v[6:9], v[164:167], v[206:209], 0
	v_mfma_f32_16x16x32_bf16 v[2:5], v[172:175], v[206:209], 0
	v_mfma_f32_16x16x32_bf16 v[46:49], v[168:171], v[184:187], v[46:49]
	v_mfma_f32_16x16x32_bf16 v[42:45], v[176:179], v[184:187], v[42:45]
	v_mfma_f32_16x16x32_bf16 v[30:33], v[168:171], v[192:195], v[30:33]
	v_mfma_f32_16x16x32_bf16 v[26:29], v[176:179], v[192:195], v[26:29]
	v_mfma_f32_16x16x32_bf16 v[14:17], v[168:171], v[200:203], v[14:17]
	v_mfma_f32_16x16x32_bf16 v[10:13], v[176:179], v[200:203], v[10:13]
	v_mfma_f32_16x16x32_bf16 v[6:9], v[168:171], v[210:213], v[6:9]
	v_mfma_f32_16x16x32_bf16 v[2:5], v[176:179], v[210:213], v[2:5]
	s_setprio 0
	s_barrier
	s_add_i32 s70, 0, 0x18000
	v_add_u32_e32 v147, s70, v143
	s_add_i32 s71, 0, 0x1c000
	ds_read_b128 v[148:151], v147
	ds_read_b128 v[152:155], v147 offset:1024
	ds_read_b128 v[156:159], v147 offset:2048
	ds_read_b128 v[160:163], v147 offset:3072
	v_add_u32_e32 v147, s71, v143
	ds_read_b128 v[164:167], v147
	ds_read_b128 v[168:171], v147 offset:1024
	ds_read_b128 v[172:175], v147 offset:2048
	ds_read_b128 v[176:179], v147 offset:3072
	s_add_u32 s42, s42, 0x20000
	s_addc_u32 s43, s43, 0
	s_mov_b32 m0, s25
	v_lshl_add_u64 v[222:223], s[42:43], 0, v[136:137]
	ds_read_b128 v[180:183], v146 offset:32768
	ds_read_b128 v[184:187], v146 offset:33792
	ds_read_b128 v[188:191], v146 offset:34816
	ds_read_b128 v[192:195], v146 offset:35840
	ds_read_b128 v[196:199], v146 offset:36864
	ds_read_b128 v[200:203], v146 offset:37888
	ds_read_b128 v[206:209], v146 offset:38912
	ds_read_b128 v[210:213], v146 offset:39936
	global_load_lds_dwordx4 v[222:223], off
	s_mov_b32 m0, s28
	v_lshl_add_u64 v[222:223], s[42:43], 0, v[132:133]
	global_load_lds_dwordx4 v[222:223], off
	s_waitcnt vmcnt(8) lgkmcnt(0)
	s_setprio 1
	s_barrier
	v_mfma_f32_16x16x32_bf16 v[126:129], v[148:151], v[180:183], v[126:129]
	v_mfma_f32_16x16x32_bf16 v[122:125], v[156:159], v[180:183], v[122:125]
	v_mfma_f32_16x16x32_bf16 v[118:121], v[148:151], v[188:191], v[118:121]
	v_mfma_f32_16x16x32_bf16 v[114:117], v[156:159], v[188:191], v[114:117]
	v_mfma_f32_16x16x32_bf16 v[102:105], v[148:151], v[196:199], v[102:105]
	v_mfma_f32_16x16x32_bf16 v[98:101], v[156:159], v[196:199], v[98:101]
	v_mfma_f32_16x16x32_bf16 v[86:89], v[148:151], v[206:209], v[86:89]
	v_mfma_f32_16x16x32_bf16 v[82:85], v[156:159], v[206:209], v[82:85]
	v_mfma_f32_16x16x32_bf16 v[126:129], v[152:155], v[184:187], v[126:129]
	v_mfma_f32_16x16x32_bf16 v[122:125], v[160:163], v[184:187], v[122:125]
	v_mfma_f32_16x16x32_bf16 v[118:121], v[152:155], v[192:195], v[118:121]
	v_mfma_f32_16x16x32_bf16 v[114:117], v[160:163], v[192:195], v[114:117]
	v_mfma_f32_16x16x32_bf16 v[102:105], v[152:155], v[200:203], v[102:105]
	v_mfma_f32_16x16x32_bf16 v[98:101], v[160:163], v[200:203], v[98:101]
	v_mfma_f32_16x16x32_bf16 v[86:89], v[152:155], v[210:213], v[86:89]
	v_mfma_f32_16x16x32_bf16 v[82:85], v[160:163], v[210:213], v[82:85]
	v_mfma_f32_16x16x32_bf16 v[110:113], v[164:167], v[180:183], v[110:113]
	v_mfma_f32_16x16x32_bf16 v[106:109], v[172:175], v[180:183], v[106:109]
	v_mfma_f32_16x16x32_bf16 v[94:97], v[164:167], v[188:191], v[94:97]
	v_mfma_f32_16x16x32_bf16 v[90:93], v[172:175], v[188:191], v[90:93]
	v_mfma_f32_16x16x32_bf16 v[78:81], v[164:167], v[196:199], v[78:81]
	v_mfma_f32_16x16x32_bf16 v[74:77], v[172:175], v[196:199], v[74:77]
	v_mfma_f32_16x16x32_bf16 v[70:73], v[164:167], v[206:209], v[70:73]
	v_mfma_f32_16x16x32_bf16 v[66:69], v[172:175], v[206:209], v[66:69]
	v_mfma_f32_16x16x32_bf16 v[110:113], v[168:171], v[184:187], v[110:113]
	v_mfma_f32_16x16x32_bf16 v[106:109], v[176:179], v[184:187], v[106:109]
	v_mfma_f32_16x16x32_bf16 v[94:97], v[168:171], v[192:195], v[94:97]
	v_mfma_f32_16x16x32_bf16 v[90:93], v[176:179], v[192:195], v[90:93]
	v_mfma_f32_16x16x32_bf16 v[78:81], v[168:171], v[200:203], v[78:81]
	v_mfma_f32_16x16x32_bf16 v[74:77], v[176:179], v[200:203], v[74:77]
	v_mfma_f32_16x16x32_bf16 v[70:73], v[168:171], v[210:213], v[70:73]
	v_mfma_f32_16x16x32_bf16 v[66:69], v[176:179], v[210:213], v[66:69]
	s_setprio 0
	s_barrier
	ds_read_b128 v[180:183], v146 offset:49152
	ds_read_b128 v[184:187], v146 offset:50176
	ds_read_b128 v[188:191], v146 offset:51200
	ds_read_b128 v[192:195], v146 offset:52224
	ds_read_b128 v[196:199], v146 offset:53248
	ds_read_b128 v[200:203], v146 offset:54272
	ds_read_b128 v[206:209], v146 offset:55296
	ds_read_b128 v[210:213], v146 offset:56320
	s_add_i32 s42, s70, s18
	s_mov_b32 m0, s42
	v_lshl_add_u64 v[214:215], v[214:215], 0, s[8:9]
	global_load_lds_dwordx4 v[214:215], off
	s_add_i32 m0, s42, 0x2000
	s_add_u32 s38, s38, 0x200080
	v_lshl_add_u64 v[214:215], v[216:217], 0, s[8:9]
	s_addc_u32 s39, s39, 0
	s_add_i32 s42, s71, s18
	global_load_lds_dwordx4 v[214:215], off
	s_mov_b32 m0, s42
	v_lshl_add_u64 v[214:215], s[38:39], 0, v[134:135]
	global_load_lds_dwordx4 v[214:215], off
	s_add_i32 m0, s42, 0x2000
	v_lshl_add_u64 v[214:215], s[38:39], 0, v[130:131]
	global_load_lds_dwordx4 v[214:215], off
	s_mov_b32 m0, s33
	v_lshl_add_u64 v[214:215], v[218:219], 0, s[8:9]
	global_load_lds_dwordx4 v[214:215], off
	s_mov_b32 m0, s34
	v_lshl_add_u64 v[214:215], v[220:221], 0, s[8:9]
	global_load_lds_dwordx4 v[214:215], off
	s_waitcnt vmcnt(8) lgkmcnt(0)
	s_setprio 1
	s_barrier
	v_mfma_f32_16x16x32_bf16 v[62:65], v[148:151], v[180:183], v[62:65]
	v_mfma_f32_16x16x32_bf16 v[58:61], v[156:159], v[180:183], v[58:61]
	v_mfma_f32_16x16x32_bf16 v[54:57], v[148:151], v[188:191], v[54:57]
	v_mfma_f32_16x16x32_bf16 v[50:53], v[156:159], v[188:191], v[50:53]
	v_mfma_f32_16x16x32_bf16 v[38:41], v[148:151], v[196:199], v[38:41]
	v_mfma_f32_16x16x32_bf16 v[34:37], v[156:159], v[196:199], v[34:37]
	v_mfma_f32_16x16x32_bf16 v[22:25], v[148:151], v[206:209], v[22:25]
	v_mfma_f32_16x16x32_bf16 v[18:21], v[156:159], v[206:209], v[18:21]
	v_mfma_f32_16x16x32_bf16 v[62:65], v[152:155], v[184:187], v[62:65]
	v_mfma_f32_16x16x32_bf16 v[58:61], v[160:163], v[184:187], v[58:61]
	v_mfma_f32_16x16x32_bf16 v[54:57], v[152:155], v[192:195], v[54:57]
	v_mfma_f32_16x16x32_bf16 v[50:53], v[160:163], v[192:195], v[50:53]
	v_mfma_f32_16x16x32_bf16 v[38:41], v[152:155], v[200:203], v[38:41]
	v_mfma_f32_16x16x32_bf16 v[34:37], v[160:163], v[200:203], v[34:37]
	v_mfma_f32_16x16x32_bf16 v[22:25], v[152:155], v[210:213], v[22:25]
	v_mfma_f32_16x16x32_bf16 v[18:21], v[160:163], v[210:213], v[18:21]
	v_mfma_f32_16x16x32_bf16 v[46:49], v[164:167], v[180:183], v[46:49]
	v_mfma_f32_16x16x32_bf16 v[42:45], v[172:175], v[180:183], v[42:45]
	v_mfma_f32_16x16x32_bf16 v[30:33], v[164:167], v[188:191], v[30:33]
	v_mfma_f32_16x16x32_bf16 v[26:29], v[172:175], v[188:191], v[26:29]
	v_mfma_f32_16x16x32_bf16 v[14:17], v[164:167], v[196:199], v[14:17]
	v_mfma_f32_16x16x32_bf16 v[10:13], v[172:175], v[196:199], v[10:13]
	v_mfma_f32_16x16x32_bf16 v[6:9], v[164:167], v[206:209], v[6:9]
	v_mfma_f32_16x16x32_bf16 v[2:5], v[172:175], v[206:209], v[2:5]
	v_mfma_f32_16x16x32_bf16 v[46:49], v[168:171], v[184:187], v[46:49]
	v_mfma_f32_16x16x32_bf16 v[42:45], v[176:179], v[184:187], v[42:45]
	v_mfma_f32_16x16x32_bf16 v[30:33], v[168:171], v[192:195], v[30:33]
	v_mfma_f32_16x16x32_bf16 v[26:29], v[176:179], v[192:195], v[26:29]
	v_mfma_f32_16x16x32_bf16 v[14:17], v[168:171], v[200:203], v[14:17]
	v_mfma_f32_16x16x32_bf16 v[10:13], v[176:179], v[200:203], v[10:13]
	v_mfma_f32_16x16x32_bf16 v[6:9], v[168:171], v[210:213], v[6:9]
	v_mfma_f32_16x16x32_bf16 v[2:5], v[176:179], v[210:213], v[2:5]
	s_setprio 0
	s_barrier
	s_add_i32 s69, s69, 2
	s_add_u32 s36, s36, 0x100
	s_addc_u32 s37, s37, 0
	s_add_u32 s67, s67, 0x100
	s_addc_u32 s68, s68, 0
	s_cmp_gt_u32 s69, 5
.LBB0_477:
	ds_read_b128 v[148:151], v144
	ds_read_b128 v[152:155], v144 offset:1024
	ds_read_b128 v[156:159], v144 offset:2048
	ds_read_b128 v[160:163], v144 offset:3072
	ds_read_b128 v[164:167], v145
	ds_read_b128 v[168:171], v145 offset:1024
	ds_read_b128 v[172:175], v145 offset:2048
	ds_read_b128 v[176:179], v145 offset:3072
	ds_read_b128 v[180:183], v146
	ds_read_b128 v[184:187], v146 offset:1024
	ds_read_b128 v[188:191], v146 offset:2048
	ds_read_b128 v[192:195], v146 offset:3072
	ds_read_b128 v[196:199], v146 offset:4096
	ds_read_b128 v[200:203], v146 offset:5120
	ds_read_b128 v[206:209], v146 offset:6144
	ds_read_b128 v[210:213], v146 offset:7168
	s_add_u32 s38, s36, 0xfffe0080
	s_addc_u32 s39, s37, -1
	s_cmp_eq_u32 s69, 4
	s_cselect_b32 s43, s63, s39
	s_cselect_b32 s42, s64, s38
	s_cselect_b32 s39, s65, s68
	s_cselect_b32 s38, s66, s67
	s_add_i32 m0, s19, 0xc000
	v_lshl_add_u64 v[214:215], s[36:37], 0, v[138:139]
	global_load_lds_dwordx4 v[214:215], off
	s_add_i32 m0, s19, 0xe000
	v_lshl_add_u64 v[214:215], s[36:37], 0, v[140:141]
	global_load_lds_dwordx4 v[214:215], off
	s_waitcnt vmcnt(8) lgkmcnt(0)
	s_setprio 1
	s_barrier
	v_mfma_f32_16x16x32_bf16 v[126:129], v[148:151], v[180:183], v[126:129]
	v_mfma_f32_16x16x32_bf16 v[122:125], v[156:159], v[180:183], v[122:125]
	v_mfma_f32_16x16x32_bf16 v[118:121], v[148:151], v[188:191], v[118:121]
	v_mfma_f32_16x16x32_bf16 v[114:117], v[156:159], v[188:191], v[114:117]
	v_mfma_f32_16x16x32_bf16 v[102:105], v[148:151], v[196:199], v[102:105]
	v_mfma_f32_16x16x32_bf16 v[98:101], v[156:159], v[196:199], v[98:101]
	v_mfma_f32_16x16x32_bf16 v[86:89], v[148:151], v[206:209], v[86:89]
	v_mfma_f32_16x16x32_bf16 v[82:85], v[156:159], v[206:209], v[82:85]
	v_mfma_f32_16x16x32_bf16 v[126:129], v[152:155], v[184:187], v[126:129]
	v_mfma_f32_16x16x32_bf16 v[122:125], v[160:163], v[184:187], v[122:125]
	v_mfma_f32_16x16x32_bf16 v[118:121], v[152:155], v[192:195], v[118:121]
	v_mfma_f32_16x16x32_bf16 v[114:117], v[160:163], v[192:195], v[114:117]
	v_mfma_f32_16x16x32_bf16 v[102:105], v[152:155], v[200:203], v[102:105]
	v_mfma_f32_16x16x32_bf16 v[98:101], v[160:163], v[200:203], v[98:101]
	v_mfma_f32_16x16x32_bf16 v[86:89], v[152:155], v[210:213], v[86:89]
	v_mfma_f32_16x16x32_bf16 v[82:85], v[160:163], v[210:213], v[82:85]
	v_mfma_f32_16x16x32_bf16 v[110:113], v[164:167], v[180:183], v[110:113]
	v_mfma_f32_16x16x32_bf16 v[106:109], v[172:175], v[180:183], v[106:109]
	v_mfma_f32_16x16x32_bf16 v[94:97], v[164:167], v[188:191], v[94:97]
	v_mfma_f32_16x16x32_bf16 v[90:93], v[172:175], v[188:191], v[90:93]
	v_mfma_f32_16x16x32_bf16 v[78:81], v[164:167], v[196:199], v[78:81]
	v_mfma_f32_16x16x32_bf16 v[74:77], v[172:175], v[196:199], v[74:77]
	v_mfma_f32_16x16x32_bf16 v[70:73], v[164:167], v[206:209], v[70:73]
	v_mfma_f32_16x16x32_bf16 v[66:69], v[172:175], v[206:209], v[66:69]
	v_mfma_f32_16x16x32_bf16 v[110:113], v[168:171], v[184:187], v[110:113]
	v_mfma_f32_16x16x32_bf16 v[106:109], v[176:179], v[184:187], v[106:109]
	v_mfma_f32_16x16x32_bf16 v[94:97], v[168:171], v[192:195], v[94:97]
	v_mfma_f32_16x16x32_bf16 v[90:93], v[176:179], v[192:195], v[90:93]
	v_mfma_f32_16x16x32_bf16 v[78:81], v[168:171], v[200:203], v[78:81]
	v_mfma_f32_16x16x32_bf16 v[74:77], v[176:179], v[200:203], v[74:77]
	v_mfma_f32_16x16x32_bf16 v[70:73], v[168:171], v[210:213], v[70:73]
	v_mfma_f32_16x16x32_bf16 v[66:69], v[176:179], v[210:213], v[66:69]
	s_setprio 0
	s_barrier
	ds_read_b128 v[180:183], v146 offset:16384
	ds_read_b128 v[184:187], v146 offset:17408
	ds_read_b128 v[188:191], v146 offset:18432
	ds_read_b128 v[192:195], v146 offset:19456
	ds_read_b128 v[196:199], v146 offset:20480
	ds_read_b128 v[200:203], v146 offset:21504
	ds_read_b128 v[206:209], v146 offset:22528
	ds_read_b128 v[210:213], v146 offset:23552
	s_add_i32 s70, s35, s18
	s_mov_b32 m0, s70
	v_lshl_add_u64 v[214:215], s[38:39], 0, v[134:135]
	global_load_lds_dwordx4 v[214:215], off
	s_add_i32 m0, s70, 0x2000
	s_add_u32 s70, s38, 0x200000
	v_lshl_add_u64 v[216:217], s[38:39], 0, v[130:131]
	s_addc_u32 s71, s39, 0
	s_add_i32 s72, s44, s18
	global_load_lds_dwordx4 v[216:217], off
	v_lshl_add_u64 v[218:219], s[70:71], 0, v[134:135]
	s_mov_b32 m0, s72
	v_lshl_add_u64 v[220:221], s[42:43], 0, v[132:133]
	global_load_lds_dwordx4 v[218:219], off
	s_add_i32 m0, s72, 0x2000
	v_lshl_add_u64 v[218:219], s[70:71], 0, v[130:131]
	global_load_lds_dwordx4 v[218:219], off
	s_mov_b32 m0, s19
	v_lshl_add_u64 v[218:219], s[42:43], 0, v[136:137]
	global_load_lds_dwordx4 v[218:219], off
	s_mov_b32 m0, s24
	s_nop 0
	global_load_lds_dwordx4 v[220:221], off
	s_waitcnt vmcnt(8) lgkmcnt(0)
	s_setprio 1
	s_barrier
	v_mfma_f32_16x16x32_bf16 v[62:65], v[148:151], v[180:183], v[62:65]
	v_mfma_f32_16x16x32_bf16 v[58:61], v[156:159], v[180:183], v[58:61]
	v_mfma_f32_16x16x32_bf16 v[54:57], v[148:151], v[188:191], v[54:57]
	v_mfma_f32_16x16x32_bf16 v[50:53], v[156:159], v[188:191], v[50:53]
	v_mfma_f32_16x16x32_bf16 v[38:41], v[148:151], v[196:199], v[38:41]
	v_mfma_f32_16x16x32_bf16 v[34:37], v[156:159], v[196:199], v[34:37]
	v_mfma_f32_16x16x32_bf16 v[22:25], v[148:151], v[206:209], v[22:25]
	v_mfma_f32_16x16x32_bf16 v[18:21], v[156:159], v[206:209], v[18:21]
	v_mfma_f32_16x16x32_bf16 v[62:65], v[152:155], v[184:187], v[62:65]
	v_mfma_f32_16x16x32_bf16 v[58:61], v[160:163], v[184:187], v[58:61]
	v_mfma_f32_16x16x32_bf16 v[54:57], v[152:155], v[192:195], v[54:57]
	v_mfma_f32_16x16x32_bf16 v[50:53], v[160:163], v[192:195], v[50:53]
	v_mfma_f32_16x16x32_bf16 v[38:41], v[152:155], v[200:203], v[38:41]
	v_mfma_f32_16x16x32_bf16 v[34:37], v[160:163], v[200:203], v[34:37]
	v_mfma_f32_16x16x32_bf16 v[22:25], v[152:155], v[210:213], v[22:25]
	v_mfma_f32_16x16x32_bf16 v[18:21], v[160:163], v[210:213], v[18:21]
	v_mfma_f32_16x16x32_bf16 v[46:49], v[164:167], v[180:183], v[46:49]
	v_mfma_f32_16x16x32_bf16 v[42:45], v[172:175], v[180:183], v[42:45]
	v_mfma_f32_16x16x32_bf16 v[30:33], v[164:167], v[188:191], v[30:33]
	v_mfma_f32_16x16x32_bf16 v[26:29], v[172:175], v[188:191], v[26:29]
	v_mfma_f32_16x16x32_bf16 v[14:17], v[164:167], v[196:199], v[14:17]
	v_mfma_f32_16x16x32_bf16 v[10:13], v[172:175], v[196:199], v[10:13]
	v_mfma_f32_16x16x32_bf16 v[6:9], v[164:167], v[206:209], v[6:9]
	v_mfma_f32_16x16x32_bf16 v[2:5], v[172:175], v[206:209], v[2:5]
	v_mfma_f32_16x16x32_bf16 v[46:49], v[168:171], v[184:187], v[46:49]
	v_mfma_f32_16x16x32_bf16 v[42:45], v[176:179], v[184:187], v[42:45]
	v_mfma_f32_16x16x32_bf16 v[30:33], v[168:171], v[192:195], v[30:33]
	v_mfma_f32_16x16x32_bf16 v[26:29], v[176:179], v[192:195], v[26:29]
	v_mfma_f32_16x16x32_bf16 v[14:17], v[168:171], v[200:203], v[14:17]
	v_mfma_f32_16x16x32_bf16 v[10:13], v[176:179], v[200:203], v[10:13]
	v_mfma_f32_16x16x32_bf16 v[6:9], v[168:171], v[210:213], v[6:9]
	v_mfma_f32_16x16x32_bf16 v[2:5], v[176:179], v[210:213], v[2:5]
	s_setprio 0
	s_barrier
	s_add_i32 s70, 0, 0x18000
	v_add_u32_e32 v147, s70, v143
	s_add_i32 s71, 0, 0x1c000
	ds_read_b128 v[148:151], v147
	ds_read_b128 v[152:155], v147 offset:1024
	ds_read_b128 v[156:159], v147 offset:2048
	ds_read_b128 v[160:163], v147 offset:3072
	v_add_u32_e32 v147, s71, v143
	ds_read_b128 v[164:167], v147
	ds_read_b128 v[168:171], v147 offset:1024
	ds_read_b128 v[172:175], v147 offset:2048
	ds_read_b128 v[176:179], v147 offset:3072
	s_add_u32 s42, s42, 0x20000
	s_addc_u32 s43, s43, 0
	s_mov_b32 m0, s25
	v_lshl_add_u64 v[222:223], s[42:43], 0, v[136:137]
	ds_read_b128 v[180:183], v146 offset:32768
	ds_read_b128 v[184:187], v146 offset:33792
	ds_read_b128 v[188:191], v146 offset:34816
	ds_read_b128 v[192:195], v146 offset:35840
	ds_read_b128 v[196:199], v146 offset:36864
	ds_read_b128 v[200:203], v146 offset:37888
	ds_read_b128 v[206:209], v146 offset:38912
	ds_read_b128 v[210:213], v146 offset:39936
	global_load_lds_dwordx4 v[222:223], off
	s_mov_b32 m0, s28
	v_lshl_add_u64 v[222:223], s[42:43], 0, v[132:133]
	global_load_lds_dwordx4 v[222:223], off
	s_waitcnt vmcnt(8) lgkmcnt(0)
	s_setprio 1
	s_barrier
	v_mfma_f32_16x16x32_bf16 v[126:129], v[148:151], v[180:183], v[126:129]
	v_mfma_f32_16x16x32_bf16 v[122:125], v[156:159], v[180:183], v[122:125]
	v_mfma_f32_16x16x32_bf16 v[118:121], v[148:151], v[188:191], v[118:121]
	v_mfma_f32_16x16x32_bf16 v[114:117], v[156:159], v[188:191], v[114:117]
	v_mfma_f32_16x16x32_bf16 v[102:105], v[148:151], v[196:199], v[102:105]
	v_mfma_f32_16x16x32_bf16 v[98:101], v[156:159], v[196:199], v[98:101]
	v_mfma_f32_16x16x32_bf16 v[86:89], v[148:151], v[206:209], v[86:89]
	v_mfma_f32_16x16x32_bf16 v[82:85], v[156:159], v[206:209], v[82:85]
	v_mfma_f32_16x16x32_bf16 v[126:129], v[152:155], v[184:187], v[126:129]
	v_mfma_f32_16x16x32_bf16 v[122:125], v[160:163], v[184:187], v[122:125]
	v_mfma_f32_16x16x32_bf16 v[118:121], v[152:155], v[192:195], v[118:121]
	v_mfma_f32_16x16x32_bf16 v[114:117], v[160:163], v[192:195], v[114:117]
	v_mfma_f32_16x16x32_bf16 v[102:105], v[152:155], v[200:203], v[102:105]
	v_mfma_f32_16x16x32_bf16 v[98:101], v[160:163], v[200:203], v[98:101]
	v_mfma_f32_16x16x32_bf16 v[86:89], v[152:155], v[210:213], v[86:89]
	v_mfma_f32_16x16x32_bf16 v[82:85], v[160:163], v[210:213], v[82:85]
	v_mfma_f32_16x16x32_bf16 v[110:113], v[164:167], v[180:183], v[110:113]
	v_mfma_f32_16x16x32_bf16 v[106:109], v[172:175], v[180:183], v[106:109]
	v_mfma_f32_16x16x32_bf16 v[94:97], v[164:167], v[188:191], v[94:97]
	v_mfma_f32_16x16x32_bf16 v[90:93], v[172:175], v[188:191], v[90:93]
	v_mfma_f32_16x16x32_bf16 v[78:81], v[164:167], v[196:199], v[78:81]
	v_mfma_f32_16x16x32_bf16 v[74:77], v[172:175], v[196:199], v[74:77]
	v_mfma_f32_16x16x32_bf16 v[70:73], v[164:167], v[206:209], v[70:73]
	v_mfma_f32_16x16x32_bf16 v[66:69], v[172:175], v[206:209], v[66:69]
	v_mfma_f32_16x16x32_bf16 v[110:113], v[168:171], v[184:187], v[110:113]
	v_mfma_f32_16x16x32_bf16 v[106:109], v[176:179], v[184:187], v[106:109]
	v_mfma_f32_16x16x32_bf16 v[94:97], v[168:171], v[192:195], v[94:97]
	v_mfma_f32_16x16x32_bf16 v[90:93], v[176:179], v[192:195], v[90:93]
	v_mfma_f32_16x16x32_bf16 v[78:81], v[168:171], v[200:203], v[78:81]
	v_mfma_f32_16x16x32_bf16 v[74:77], v[176:179], v[200:203], v[74:77]
	v_mfma_f32_16x16x32_bf16 v[70:73], v[168:171], v[210:213], v[70:73]
	v_mfma_f32_16x16x32_bf16 v[66:69], v[176:179], v[210:213], v[66:69]
	s_setprio 0
	s_barrier
	ds_read_b128 v[180:183], v146 offset:49152
	ds_read_b128 v[184:187], v146 offset:50176
	ds_read_b128 v[188:191], v146 offset:51200
	ds_read_b128 v[192:195], v146 offset:52224
	ds_read_b128 v[196:199], v146 offset:53248
	ds_read_b128 v[200:203], v146 offset:54272
	ds_read_b128 v[206:209], v146 offset:55296
	ds_read_b128 v[210:213], v146 offset:56320
	s_add_i32 s42, s70, s18
	s_mov_b32 m0, s42
	v_lshl_add_u64 v[214:215], v[214:215], 0, s[8:9]
	global_load_lds_dwordx4 v[214:215], off
	s_add_i32 m0, s42, 0x2000
	s_add_u32 s38, s38, 0x200080
	v_lshl_add_u64 v[214:215], v[216:217], 0, s[8:9]
	s_addc_u32 s39, s39, 0
	s_add_i32 s42, s71, s18
	global_load_lds_dwordx4 v[214:215], off
	s_mov_b32 m0, s42
	v_lshl_add_u64 v[214:215], s[38:39], 0, v[134:135]
	global_load_lds_dwordx4 v[214:215], off
	s_add_i32 m0, s42, 0x2000
	v_lshl_add_u64 v[214:215], s[38:39], 0, v[130:131]
	global_load_lds_dwordx4 v[214:215], off
	s_mov_b32 m0, s33
	v_lshl_add_u64 v[214:215], v[218:219], 0, s[8:9]
	global_load_lds_dwordx4 v[214:215], off
	s_mov_b32 m0, s34
	v_lshl_add_u64 v[214:215], v[220:221], 0, s[8:9]
	global_load_lds_dwordx4 v[214:215], off
	s_waitcnt vmcnt(8) lgkmcnt(0)
	s_setprio 1
	s_barrier
	v_mfma_f32_16x16x32_bf16 v[62:65], v[148:151], v[180:183], v[62:65]
	v_mfma_f32_16x16x32_bf16 v[58:61], v[156:159], v[180:183], v[58:61]
	v_mfma_f32_16x16x32_bf16 v[54:57], v[148:151], v[188:191], v[54:57]
	v_mfma_f32_16x16x32_bf16 v[50:53], v[156:159], v[188:191], v[50:53]
	v_mfma_f32_16x16x32_bf16 v[38:41], v[148:151], v[196:199], v[38:41]
	v_mfma_f32_16x16x32_bf16 v[34:37], v[156:159], v[196:199], v[34:37]
	v_mfma_f32_16x16x32_bf16 v[22:25], v[148:151], v[206:209], v[22:25]
	v_mfma_f32_16x16x32_bf16 v[18:21], v[156:159], v[206:209], v[18:21]
	v_mfma_f32_16x16x32_bf16 v[62:65], v[152:155], v[184:187], v[62:65]
	v_mfma_f32_16x16x32_bf16 v[58:61], v[160:163], v[184:187], v[58:61]
	v_mfma_f32_16x16x32_bf16 v[54:57], v[152:155], v[192:195], v[54:57]
	v_mfma_f32_16x16x32_bf16 v[50:53], v[160:163], v[192:195], v[50:53]
	v_mfma_f32_16x16x32_bf16 v[38:41], v[152:155], v[200:203], v[38:41]
	v_mfma_f32_16x16x32_bf16 v[34:37], v[160:163], v[200:203], v[34:37]
	v_mfma_f32_16x16x32_bf16 v[22:25], v[152:155], v[210:213], v[22:25]
	v_mfma_f32_16x16x32_bf16 v[18:21], v[160:163], v[210:213], v[18:21]
	v_mfma_f32_16x16x32_bf16 v[46:49], v[164:167], v[180:183], v[46:49]
	v_mfma_f32_16x16x32_bf16 v[42:45], v[172:175], v[180:183], v[42:45]
	v_mfma_f32_16x16x32_bf16 v[30:33], v[164:167], v[188:191], v[30:33]
	v_mfma_f32_16x16x32_bf16 v[26:29], v[172:175], v[188:191], v[26:29]
	v_mfma_f32_16x16x32_bf16 v[14:17], v[164:167], v[196:199], v[14:17]
	v_mfma_f32_16x16x32_bf16 v[10:13], v[172:175], v[196:199], v[10:13]
	v_mfma_f32_16x16x32_bf16 v[6:9], v[164:167], v[206:209], v[6:9]
	v_mfma_f32_16x16x32_bf16 v[2:5], v[172:175], v[206:209], v[2:5]
	v_mfma_f32_16x16x32_bf16 v[46:49], v[168:171], v[184:187], v[46:49]
	v_mfma_f32_16x16x32_bf16 v[42:45], v[176:179], v[184:187], v[42:45]
	v_mfma_f32_16x16x32_bf16 v[30:33], v[168:171], v[192:195], v[30:33]
	v_mfma_f32_16x16x32_bf16 v[26:29], v[176:179], v[192:195], v[26:29]
	v_mfma_f32_16x16x32_bf16 v[14:17], v[168:171], v[200:203], v[14:17]
	v_mfma_f32_16x16x32_bf16 v[10:13], v[176:179], v[200:203], v[10:13]
	v_mfma_f32_16x16x32_bf16 v[6:9], v[168:171], v[210:213], v[6:9]
	v_mfma_f32_16x16x32_bf16 v[2:5], v[176:179], v[210:213], v[2:5]
	s_setprio 0
	s_barrier
	s_add_i32 s69, s69, 2
	s_add_u32 s36, s36, 0x100
	s_addc_u32 s37, s37, 0
	s_add_u32 s67, s67, 0x100
	s_addc_u32 s68, s68, 0
	s_cmp_gt_u32 s69, 5
	s_cbranch_scc0 .LBB0_477
	s_and_b64 vcc, exec, s[10:11]
	s_cbranch_vccz .LBB0_480
	s_barrier

.LBB0_565:
	v_readlane_b32 s62, v249, 27
	v_readlane_b32 s63, v249, 28
	s_add_u32 s72, s62, s68
	s_addc_u32 s73, s63, s69
	s_and_b64 s[62:63], s[70:71], exec
	s_cselect_b32 s31, s73, s77
	s_cselect_b32 s33, s72, s76
	s_add_u32 s74, s35, s66
	s_addc_u32 s75, s85, s67
	s_and_b64 s[62:63], s[70:71], exec
	s_cselect_b32 s34, s75, s79
	s_cselect_b32 s39, s74, s78
	s_add_i32 s45, s7, -2
	s_add_u32 s76, s76, 0x40080
	s_addc_u32 s77, s77, 0
	s_add_u32 s47, s78, 0x100
	s_addc_u32 s62, s79, 0
	s_mov_b32 s63, 0
	ds_read_b128 v[114:117], v190
	ds_read_b128 v[118:121], v190 offset:1024
	ds_read_b128 v[122:125], v190 offset:2048
	ds_read_b128 v[126:129], v190 offset:3072
	ds_read_b128 v[146:149], v191
	ds_read_b128 v[150:153], v191 offset:1024
	ds_read_b128 v[154:157], v191 offset:2048
	ds_read_b128 v[158:161], v191 offset:3072
	ds_read_b128 v[162:165], v192
	ds_read_b128 v[166:169], v192 offset:1024
	ds_read_b128 v[194:197], v192 offset:2048
	ds_read_b128 v[198:201], v192 offset:3072
	ds_read_b128 v[206:209], v192 offset:4096
	ds_read_b128 v[210:213], v192 offset:5120
	ds_read_b128 v[214:217], v192 offset:6144
	ds_read_b128 v[218:221], v192 offset:7168
	s_waitcnt vmcnt(0)
	s_add_i32 s82, s63, 2
	s_add_u32 s78, s76, 0xfffc0080
	s_addc_u32 s79, s77, -1
	s_cmp_eq_u32 s45, s63
	s_cselect_b32 s81, s31, s79
	s_cselect_b32 s80, s33, s78
	s_cselect_b32 s79, s34, s62
	s_cselect_b32 s78, s39, s47
	s_add_i32 m0, s87, 0xc000
	v_lshl_add_u64 v[186:187], s[76:77], 0, v[180:181]
	global_load_lds_dwordx4 v[186:187], off
	s_add_i32 m0, s87, 0xe000
	v_lshl_add_u64 v[186:187], s[76:77], 0, v[182:183]
	global_load_lds_dwordx4 v[186:187], off
	s_waitcnt vmcnt(8)
	s_waitcnt lgkmcnt(0)
	s_setprio 1
	s_barrier
	v_mfma_f32_16x16x32_bf16 v[142:145], v[114:117], v[162:165], 0
	v_mfma_f32_16x16x32_bf16 v[138:141], v[122:125], v[162:165], 0
	v_mfma_f32_16x16x32_bf16 v[110:113], v[114:117], v[194:197], 0
	v_mfma_f32_16x16x32_bf16 v[106:109], v[122:125], v[194:197], 0
	v_mfma_f32_16x16x32_bf16 v[98:101], v[114:117], v[206:209], 0
	v_mfma_f32_16x16x32_bf16 v[90:93], v[122:125], v[206:209], 0
	v_mfma_f32_16x16x32_bf16 v[82:85], v[114:117], v[214:217], 0
	v_mfma_f32_16x16x32_bf16 v[74:77], v[122:125], v[214:217], 0
	v_mfma_f32_16x16x32_bf16 v[142:145], v[118:121], v[166:169], v[142:145]
	v_mfma_f32_16x16x32_bf16 v[138:141], v[126:129], v[166:169], v[138:141]
	v_mfma_f32_16x16x32_bf16 v[110:113], v[118:121], v[198:201], v[110:113]
	v_mfma_f32_16x16x32_bf16 v[106:109], v[126:129], v[198:201], v[106:109]
	v_mfma_f32_16x16x32_bf16 v[98:101], v[118:121], v[210:213], v[98:101]
	v_mfma_f32_16x16x32_bf16 v[90:93], v[126:129], v[210:213], v[90:93]
	v_mfma_f32_16x16x32_bf16 v[82:85], v[118:121], v[218:221], v[82:85]
	v_mfma_f32_16x16x32_bf16 v[74:77], v[126:129], v[218:221], v[74:77]
	v_mfma_f32_16x16x32_bf16 v[134:137], v[146:149], v[162:165], 0
	v_mfma_f32_16x16x32_bf16 v[130:133], v[154:157], v[162:165], 0
	v_mfma_f32_16x16x32_bf16 v[102:105], v[146:149], v[194:197], 0
	v_mfma_f32_16x16x32_bf16 v[94:97], v[154:157], v[194:197], 0
	v_mfma_f32_16x16x32_bf16 v[86:89], v[146:149], v[206:209], 0
	v_mfma_f32_16x16x32_bf16 v[78:81], v[154:157], v[206:209], 0
	v_mfma_f32_16x16x32_bf16 v[70:73], v[146:149], v[214:217], 0
	v_mfma_f32_16x16x32_bf16 v[66:69], v[154:157], v[214:217], 0
	v_mfma_f32_16x16x32_bf16 v[134:137], v[150:153], v[166:169], v[134:137]
	v_mfma_f32_16x16x32_bf16 v[130:133], v[158:161], v[166:169], v[130:133]
	v_mfma_f32_16x16x32_bf16 v[102:105], v[150:153], v[198:201], v[102:105]
	v_mfma_f32_16x16x32_bf16 v[94:97], v[158:161], v[198:201], v[94:97]
	v_mfma_f32_16x16x32_bf16 v[86:89], v[150:153], v[210:213], v[86:89]
	v_mfma_f32_16x16x32_bf16 v[78:81], v[158:161], v[210:213], v[78:81]
	v_mfma_f32_16x16x32_bf16 v[70:73], v[150:153], v[218:221], v[70:73]
	v_mfma_f32_16x16x32_bf16 v[66:69], v[158:161], v[218:221], v[66:69]
	s_setprio 0
	s_barrier
	ds_read_b128 v[162:165], v192 offset:16384
	ds_read_b128 v[166:169], v192 offset:17408
	ds_read_b128 v[194:197], v192 offset:18432
	ds_read_b128 v[198:201], v192 offset:19456
	ds_read_b128 v[206:209], v192 offset:20480
	ds_read_b128 v[210:213], v192 offset:21504
	ds_read_b128 v[214:217], v192 offset:22528
	ds_read_b128 v[218:221], v192 offset:23552
	s_add_i32 s63, s24, s86
	s_mov_b32 m0, s63
	v_lshl_add_u64 v[186:187], s[78:79], 0, v[172:173]
	global_load_lds_dwordx4 v[186:187], off
	s_add_i32 m0, s63, 0x2000
	s_add_u32 vcc_lo, s78, 0x40000
	v_lshl_add_u64 v[202:203], s[78:79], 0, v[176:177]
	s_addc_u32 vcc_hi, s79, 0
	s_add_i32 s63, s25, s86
	global_load_lds_dwordx4 v[202:203], off
	v_lshl_add_u64 v[222:223], vcc, 0, v[172:173]
	s_mov_b32 m0, s63
	v_lshl_add_u64 v[224:225], s[80:81], 0, v[174:175]
	global_load_lds_dwordx4 v[222:223], off
	s_add_i32 m0, s63, 0x2000
	v_lshl_add_u64 v[222:223], vcc, 0, v[176:177]
	global_load_lds_dwordx4 v[222:223], off
	s_mov_b32 m0, s87
	v_lshl_add_u64 v[222:223], s[80:81], 0, v[170:171]
	global_load_lds_dwordx4 v[222:223], off
	s_mov_b32 m0, s88
	s_nop 0
	global_load_lds_dwordx4 v[224:225], off
	s_waitcnt vmcnt(8) lgkmcnt(0)
	s_setprio 1
	s_barrier
	v_mfma_f32_16x16x32_bf16 v[62:65], v[114:117], v[162:165], 0
	v_mfma_f32_16x16x32_bf16 v[58:61], v[122:125], v[162:165], 0
	v_mfma_f32_16x16x32_bf16 v[50:53], v[114:117], v[194:197], 0
	v_mfma_f32_16x16x32_bf16 v[42:45], v[122:125], v[194:197], 0
	v_mfma_f32_16x16x32_bf16 v[34:37], v[114:117], v[206:209], 0
	v_mfma_f32_16x16x32_bf16 v[26:29], v[122:125], v[206:209], 0
	v_mfma_f32_16x16x32_bf16 v[18:21], v[114:117], v[214:217], 0
	v_mfma_f32_16x16x32_bf16 v[10:13], v[122:125], v[214:217], 0
	v_mfma_f32_16x16x32_bf16 v[62:65], v[118:121], v[166:169], v[62:65]
	v_mfma_f32_16x16x32_bf16 v[58:61], v[126:129], v[166:169], v[58:61]
	v_mfma_f32_16x16x32_bf16 v[50:53], v[118:121], v[198:201], v[50:53]
	v_mfma_f32_16x16x32_bf16 v[42:45], v[126:129], v[198:201], v[42:45]
	v_mfma_f32_16x16x32_bf16 v[34:37], v[118:121], v[210:213], v[34:37]
	v_mfma_f32_16x16x32_bf16 v[26:29], v[126:129], v[210:213], v[26:29]
	v_mfma_f32_16x16x32_bf16 v[18:21], v[118:121], v[218:221], v[18:21]
	v_mfma_f32_16x16x32_bf16 v[10:13], v[126:129], v[218:221], v[10:13]
	v_mfma_f32_16x16x32_bf16 v[54:57], v[146:149], v[162:165], 0
	v_mfma_f32_16x16x32_bf16 v[46:49], v[154:157], v[162:165], 0
	v_mfma_f32_16x16x32_bf16 v[38:41], v[146:149], v[194:197], 0
	v_mfma_f32_16x16x32_bf16 v[30:33], v[154:157], v[194:197], 0
	v_mfma_f32_16x16x32_bf16 v[22:25], v[146:149], v[206:209], 0
	v_mfma_f32_16x16x32_bf16 v[14:17], v[154:157], v[206:209], 0
	v_mfma_f32_16x16x32_bf16 v[6:9], v[146:149], v[214:217], 0
	v_mfma_f32_16x16x32_bf16 v[2:5], v[154:157], v[214:217], 0
	v_mfma_f32_16x16x32_bf16 v[54:57], v[150:153], v[166:169], v[54:57]
	v_mfma_f32_16x16x32_bf16 v[46:49], v[158:161], v[166:169], v[46:49]
	v_mfma_f32_16x16x32_bf16 v[38:41], v[150:153], v[198:201], v[38:41]
	v_mfma_f32_16x16x32_bf16 v[30:33], v[158:161], v[198:201], v[30:33]
	v_mfma_f32_16x16x32_bf16 v[22:25], v[150:153], v[210:213], v[22:25]
	v_mfma_f32_16x16x32_bf16 v[14:17], v[158:161], v[210:213], v[14:17]
	v_mfma_f32_16x16x32_bf16 v[6:9], v[150:153], v[218:221], v[6:9]
	v_mfma_f32_16x16x32_bf16 v[2:5], v[158:161], v[218:221], v[2:5]
	s_setprio 0
	s_barrier
	s_add_i32 s63, 0, 0x18000
	s_add_i32 s83, 0, 0x1c000
	v_add_u32_e32 v126, s63, v189
	v_add_u32_e32 v158, s83, v189
	ds_read_b128 v[114:117], v126
	ds_read_b128 v[118:121], v126 offset:1024
	ds_read_b128 v[122:125], v126 offset:2048
	ds_read_b128 v[126:129], v126 offset:3072
	ds_read_b128 v[146:149], v158
	ds_read_b128 v[150:153], v158 offset:1024
	ds_read_b128 v[154:157], v158 offset:2048
	ds_read_b128 v[158:161], v158 offset:3072
	s_add_u32 s80, s80, 0x40000
	s_addc_u32 s81, s81, 0
	s_mov_b32 m0, s89
	v_lshl_add_u64 v[226:227], s[80:81], 0, v[170:171]
	ds_read_b128 v[162:165], v192 offset:32768
	ds_read_b128 v[166:169], v192 offset:33792
	ds_read_b128 v[194:197], v192 offset:34816
	ds_read_b128 v[198:201], v192 offset:35840
	ds_read_b128 v[206:209], v192 offset:36864
	ds_read_b128 v[210:213], v192 offset:37888
	ds_read_b128 v[214:217], v192 offset:38912
	ds_read_b128 v[218:221], v192 offset:39936
	global_load_lds_dwordx4 v[226:227], off
	s_mov_b32 m0, s90
	v_lshl_add_u64 v[226:227], s[80:81], 0, v[174:175]
	global_load_lds_dwordx4 v[226:227], off
	s_waitcnt vmcnt(8) lgkmcnt(0)
	s_setprio 1
	s_barrier
	v_mfma_f32_16x16x32_bf16 v[142:145], v[114:117], v[162:165], v[142:145]
	v_mfma_f32_16x16x32_bf16 v[138:141], v[122:125], v[162:165], v[138:141]
	v_mfma_f32_16x16x32_bf16 v[110:113], v[114:117], v[194:197], v[110:113]
	v_mfma_f32_16x16x32_bf16 v[106:109], v[122:125], v[194:197], v[106:109]
	v_mfma_f32_16x16x32_bf16 v[98:101], v[114:117], v[206:209], v[98:101]
	v_mfma_f32_16x16x32_bf16 v[90:93], v[122:125], v[206:209], v[90:93]
	v_mfma_f32_16x16x32_bf16 v[82:85], v[114:117], v[214:217], v[82:85]
	v_mfma_f32_16x16x32_bf16 v[74:77], v[122:125], v[214:217], v[74:77]
	v_mfma_f32_16x16x32_bf16 v[142:145], v[118:121], v[166:169], v[142:145]
	v_mfma_f32_16x16x32_bf16 v[138:141], v[126:129], v[166:169], v[138:141]
	v_mfma_f32_16x16x32_bf16 v[110:113], v[118:121], v[198:201], v[110:113]
	v_mfma_f32_16x16x32_bf16 v[106:109], v[126:129], v[198:201], v[106:109]
	v_mfma_f32_16x16x32_bf16 v[98:101], v[118:121], v[210:213], v[98:101]
	v_mfma_f32_16x16x32_bf16 v[90:93], v[126:129], v[210:213], v[90:93]
	v_mfma_f32_16x16x32_bf16 v[82:85], v[118:121], v[218:221], v[82:85]
	v_mfma_f32_16x16x32_bf16 v[74:77], v[126:129], v[218:221], v[74:77]
	v_mfma_f32_16x16x32_bf16 v[134:137], v[146:149], v[162:165], v[134:137]
	v_mfma_f32_16x16x32_bf16 v[130:133], v[154:157], v[162:165], v[130:133]
	v_mfma_f32_16x16x32_bf16 v[102:105], v[146:149], v[194:197], v[102:105]
	v_mfma_f32_16x16x32_bf16 v[94:97], v[154:157], v[194:197], v[94:97]
	v_mfma_f32_16x16x32_bf16 v[86:89], v[146:149], v[206:209], v[86:89]
	v_mfma_f32_16x16x32_bf16 v[78:81], v[154:157], v[206:209], v[78:81]
	v_mfma_f32_16x16x32_bf16 v[70:73], v[146:149], v[214:217], v[70:73]
	v_mfma_f32_16x16x32_bf16 v[66:69], v[154:157], v[214:217], v[66:69]
	v_mfma_f32_16x16x32_bf16 v[134:137], v[150:153], v[166:169], v[134:137]
	v_mfma_f32_16x16x32_bf16 v[130:133], v[158:161], v[166:169], v[130:133]
	v_mfma_f32_16x16x32_bf16 v[102:105], v[150:153], v[198:201], v[102:105]
	v_mfma_f32_16x16x32_bf16 v[94:97], v[158:161], v[198:201], v[94:97]
	v_mfma_f32_16x16x32_bf16 v[86:89], v[150:153], v[210:213], v[86:89]
	v_mfma_f32_16x16x32_bf16 v[78:81], v[158:161], v[210:213], v[78:81]
	v_mfma_f32_16x16x32_bf16 v[70:73], v[150:153], v[218:221], v[70:73]
	v_mfma_f32_16x16x32_bf16 v[66:69], v[158:161], v[218:221], v[66:69]
	s_setprio 0
	s_barrier
	ds_read_b128 v[162:165], v192 offset:49152
	ds_read_b128 v[166:169], v192 offset:50176
	ds_read_b128 v[194:197], v192 offset:51200
	ds_read_b128 v[198:201], v192 offset:52224
	ds_read_b128 v[206:209], v192 offset:53248
	ds_read_b128 v[210:213], v192 offset:54272
	ds_read_b128 v[214:217], v192 offset:55296
	ds_read_b128 v[218:221], v192 offset:56320
	s_add_i32 s63, s63, s86
	s_mov_b32 m0, s63
	v_lshl_add_u64 v[186:187], v[186:187], 0, s[22:23]
	global_load_lds_dwordx4 v[186:187], off
	s_add_i32 m0, s63, 0x2000
	s_add_u32 s78, s78, 0x40080
	v_lshl_add_u64 v[186:187], v[202:203], 0, s[22:23]
	s_addc_u32 s79, s79, 0
	s_add_i32 s63, s83, s86
	global_load_lds_dwordx4 v[186:187], off
	s_mov_b32 m0, s63
	v_lshl_add_u64 v[186:187], s[78:79], 0, v[172:173]
	global_load_lds_dwordx4 v[186:187], off
	s_add_i32 m0, s63, 0x2000
	v_lshl_add_u64 v[186:187], s[78:79], 0, v[176:177]
	global_load_lds_dwordx4 v[186:187], off
	s_mov_b32 m0, s95
	v_lshl_add_u64 v[186:187], v[222:223], 0, s[22:23]
	global_load_lds_dwordx4 v[186:187], off
	s_mov_b32 m0, s96
	v_lshl_add_u64 v[186:187], v[224:225], 0, s[22:23]
	global_load_lds_dwordx4 v[186:187], off
	s_waitcnt vmcnt(8) lgkmcnt(0)
	s_setprio 1
	s_barrier
	v_mfma_f32_16x16x32_bf16 v[62:65], v[114:117], v[162:165], v[62:65]
	v_mfma_f32_16x16x32_bf16 v[58:61], v[122:125], v[162:165], v[58:61]
	v_mfma_f32_16x16x32_bf16 v[50:53], v[114:117], v[194:197], v[50:53]
	v_mfma_f32_16x16x32_bf16 v[42:45], v[122:125], v[194:197], v[42:45]
	v_mfma_f32_16x16x32_bf16 v[34:37], v[114:117], v[206:209], v[34:37]
	v_mfma_f32_16x16x32_bf16 v[26:29], v[122:125], v[206:209], v[26:29]
	v_mfma_f32_16x16x32_bf16 v[18:21], v[114:117], v[214:217], v[18:21]
	v_mfma_f32_16x16x32_bf16 v[10:13], v[122:125], v[214:217], v[10:13]
	v_mfma_f32_16x16x32_bf16 v[62:65], v[118:121], v[166:169], v[62:65]
	v_mfma_f32_16x16x32_bf16 v[58:61], v[126:129], v[166:169], v[58:61]
	v_mfma_f32_16x16x32_bf16 v[50:53], v[118:121], v[198:201], v[50:53]
	v_mfma_f32_16x16x32_bf16 v[42:45], v[126:129], v[198:201], v[42:45]
	v_mfma_f32_16x16x32_bf16 v[34:37], v[118:121], v[210:213], v[34:37]
	v_mfma_f32_16x16x32_bf16 v[26:29], v[126:129], v[210:213], v[26:29]
	v_mfma_f32_16x16x32_bf16 v[18:21], v[118:121], v[218:221], v[18:21]
	v_mfma_f32_16x16x32_bf16 v[10:13], v[126:129], v[218:221], v[10:13]
	v_mfma_f32_16x16x32_bf16 v[54:57], v[146:149], v[162:165], v[54:57]
	v_mfma_f32_16x16x32_bf16 v[46:49], v[154:157], v[162:165], v[46:49]
	v_mfma_f32_16x16x32_bf16 v[38:41], v[146:149], v[194:197], v[38:41]
	v_mfma_f32_16x16x32_bf16 v[30:33], v[154:157], v[194:197], v[30:33]
	v_mfma_f32_16x16x32_bf16 v[22:25], v[146:149], v[206:209], v[22:25]
	v_mfma_f32_16x16x32_bf16 v[14:17], v[154:157], v[206:209], v[14:17]
	v_mfma_f32_16x16x32_bf16 v[6:9], v[146:149], v[214:217], v[6:9]
	v_mfma_f32_16x16x32_bf16 v[2:5], v[154:157], v[214:217], v[2:5]
	v_mfma_f32_16x16x32_bf16 v[54:57], v[150:153], v[166:169], v[54:57]
	v_mfma_f32_16x16x32_bf16 v[46:49], v[158:161], v[166:169], v[46:49]
	v_mfma_f32_16x16x32_bf16 v[38:41], v[150:153], v[198:201], v[38:41]
	v_mfma_f32_16x16x32_bf16 v[30:33], v[158:161], v[198:201], v[30:33]
	v_mfma_f32_16x16x32_bf16 v[22:25], v[150:153], v[210:213], v[22:25]
	v_mfma_f32_16x16x32_bf16 v[14:17], v[158:161], v[210:213], v[14:17]
	v_mfma_f32_16x16x32_bf16 v[6:9], v[150:153], v[218:221], v[6:9]
	v_mfma_f32_16x16x32_bf16 v[2:5], v[158:161], v[218:221], v[2:5]
	s_setprio 0
	s_barrier
	s_add_u32 s76, s76, 0x100
	s_addc_u32 s77, s77, 0
	s_add_u32 s47, s47, 0x100
	s_addc_u32 s62, s62, 0
	s_cmp_ge_i32 s82, s7
	s_mov_b32 s63, s82
.LBB0_566:
	ds_read_b128 v[114:117], v190
	ds_read_b128 v[118:121], v190 offset:1024
	ds_read_b128 v[122:125], v190 offset:2048
	ds_read_b128 v[126:129], v190 offset:3072
	ds_read_b128 v[146:149], v191
	ds_read_b128 v[150:153], v191 offset:1024
	ds_read_b128 v[154:157], v191 offset:2048
	ds_read_b128 v[158:161], v191 offset:3072
	ds_read_b128 v[162:165], v192
	ds_read_b128 v[166:169], v192 offset:1024
	ds_read_b128 v[194:197], v192 offset:2048
	ds_read_b128 v[198:201], v192 offset:3072
	ds_read_b128 v[206:209], v192 offset:4096
	ds_read_b128 v[210:213], v192 offset:5120
	ds_read_b128 v[214:217], v192 offset:6144
	ds_read_b128 v[218:221], v192 offset:7168
	s_waitcnt vmcnt(0)
	s_add_i32 s82, s63, 2
	s_add_u32 s78, s76, 0xfffc0080
	s_addc_u32 s79, s77, -1
	s_cmp_eq_u32 s45, s63
	s_cselect_b32 s81, s31, s79
	s_cselect_b32 s80, s33, s78
	s_cselect_b32 s79, s34, s62
	s_cselect_b32 s78, s39, s47
	s_add_i32 m0, s87, 0xc000
	v_lshl_add_u64 v[186:187], s[76:77], 0, v[180:181]
	global_load_lds_dwordx4 v[186:187], off
	s_add_i32 m0, s87, 0xe000
	v_lshl_add_u64 v[186:187], s[76:77], 0, v[182:183]
	global_load_lds_dwordx4 v[186:187], off
	s_waitcnt vmcnt(8)
	s_waitcnt lgkmcnt(0)
	s_setprio 1
	s_barrier
	v_mfma_f32_16x16x32_bf16 v[142:145], v[114:117], v[162:165], v[142:145]
	v_mfma_f32_16x16x32_bf16 v[138:141], v[122:125], v[162:165], v[138:141]
	v_mfma_f32_16x16x32_bf16 v[110:113], v[114:117], v[194:197], v[110:113]
	v_mfma_f32_16x16x32_bf16 v[106:109], v[122:125], v[194:197], v[106:109]
	v_mfma_f32_16x16x32_bf16 v[98:101], v[114:117], v[206:209], v[98:101]
	v_mfma_f32_16x16x32_bf16 v[90:93], v[122:125], v[206:209], v[90:93]
	v_mfma_f32_16x16x32_bf16 v[82:85], v[114:117], v[214:217], v[82:85]
	v_mfma_f32_16x16x32_bf16 v[74:77], v[122:125], v[214:217], v[74:77]
	v_mfma_f32_16x16x32_bf16 v[142:145], v[118:121], v[166:169], v[142:145]
	v_mfma_f32_16x16x32_bf16 v[138:141], v[126:129], v[166:169], v[138:141]
	v_mfma_f32_16x16x32_bf16 v[110:113], v[118:121], v[198:201], v[110:113]
	v_mfma_f32_16x16x32_bf16 v[106:109], v[126:129], v[198:201], v[106:109]
	v_mfma_f32_16x16x32_bf16 v[98:101], v[118:121], v[210:213], v[98:101]
	v_mfma_f32_16x16x32_bf16 v[90:93], v[126:129], v[210:213], v[90:93]
	v_mfma_f32_16x16x32_bf16 v[82:85], v[118:121], v[218:221], v[82:85]
	v_mfma_f32_16x16x32_bf16 v[74:77], v[126:129], v[218:221], v[74:77]
	v_mfma_f32_16x16x32_bf16 v[134:137], v[146:149], v[162:165], v[134:137]
	v_mfma_f32_16x16x32_bf16 v[130:133], v[154:157], v[162:165], v[130:133]
	v_mfma_f32_16x16x32_bf16 v[102:105], v[146:149], v[194:197], v[102:105]
	v_mfma_f32_16x16x32_bf16 v[94:97], v[154:157], v[194:197], v[94:97]
	v_mfma_f32_16x16x32_bf16 v[86:89], v[146:149], v[206:209], v[86:89]
	v_mfma_f32_16x16x32_bf16 v[78:81], v[154:157], v[206:209], v[78:81]
	v_mfma_f32_16x16x32_bf16 v[70:73], v[146:149], v[214:217], v[70:73]
	v_mfma_f32_16x16x32_bf16 v[66:69], v[154:157], v[214:217], v[66:69]
	v_mfma_f32_16x16x32_bf16 v[134:137], v[150:153], v[166:169], v[134:137]
	v_mfma_f32_16x16x32_bf16 v[130:133], v[158:161], v[166:169], v[130:133]
	v_mfma_f32_16x16x32_bf16 v[102:105], v[150:153], v[198:201], v[102:105]
	v_mfma_f32_16x16x32_bf16 v[94:97], v[158:161], v[198:201], v[94:97]
	v_mfma_f32_16x16x32_bf16 v[86:89], v[150:153], v[210:213], v[86:89]
	v_mfma_f32_16x16x32_bf16 v[78:81], v[158:161], v[210:213], v[78:81]
	v_mfma_f32_16x16x32_bf16 v[70:73], v[150:153], v[218:221], v[70:73]
	v_mfma_f32_16x16x32_bf16 v[66:69], v[158:161], v[218:221], v[66:69]
	s_setprio 0
	s_barrier
	ds_read_b128 v[162:165], v192 offset:16384
	ds_read_b128 v[166:169], v192 offset:17408
	ds_read_b128 v[194:197], v192 offset:18432
	ds_read_b128 v[198:201], v192 offset:19456
	ds_read_b128 v[206:209], v192 offset:20480
	ds_read_b128 v[210:213], v192 offset:21504
	ds_read_b128 v[214:217], v192 offset:22528
	ds_read_b128 v[218:221], v192 offset:23552
	s_add_i32 s63, s24, s86
	s_mov_b32 m0, s63
	v_lshl_add_u64 v[186:187], s[78:79], 0, v[172:173]
	global_load_lds_dwordx4 v[186:187], off
	s_add_i32 m0, s63, 0x2000
	s_add_u32 vcc_lo, s78, 0x40000
	v_lshl_add_u64 v[202:203], s[78:79], 0, v[176:177]
	s_addc_u32 vcc_hi, s79, 0
	s_add_i32 s63, s25, s86
	global_load_lds_dwordx4 v[202:203], off
	v_lshl_add_u64 v[222:223], vcc, 0, v[172:173]
	s_mov_b32 m0, s63
	v_lshl_add_u64 v[224:225], s[80:81], 0, v[174:175]
	global_load_lds_dwordx4 v[222:223], off
	s_add_i32 m0, s63, 0x2000
	v_lshl_add_u64 v[222:223], vcc, 0, v[176:177]
	global_load_lds_dwordx4 v[222:223], off
	s_mov_b32 m0, s87
	v_lshl_add_u64 v[222:223], s[80:81], 0, v[170:171]
	global_load_lds_dwordx4 v[222:223], off
	s_mov_b32 m0, s88
	s_nop 0
	global_load_lds_dwordx4 v[224:225], off
	s_waitcnt vmcnt(8) lgkmcnt(0)
	s_setprio 1
	s_barrier
	v_mfma_f32_16x16x32_bf16 v[62:65], v[114:117], v[162:165], v[62:65]
	v_mfma_f32_16x16x32_bf16 v[58:61], v[122:125], v[162:165], v[58:61]
	v_mfma_f32_16x16x32_bf16 v[50:53], v[114:117], v[194:197], v[50:53]
	v_mfma_f32_16x16x32_bf16 v[42:45], v[122:125], v[194:197], v[42:45]
	v_mfma_f32_16x16x32_bf16 v[34:37], v[114:117], v[206:209], v[34:37]
	v_mfma_f32_16x16x32_bf16 v[26:29], v[122:125], v[206:209], v[26:29]
	v_mfma_f32_16x16x32_bf16 v[18:21], v[114:117], v[214:217], v[18:21]
	v_mfma_f32_16x16x32_bf16 v[10:13], v[122:125], v[214:217], v[10:13]
	v_mfma_f32_16x16x32_bf16 v[62:65], v[118:121], v[166:169], v[62:65]
	v_mfma_f32_16x16x32_bf16 v[58:61], v[126:129], v[166:169], v[58:61]
	v_mfma_f32_16x16x32_bf16 v[50:53], v[118:121], v[198:201], v[50:53]
	v_mfma_f32_16x16x32_bf16 v[42:45], v[126:129], v[198:201], v[42:45]
	v_mfma_f32_16x16x32_bf16 v[34:37], v[118:121], v[210:213], v[34:37]
	v_mfma_f32_16x16x32_bf16 v[26:29], v[126:129], v[210:213], v[26:29]
	v_mfma_f32_16x16x32_bf16 v[18:21], v[118:121], v[218:221], v[18:21]
	v_mfma_f32_16x16x32_bf16 v[10:13], v[126:129], v[218:221], v[10:13]
	v_mfma_f32_16x16x32_bf16 v[54:57], v[146:149], v[162:165], v[54:57]
	v_mfma_f32_16x16x32_bf16 v[46:49], v[154:157], v[162:165], v[46:49]
	v_mfma_f32_16x16x32_bf16 v[38:41], v[146:149], v[194:197], v[38:41]
	v_mfma_f32_16x16x32_bf16 v[30:33], v[154:157], v[194:197], v[30:33]
	v_mfma_f32_16x16x32_bf16 v[22:25], v[146:149], v[206:209], v[22:25]
	v_mfma_f32_16x16x32_bf16 v[14:17], v[154:157], v[206:209], v[14:17]
	v_mfma_f32_16x16x32_bf16 v[6:9], v[146:149], v[214:217], v[6:9]
	v_mfma_f32_16x16x32_bf16 v[2:5], v[154:157], v[214:217], v[2:5]
	v_mfma_f32_16x16x32_bf16 v[54:57], v[150:153], v[166:169], v[54:57]
	v_mfma_f32_16x16x32_bf16 v[46:49], v[158:161], v[166:169], v[46:49]
	v_mfma_f32_16x16x32_bf16 v[38:41], v[150:153], v[198:201], v[38:41]
	v_mfma_f32_16x16x32_bf16 v[30:33], v[158:161], v[198:201], v[30:33]
	v_mfma_f32_16x16x32_bf16 v[22:25], v[150:153], v[210:213], v[22:25]
	v_mfma_f32_16x16x32_bf16 v[14:17], v[158:161], v[210:213], v[14:17]
	v_mfma_f32_16x16x32_bf16 v[6:9], v[150:153], v[218:221], v[6:9]
	v_mfma_f32_16x16x32_bf16 v[2:5], v[158:161], v[218:221], v[2:5]
	s_setprio 0
	s_barrier
	s_add_i32 s63, 0, 0x18000
	s_add_i32 s83, 0, 0x1c000
	v_add_u32_e32 v126, s63, v189
	v_add_u32_e32 v158, s83, v189
	ds_read_b128 v[114:117], v126
	ds_read_b128 v[118:121], v126 offset:1024
	ds_read_b128 v[122:125], v126 offset:2048
	ds_read_b128 v[126:129], v126 offset:3072
	ds_read_b128 v[146:149], v158
	ds_read_b128 v[150:153], v158 offset:1024
	ds_read_b128 v[154:157], v158 offset:2048
	ds_read_b128 v[158:161], v158 offset:3072
	s_add_u32 s80, s80, 0x40000
	s_addc_u32 s81, s81, 0
	s_mov_b32 m0, s89
	v_lshl_add_u64 v[226:227], s[80:81], 0, v[170:171]
	ds_read_b128 v[162:165], v192 offset:32768
	ds_read_b128 v[166:169], v192 offset:33792
	ds_read_b128 v[194:197], v192 offset:34816
	ds_read_b128 v[198:201], v192 offset:35840
	ds_read_b128 v[206:209], v192 offset:36864
	ds_read_b128 v[210:213], v192 offset:37888
	ds_read_b128 v[214:217], v192 offset:38912
	ds_read_b128 v[218:221], v192 offset:39936
	global_load_lds_dwordx4 v[226:227], off
	s_mov_b32 m0, s90
	v_lshl_add_u64 v[226:227], s[80:81], 0, v[174:175]
	global_load_lds_dwordx4 v[226:227], off
	s_waitcnt vmcnt(8) lgkmcnt(0)
	s_setprio 1
	s_barrier
	v_mfma_f32_16x16x32_bf16 v[142:145], v[114:117], v[162:165], v[142:145]
	v_mfma_f32_16x16x32_bf16 v[138:141], v[122:125], v[162:165], v[138:141]
	v_mfma_f32_16x16x32_bf16 v[110:113], v[114:117], v[194:197], v[110:113]
	v_mfma_f32_16x16x32_bf16 v[106:109], v[122:125], v[194:197], v[106:109]
	v_mfma_f32_16x16x32_bf16 v[98:101], v[114:117], v[206:209], v[98:101]
	v_mfma_f32_16x16x32_bf16 v[90:93], v[122:125], v[206:209], v[90:93]
	v_mfma_f32_16x16x32_bf16 v[82:85], v[114:117], v[214:217], v[82:85]
	v_mfma_f32_16x16x32_bf16 v[74:77], v[122:125], v[214:217], v[74:77]
	v_mfma_f32_16x16x32_bf16 v[142:145], v[118:121], v[166:169], v[142:145]
	v_mfma_f32_16x16x32_bf16 v[138:141], v[126:129], v[166:169], v[138:141]
	v_mfma_f32_16x16x32_bf16 v[110:113], v[118:121], v[198:201], v[110:113]
	v_mfma_f32_16x16x32_bf16 v[106:109], v[126:129], v[198:201], v[106:109]
	v_mfma_f32_16x16x32_bf16 v[98:101], v[118:121], v[210:213], v[98:101]
	v_mfma_f32_16x16x32_bf16 v[90:93], v[126:129], v[210:213], v[90:93]
	v_mfma_f32_16x16x32_bf16 v[82:85], v[118:121], v[218:221], v[82:85]
	v_mfma_f32_16x16x32_bf16 v[74:77], v[126:129], v[218:221], v[74:77]
	v_mfma_f32_16x16x32_bf16 v[134:137], v[146:149], v[162:165], v[134:137]
	v_mfma_f32_16x16x32_bf16 v[130:133], v[154:157], v[162:165], v[130:133]
	v_mfma_f32_16x16x32_bf16 v[102:105], v[146:149], v[194:197], v[102:105]
	v_mfma_f32_16x16x32_bf16 v[94:97], v[154:157], v[194:197], v[94:97]
	v_mfma_f32_16x16x32_bf16 v[86:89], v[146:149], v[206:209], v[86:89]
	v_mfma_f32_16x16x32_bf16 v[78:81], v[154:157], v[206:209], v[78:81]
	v_mfma_f32_16x16x32_bf16 v[70:73], v[146:149], v[214:217], v[70:73]
	v_mfma_f32_16x16x32_bf16 v[66:69], v[154:157], v[214:217], v[66:69]
	v_mfma_f32_16x16x32_bf16 v[134:137], v[150:153], v[166:169], v[134:137]
	v_mfma_f32_16x16x32_bf16 v[130:133], v[158:161], v[166:169], v[130:133]
	v_mfma_f32_16x16x32_bf16 v[102:105], v[150:153], v[198:201], v[102:105]
	v_mfma_f32_16x16x32_bf16 v[94:97], v[158:161], v[198:201], v[94:97]
	v_mfma_f32_16x16x32_bf16 v[86:89], v[150:153], v[210:213], v[86:89]
	v_mfma_f32_16x16x32_bf16 v[78:81], v[158:161], v[210:213], v[78:81]
	v_mfma_f32_16x16x32_bf16 v[70:73], v[150:153], v[218:221], v[70:73]
	v_mfma_f32_16x16x32_bf16 v[66:69], v[158:161], v[218:221], v[66:69]
	s_setprio 0
	s_barrier
	ds_read_b128 v[162:165], v192 offset:49152
	ds_read_b128 v[166:169], v192 offset:50176
	ds_read_b128 v[194:197], v192 offset:51200
	ds_read_b128 v[198:201], v192 offset:52224
	ds_read_b128 v[206:209], v192 offset:53248
	ds_read_b128 v[210:213], v192 offset:54272
	ds_read_b128 v[214:217], v192 offset:55296
	ds_read_b128 v[218:221], v192 offset:56320
	s_add_i32 s63, s63, s86
	s_mov_b32 m0, s63
	v_lshl_add_u64 v[186:187], v[186:187], 0, s[22:23]
	global_load_lds_dwordx4 v[186:187], off
	s_add_i32 m0, s63, 0x2000
	s_add_u32 s78, s78, 0x40080
	v_lshl_add_u64 v[186:187], v[202:203], 0, s[22:23]
	s_addc_u32 s79, s79, 0
	s_add_i32 s63, s83, s86
	global_load_lds_dwordx4 v[186:187], off
	s_mov_b32 m0, s63
	v_lshl_add_u64 v[186:187], s[78:79], 0, v[172:173]
	global_load_lds_dwordx4 v[186:187], off
	s_add_i32 m0, s63, 0x2000
	v_lshl_add_u64 v[186:187], s[78:79], 0, v[176:177]
	global_load_lds_dwordx4 v[186:187], off
	s_mov_b32 m0, s95
	v_lshl_add_u64 v[186:187], v[222:223], 0, s[22:23]
	global_load_lds_dwordx4 v[186:187], off
	s_mov_b32 m0, s96
	v_lshl_add_u64 v[186:187], v[224:225], 0, s[22:23]
	global_load_lds_dwordx4 v[186:187], off
	s_waitcnt vmcnt(8) lgkmcnt(0)
	s_setprio 1
	s_barrier
	v_mfma_f32_16x16x32_bf16 v[62:65], v[114:117], v[162:165], v[62:65]
	v_mfma_f32_16x16x32_bf16 v[58:61], v[122:125], v[162:165], v[58:61]
	v_mfma_f32_16x16x32_bf16 v[50:53], v[114:117], v[194:197], v[50:53]
	v_mfma_f32_16x16x32_bf16 v[42:45], v[122:125], v[194:197], v[42:45]
	v_mfma_f32_16x16x32_bf16 v[34:37], v[114:117], v[206:209], v[34:37]
	v_mfma_f32_16x16x32_bf16 v[26:29], v[122:125], v[206:209], v[26:29]
	v_mfma_f32_16x16x32_bf16 v[18:21], v[114:117], v[214:217], v[18:21]
	v_mfma_f32_16x16x32_bf16 v[10:13], v[122:125], v[214:217], v[10:13]
	v_mfma_f32_16x16x32_bf16 v[62:65], v[118:121], v[166:169], v[62:65]
	v_mfma_f32_16x16x32_bf16 v[58:61], v[126:129], v[166:169], v[58:61]
	v_mfma_f32_16x16x32_bf16 v[50:53], v[118:121], v[198:201], v[50:53]
	v_mfma_f32_16x16x32_bf16 v[42:45], v[126:129], v[198:201], v[42:45]
	v_mfma_f32_16x16x32_bf16 v[34:37], v[118:121], v[210:213], v[34:37]
	v_mfma_f32_16x16x32_bf16 v[26:29], v[126:129], v[210:213], v[26:29]
	v_mfma_f32_16x16x32_bf16 v[18:21], v[118:121], v[218:221], v[18:21]
	v_mfma_f32_16x16x32_bf16 v[10:13], v[126:129], v[218:221], v[10:13]
	v_mfma_f32_16x16x32_bf16 v[54:57], v[146:149], v[162:165], v[54:57]
	v_mfma_f32_16x16x32_bf16 v[46:49], v[154:157], v[162:165], v[46:49]
	v_mfma_f32_16x16x32_bf16 v[38:41], v[146:149], v[194:197], v[38:41]
	v_mfma_f32_16x16x32_bf16 v[30:33], v[154:157], v[194:197], v[30:33]
	v_mfma_f32_16x16x32_bf16 v[22:25], v[146:149], v[206:209], v[22:25]
	v_mfma_f32_16x16x32_bf16 v[14:17], v[154:157], v[206:209], v[14:17]
	v_mfma_f32_16x16x32_bf16 v[6:9], v[146:149], v[214:217], v[6:9]
	v_mfma_f32_16x16x32_bf16 v[2:5], v[154:157], v[214:217], v[2:5]
	v_mfma_f32_16x16x32_bf16 v[54:57], v[150:153], v[166:169], v[54:57]
	v_mfma_f32_16x16x32_bf16 v[46:49], v[158:161], v[166:169], v[46:49]
	v_mfma_f32_16x16x32_bf16 v[38:41], v[150:153], v[198:201], v[38:41]
	v_mfma_f32_16x16x32_bf16 v[30:33], v[158:161], v[198:201], v[30:33]
	v_mfma_f32_16x16x32_bf16 v[22:25], v[150:153], v[210:213], v[22:25]
	v_mfma_f32_16x16x32_bf16 v[14:17], v[158:161], v[210:213], v[14:17]
	v_mfma_f32_16x16x32_bf16 v[6:9], v[150:153], v[218:221], v[6:9]
	v_mfma_f32_16x16x32_bf16 v[2:5], v[158:161], v[218:221], v[2:5]
	s_setprio 0
	s_barrier
	s_add_u32 s76, s76, 0x100
	s_addc_u32 s77, s77, 0
	s_add_u32 s47, s47, 0x100
	s_addc_u32 s62, s62, 0
	s_cmp_ge_i32 s82, s7
	s_mov_b32 s63, s82
	s_cbranch_scc0 .LBB0_566
	s_and_b64 vcc, exec, s[26:27]
	s_cbranch_vccz .LBB0_569
	s_barrier

.LBB0_744:
	s_add_u32 s36, s96, s22
	s_addc_u32 s37, s97, s23
	s_and_b64 s[14:15], s[4:5], exec
	s_cselect_b32 s14, s37, s43
	s_cselect_b32 s15, s36, s42
	s_add_u32 s38, s2, s26
	s_addc_u32 s39, s3, s27
	s_and_b64 s[46:47], s[4:5], exec
	s_cselect_b32 s21, s39, s45
	s_cselect_b32 s65, s38, s44
	s_add_u32 s42, s42, 0x40080
	s_addc_u32 s43, s43, 0
	s_add_u32 s66, s44, 0x100
	s_addc_u32 s67, s45, 0
	s_mov_b32 s68, -2
	ds_read_b128 v[154:157], v150
	ds_read_b128 v[158:161], v150 offset:1024
	ds_read_b128 v[162:165], v150 offset:2048
	ds_read_b128 v[166:169], v150 offset:3072
	ds_read_b128 v[170:173], v151
	ds_read_b128 v[174:177], v151 offset:1024
	ds_read_b128 v[178:181], v151 offset:2048
	ds_read_b128 v[182:185], v151 offset:3072
	ds_read_b128 v[186:189], v152
	ds_read_b128 v[190:193], v152 offset:1024
	ds_read_b128 v[194:197], v152 offset:2048
	ds_read_b128 v[198:201], v152 offset:3072
	ds_read_b128 v[206:209], v152 offset:4096
	ds_read_b128 v[210:213], v152 offset:5120
	ds_read_b128 v[214:217], v152 offset:6144
	ds_read_b128 v[218:221], v152 offset:7168
	s_add_u32 s44, s42, 0xfffc0080
	s_addc_u32 s45, s43, -1
	s_cmp_eq_u32 s68, 12
	s_cselect_b32 s47, s14, s45
	s_cselect_b32 s46, s15, s44
	s_cselect_b32 s45, s21, s67
	s_cselect_b32 s44, s65, s66
	s_add_i32 m0, s19, 0xc000
	v_lshl_add_u64 v[146:147], s[42:43], 0, v[138:139]
	global_load_lds_dwordx4 v[146:147], off
	s_add_i32 m0, s19, 0xe000
	v_lshl_add_u64 v[146:147], s[42:43], 0, v[140:141]
	global_load_lds_dwordx4 v[146:147], off
	s_waitcnt vmcnt(8) lgkmcnt(0)
	s_setprio 1
	s_barrier
	v_mfma_f32_16x16x32_bf16 v[126:129], v[154:157], v[186:189], 0
	v_mfma_f32_16x16x32_bf16 v[122:125], v[162:165], v[186:189], 0
	v_mfma_f32_16x16x32_bf16 v[110:113], v[154:157], v[194:197], 0
	v_mfma_f32_16x16x32_bf16 v[106:109], v[162:165], v[194:197], 0
	v_mfma_f32_16x16x32_bf16 v[94:97], v[154:157], v[206:209], 0
	v_mfma_f32_16x16x32_bf16 v[90:93], v[162:165], v[206:209], 0
	v_mfma_f32_16x16x32_bf16 v[78:81], v[154:157], v[214:217], 0
	v_mfma_f32_16x16x32_bf16 v[74:77], v[162:165], v[214:217], 0
	v_mfma_f32_16x16x32_bf16 v[126:129], v[158:161], v[190:193], v[126:129]
	v_mfma_f32_16x16x32_bf16 v[122:125], v[166:169], v[190:193], v[122:125]
	v_mfma_f32_16x16x32_bf16 v[110:113], v[158:161], v[198:201], v[110:113]
	v_mfma_f32_16x16x32_bf16 v[106:109], v[166:169], v[198:201], v[106:109]
	v_mfma_f32_16x16x32_bf16 v[94:97], v[158:161], v[210:213], v[94:97]
	v_mfma_f32_16x16x32_bf16 v[90:93], v[166:169], v[210:213], v[90:93]
	v_mfma_f32_16x16x32_bf16 v[78:81], v[158:161], v[218:221], v[78:81]
	v_mfma_f32_16x16x32_bf16 v[74:77], v[166:169], v[218:221], v[74:77]
	v_mfma_f32_16x16x32_bf16 v[118:121], v[170:173], v[186:189], 0
	v_mfma_f32_16x16x32_bf16 v[114:117], v[178:181], v[186:189], 0
	v_mfma_f32_16x16x32_bf16 v[102:105], v[170:173], v[194:197], 0
	v_mfma_f32_16x16x32_bf16 v[98:101], v[178:181], v[194:197], 0
	v_mfma_f32_16x16x32_bf16 v[86:89], v[170:173], v[206:209], 0
	v_mfma_f32_16x16x32_bf16 v[82:85], v[178:181], v[206:209], 0
	v_mfma_f32_16x16x32_bf16 v[70:73], v[170:173], v[214:217], 0
	v_mfma_f32_16x16x32_bf16 v[66:69], v[178:181], v[214:217], 0
	v_mfma_f32_16x16x32_bf16 v[118:121], v[174:177], v[190:193], v[118:121]
	v_mfma_f32_16x16x32_bf16 v[114:117], v[182:185], v[190:193], v[114:117]
	v_mfma_f32_16x16x32_bf16 v[102:105], v[174:177], v[198:201], v[102:105]
	v_mfma_f32_16x16x32_bf16 v[98:101], v[182:185], v[198:201], v[98:101]
	v_mfma_f32_16x16x32_bf16 v[86:89], v[174:177], v[210:213], v[86:89]
	v_mfma_f32_16x16x32_bf16 v[82:85], v[182:185], v[210:213], v[82:85]
	v_mfma_f32_16x16x32_bf16 v[70:73], v[174:177], v[218:221], v[70:73]
	v_mfma_f32_16x16x32_bf16 v[66:69], v[182:185], v[218:221], v[66:69]
	s_setprio 0
	s_barrier
	ds_read_b128 v[186:189], v152 offset:16384
	ds_read_b128 v[190:193], v152 offset:17408
	ds_read_b128 v[194:197], v152 offset:18432
	ds_read_b128 v[198:201], v152 offset:19456
	ds_read_b128 v[206:209], v152 offset:20480
	ds_read_b128 v[210:213], v152 offset:21504
	ds_read_b128 v[214:217], v152 offset:22528
	ds_read_b128 v[218:221], v152 offset:23552
	s_add_i32 s69, s49, s16
	s_mov_b32 m0, s69
	v_lshl_add_u64 v[146:147], s[44:45], 0, v[134:135]
	global_load_lds_dwordx4 v[146:147], off
	s_add_i32 m0, s69, 0x2000
	s_add_u32 s70, s44, 0x40000
	v_lshl_add_u64 v[202:203], s[44:45], 0, v[130:131]
	s_addc_u32 s71, s45, 0
	s_add_i32 s69, s62, s16
	global_load_lds_dwordx4 v[202:203], off
	v_lshl_add_u64 v[222:223], s[70:71], 0, v[134:135]
	s_mov_b32 m0, s69
	v_lshl_add_u64 v[224:225], s[46:47], 0, v[132:133]
	global_load_lds_dwordx4 v[222:223], off
	s_add_i32 m0, s69, 0x2000
	v_lshl_add_u64 v[222:223], s[70:71], 0, v[130:131]
	global_load_lds_dwordx4 v[222:223], off
	s_mov_b32 m0, s19
	v_lshl_add_u64 v[222:223], s[46:47], 0, v[136:137]
	global_load_lds_dwordx4 v[222:223], off
	s_mov_b32 m0, s24
	s_nop 0
	global_load_lds_dwordx4 v[224:225], off
	s_waitcnt vmcnt(8) lgkmcnt(0)
	s_setprio 1
	s_barrier
	v_mfma_f32_16x16x32_bf16 v[62:65], v[154:157], v[186:189], 0
	v_mfma_f32_16x16x32_bf16 v[58:61], v[162:165], v[186:189], 0
	v_mfma_f32_16x16x32_bf16 v[46:49], v[154:157], v[194:197], 0
	v_mfma_f32_16x16x32_bf16 v[42:45], v[162:165], v[194:197], 0
	v_mfma_f32_16x16x32_bf16 v[30:33], v[154:157], v[206:209], 0
	v_mfma_f32_16x16x32_bf16 v[26:29], v[162:165], v[206:209], 0
	v_mfma_f32_16x16x32_bf16 v[14:17], v[154:157], v[214:217], 0
	v_mfma_f32_16x16x32_bf16 v[10:13], v[162:165], v[214:217], 0
	v_mfma_f32_16x16x32_bf16 v[62:65], v[158:161], v[190:193], v[62:65]
	v_mfma_f32_16x16x32_bf16 v[58:61], v[166:169], v[190:193], v[58:61]
	v_mfma_f32_16x16x32_bf16 v[46:49], v[158:161], v[198:201], v[46:49]
	v_mfma_f32_16x16x32_bf16 v[42:45], v[166:169], v[198:201], v[42:45]
	v_mfma_f32_16x16x32_bf16 v[30:33], v[158:161], v[210:213], v[30:33]
	v_mfma_f32_16x16x32_bf16 v[26:29], v[166:169], v[210:213], v[26:29]
	v_mfma_f32_16x16x32_bf16 v[14:17], v[158:161], v[218:221], v[14:17]
	v_mfma_f32_16x16x32_bf16 v[10:13], v[166:169], v[218:221], v[10:13]
	v_mfma_f32_16x16x32_bf16 v[54:57], v[170:173], v[186:189], 0
	v_mfma_f32_16x16x32_bf16 v[50:53], v[178:181], v[186:189], 0
	v_mfma_f32_16x16x32_bf16 v[38:41], v[170:173], v[194:197], 0
	v_mfma_f32_16x16x32_bf16 v[34:37], v[178:181], v[194:197], 0
	v_mfma_f32_16x16x32_bf16 v[22:25], v[170:173], v[206:209], 0
	v_mfma_f32_16x16x32_bf16 v[18:21], v[178:181], v[206:209], 0
	v_mfma_f32_16x16x32_bf16 v[6:9], v[170:173], v[214:217], 0
	v_mfma_f32_16x16x32_bf16 v[2:5], v[178:181], v[214:217], 0
	v_mfma_f32_16x16x32_bf16 v[54:57], v[174:177], v[190:193], v[54:57]
	v_mfma_f32_16x16x32_bf16 v[50:53], v[182:185], v[190:193], v[50:53]
	v_mfma_f32_16x16x32_bf16 v[38:41], v[174:177], v[198:201], v[38:41]
	v_mfma_f32_16x16x32_bf16 v[34:37], v[182:185], v[198:201], v[34:37]
	v_mfma_f32_16x16x32_bf16 v[22:25], v[174:177], v[210:213], v[22:25]
	v_mfma_f32_16x16x32_bf16 v[18:21], v[182:185], v[210:213], v[18:21]
	v_mfma_f32_16x16x32_bf16 v[6:9], v[174:177], v[218:221], v[6:9]
	v_mfma_f32_16x16x32_bf16 v[2:5], v[182:185], v[218:221], v[2:5]
	s_setprio 0
	s_barrier
	s_add_i32 s69, 0, 0x18000
	v_add_u32_e32 v153, s69, v149
	s_add_i32 s70, 0, 0x1c000
	ds_read_b128 v[154:157], v153
	ds_read_b128 v[158:161], v153 offset:1024
	ds_read_b128 v[162:165], v153 offset:2048
	ds_read_b128 v[166:169], v153 offset:3072
	v_add_u32_e32 v153, s70, v149
	ds_read_b128 v[170:173], v153
	ds_read_b128 v[174:177], v153 offset:1024
	ds_read_b128 v[178:181], v153 offset:2048
	ds_read_b128 v[182:185], v153 offset:3072
	s_add_u32 s46, s46, 0x40000
	s_addc_u32 s47, s47, 0
	s_mov_b32 m0, s25
	v_lshl_add_u64 v[226:227], s[46:47], 0, v[136:137]
	ds_read_b128 v[186:189], v152 offset:32768
	ds_read_b128 v[190:193], v152 offset:33792
	ds_read_b128 v[194:197], v152 offset:34816
	ds_read_b128 v[198:201], v152 offset:35840
	ds_read_b128 v[206:209], v152 offset:36864
	ds_read_b128 v[210:213], v152 offset:37888
	ds_read_b128 v[214:217], v152 offset:38912
	ds_read_b128 v[218:221], v152 offset:39936
	global_load_lds_dwordx4 v[226:227], off
	s_mov_b32 m0, s28
	v_lshl_add_u64 v[226:227], s[46:47], 0, v[132:133]
	global_load_lds_dwordx4 v[226:227], off
	s_waitcnt vmcnt(8) lgkmcnt(0)
	s_setprio 1
	s_barrier
	v_mfma_f32_16x16x32_bf16 v[126:129], v[154:157], v[186:189], v[126:129]
	v_mfma_f32_16x16x32_bf16 v[122:125], v[162:165], v[186:189], v[122:125]
	v_mfma_f32_16x16x32_bf16 v[110:113], v[154:157], v[194:197], v[110:113]
	v_mfma_f32_16x16x32_bf16 v[106:109], v[162:165], v[194:197], v[106:109]
	v_mfma_f32_16x16x32_bf16 v[94:97], v[154:157], v[206:209], v[94:97]
	v_mfma_f32_16x16x32_bf16 v[90:93], v[162:165], v[206:209], v[90:93]
	v_mfma_f32_16x16x32_bf16 v[78:81], v[154:157], v[214:217], v[78:81]
	v_mfma_f32_16x16x32_bf16 v[74:77], v[162:165], v[214:217], v[74:77]
	v_mfma_f32_16x16x32_bf16 v[126:129], v[158:161], v[190:193], v[126:129]
	v_mfma_f32_16x16x32_bf16 v[122:125], v[166:169], v[190:193], v[122:125]
	v_mfma_f32_16x16x32_bf16 v[110:113], v[158:161], v[198:201], v[110:113]
	v_mfma_f32_16x16x32_bf16 v[106:109], v[166:169], v[198:201], v[106:109]
	v_mfma_f32_16x16x32_bf16 v[94:97], v[158:161], v[210:213], v[94:97]
	v_mfma_f32_16x16x32_bf16 v[90:93], v[166:169], v[210:213], v[90:93]
	v_mfma_f32_16x16x32_bf16 v[78:81], v[158:161], v[218:221], v[78:81]
	v_mfma_f32_16x16x32_bf16 v[74:77], v[166:169], v[218:221], v[74:77]
	v_mfma_f32_16x16x32_bf16 v[118:121], v[170:173], v[186:189], v[118:121]
	v_mfma_f32_16x16x32_bf16 v[114:117], v[178:181], v[186:189], v[114:117]
	v_mfma_f32_16x16x32_bf16 v[102:105], v[170:173], v[194:197], v[102:105]
	v_mfma_f32_16x16x32_bf16 v[98:101], v[178:181], v[194:197], v[98:101]
	v_mfma_f32_16x16x32_bf16 v[86:89], v[170:173], v[206:209], v[86:89]
	v_mfma_f32_16x16x32_bf16 v[82:85], v[178:181], v[206:209], v[82:85]
	v_mfma_f32_16x16x32_bf16 v[70:73], v[170:173], v[214:217], v[70:73]
	v_mfma_f32_16x16x32_bf16 v[66:69], v[178:181], v[214:217], v[66:69]
	v_mfma_f32_16x16x32_bf16 v[118:121], v[174:177], v[190:193], v[118:121]
	v_mfma_f32_16x16x32_bf16 v[114:117], v[182:185], v[190:193], v[114:117]
	v_mfma_f32_16x16x32_bf16 v[102:105], v[174:177], v[198:201], v[102:105]
	v_mfma_f32_16x16x32_bf16 v[98:101], v[182:185], v[198:201], v[98:101]
	v_mfma_f32_16x16x32_bf16 v[86:89], v[174:177], v[210:213], v[86:89]
	v_mfma_f32_16x16x32_bf16 v[82:85], v[182:185], v[210:213], v[82:85]
	v_mfma_f32_16x16x32_bf16 v[70:73], v[174:177], v[218:221], v[70:73]
	v_mfma_f32_16x16x32_bf16 v[66:69], v[182:185], v[218:221], v[66:69]
	s_setprio 0
	s_barrier
	ds_read_b128 v[186:189], v152 offset:49152
	ds_read_b128 v[190:193], v152 offset:50176
	ds_read_b128 v[194:197], v152 offset:51200
	ds_read_b128 v[198:201], v152 offset:52224
	ds_read_b128 v[206:209], v152 offset:53248
	ds_read_b128 v[210:213], v152 offset:54272
	ds_read_b128 v[214:217], v152 offset:55296
	ds_read_b128 v[218:221], v152 offset:56320
	s_add_i32 s46, s69, s16
	s_mov_b32 m0, s46
	v_lshl_add_u64 v[146:147], v[146:147], 0, s[10:11]
	global_load_lds_dwordx4 v[146:147], off
	s_add_i32 m0, s46, 0x2000
	s_add_u32 s44, s44, 0x40080
	v_lshl_add_u64 v[146:147], v[202:203], 0, s[10:11]
	s_addc_u32 s45, s45, 0
	s_add_i32 s46, s70, s16
	global_load_lds_dwordx4 v[146:147], off
	s_mov_b32 m0, s46
	v_lshl_add_u64 v[146:147], s[44:45], 0, v[134:135]
	global_load_lds_dwordx4 v[146:147], off
	s_add_i32 m0, s46, 0x2000
	v_lshl_add_u64 v[146:147], s[44:45], 0, v[130:131]
	global_load_lds_dwordx4 v[146:147], off
	s_mov_b32 m0, s33
	v_lshl_add_u64 v[146:147], v[222:223], 0, s[10:11]
	global_load_lds_dwordx4 v[146:147], off
	s_mov_b32 m0, s35
	v_lshl_add_u64 v[146:147], v[224:225], 0, s[10:11]
	global_load_lds_dwordx4 v[146:147], off
	s_waitcnt vmcnt(8) lgkmcnt(0)
	s_setprio 1
	s_barrier
	v_mfma_f32_16x16x32_bf16 v[62:65], v[154:157], v[186:189], v[62:65]
	v_mfma_f32_16x16x32_bf16 v[58:61], v[162:165], v[186:189], v[58:61]
	v_mfma_f32_16x16x32_bf16 v[46:49], v[154:157], v[194:197], v[46:49]
	v_mfma_f32_16x16x32_bf16 v[42:45], v[162:165], v[194:197], v[42:45]
	v_mfma_f32_16x16x32_bf16 v[30:33], v[154:157], v[206:209], v[30:33]
	v_mfma_f32_16x16x32_bf16 v[26:29], v[162:165], v[206:209], v[26:29]
	v_mfma_f32_16x16x32_bf16 v[14:17], v[154:157], v[214:217], v[14:17]
	v_mfma_f32_16x16x32_bf16 v[10:13], v[162:165], v[214:217], v[10:13]
	v_mfma_f32_16x16x32_bf16 v[62:65], v[158:161], v[190:193], v[62:65]
	v_mfma_f32_16x16x32_bf16 v[58:61], v[166:169], v[190:193], v[58:61]
	v_mfma_f32_16x16x32_bf16 v[46:49], v[158:161], v[198:201], v[46:49]
	v_mfma_f32_16x16x32_bf16 v[42:45], v[166:169], v[198:201], v[42:45]
	v_mfma_f32_16x16x32_bf16 v[30:33], v[158:161], v[210:213], v[30:33]
	v_mfma_f32_16x16x32_bf16 v[26:29], v[166:169], v[210:213], v[26:29]
	v_mfma_f32_16x16x32_bf16 v[14:17], v[158:161], v[218:221], v[14:17]
	v_mfma_f32_16x16x32_bf16 v[10:13], v[166:169], v[218:221], v[10:13]
	v_mfma_f32_16x16x32_bf16 v[54:57], v[170:173], v[186:189], v[54:57]
	v_mfma_f32_16x16x32_bf16 v[50:53], v[178:181], v[186:189], v[50:53]
	v_mfma_f32_16x16x32_bf16 v[38:41], v[170:173], v[194:197], v[38:41]
	v_mfma_f32_16x16x32_bf16 v[34:37], v[178:181], v[194:197], v[34:37]
	v_mfma_f32_16x16x32_bf16 v[22:25], v[170:173], v[206:209], v[22:25]
	v_mfma_f32_16x16x32_bf16 v[18:21], v[178:181], v[206:209], v[18:21]
	v_mfma_f32_16x16x32_bf16 v[6:9], v[170:173], v[214:217], v[6:9]
	v_mfma_f32_16x16x32_bf16 v[2:5], v[178:181], v[214:217], v[2:5]
	v_mfma_f32_16x16x32_bf16 v[54:57], v[174:177], v[190:193], v[54:57]
	v_mfma_f32_16x16x32_bf16 v[50:53], v[182:185], v[190:193], v[50:53]
	v_mfma_f32_16x16x32_bf16 v[38:41], v[174:177], v[198:201], v[38:41]
	v_mfma_f32_16x16x32_bf16 v[34:37], v[182:185], v[198:201], v[34:37]
	v_mfma_f32_16x16x32_bf16 v[22:25], v[174:177], v[210:213], v[22:25]
	v_mfma_f32_16x16x32_bf16 v[18:21], v[182:185], v[210:213], v[18:21]
	v_mfma_f32_16x16x32_bf16 v[6:9], v[174:177], v[218:221], v[6:9]
	v_mfma_f32_16x16x32_bf16 v[2:5], v[182:185], v[218:221], v[2:5]
	s_setprio 0
	s_barrier
	s_add_i32 s68, s68, 2
	s_add_u32 s42, s42, 0x100
	s_addc_u32 s43, s43, 0
	s_add_u32 s66, s66, 0x100
	s_addc_u32 s67, s67, 0
	s_cmp_gt_u32 s68, 13
.LBB0_745:
	ds_read_b128 v[154:157], v150
	ds_read_b128 v[158:161], v150 offset:1024
	ds_read_b128 v[162:165], v150 offset:2048
	ds_read_b128 v[166:169], v150 offset:3072
	ds_read_b128 v[170:173], v151
	ds_read_b128 v[174:177], v151 offset:1024
	ds_read_b128 v[178:181], v151 offset:2048
	ds_read_b128 v[182:185], v151 offset:3072
	ds_read_b128 v[186:189], v152
	ds_read_b128 v[190:193], v152 offset:1024
	ds_read_b128 v[194:197], v152 offset:2048
	ds_read_b128 v[198:201], v152 offset:3072
	ds_read_b128 v[206:209], v152 offset:4096
	ds_read_b128 v[210:213], v152 offset:5120
	ds_read_b128 v[214:217], v152 offset:6144
	ds_read_b128 v[218:221], v152 offset:7168
	s_add_u32 s44, s42, 0xfffc0080
	s_addc_u32 s45, s43, -1
	s_cmp_eq_u32 s68, 12
	s_cselect_b32 s47, s14, s45
	s_cselect_b32 s46, s15, s44
	s_cselect_b32 s45, s21, s67
	s_cselect_b32 s44, s65, s66
	s_add_i32 m0, s19, 0xc000
	v_lshl_add_u64 v[146:147], s[42:43], 0, v[138:139]
	global_load_lds_dwordx4 v[146:147], off
	s_add_i32 m0, s19, 0xe000
	v_lshl_add_u64 v[146:147], s[42:43], 0, v[140:141]
	global_load_lds_dwordx4 v[146:147], off
	s_waitcnt vmcnt(8) lgkmcnt(0)
	s_setprio 1
	s_barrier
	v_mfma_f32_16x16x32_bf16 v[126:129], v[154:157], v[186:189], v[126:129]
	v_mfma_f32_16x16x32_bf16 v[122:125], v[162:165], v[186:189], v[122:125]
	v_mfma_f32_16x16x32_bf16 v[110:113], v[154:157], v[194:197], v[110:113]
	v_mfma_f32_16x16x32_bf16 v[106:109], v[162:165], v[194:197], v[106:109]
	v_mfma_f32_16x16x32_bf16 v[94:97], v[154:157], v[206:209], v[94:97]
	v_mfma_f32_16x16x32_bf16 v[90:93], v[162:165], v[206:209], v[90:93]
	v_mfma_f32_16x16x32_bf16 v[78:81], v[154:157], v[214:217], v[78:81]
	v_mfma_f32_16x16x32_bf16 v[74:77], v[162:165], v[214:217], v[74:77]
	v_mfma_f32_16x16x32_bf16 v[126:129], v[158:161], v[190:193], v[126:129]
	v_mfma_f32_16x16x32_bf16 v[122:125], v[166:169], v[190:193], v[122:125]
	v_mfma_f32_16x16x32_bf16 v[110:113], v[158:161], v[198:201], v[110:113]
	v_mfma_f32_16x16x32_bf16 v[106:109], v[166:169], v[198:201], v[106:109]
	v_mfma_f32_16x16x32_bf16 v[94:97], v[158:161], v[210:213], v[94:97]
	v_mfma_f32_16x16x32_bf16 v[90:93], v[166:169], v[210:213], v[90:93]
	v_mfma_f32_16x16x32_bf16 v[78:81], v[158:161], v[218:221], v[78:81]
	v_mfma_f32_16x16x32_bf16 v[74:77], v[166:169], v[218:221], v[74:77]
	v_mfma_f32_16x16x32_bf16 v[118:121], v[170:173], v[186:189], v[118:121]
	v_mfma_f32_16x16x32_bf16 v[114:117], v[178:181], v[186:189], v[114:117]
	v_mfma_f32_16x16x32_bf16 v[102:105], v[170:173], v[194:197], v[102:105]
	v_mfma_f32_16x16x32_bf16 v[98:101], v[178:181], v[194:197], v[98:101]
	v_mfma_f32_16x16x32_bf16 v[86:89], v[170:173], v[206:209], v[86:89]
	v_mfma_f32_16x16x32_bf16 v[82:85], v[178:181], v[206:209], v[82:85]
	v_mfma_f32_16x16x32_bf16 v[70:73], v[170:173], v[214:217], v[70:73]
	v_mfma_f32_16x16x32_bf16 v[66:69], v[178:181], v[214:217], v[66:69]
	v_mfma_f32_16x16x32_bf16 v[118:121], v[174:177], v[190:193], v[118:121]
	v_mfma_f32_16x16x32_bf16 v[114:117], v[182:185], v[190:193], v[114:117]
	v_mfma_f32_16x16x32_bf16 v[102:105], v[174:177], v[198:201], v[102:105]
	v_mfma_f32_16x16x32_bf16 v[98:101], v[182:185], v[198:201], v[98:101]
	v_mfma_f32_16x16x32_bf16 v[86:89], v[174:177], v[210:213], v[86:89]
	v_mfma_f32_16x16x32_bf16 v[82:85], v[182:185], v[210:213], v[82:85]
	v_mfma_f32_16x16x32_bf16 v[70:73], v[174:177], v[218:221], v[70:73]
	v_mfma_f32_16x16x32_bf16 v[66:69], v[182:185], v[218:221], v[66:69]
	s_setprio 0
	s_barrier
	ds_read_b128 v[186:189], v152 offset:16384
	ds_read_b128 v[190:193], v152 offset:17408
	ds_read_b128 v[194:197], v152 offset:18432
	ds_read_b128 v[198:201], v152 offset:19456
	ds_read_b128 v[206:209], v152 offset:20480
	ds_read_b128 v[210:213], v152 offset:21504
	ds_read_b128 v[214:217], v152 offset:22528
	ds_read_b128 v[218:221], v152 offset:23552
	s_add_i32 s69, s49, s16
	s_mov_b32 m0, s69
	v_lshl_add_u64 v[146:147], s[44:45], 0, v[134:135]
	global_load_lds_dwordx4 v[146:147], off
	s_add_i32 m0, s69, 0x2000
	s_add_u32 s70, s44, 0x40000
	v_lshl_add_u64 v[202:203], s[44:45], 0, v[130:131]
	s_addc_u32 s71, s45, 0
	s_add_i32 s69, s62, s16
	global_load_lds_dwordx4 v[202:203], off
	v_lshl_add_u64 v[222:223], s[70:71], 0, v[134:135]
	s_mov_b32 m0, s69
	v_lshl_add_u64 v[224:225], s[46:47], 0, v[132:133]
	global_load_lds_dwordx4 v[222:223], off
	s_add_i32 m0, s69, 0x2000
	v_lshl_add_u64 v[222:223], s[70:71], 0, v[130:131]
	global_load_lds_dwordx4 v[222:223], off
	s_mov_b32 m0, s19
	v_lshl_add_u64 v[222:223], s[46:47], 0, v[136:137]
	global_load_lds_dwordx4 v[222:223], off
	s_mov_b32 m0, s24
	s_nop 0
	global_load_lds_dwordx4 v[224:225], off
	s_waitcnt vmcnt(8) lgkmcnt(0)
	s_setprio 1
	s_barrier
	v_mfma_f32_16x16x32_bf16 v[62:65], v[154:157], v[186:189], v[62:65]
	v_mfma_f32_16x16x32_bf16 v[58:61], v[162:165], v[186:189], v[58:61]
	v_mfma_f32_16x16x32_bf16 v[46:49], v[154:157], v[194:197], v[46:49]
	v_mfma_f32_16x16x32_bf16 v[42:45], v[162:165], v[194:197], v[42:45]
	v_mfma_f32_16x16x32_bf16 v[30:33], v[154:157], v[206:209], v[30:33]
	v_mfma_f32_16x16x32_bf16 v[26:29], v[162:165], v[206:209], v[26:29]
	v_mfma_f32_16x16x32_bf16 v[14:17], v[154:157], v[214:217], v[14:17]
	v_mfma_f32_16x16x32_bf16 v[10:13], v[162:165], v[214:217], v[10:13]
	v_mfma_f32_16x16x32_bf16 v[62:65], v[158:161], v[190:193], v[62:65]
	v_mfma_f32_16x16x32_bf16 v[58:61], v[166:169], v[190:193], v[58:61]
	v_mfma_f32_16x16x32_bf16 v[46:49], v[158:161], v[198:201], v[46:49]
	v_mfma_f32_16x16x32_bf16 v[42:45], v[166:169], v[198:201], v[42:45]
	v_mfma_f32_16x16x32_bf16 v[30:33], v[158:161], v[210:213], v[30:33]
	v_mfma_f32_16x16x32_bf16 v[26:29], v[166:169], v[210:213], v[26:29]
	v_mfma_f32_16x16x32_bf16 v[14:17], v[158:161], v[218:221], v[14:17]
	v_mfma_f32_16x16x32_bf16 v[10:13], v[166:169], v[218:221], v[10:13]
	v_mfma_f32_16x16x32_bf16 v[54:57], v[170:173], v[186:189], v[54:57]
	v_mfma_f32_16x16x32_bf16 v[50:53], v[178:181], v[186:189], v[50:53]
	v_mfma_f32_16x16x32_bf16 v[38:41], v[170:173], v[194:197], v[38:41]
	v_mfma_f32_16x16x32_bf16 v[34:37], v[178:181], v[194:197], v[34:37]
	v_mfma_f32_16x16x32_bf16 v[22:25], v[170:173], v[206:209], v[22:25]
	v_mfma_f32_16x16x32_bf16 v[18:21], v[178:181], v[206:209], v[18:21]
	v_mfma_f32_16x16x32_bf16 v[6:9], v[170:173], v[214:217], v[6:9]
	v_mfma_f32_16x16x32_bf16 v[2:5], v[178:181], v[214:217], v[2:5]
	v_mfma_f32_16x16x32_bf16 v[54:57], v[174:177], v[190:193], v[54:57]
	v_mfma_f32_16x16x32_bf16 v[50:53], v[182:185], v[190:193], v[50:53]
	v_mfma_f32_16x16x32_bf16 v[38:41], v[174:177], v[198:201], v[38:41]
	v_mfma_f32_16x16x32_bf16 v[34:37], v[182:185], v[198:201], v[34:37]
	v_mfma_f32_16x16x32_bf16 v[22:25], v[174:177], v[210:213], v[22:25]
	v_mfma_f32_16x16x32_bf16 v[18:21], v[182:185], v[210:213], v[18:21]
	v_mfma_f32_16x16x32_bf16 v[6:9], v[174:177], v[218:221], v[6:9]
	v_mfma_f32_16x16x32_bf16 v[2:5], v[182:185], v[218:221], v[2:5]
	s_setprio 0
	s_barrier
	s_add_i32 s69, 0, 0x18000
	v_add_u32_e32 v153, s69, v149
	s_add_i32 s70, 0, 0x1c000
	ds_read_b128 v[154:157], v153
	ds_read_b128 v[158:161], v153 offset:1024
	ds_read_b128 v[162:165], v153 offset:2048
	ds_read_b128 v[166:169], v153 offset:3072
	v_add_u32_e32 v153, s70, v149
	ds_read_b128 v[170:173], v153
	ds_read_b128 v[174:177], v153 offset:1024
	ds_read_b128 v[178:181], v153 offset:2048
	ds_read_b128 v[182:185], v153 offset:3072
	s_add_u32 s46, s46, 0x40000
	s_addc_u32 s47, s47, 0
	s_mov_b32 m0, s25
	v_lshl_add_u64 v[226:227], s[46:47], 0, v[136:137]
	ds_read_b128 v[186:189], v152 offset:32768
	ds_read_b128 v[190:193], v152 offset:33792
	ds_read_b128 v[194:197], v152 offset:34816
	ds_read_b128 v[198:201], v152 offset:35840
	ds_read_b128 v[206:209], v152 offset:36864
	ds_read_b128 v[210:213], v152 offset:37888
	ds_read_b128 v[214:217], v152 offset:38912
	ds_read_b128 v[218:221], v152 offset:39936
	global_load_lds_dwordx4 v[226:227], off
	s_mov_b32 m0, s28
	v_lshl_add_u64 v[226:227], s[46:47], 0, v[132:133]
	global_load_lds_dwordx4 v[226:227], off
	s_waitcnt vmcnt(8) lgkmcnt(0)
	s_setprio 1
	s_barrier
	v_mfma_f32_16x16x32_bf16 v[126:129], v[154:157], v[186:189], v[126:129]
	v_mfma_f32_16x16x32_bf16 v[122:125], v[162:165], v[186:189], v[122:125]
	v_mfma_f32_16x16x32_bf16 v[110:113], v[154:157], v[194:197], v[110:113]
	v_mfma_f32_16x16x32_bf16 v[106:109], v[162:165], v[194:197], v[106:109]
	v_mfma_f32_16x16x32_bf16 v[94:97], v[154:157], v[206:209], v[94:97]
	v_mfma_f32_16x16x32_bf16 v[90:93], v[162:165], v[206:209], v[90:93]
	v_mfma_f32_16x16x32_bf16 v[78:81], v[154:157], v[214:217], v[78:81]
	v_mfma_f32_16x16x32_bf16 v[74:77], v[162:165], v[214:217], v[74:77]
	v_mfma_f32_16x16x32_bf16 v[126:129], v[158:161], v[190:193], v[126:129]
	v_mfma_f32_16x16x32_bf16 v[122:125], v[166:169], v[190:193], v[122:125]
	v_mfma_f32_16x16x32_bf16 v[110:113], v[158:161], v[198:201], v[110:113]
	v_mfma_f32_16x16x32_bf16 v[106:109], v[166:169], v[198:201], v[106:109]
	v_mfma_f32_16x16x32_bf16 v[94:97], v[158:161], v[210:213], v[94:97]
	v_mfma_f32_16x16x32_bf16 v[90:93], v[166:169], v[210:213], v[90:93]
	v_mfma_f32_16x16x32_bf16 v[78:81], v[158:161], v[218:221], v[78:81]
	v_mfma_f32_16x16x32_bf16 v[74:77], v[166:169], v[218:221], v[74:77]
	v_mfma_f32_16x16x32_bf16 v[118:121], v[170:173], v[186:189], v[118:121]
	v_mfma_f32_16x16x32_bf16 v[114:117], v[178:181], v[186:189], v[114:117]
	v_mfma_f32_16x16x32_bf16 v[102:105], v[170:173], v[194:197], v[102:105]
	v_mfma_f32_16x16x32_bf16 v[98:101], v[178:181], v[194:197], v[98:101]
	v_mfma_f32_16x16x32_bf16 v[86:89], v[170:173], v[206:209], v[86:89]
	v_mfma_f32_16x16x32_bf16 v[82:85], v[178:181], v[206:209], v[82:85]
	v_mfma_f32_16x16x32_bf16 v[70:73], v[170:173], v[214:217], v[70:73]
	v_mfma_f32_16x16x32_bf16 v[66:69], v[178:181], v[214:217], v[66:69]
	v_mfma_f32_16x16x32_bf16 v[118:121], v[174:177], v[190:193], v[118:121]
	v_mfma_f32_16x16x32_bf16 v[114:117], v[182:185], v[190:193], v[114:117]
	v_mfma_f32_16x16x32_bf16 v[102:105], v[174:177], v[198:201], v[102:105]
	v_mfma_f32_16x16x32_bf16 v[98:101], v[182:185], v[198:201], v[98:101]
	v_mfma_f32_16x16x32_bf16 v[86:89], v[174:177], v[210:213], v[86:89]
	v_mfma_f32_16x16x32_bf16 v[82:85], v[182:185], v[210:213], v[82:85]
	v_mfma_f32_16x16x32_bf16 v[70:73], v[174:177], v[218:221], v[70:73]
	v_mfma_f32_16x16x32_bf16 v[66:69], v[182:185], v[218:221], v[66:69]
	s_setprio 0
	s_barrier
	ds_read_b128 v[186:189], v152 offset:49152
	ds_read_b128 v[190:193], v152 offset:50176
	ds_read_b128 v[194:197], v152 offset:51200
	ds_read_b128 v[198:201], v152 offset:52224
	ds_read_b128 v[206:209], v152 offset:53248
	ds_read_b128 v[210:213], v152 offset:54272
	ds_read_b128 v[214:217], v152 offset:55296
	ds_read_b128 v[218:221], v152 offset:56320
	s_add_i32 s46, s69, s16
	s_mov_b32 m0, s46
	v_lshl_add_u64 v[146:147], v[146:147], 0, s[10:11]
	global_load_lds_dwordx4 v[146:147], off
	s_add_i32 m0, s46, 0x2000
	s_add_u32 s44, s44, 0x40080
	v_lshl_add_u64 v[146:147], v[202:203], 0, s[10:11]
	s_addc_u32 s45, s45, 0
	s_add_i32 s46, s70, s16
	global_load_lds_dwordx4 v[146:147], off
	s_mov_b32 m0, s46
	v_lshl_add_u64 v[146:147], s[44:45], 0, v[134:135]
	global_load_lds_dwordx4 v[146:147], off
	s_add_i32 m0, s46, 0x2000
	v_lshl_add_u64 v[146:147], s[44:45], 0, v[130:131]
	global_load_lds_dwordx4 v[146:147], off
	s_mov_b32 m0, s33
	v_lshl_add_u64 v[146:147], v[222:223], 0, s[10:11]
	global_load_lds_dwordx4 v[146:147], off
	s_mov_b32 m0, s35
	v_lshl_add_u64 v[146:147], v[224:225], 0, s[10:11]
	global_load_lds_dwordx4 v[146:147], off
	s_waitcnt vmcnt(8) lgkmcnt(0)
	s_setprio 1
	s_barrier
	v_mfma_f32_16x16x32_bf16 v[62:65], v[154:157], v[186:189], v[62:65]
	v_mfma_f32_16x16x32_bf16 v[58:61], v[162:165], v[186:189], v[58:61]
	v_mfma_f32_16x16x32_bf16 v[46:49], v[154:157], v[194:197], v[46:49]
	v_mfma_f32_16x16x32_bf16 v[42:45], v[162:165], v[194:197], v[42:45]
	v_mfma_f32_16x16x32_bf16 v[30:33], v[154:157], v[206:209], v[30:33]
	v_mfma_f32_16x16x32_bf16 v[26:29], v[162:165], v[206:209], v[26:29]
	v_mfma_f32_16x16x32_bf16 v[14:17], v[154:157], v[214:217], v[14:17]
	v_mfma_f32_16x16x32_bf16 v[10:13], v[162:165], v[214:217], v[10:13]
	v_mfma_f32_16x16x32_bf16 v[62:65], v[158:161], v[190:193], v[62:65]
	v_mfma_f32_16x16x32_bf16 v[58:61], v[166:169], v[190:193], v[58:61]
	v_mfma_f32_16x16x32_bf16 v[46:49], v[158:161], v[198:201], v[46:49]
	v_mfma_f32_16x16x32_bf16 v[42:45], v[166:169], v[198:201], v[42:45]
	v_mfma_f32_16x16x32_bf16 v[30:33], v[158:161], v[210:213], v[30:33]
	v_mfma_f32_16x16x32_bf16 v[26:29], v[166:169], v[210:213], v[26:29]
	v_mfma_f32_16x16x32_bf16 v[14:17], v[158:161], v[218:221], v[14:17]
	v_mfma_f32_16x16x32_bf16 v[10:13], v[166:169], v[218:221], v[10:13]
	v_mfma_f32_16x16x32_bf16 v[54:57], v[170:173], v[186:189], v[54:57]
	v_mfma_f32_16x16x32_bf16 v[50:53], v[178:181], v[186:189], v[50:53]
	v_mfma_f32_16x16x32_bf16 v[38:41], v[170:173], v[194:197], v[38:41]
	v_mfma_f32_16x16x32_bf16 v[34:37], v[178:181], v[194:197], v[34:37]
	v_mfma_f32_16x16x32_bf16 v[22:25], v[170:173], v[206:209], v[22:25]
	v_mfma_f32_16x16x32_bf16 v[18:21], v[178:181], v[206:209], v[18:21]
	v_mfma_f32_16x16x32_bf16 v[6:9], v[170:173], v[214:217], v[6:9]
	v_mfma_f32_16x16x32_bf16 v[2:5], v[178:181], v[214:217], v[2:5]
	v_mfma_f32_16x16x32_bf16 v[54:57], v[174:177], v[190:193], v[54:57]
	v_mfma_f32_16x16x32_bf16 v[50:53], v[182:185], v[190:193], v[50:53]
	v_mfma_f32_16x16x32_bf16 v[38:41], v[174:177], v[198:201], v[38:41]
	v_mfma_f32_16x16x32_bf16 v[34:37], v[182:185], v[198:201], v[34:37]
	v_mfma_f32_16x16x32_bf16 v[22:25], v[174:177], v[210:213], v[22:25]
	v_mfma_f32_16x16x32_bf16 v[18:21], v[182:185], v[210:213], v[18:21]
	v_mfma_f32_16x16x32_bf16 v[6:9], v[174:177], v[218:221], v[6:9]
	v_mfma_f32_16x16x32_bf16 v[2:5], v[182:185], v[218:221], v[2:5]
	s_setprio 0
	s_barrier
	s_add_i32 s68, s68, 2
	s_add_u32 s42, s42, 0x100
	s_addc_u32 s43, s43, 0
	s_add_u32 s66, s66, 0x100
	s_addc_u32 s67, s67, 0
	s_cmp_gt_u32 s68, 13
	s_cbranch_scc0 .LBB0_745
	s_and_b64 vcc, exec, s[12:13]
	s_cbranch_vccz .LBB0_748
	s_barrier

.LBB0_833:
	s_add_u32 s72, s0, s68
	s_addc_u32 s73, s1, s69
	s_and_b64 s[62:63], s[70:71], exec
	s_cselect_b32 s15, s73, s77
	s_cselect_b32 s33, s72, s76
	s_add_u32 s74, s35, s66
	s_addc_u32 s75, s85, s67
	s_and_b64 s[62:63], s[70:71], exec
	s_cselect_b32 s34, s75, s79
	s_cselect_b32 s39, s74, s78
	s_add_i32 s45, s7, -2
	s_add_u32 s76, s76, 0x100080
	s_addc_u32 s77, s77, 0
	s_add_u32 s47, s78, 0x100
	s_addc_u32 s62, s79, 0
	s_mov_b32 s63, 0
	s_waitcnt vmcnt(0)
	ds_read_b128 v[114:117], v190
	ds_read_b128 v[118:121], v190 offset:1024
	ds_read_b128 v[122:125], v190 offset:2048
	ds_read_b128 v[126:129], v190 offset:3072
	ds_read_b128 v[146:149], v191
	ds_read_b128 v[150:153], v191 offset:1024
	ds_read_b128 v[154:157], v191 offset:2048
	ds_read_b128 v[158:161], v191 offset:3072
	ds_read_b128 v[162:165], v192
	ds_read_b128 v[166:169], v192 offset:1024
	ds_read_b128 v[194:197], v192 offset:2048
	ds_read_b128 v[198:201], v192 offset:3072
	ds_read_b128 v[206:209], v192 offset:4096
	ds_read_b128 v[210:213], v192 offset:5120
	ds_read_b128 v[214:217], v192 offset:6144
	ds_read_b128 v[218:221], v192 offset:7168
	s_add_i32 s82, s63, 2
	s_add_u32 s78, s76, 0xfff00080
	s_addc_u32 s79, s77, -1
	s_cmp_eq_u32 s45, s63
	s_cselect_b32 s81, s15, s79
	s_cselect_b32 s80, s33, s78
	s_cselect_b32 s79, s34, s62
	s_cselect_b32 s78, s39, s47
	s_add_i32 m0, s87, 0xc000
	v_lshl_add_u64 v[186:187], s[76:77], 0, v[180:181]
	global_load_lds_dwordx4 v[186:187], off
	s_add_i32 m0, s87, 0xe000
	v_lshl_add_u64 v[186:187], s[76:77], 0, v[182:183]
	global_load_lds_dwordx4 v[186:187], off
	s_waitcnt vmcnt(8) lgkmcnt(0)
	s_setprio 1
	s_barrier
	v_mfma_f32_16x16x32_bf16 v[142:145], v[114:117], v[162:165], 0
	v_mfma_f32_16x16x32_bf16 v[138:141], v[122:125], v[162:165], 0
	v_mfma_f32_16x16x32_bf16 v[110:113], v[114:117], v[194:197], 0
	v_mfma_f32_16x16x32_bf16 v[106:109], v[122:125], v[194:197], 0
	v_mfma_f32_16x16x32_bf16 v[98:101], v[114:117], v[206:209], 0
	v_mfma_f32_16x16x32_bf16 v[90:93], v[122:125], v[206:209], 0
	v_mfma_f32_16x16x32_bf16 v[82:85], v[114:117], v[214:217], 0
	v_mfma_f32_16x16x32_bf16 v[74:77], v[122:125], v[214:217], 0
	v_mfma_f32_16x16x32_bf16 v[142:145], v[118:121], v[166:169], v[142:145]
	v_mfma_f32_16x16x32_bf16 v[138:141], v[126:129], v[166:169], v[138:141]
	v_mfma_f32_16x16x32_bf16 v[110:113], v[118:121], v[198:201], v[110:113]
	v_mfma_f32_16x16x32_bf16 v[106:109], v[126:129], v[198:201], v[106:109]
	v_mfma_f32_16x16x32_bf16 v[98:101], v[118:121], v[210:213], v[98:101]
	v_mfma_f32_16x16x32_bf16 v[90:93], v[126:129], v[210:213], v[90:93]
	v_mfma_f32_16x16x32_bf16 v[82:85], v[118:121], v[218:221], v[82:85]
	v_mfma_f32_16x16x32_bf16 v[74:77], v[126:129], v[218:221], v[74:77]
	v_mfma_f32_16x16x32_bf16 v[134:137], v[146:149], v[162:165], 0
	v_mfma_f32_16x16x32_bf16 v[130:133], v[154:157], v[162:165], 0
	v_mfma_f32_16x16x32_bf16 v[102:105], v[146:149], v[194:197], 0
	v_mfma_f32_16x16x32_bf16 v[94:97], v[154:157], v[194:197], 0
	v_mfma_f32_16x16x32_bf16 v[86:89], v[146:149], v[206:209], 0
	v_mfma_f32_16x16x32_bf16 v[78:81], v[154:157], v[206:209], 0
	v_mfma_f32_16x16x32_bf16 v[70:73], v[146:149], v[214:217], 0
	v_mfma_f32_16x16x32_bf16 v[66:69], v[154:157], v[214:217], 0
	v_mfma_f32_16x16x32_bf16 v[134:137], v[150:153], v[166:169], v[134:137]
	v_mfma_f32_16x16x32_bf16 v[130:133], v[158:161], v[166:169], v[130:133]
	v_mfma_f32_16x16x32_bf16 v[102:105], v[150:153], v[198:201], v[102:105]
	v_mfma_f32_16x16x32_bf16 v[94:97], v[158:161], v[198:201], v[94:97]
	v_mfma_f32_16x16x32_bf16 v[86:89], v[150:153], v[210:213], v[86:89]
	v_mfma_f32_16x16x32_bf16 v[78:81], v[158:161], v[210:213], v[78:81]
	v_mfma_f32_16x16x32_bf16 v[70:73], v[150:153], v[218:221], v[70:73]
	v_mfma_f32_16x16x32_bf16 v[66:69], v[158:161], v[218:221], v[66:69]
	s_setprio 0
	s_barrier
	ds_read_b128 v[162:165], v192 offset:16384
	ds_read_b128 v[166:169], v192 offset:17408
	ds_read_b128 v[194:197], v192 offset:18432
	ds_read_b128 v[198:201], v192 offset:19456
	ds_read_b128 v[206:209], v192 offset:20480
	ds_read_b128 v[210:213], v192 offset:21504
	ds_read_b128 v[214:217], v192 offset:22528
	ds_read_b128 v[218:221], v192 offset:23552
	s_add_i32 s63, s24, s86
	s_mov_b32 m0, s63
	v_lshl_add_u64 v[186:187], s[78:79], 0, v[172:173]
	global_load_lds_dwordx4 v[186:187], off
	s_add_i32 m0, s63, 0x2000
	s_add_u32 vcc_lo, s78, 0x100000
	v_lshl_add_u64 v[202:203], s[78:79], 0, v[176:177]
	s_addc_u32 vcc_hi, s79, 0
	s_add_i32 s63, s25, s86
	global_load_lds_dwordx4 v[202:203], off
	v_lshl_add_u64 v[222:223], vcc, 0, v[172:173]
	s_mov_b32 m0, s63
	v_lshl_add_u64 v[224:225], s[80:81], 0, v[174:175]
	global_load_lds_dwordx4 v[222:223], off
	s_add_i32 m0, s63, 0x2000
	v_lshl_add_u64 v[222:223], vcc, 0, v[176:177]
	global_load_lds_dwordx4 v[222:223], off
	s_mov_b32 m0, s87
	v_lshl_add_u64 v[222:223], s[80:81], 0, v[170:171]
	global_load_lds_dwordx4 v[222:223], off
	s_mov_b32 m0, s88
	s_nop 0
	global_load_lds_dwordx4 v[224:225], off
	s_waitcnt vmcnt(8) lgkmcnt(0)
	s_setprio 1
	s_barrier
	v_mfma_f32_16x16x32_bf16 v[62:65], v[114:117], v[162:165], 0
	v_mfma_f32_16x16x32_bf16 v[58:61], v[122:125], v[162:165], 0
	v_mfma_f32_16x16x32_bf16 v[50:53], v[114:117], v[194:197], 0
	v_mfma_f32_16x16x32_bf16 v[42:45], v[122:125], v[194:197], 0
	v_mfma_f32_16x16x32_bf16 v[34:37], v[114:117], v[206:209], 0
	v_mfma_f32_16x16x32_bf16 v[26:29], v[122:125], v[206:209], 0
	v_mfma_f32_16x16x32_bf16 v[18:21], v[114:117], v[214:217], 0
	v_mfma_f32_16x16x32_bf16 v[10:13], v[122:125], v[214:217], 0
	v_mfma_f32_16x16x32_bf16 v[62:65], v[118:121], v[166:169], v[62:65]
	v_mfma_f32_16x16x32_bf16 v[58:61], v[126:129], v[166:169], v[58:61]
	v_mfma_f32_16x16x32_bf16 v[50:53], v[118:121], v[198:201], v[50:53]
	v_mfma_f32_16x16x32_bf16 v[42:45], v[126:129], v[198:201], v[42:45]
	v_mfma_f32_16x16x32_bf16 v[34:37], v[118:121], v[210:213], v[34:37]
	v_mfma_f32_16x16x32_bf16 v[26:29], v[126:129], v[210:213], v[26:29]
	v_mfma_f32_16x16x32_bf16 v[18:21], v[118:121], v[218:221], v[18:21]
	v_mfma_f32_16x16x32_bf16 v[10:13], v[126:129], v[218:221], v[10:13]
	v_mfma_f32_16x16x32_bf16 v[54:57], v[146:149], v[162:165], 0
	v_mfma_f32_16x16x32_bf16 v[46:49], v[154:157], v[162:165], 0
	v_mfma_f32_16x16x32_bf16 v[38:41], v[146:149], v[194:197], 0
	v_mfma_f32_16x16x32_bf16 v[30:33], v[154:157], v[194:197], 0
	v_mfma_f32_16x16x32_bf16 v[22:25], v[146:149], v[206:209], 0
	v_mfma_f32_16x16x32_bf16 v[14:17], v[154:157], v[206:209], 0
	v_mfma_f32_16x16x32_bf16 v[6:9], v[146:149], v[214:217], 0
	v_mfma_f32_16x16x32_bf16 v[2:5], v[154:157], v[214:217], 0
	v_mfma_f32_16x16x32_bf16 v[54:57], v[150:153], v[166:169], v[54:57]
	v_mfma_f32_16x16x32_bf16 v[46:49], v[158:161], v[166:169], v[46:49]
	v_mfma_f32_16x16x32_bf16 v[38:41], v[150:153], v[198:201], v[38:41]
	v_mfma_f32_16x16x32_bf16 v[30:33], v[158:161], v[198:201], v[30:33]
	v_mfma_f32_16x16x32_bf16 v[22:25], v[150:153], v[210:213], v[22:25]
	v_mfma_f32_16x16x32_bf16 v[14:17], v[158:161], v[210:213], v[14:17]
	v_mfma_f32_16x16x32_bf16 v[6:9], v[150:153], v[218:221], v[6:9]
	v_mfma_f32_16x16x32_bf16 v[2:5], v[158:161], v[218:221], v[2:5]
	s_setprio 0
	s_barrier
	s_add_i32 s63, 0, 0x18000
	s_add_i32 s83, 0, 0x1c000
	v_add_u32_e32 v126, s63, v189
	v_add_u32_e32 v158, s83, v189
	ds_read_b128 v[114:117], v126
	ds_read_b128 v[118:121], v126 offset:1024
	ds_read_b128 v[122:125], v126 offset:2048
	ds_read_b128 v[126:129], v126 offset:3072
	ds_read_b128 v[146:149], v158
	ds_read_b128 v[150:153], v158 offset:1024
	ds_read_b128 v[154:157], v158 offset:2048
	ds_read_b128 v[158:161], v158 offset:3072
	s_add_u32 s80, s80, 0x100000
	s_addc_u32 s81, s81, 0
	s_mov_b32 m0, s89
	v_lshl_add_u64 v[226:227], s[80:81], 0, v[170:171]
	ds_read_b128 v[162:165], v192 offset:32768
	ds_read_b128 v[166:169], v192 offset:33792
	ds_read_b128 v[194:197], v192 offset:34816
	ds_read_b128 v[198:201], v192 offset:35840
	ds_read_b128 v[206:209], v192 offset:36864
	ds_read_b128 v[210:213], v192 offset:37888
	ds_read_b128 v[214:217], v192 offset:38912
	ds_read_b128 v[218:221], v192 offset:39936
	global_load_lds_dwordx4 v[226:227], off
	s_mov_b32 m0, s90
	v_lshl_add_u64 v[226:227], s[80:81], 0, v[174:175]
	global_load_lds_dwordx4 v[226:227], off
	s_waitcnt vmcnt(8) lgkmcnt(0)
	s_setprio 1
	s_barrier
	v_mfma_f32_16x16x32_bf16 v[142:145], v[114:117], v[162:165], v[142:145]
	v_mfma_f32_16x16x32_bf16 v[138:141], v[122:125], v[162:165], v[138:141]
	v_mfma_f32_16x16x32_bf16 v[110:113], v[114:117], v[194:197], v[110:113]
	v_mfma_f32_16x16x32_bf16 v[106:109], v[122:125], v[194:197], v[106:109]
	v_mfma_f32_16x16x32_bf16 v[98:101], v[114:117], v[206:209], v[98:101]
	v_mfma_f32_16x16x32_bf16 v[90:93], v[122:125], v[206:209], v[90:93]
	v_mfma_f32_16x16x32_bf16 v[82:85], v[114:117], v[214:217], v[82:85]
	v_mfma_f32_16x16x32_bf16 v[74:77], v[122:125], v[214:217], v[74:77]
	v_mfma_f32_16x16x32_bf16 v[142:145], v[118:121], v[166:169], v[142:145]
	v_mfma_f32_16x16x32_bf16 v[138:141], v[126:129], v[166:169], v[138:141]
	v_mfma_f32_16x16x32_bf16 v[110:113], v[118:121], v[198:201], v[110:113]
	v_mfma_f32_16x16x32_bf16 v[106:109], v[126:129], v[198:201], v[106:109]
	v_mfma_f32_16x16x32_bf16 v[98:101], v[118:121], v[210:213], v[98:101]
	v_mfma_f32_16x16x32_bf16 v[90:93], v[126:129], v[210:213], v[90:93]
	v_mfma_f32_16x16x32_bf16 v[82:85], v[118:121], v[218:221], v[82:85]
	v_mfma_f32_16x16x32_bf16 v[74:77], v[126:129], v[218:221], v[74:77]
	v_mfma_f32_16x16x32_bf16 v[134:137], v[146:149], v[162:165], v[134:137]
	v_mfma_f32_16x16x32_bf16 v[130:133], v[154:157], v[162:165], v[130:133]
	v_mfma_f32_16x16x32_bf16 v[102:105], v[146:149], v[194:197], v[102:105]
	v_mfma_f32_16x16x32_bf16 v[94:97], v[154:157], v[194:197], v[94:97]
	v_mfma_f32_16x16x32_bf16 v[86:89], v[146:149], v[206:209], v[86:89]
	v_mfma_f32_16x16x32_bf16 v[78:81], v[154:157], v[206:209], v[78:81]
	v_mfma_f32_16x16x32_bf16 v[70:73], v[146:149], v[214:217], v[70:73]
	v_mfma_f32_16x16x32_bf16 v[66:69], v[154:157], v[214:217], v[66:69]
	v_mfma_f32_16x16x32_bf16 v[134:137], v[150:153], v[166:169], v[134:137]
	v_mfma_f32_16x16x32_bf16 v[130:133], v[158:161], v[166:169], v[130:133]
	v_mfma_f32_16x16x32_bf16 v[102:105], v[150:153], v[198:201], v[102:105]
	v_mfma_f32_16x16x32_bf16 v[94:97], v[158:161], v[198:201], v[94:97]
	v_mfma_f32_16x16x32_bf16 v[86:89], v[150:153], v[210:213], v[86:89]
	v_mfma_f32_16x16x32_bf16 v[78:81], v[158:161], v[210:213], v[78:81]
	v_mfma_f32_16x16x32_bf16 v[70:73], v[150:153], v[218:221], v[70:73]
	v_mfma_f32_16x16x32_bf16 v[66:69], v[158:161], v[218:221], v[66:69]
	s_setprio 0
	s_barrier
	ds_read_b128 v[162:165], v192 offset:49152
	ds_read_b128 v[166:169], v192 offset:50176
	ds_read_b128 v[194:197], v192 offset:51200
	ds_read_b128 v[198:201], v192 offset:52224
	ds_read_b128 v[206:209], v192 offset:53248
	ds_read_b128 v[210:213], v192 offset:54272
	ds_read_b128 v[214:217], v192 offset:55296
	ds_read_b128 v[218:221], v192 offset:56320
	s_add_i32 s63, s63, s86
	s_mov_b32 m0, s63
	v_lshl_add_u64 v[186:187], v[186:187], 0, s[22:23]
	global_load_lds_dwordx4 v[186:187], off
	s_add_i32 m0, s63, 0x2000
	s_add_u32 s78, s78, 0x100080
	v_lshl_add_u64 v[186:187], v[202:203], 0, s[22:23]
	s_addc_u32 s79, s79, 0
	s_add_i32 s63, s83, s86
	global_load_lds_dwordx4 v[186:187], off
	s_mov_b32 m0, s63
	v_lshl_add_u64 v[186:187], s[78:79], 0, v[172:173]
	global_load_lds_dwordx4 v[186:187], off
	s_add_i32 m0, s63, 0x2000
	v_lshl_add_u64 v[186:187], s[78:79], 0, v[176:177]
	global_load_lds_dwordx4 v[186:187], off
	s_mov_b32 m0, s95
	v_lshl_add_u64 v[186:187], v[222:223], 0, s[22:23]
	global_load_lds_dwordx4 v[186:187], off
	s_mov_b32 m0, s96
	v_lshl_add_u64 v[186:187], v[224:225], 0, s[22:23]
	global_load_lds_dwordx4 v[186:187], off
	s_waitcnt vmcnt(8) lgkmcnt(0)
	s_setprio 1
	s_barrier
	v_mfma_f32_16x16x32_bf16 v[62:65], v[114:117], v[162:165], v[62:65]
	v_mfma_f32_16x16x32_bf16 v[58:61], v[122:125], v[162:165], v[58:61]
	v_mfma_f32_16x16x32_bf16 v[50:53], v[114:117], v[194:197], v[50:53]
	v_mfma_f32_16x16x32_bf16 v[42:45], v[122:125], v[194:197], v[42:45]
	v_mfma_f32_16x16x32_bf16 v[34:37], v[114:117], v[206:209], v[34:37]
	v_mfma_f32_16x16x32_bf16 v[26:29], v[122:125], v[206:209], v[26:29]
	v_mfma_f32_16x16x32_bf16 v[18:21], v[114:117], v[214:217], v[18:21]
	v_mfma_f32_16x16x32_bf16 v[10:13], v[122:125], v[214:217], v[10:13]
	v_mfma_f32_16x16x32_bf16 v[62:65], v[118:121], v[166:169], v[62:65]
	v_mfma_f32_16x16x32_bf16 v[58:61], v[126:129], v[166:169], v[58:61]
	v_mfma_f32_16x16x32_bf16 v[50:53], v[118:121], v[198:201], v[50:53]
	v_mfma_f32_16x16x32_bf16 v[42:45], v[126:129], v[198:201], v[42:45]
	v_mfma_f32_16x16x32_bf16 v[34:37], v[118:121], v[210:213], v[34:37]
	v_mfma_f32_16x16x32_bf16 v[26:29], v[126:129], v[210:213], v[26:29]
	v_mfma_f32_16x16x32_bf16 v[18:21], v[118:121], v[218:221], v[18:21]
	v_mfma_f32_16x16x32_bf16 v[10:13], v[126:129], v[218:221], v[10:13]
	v_mfma_f32_16x16x32_bf16 v[54:57], v[146:149], v[162:165], v[54:57]
	v_mfma_f32_16x16x32_bf16 v[46:49], v[154:157], v[162:165], v[46:49]
	v_mfma_f32_16x16x32_bf16 v[38:41], v[146:149], v[194:197], v[38:41]
	v_mfma_f32_16x16x32_bf16 v[30:33], v[154:157], v[194:197], v[30:33]
	v_mfma_f32_16x16x32_bf16 v[22:25], v[146:149], v[206:209], v[22:25]
	v_mfma_f32_16x16x32_bf16 v[14:17], v[154:157], v[206:209], v[14:17]
	v_mfma_f32_16x16x32_bf16 v[6:9], v[146:149], v[214:217], v[6:9]
	v_mfma_f32_16x16x32_bf16 v[2:5], v[154:157], v[214:217], v[2:5]
	v_mfma_f32_16x16x32_bf16 v[54:57], v[150:153], v[166:169], v[54:57]
	v_mfma_f32_16x16x32_bf16 v[46:49], v[158:161], v[166:169], v[46:49]
	v_mfma_f32_16x16x32_bf16 v[38:41], v[150:153], v[198:201], v[38:41]
	v_mfma_f32_16x16x32_bf16 v[30:33], v[158:161], v[198:201], v[30:33]
	v_mfma_f32_16x16x32_bf16 v[22:25], v[150:153], v[210:213], v[22:25]
	v_mfma_f32_16x16x32_bf16 v[14:17], v[158:161], v[210:213], v[14:17]
	v_mfma_f32_16x16x32_bf16 v[6:9], v[150:153], v[218:221], v[6:9]
	v_mfma_f32_16x16x32_bf16 v[2:5], v[158:161], v[218:221], v[2:5]
	s_setprio 0
	s_barrier
	s_add_u32 s76, s76, 0x100
	s_addc_u32 s77, s77, 0
	s_add_u32 s47, s47, 0x100
	s_addc_u32 s62, s62, 0
	s_cmp_ge_i32 s82, s7
	s_mov_b32 s63, s82
.LBB0_834:
	ds_read_b128 v[114:117], v190
	ds_read_b128 v[118:121], v190 offset:1024
	ds_read_b128 v[122:125], v190 offset:2048
	ds_read_b128 v[126:129], v190 offset:3072
	ds_read_b128 v[146:149], v191
	ds_read_b128 v[150:153], v191 offset:1024
	ds_read_b128 v[154:157], v191 offset:2048
	ds_read_b128 v[158:161], v191 offset:3072
	ds_read_b128 v[162:165], v192
	ds_read_b128 v[166:169], v192 offset:1024
	ds_read_b128 v[194:197], v192 offset:2048
	ds_read_b128 v[198:201], v192 offset:3072
	ds_read_b128 v[206:209], v192 offset:4096
	ds_read_b128 v[210:213], v192 offset:5120
	ds_read_b128 v[214:217], v192 offset:6144
	ds_read_b128 v[218:221], v192 offset:7168
	s_add_i32 s82, s63, 2
	s_add_u32 s78, s76, 0xfff00080
	s_addc_u32 s79, s77, -1
	s_cmp_eq_u32 s45, s63
	s_cselect_b32 s81, s15, s79
	s_cselect_b32 s80, s33, s78
	s_cselect_b32 s79, s34, s62
	s_cselect_b32 s78, s39, s47
	s_add_i32 m0, s87, 0xc000
	v_lshl_add_u64 v[186:187], s[76:77], 0, v[180:181]
	global_load_lds_dwordx4 v[186:187], off
	s_add_i32 m0, s87, 0xe000
	v_lshl_add_u64 v[186:187], s[76:77], 0, v[182:183]
	global_load_lds_dwordx4 v[186:187], off
	s_waitcnt vmcnt(8) lgkmcnt(0)
	s_setprio 1
	s_barrier
	v_mfma_f32_16x16x32_bf16 v[142:145], v[114:117], v[162:165], v[142:145]
	v_mfma_f32_16x16x32_bf16 v[138:141], v[122:125], v[162:165], v[138:141]
	v_mfma_f32_16x16x32_bf16 v[110:113], v[114:117], v[194:197], v[110:113]
	v_mfma_f32_16x16x32_bf16 v[106:109], v[122:125], v[194:197], v[106:109]
	v_mfma_f32_16x16x32_bf16 v[98:101], v[114:117], v[206:209], v[98:101]
	v_mfma_f32_16x16x32_bf16 v[90:93], v[122:125], v[206:209], v[90:93]
	v_mfma_f32_16x16x32_bf16 v[82:85], v[114:117], v[214:217], v[82:85]
	v_mfma_f32_16x16x32_bf16 v[74:77], v[122:125], v[214:217], v[74:77]
	v_mfma_f32_16x16x32_bf16 v[142:145], v[118:121], v[166:169], v[142:145]
	v_mfma_f32_16x16x32_bf16 v[138:141], v[126:129], v[166:169], v[138:141]
	v_mfma_f32_16x16x32_bf16 v[110:113], v[118:121], v[198:201], v[110:113]
	v_mfma_f32_16x16x32_bf16 v[106:109], v[126:129], v[198:201], v[106:109]
	v_mfma_f32_16x16x32_bf16 v[98:101], v[118:121], v[210:213], v[98:101]
	v_mfma_f32_16x16x32_bf16 v[90:93], v[126:129], v[210:213], v[90:93]
	v_mfma_f32_16x16x32_bf16 v[82:85], v[118:121], v[218:221], v[82:85]
	v_mfma_f32_16x16x32_bf16 v[74:77], v[126:129], v[218:221], v[74:77]
	v_mfma_f32_16x16x32_bf16 v[134:137], v[146:149], v[162:165], v[134:137]
	v_mfma_f32_16x16x32_bf16 v[130:133], v[154:157], v[162:165], v[130:133]
	v_mfma_f32_16x16x32_bf16 v[102:105], v[146:149], v[194:197], v[102:105]
	v_mfma_f32_16x16x32_bf16 v[94:97], v[154:157], v[194:197], v[94:97]
	v_mfma_f32_16x16x32_bf16 v[86:89], v[146:149], v[206:209], v[86:89]
	v_mfma_f32_16x16x32_bf16 v[78:81], v[154:157], v[206:209], v[78:81]
	v_mfma_f32_16x16x32_bf16 v[70:73], v[146:149], v[214:217], v[70:73]
	v_mfma_f32_16x16x32_bf16 v[66:69], v[154:157], v[214:217], v[66:69]
	v_mfma_f32_16x16x32_bf16 v[134:137], v[150:153], v[166:169], v[134:137]
	v_mfma_f32_16x16x32_bf16 v[130:133], v[158:161], v[166:169], v[130:133]
	v_mfma_f32_16x16x32_bf16 v[102:105], v[150:153], v[198:201], v[102:105]
	v_mfma_f32_16x16x32_bf16 v[94:97], v[158:161], v[198:201], v[94:97]
	v_mfma_f32_16x16x32_bf16 v[86:89], v[150:153], v[210:213], v[86:89]
	v_mfma_f32_16x16x32_bf16 v[78:81], v[158:161], v[210:213], v[78:81]
	v_mfma_f32_16x16x32_bf16 v[70:73], v[150:153], v[218:221], v[70:73]
	v_mfma_f32_16x16x32_bf16 v[66:69], v[158:161], v[218:221], v[66:69]
	s_setprio 0
	s_barrier
	ds_read_b128 v[162:165], v192 offset:16384
	ds_read_b128 v[166:169], v192 offset:17408
	ds_read_b128 v[194:197], v192 offset:18432
	ds_read_b128 v[198:201], v192 offset:19456
	ds_read_b128 v[206:209], v192 offset:20480
	ds_read_b128 v[210:213], v192 offset:21504
	ds_read_b128 v[214:217], v192 offset:22528
	ds_read_b128 v[218:221], v192 offset:23552
	s_add_i32 s63, s24, s86
	s_mov_b32 m0, s63
	v_lshl_add_u64 v[186:187], s[78:79], 0, v[172:173]
	global_load_lds_dwordx4 v[186:187], off
	s_add_i32 m0, s63, 0x2000
	s_add_u32 vcc_lo, s78, 0x100000
	v_lshl_add_u64 v[202:203], s[78:79], 0, v[176:177]
	s_addc_u32 vcc_hi, s79, 0
	s_add_i32 s63, s25, s86
	global_load_lds_dwordx4 v[202:203], off
	v_lshl_add_u64 v[222:223], vcc, 0, v[172:173]
	s_mov_b32 m0, s63
	v_lshl_add_u64 v[224:225], s[80:81], 0, v[174:175]
	global_load_lds_dwordx4 v[222:223], off
	s_add_i32 m0, s63, 0x2000
	v_lshl_add_u64 v[222:223], vcc, 0, v[176:177]
	global_load_lds_dwordx4 v[222:223], off
	s_mov_b32 m0, s87
	v_lshl_add_u64 v[222:223], s[80:81], 0, v[170:171]
	global_load_lds_dwordx4 v[222:223], off
	s_mov_b32 m0, s88
	s_nop 0
	global_load_lds_dwordx4 v[224:225], off
	s_waitcnt vmcnt(8) lgkmcnt(0)
	s_setprio 1
	s_barrier
	v_mfma_f32_16x16x32_bf16 v[62:65], v[114:117], v[162:165], v[62:65]
	v_mfma_f32_16x16x32_bf16 v[58:61], v[122:125], v[162:165], v[58:61]
	v_mfma_f32_16x16x32_bf16 v[50:53], v[114:117], v[194:197], v[50:53]
	v_mfma_f32_16x16x32_bf16 v[42:45], v[122:125], v[194:197], v[42:45]
	v_mfma_f32_16x16x32_bf16 v[34:37], v[114:117], v[206:209], v[34:37]
	v_mfma_f32_16x16x32_bf16 v[26:29], v[122:125], v[206:209], v[26:29]
	v_mfma_f32_16x16x32_bf16 v[18:21], v[114:117], v[214:217], v[18:21]
	v_mfma_f32_16x16x32_bf16 v[10:13], v[122:125], v[214:217], v[10:13]
	v_mfma_f32_16x16x32_bf16 v[62:65], v[118:121], v[166:169], v[62:65]
	v_mfma_f32_16x16x32_bf16 v[58:61], v[126:129], v[166:169], v[58:61]
	v_mfma_f32_16x16x32_bf16 v[50:53], v[118:121], v[198:201], v[50:53]
	v_mfma_f32_16x16x32_bf16 v[42:45], v[126:129], v[198:201], v[42:45]
	v_mfma_f32_16x16x32_bf16 v[34:37], v[118:121], v[210:213], v[34:37]
	v_mfma_f32_16x16x32_bf16 v[26:29], v[126:129], v[210:213], v[26:29]
	v_mfma_f32_16x16x32_bf16 v[18:21], v[118:121], v[218:221], v[18:21]
	v_mfma_f32_16x16x32_bf16 v[10:13], v[126:129], v[218:221], v[10:13]
	v_mfma_f32_16x16x32_bf16 v[54:57], v[146:149], v[162:165], v[54:57]
	v_mfma_f32_16x16x32_bf16 v[46:49], v[154:157], v[162:165], v[46:49]
	v_mfma_f32_16x16x32_bf16 v[38:41], v[146:149], v[194:197], v[38:41]
	v_mfma_f32_16x16x32_bf16 v[30:33], v[154:157], v[194:197], v[30:33]
	v_mfma_f32_16x16x32_bf16 v[22:25], v[146:149], v[206:209], v[22:25]
	v_mfma_f32_16x16x32_bf16 v[14:17], v[154:157], v[206:209], v[14:17]
	v_mfma_f32_16x16x32_bf16 v[6:9], v[146:149], v[214:217], v[6:9]
	v_mfma_f32_16x16x32_bf16 v[2:5], v[154:157], v[214:217], v[2:5]
	v_mfma_f32_16x16x32_bf16 v[54:57], v[150:153], v[166:169], v[54:57]
	v_mfma_f32_16x16x32_bf16 v[46:49], v[158:161], v[166:169], v[46:49]
	v_mfma_f32_16x16x32_bf16 v[38:41], v[150:153], v[198:201], v[38:41]
	v_mfma_f32_16x16x32_bf16 v[30:33], v[158:161], v[198:201], v[30:33]
	v_mfma_f32_16x16x32_bf16 v[22:25], v[150:153], v[210:213], v[22:25]
	v_mfma_f32_16x16x32_bf16 v[14:17], v[158:161], v[210:213], v[14:17]
	v_mfma_f32_16x16x32_bf16 v[6:9], v[150:153], v[218:221], v[6:9]
	v_mfma_f32_16x16x32_bf16 v[2:5], v[158:161], v[218:221], v[2:5]
	s_setprio 0
	s_barrier
	s_add_i32 s63, 0, 0x18000
	s_add_i32 s83, 0, 0x1c000
	v_add_u32_e32 v126, s63, v189
	v_add_u32_e32 v158, s83, v189
	ds_read_b128 v[114:117], v126
	ds_read_b128 v[118:121], v126 offset:1024
	ds_read_b128 v[122:125], v126 offset:2048
	ds_read_b128 v[126:129], v126 offset:3072
	ds_read_b128 v[146:149], v158
	ds_read_b128 v[150:153], v158 offset:1024
	ds_read_b128 v[154:157], v158 offset:2048
	ds_read_b128 v[158:161], v158 offset:3072
	s_add_u32 s80, s80, 0x100000
	s_addc_u32 s81, s81, 0
	s_mov_b32 m0, s89
	v_lshl_add_u64 v[226:227], s[80:81], 0, v[170:171]
	ds_read_b128 v[162:165], v192 offset:32768
	ds_read_b128 v[166:169], v192 offset:33792
	ds_read_b128 v[194:197], v192 offset:34816
	ds_read_b128 v[198:201], v192 offset:35840
	ds_read_b128 v[206:209], v192 offset:36864
	ds_read_b128 v[210:213], v192 offset:37888
	ds_read_b128 v[214:217], v192 offset:38912
	ds_read_b128 v[218:221], v192 offset:39936
	global_load_lds_dwordx4 v[226:227], off
	s_mov_b32 m0, s90
	v_lshl_add_u64 v[226:227], s[80:81], 0, v[174:175]
	global_load_lds_dwordx4 v[226:227], off
	s_waitcnt vmcnt(8) lgkmcnt(0)
	s_setprio 1
	s_barrier
	v_mfma_f32_16x16x32_bf16 v[142:145], v[114:117], v[162:165], v[142:145]
	v_mfma_f32_16x16x32_bf16 v[138:141], v[122:125], v[162:165], v[138:141]
	v_mfma_f32_16x16x32_bf16 v[110:113], v[114:117], v[194:197], v[110:113]
	v_mfma_f32_16x16x32_bf16 v[106:109], v[122:125], v[194:197], v[106:109]
	v_mfma_f32_16x16x32_bf16 v[98:101], v[114:117], v[206:209], v[98:101]
	v_mfma_f32_16x16x32_bf16 v[90:93], v[122:125], v[206:209], v[90:93]
	v_mfma_f32_16x16x32_bf16 v[82:85], v[114:117], v[214:217], v[82:85]
	v_mfma_f32_16x16x32_bf16 v[74:77], v[122:125], v[214:217], v[74:77]
	v_mfma_f32_16x16x32_bf16 v[142:145], v[118:121], v[166:169], v[142:145]
	v_mfma_f32_16x16x32_bf16 v[138:141], v[126:129], v[166:169], v[138:141]
	v_mfma_f32_16x16x32_bf16 v[110:113], v[118:121], v[198:201], v[110:113]
	v_mfma_f32_16x16x32_bf16 v[106:109], v[126:129], v[198:201], v[106:109]
	v_mfma_f32_16x16x32_bf16 v[98:101], v[118:121], v[210:213], v[98:101]
	v_mfma_f32_16x16x32_bf16 v[90:93], v[126:129], v[210:213], v[90:93]
	v_mfma_f32_16x16x32_bf16 v[82:85], v[118:121], v[218:221], v[82:85]
	v_mfma_f32_16x16x32_bf16 v[74:77], v[126:129], v[218:221], v[74:77]
	v_mfma_f32_16x16x32_bf16 v[134:137], v[146:149], v[162:165], v[134:137]
	v_mfma_f32_16x16x32_bf16 v[130:133], v[154:157], v[162:165], v[130:133]
	v_mfma_f32_16x16x32_bf16 v[102:105], v[146:149], v[194:197], v[102:105]
	v_mfma_f32_16x16x32_bf16 v[94:97], v[154:157], v[194:197], v[94:97]
	v_mfma_f32_16x16x32_bf16 v[86:89], v[146:149], v[206:209], v[86:89]
	v_mfma_f32_16x16x32_bf16 v[78:81], v[154:157], v[206:209], v[78:81]
	v_mfma_f32_16x16x32_bf16 v[70:73], v[146:149], v[214:217], v[70:73]
	v_mfma_f32_16x16x32_bf16 v[66:69], v[154:157], v[214:217], v[66:69]
	v_mfma_f32_16x16x32_bf16 v[134:137], v[150:153], v[166:169], v[134:137]
	v_mfma_f32_16x16x32_bf16 v[130:133], v[158:161], v[166:169], v[130:133]
	v_mfma_f32_16x16x32_bf16 v[102:105], v[150:153], v[198:201], v[102:105]
	v_mfma_f32_16x16x32_bf16 v[94:97], v[158:161], v[198:201], v[94:97]
	v_mfma_f32_16x16x32_bf16 v[86:89], v[150:153], v[210:213], v[86:89]
	v_mfma_f32_16x16x32_bf16 v[78:81], v[158:161], v[210:213], v[78:81]
	v_mfma_f32_16x16x32_bf16 v[70:73], v[150:153], v[218:221], v[70:73]
	v_mfma_f32_16x16x32_bf16 v[66:69], v[158:161], v[218:221], v[66:69]
	s_setprio 0
	s_barrier
	ds_read_b128 v[162:165], v192 offset:49152
	ds_read_b128 v[166:169], v192 offset:50176
	ds_read_b128 v[194:197], v192 offset:51200
	ds_read_b128 v[198:201], v192 offset:52224
	ds_read_b128 v[206:209], v192 offset:53248
	ds_read_b128 v[210:213], v192 offset:54272
	ds_read_b128 v[214:217], v192 offset:55296
	ds_read_b128 v[218:221], v192 offset:56320
	s_add_i32 s63, s63, s86
	s_mov_b32 m0, s63
	v_lshl_add_u64 v[186:187], v[186:187], 0, s[22:23]
	global_load_lds_dwordx4 v[186:187], off
	s_add_i32 m0, s63, 0x2000
	s_add_u32 s78, s78, 0x100080
	v_lshl_add_u64 v[186:187], v[202:203], 0, s[22:23]
	s_addc_u32 s79, s79, 0
	s_add_i32 s63, s83, s86
	global_load_lds_dwordx4 v[186:187], off
	s_mov_b32 m0, s63
	v_lshl_add_u64 v[186:187], s[78:79], 0, v[172:173]
	global_load_lds_dwordx4 v[186:187], off
	s_add_i32 m0, s63, 0x2000
	v_lshl_add_u64 v[186:187], s[78:79], 0, v[176:177]
	global_load_lds_dwordx4 v[186:187], off
	s_mov_b32 m0, s95
	v_lshl_add_u64 v[186:187], v[222:223], 0, s[22:23]
	global_load_lds_dwordx4 v[186:187], off
	s_mov_b32 m0, s96
	v_lshl_add_u64 v[186:187], v[224:225], 0, s[22:23]
	global_load_lds_dwordx4 v[186:187], off
	s_waitcnt vmcnt(8) lgkmcnt(0)
	s_setprio 1
	s_barrier
	v_mfma_f32_16x16x32_bf16 v[62:65], v[114:117], v[162:165], v[62:65]
	v_mfma_f32_16x16x32_bf16 v[58:61], v[122:125], v[162:165], v[58:61]
	v_mfma_f32_16x16x32_bf16 v[50:53], v[114:117], v[194:197], v[50:53]
	v_mfma_f32_16x16x32_bf16 v[42:45], v[122:125], v[194:197], v[42:45]
	v_mfma_f32_16x16x32_bf16 v[34:37], v[114:117], v[206:209], v[34:37]
	v_mfma_f32_16x16x32_bf16 v[26:29], v[122:125], v[206:209], v[26:29]
	v_mfma_f32_16x16x32_bf16 v[18:21], v[114:117], v[214:217], v[18:21]
	v_mfma_f32_16x16x32_bf16 v[10:13], v[122:125], v[214:217], v[10:13]
	v_mfma_f32_16x16x32_bf16 v[62:65], v[118:121], v[166:169], v[62:65]
	v_mfma_f32_16x16x32_bf16 v[58:61], v[126:129], v[166:169], v[58:61]
	v_mfma_f32_16x16x32_bf16 v[50:53], v[118:121], v[198:201], v[50:53]
	v_mfma_f32_16x16x32_bf16 v[42:45], v[126:129], v[198:201], v[42:45]
	v_mfma_f32_16x16x32_bf16 v[34:37], v[118:121], v[210:213], v[34:37]
	v_mfma_f32_16x16x32_bf16 v[26:29], v[126:129], v[210:213], v[26:29]
	v_mfma_f32_16x16x32_bf16 v[18:21], v[118:121], v[218:221], v[18:21]
	v_mfma_f32_16x16x32_bf16 v[10:13], v[126:129], v[218:221], v[10:13]
	v_mfma_f32_16x16x32_bf16 v[54:57], v[146:149], v[162:165], v[54:57]
	v_mfma_f32_16x16x32_bf16 v[46:49], v[154:157], v[162:165], v[46:49]
	v_mfma_f32_16x16x32_bf16 v[38:41], v[146:149], v[194:197], v[38:41]
	v_mfma_f32_16x16x32_bf16 v[30:33], v[154:157], v[194:197], v[30:33]
	v_mfma_f32_16x16x32_bf16 v[22:25], v[146:149], v[206:209], v[22:25]
	v_mfma_f32_16x16x32_bf16 v[14:17], v[154:157], v[206:209], v[14:17]
	v_mfma_f32_16x16x32_bf16 v[6:9], v[146:149], v[214:217], v[6:9]
	v_mfma_f32_16x16x32_bf16 v[2:5], v[154:157], v[214:217], v[2:5]
	v_mfma_f32_16x16x32_bf16 v[54:57], v[150:153], v[166:169], v[54:57]
	v_mfma_f32_16x16x32_bf16 v[46:49], v[158:161], v[166:169], v[46:49]
	v_mfma_f32_16x16x32_bf16 v[38:41], v[150:153], v[198:201], v[38:41]
	v_mfma_f32_16x16x32_bf16 v[30:33], v[158:161], v[198:201], v[30:33]
	v_mfma_f32_16x16x32_bf16 v[22:25], v[150:153], v[210:213], v[22:25]
	v_mfma_f32_16x16x32_bf16 v[14:17], v[158:161], v[210:213], v[14:17]
	v_mfma_f32_16x16x32_bf16 v[6:9], v[150:153], v[218:221], v[6:9]
	v_mfma_f32_16x16x32_bf16 v[2:5], v[158:161], v[218:221], v[2:5]
	s_setprio 0
	s_barrier
	s_add_u32 s76, s76, 0x100
	s_addc_u32 s77, s77, 0
	s_add_u32 s47, s47, 0x100
	s_addc_u32 s62, s62, 0
	s_cmp_ge_i32 s82, s7
	s_mov_b32 s63, s82
	s_cbranch_scc0 .LBB0_834
	s_and_b64 vcc, exec, s[26:27]
	s_cbranch_vccz .LBB0_837
	s_barrier

.LBB0_1012:
	s_add_u32 s48, s96, s44
	s_addc_u32 s49, s97, s45
	s_and_b64 s[14:15], s[4:5], exec
	s_cselect_b32 s6, s49, s65
	s_cselect_b32 s14, s48, s64
	s_add_u32 s50, s3, s46
	s_addc_u32 s51, s35, s47
	s_and_b64 s[18:19], s[4:5], exec
	s_cselect_b32 s15, s51, s67
	s_cselect_b32 s17, s50, s66
	s_add_u32 s64, s64, 0x40080
	s_addc_u32 s65, s65, 0
	s_add_u32 s18, s66, 0x100
	s_addc_u32 s19, s67, 0
	s_mov_b32 s24, -2
	s_waitcnt vmcnt(0)
	ds_read_b128 v[130:133], v172
	ds_read_b128 v[134:137], v172 offset:1024
	ds_read_b128 v[138:141], v172 offset:2048
	ds_read_b128 v[142:145], v172 offset:3072
	ds_read_b128 v[164:167], v173
	ds_read_b128 v[176:179], v173 offset:1024
	ds_read_b128 v[180:183], v173 offset:2048
	ds_read_b128 v[184:187], v173 offset:3072
	ds_read_b128 v[188:191], v174
	ds_read_b128 v[192:195], v174 offset:1024
	ds_read_b128 v[196:199], v174 offset:2048
	ds_read_b128 v[200:203], v174 offset:3072
	ds_read_b128 v[206:209], v174 offset:4096
	ds_read_b128 v[210:213], v174 offset:5120
	ds_read_b128 v[214:217], v174 offset:6144
	ds_read_b128 v[218:221], v174 offset:7168
	s_add_u32 s25, s64, 0xfffc0080
	s_addc_u32 s28, s65, -1
	s_cmp_eq_u32 s24, 12
	s_cselect_b32 s69, s6, s28
	s_cselect_b32 s68, s14, s25
	s_cselect_b32 s67, s15, s19
	s_cselect_b32 s66, s17, s18
	s_add_i32 m0, s73, 0xc000
	v_lshl_add_u64 v[168:169], s[64:65], 0, v[156:157]
	global_load_lds_dwordx4 v[168:169], off
	s_add_i32 m0, s73, 0xe000
	v_lshl_add_u64 v[168:169], s[64:65], 0, v[158:159]
	global_load_lds_dwordx4 v[168:169], off
	s_waitcnt vmcnt(8) lgkmcnt(0)
	s_setprio 1
	s_barrier
	v_mfma_f32_16x16x32_bf16 v[126:129], v[130:133], v[188:191], 0
	v_mfma_f32_16x16x32_bf16 v[122:125], v[138:141], v[188:191], 0
	v_mfma_f32_16x16x32_bf16 v[110:113], v[130:133], v[196:199], 0
	v_mfma_f32_16x16x32_bf16 v[106:109], v[138:141], v[196:199], 0
	v_mfma_f32_16x16x32_bf16 v[94:97], v[130:133], v[206:209], 0
	v_mfma_f32_16x16x32_bf16 v[90:93], v[138:141], v[206:209], 0
	v_mfma_f32_16x16x32_bf16 v[78:81], v[130:133], v[214:217], 0
	v_mfma_f32_16x16x32_bf16 v[74:77], v[138:141], v[214:217], 0
	v_mfma_f32_16x16x32_bf16 v[126:129], v[134:137], v[192:195], v[126:129]
	v_mfma_f32_16x16x32_bf16 v[122:125], v[142:145], v[192:195], v[122:125]
	v_mfma_f32_16x16x32_bf16 v[110:113], v[134:137], v[200:203], v[110:113]
	v_mfma_f32_16x16x32_bf16 v[106:109], v[142:145], v[200:203], v[106:109]
	v_mfma_f32_16x16x32_bf16 v[94:97], v[134:137], v[210:213], v[94:97]
	v_mfma_f32_16x16x32_bf16 v[90:93], v[142:145], v[210:213], v[90:93]
	v_mfma_f32_16x16x32_bf16 v[78:81], v[134:137], v[218:221], v[78:81]
	v_mfma_f32_16x16x32_bf16 v[74:77], v[142:145], v[218:221], v[74:77]
	v_mfma_f32_16x16x32_bf16 v[118:121], v[164:167], v[188:191], 0
	v_mfma_f32_16x16x32_bf16 v[114:117], v[180:183], v[188:191], 0
	v_mfma_f32_16x16x32_bf16 v[102:105], v[164:167], v[196:199], 0
	v_mfma_f32_16x16x32_bf16 v[98:101], v[180:183], v[196:199], 0
	v_mfma_f32_16x16x32_bf16 v[86:89], v[164:167], v[206:209], 0
	v_mfma_f32_16x16x32_bf16 v[82:85], v[180:183], v[206:209], 0
	v_mfma_f32_16x16x32_bf16 v[70:73], v[164:167], v[214:217], 0
	v_mfma_f32_16x16x32_bf16 v[66:69], v[180:183], v[214:217], 0
	v_mfma_f32_16x16x32_bf16 v[118:121], v[176:179], v[192:195], v[118:121]
	v_mfma_f32_16x16x32_bf16 v[114:117], v[184:187], v[192:195], v[114:117]
	v_mfma_f32_16x16x32_bf16 v[102:105], v[176:179], v[200:203], v[102:105]
	v_mfma_f32_16x16x32_bf16 v[98:101], v[184:187], v[200:203], v[98:101]
	v_mfma_f32_16x16x32_bf16 v[86:89], v[176:179], v[210:213], v[86:89]
	v_mfma_f32_16x16x32_bf16 v[82:85], v[184:187], v[210:213], v[82:85]
	v_mfma_f32_16x16x32_bf16 v[70:73], v[176:179], v[218:221], v[70:73]
	v_mfma_f32_16x16x32_bf16 v[66:69], v[184:187], v[218:221], v[66:69]
	s_setprio 0
	s_barrier
	ds_read_b128 v[188:191], v174 offset:16384
	ds_read_b128 v[192:195], v174 offset:17408
	ds_read_b128 v[196:199], v174 offset:18432
	ds_read_b128 v[200:203], v174 offset:19456
	ds_read_b128 v[206:209], v174 offset:20480
	ds_read_b128 v[210:213], v174 offset:21504
	ds_read_b128 v[214:217], v174 offset:22528
	ds_read_b128 v[218:221], v174 offset:23552
	s_add_i32 s25, s82, s70
	s_mov_b32 m0, s25
	v_lshl_add_u64 v[168:169], s[66:67], 0, v[150:151]
	global_load_lds_dwordx4 v[168:169], off
	s_add_i32 m0, s25, 0x2000
	s_add_u32 s28, s66, 0x40000
	v_lshl_add_u64 v[222:223], s[66:67], 0, v[146:147]
	s_addc_u32 s29, s67, 0
	s_add_i32 s25, s83, s70
	global_load_lds_dwordx4 v[222:223], off
	v_lshl_add_u64 v[224:225], s[28:29], 0, v[150:151]
	s_mov_b32 m0, s25
	v_lshl_add_u64 v[226:227], s[68:69], 0, v[148:149]
	global_load_lds_dwordx4 v[224:225], off
	s_add_i32 m0, s25, 0x2000
	v_lshl_add_u64 v[224:225], s[28:29], 0, v[146:147]
	global_load_lds_dwordx4 v[224:225], off
	s_mov_b32 m0, s73
	v_lshl_add_u64 v[224:225], s[68:69], 0, v[152:153]
	global_load_lds_dwordx4 v[224:225], off
	s_mov_b32 m0, s74
	s_nop 0
	global_load_lds_dwordx4 v[226:227], off
	s_waitcnt vmcnt(8) lgkmcnt(0)
	s_setprio 1
	s_barrier
	v_mfma_f32_16x16x32_bf16 v[62:65], v[130:133], v[188:191], 0
	v_mfma_f32_16x16x32_bf16 v[58:61], v[138:141], v[188:191], 0
	v_mfma_f32_16x16x32_bf16 v[46:49], v[130:133], v[196:199], 0
	v_mfma_f32_16x16x32_bf16 v[42:45], v[138:141], v[196:199], 0
	v_mfma_f32_16x16x32_bf16 v[30:33], v[130:133], v[206:209], 0
	v_mfma_f32_16x16x32_bf16 v[26:29], v[138:141], v[206:209], 0
	v_mfma_f32_16x16x32_bf16 v[14:17], v[130:133], v[214:217], 0
	v_mfma_f32_16x16x32_bf16 v[10:13], v[138:141], v[214:217], 0
	v_mfma_f32_16x16x32_bf16 v[62:65], v[134:137], v[192:195], v[62:65]
	v_mfma_f32_16x16x32_bf16 v[58:61], v[142:145], v[192:195], v[58:61]
	v_mfma_f32_16x16x32_bf16 v[46:49], v[134:137], v[200:203], v[46:49]
	v_mfma_f32_16x16x32_bf16 v[42:45], v[142:145], v[200:203], v[42:45]
	v_mfma_f32_16x16x32_bf16 v[30:33], v[134:137], v[210:213], v[30:33]
	v_mfma_f32_16x16x32_bf16 v[26:29], v[142:145], v[210:213], v[26:29]
	v_mfma_f32_16x16x32_bf16 v[14:17], v[134:137], v[218:221], v[14:17]
	v_mfma_f32_16x16x32_bf16 v[10:13], v[142:145], v[218:221], v[10:13]
	v_mfma_f32_16x16x32_bf16 v[54:57], v[164:167], v[188:191], 0
	v_mfma_f32_16x16x32_bf16 v[50:53], v[180:183], v[188:191], 0
	v_mfma_f32_16x16x32_bf16 v[38:41], v[164:167], v[196:199], 0
	v_mfma_f32_16x16x32_bf16 v[34:37], v[180:183], v[196:199], 0
	v_mfma_f32_16x16x32_bf16 v[22:25], v[164:167], v[206:209], 0
	v_mfma_f32_16x16x32_bf16 v[18:21], v[180:183], v[206:209], 0
	v_mfma_f32_16x16x32_bf16 v[6:9], v[164:167], v[214:217], 0
	v_mfma_f32_16x16x32_bf16 v[2:5], v[180:183], v[214:217], 0
	v_mfma_f32_16x16x32_bf16 v[54:57], v[176:179], v[192:195], v[54:57]
	v_mfma_f32_16x16x32_bf16 v[50:53], v[184:187], v[192:195], v[50:53]
	v_mfma_f32_16x16x32_bf16 v[38:41], v[176:179], v[200:203], v[38:41]
	v_mfma_f32_16x16x32_bf16 v[34:37], v[184:187], v[200:203], v[34:37]
	v_mfma_f32_16x16x32_bf16 v[22:25], v[176:179], v[210:213], v[22:25]
	v_mfma_f32_16x16x32_bf16 v[18:21], v[184:187], v[210:213], v[18:21]
	v_mfma_f32_16x16x32_bf16 v[6:9], v[176:179], v[218:221], v[6:9]
	v_mfma_f32_16x16x32_bf16 v[2:5], v[184:187], v[218:221], v[2:5]
	s_setprio 0
	s_barrier
	s_add_i32 s25, 0, 0x18000
	s_add_i32 s30, 0, 0x1c000
	v_add_u32_e32 v142, s25, v171
	v_add_u32_e32 v175, s30, v171
	ds_read_b128 v[130:133], v142
	ds_read_b128 v[134:137], v142 offset:1024
	ds_read_b128 v[138:141], v142 offset:2048
	ds_read_b128 v[142:145], v142 offset:3072
	ds_read_b128 v[164:167], v175
	ds_read_b128 v[176:179], v175 offset:1024
	ds_read_b128 v[180:183], v175 offset:2048
	ds_read_b128 v[184:187], v175 offset:3072
	s_add_u32 s28, s68, 0x40000
	s_addc_u32 s29, s69, 0
	s_mov_b32 m0, s75
	v_lshl_add_u64 v[228:229], s[28:29], 0, v[152:153]
	ds_read_b128 v[188:191], v174 offset:32768
	ds_read_b128 v[192:195], v174 offset:33792
	ds_read_b128 v[196:199], v174 offset:34816
	ds_read_b128 v[200:203], v174 offset:35840
	ds_read_b128 v[206:209], v174 offset:36864
	ds_read_b128 v[210:213], v174 offset:37888
	ds_read_b128 v[214:217], v174 offset:38912
	ds_read_b128 v[218:221], v174 offset:39936
	global_load_lds_dwordx4 v[228:229], off
	s_mov_b32 m0, s76
	v_lshl_add_u64 v[228:229], s[28:29], 0, v[148:149]
	global_load_lds_dwordx4 v[228:229], off
	s_waitcnt vmcnt(8) lgkmcnt(0)
	s_setprio 1
	s_barrier
	v_mfma_f32_16x16x32_bf16 v[126:129], v[130:133], v[188:191], v[126:129]
	v_mfma_f32_16x16x32_bf16 v[122:125], v[138:141], v[188:191], v[122:125]
	v_mfma_f32_16x16x32_bf16 v[110:113], v[130:133], v[196:199], v[110:113]
	v_mfma_f32_16x16x32_bf16 v[106:109], v[138:141], v[196:199], v[106:109]
	v_mfma_f32_16x16x32_bf16 v[94:97], v[130:133], v[206:209], v[94:97]
	v_mfma_f32_16x16x32_bf16 v[90:93], v[138:141], v[206:209], v[90:93]
	v_mfma_f32_16x16x32_bf16 v[78:81], v[130:133], v[214:217], v[78:81]
	v_mfma_f32_16x16x32_bf16 v[74:77], v[138:141], v[214:217], v[74:77]
	v_mfma_f32_16x16x32_bf16 v[126:129], v[134:137], v[192:195], v[126:129]
	v_mfma_f32_16x16x32_bf16 v[122:125], v[142:145], v[192:195], v[122:125]
	v_mfma_f32_16x16x32_bf16 v[110:113], v[134:137], v[200:203], v[110:113]
	v_mfma_f32_16x16x32_bf16 v[106:109], v[142:145], v[200:203], v[106:109]
	v_mfma_f32_16x16x32_bf16 v[94:97], v[134:137], v[210:213], v[94:97]
	v_mfma_f32_16x16x32_bf16 v[90:93], v[142:145], v[210:213], v[90:93]
	v_mfma_f32_16x16x32_bf16 v[78:81], v[134:137], v[218:221], v[78:81]
	v_mfma_f32_16x16x32_bf16 v[74:77], v[142:145], v[218:221], v[74:77]
	v_mfma_f32_16x16x32_bf16 v[118:121], v[164:167], v[188:191], v[118:121]
	v_mfma_f32_16x16x32_bf16 v[114:117], v[180:183], v[188:191], v[114:117]
	v_mfma_f32_16x16x32_bf16 v[102:105], v[164:167], v[196:199], v[102:105]
	v_mfma_f32_16x16x32_bf16 v[98:101], v[180:183], v[196:199], v[98:101]
	v_mfma_f32_16x16x32_bf16 v[86:89], v[164:167], v[206:209], v[86:89]
	v_mfma_f32_16x16x32_bf16 v[82:85], v[180:183], v[206:209], v[82:85]
	v_mfma_f32_16x16x32_bf16 v[70:73], v[164:167], v[214:217], v[70:73]
	v_mfma_f32_16x16x32_bf16 v[66:69], v[180:183], v[214:217], v[66:69]
	v_mfma_f32_16x16x32_bf16 v[118:121], v[176:179], v[192:195], v[118:121]
	v_mfma_f32_16x16x32_bf16 v[114:117], v[184:187], v[192:195], v[114:117]
	v_mfma_f32_16x16x32_bf16 v[102:105], v[176:179], v[200:203], v[102:105]
	v_mfma_f32_16x16x32_bf16 v[98:101], v[184:187], v[200:203], v[98:101]
	v_mfma_f32_16x16x32_bf16 v[86:89], v[176:179], v[210:213], v[86:89]
	v_mfma_f32_16x16x32_bf16 v[82:85], v[184:187], v[210:213], v[82:85]
	v_mfma_f32_16x16x32_bf16 v[70:73], v[176:179], v[218:221], v[70:73]
	v_mfma_f32_16x16x32_bf16 v[66:69], v[184:187], v[218:221], v[66:69]
	s_setprio 0
	s_barrier
	ds_read_b128 v[188:191], v174 offset:49152
	ds_read_b128 v[192:195], v174 offset:50176
	ds_read_b128 v[196:199], v174 offset:51200
	ds_read_b128 v[200:203], v174 offset:52224
	ds_read_b128 v[206:209], v174 offset:53248
	ds_read_b128 v[210:213], v174 offset:54272
	ds_read_b128 v[214:217], v174 offset:55296
	ds_read_b128 v[218:221], v174 offset:56320
	s_add_i32 s25, s25, s70
	s_mov_b32 m0, s25
	v_lshl_add_u64 v[168:169], v[168:169], 0, s[36:37]
	global_load_lds_dwordx4 v[168:169], off
	s_add_i32 m0, s25, 0x2000
	s_add_u32 s28, s66, 0x40080
	v_lshl_add_u64 v[168:169], v[222:223], 0, s[36:37]
	s_addc_u32 s29, s67, 0
	s_add_i32 s25, s30, s70
	global_load_lds_dwordx4 v[168:169], off
	s_mov_b32 m0, s25
	v_lshl_add_u64 v[168:169], s[28:29], 0, v[150:151]
	global_load_lds_dwordx4 v[168:169], off
	s_add_i32 m0, s25, 0x2000
	v_lshl_add_u64 v[168:169], s[28:29], 0, v[146:147]
	global_load_lds_dwordx4 v[168:169], off
	s_mov_b32 m0, s79
	v_lshl_add_u64 v[168:169], v[224:225], 0, s[36:37]
	global_load_lds_dwordx4 v[168:169], off
	s_mov_b32 m0, s80
	v_lshl_add_u64 v[168:169], v[226:227], 0, s[36:37]
	global_load_lds_dwordx4 v[168:169], off
	s_waitcnt vmcnt(8) lgkmcnt(0)
	s_setprio 1
	s_barrier
	v_mfma_f32_16x16x32_bf16 v[62:65], v[130:133], v[188:191], v[62:65]
	v_mfma_f32_16x16x32_bf16 v[58:61], v[138:141], v[188:191], v[58:61]
	v_mfma_f32_16x16x32_bf16 v[46:49], v[130:133], v[196:199], v[46:49]
	v_mfma_f32_16x16x32_bf16 v[42:45], v[138:141], v[196:199], v[42:45]
	v_mfma_f32_16x16x32_bf16 v[30:33], v[130:133], v[206:209], v[30:33]
	v_mfma_f32_16x16x32_bf16 v[26:29], v[138:141], v[206:209], v[26:29]
	v_mfma_f32_16x16x32_bf16 v[14:17], v[130:133], v[214:217], v[14:17]
	v_mfma_f32_16x16x32_bf16 v[10:13], v[138:141], v[214:217], v[10:13]
	v_mfma_f32_16x16x32_bf16 v[62:65], v[134:137], v[192:195], v[62:65]
	v_mfma_f32_16x16x32_bf16 v[58:61], v[142:145], v[192:195], v[58:61]
	v_mfma_f32_16x16x32_bf16 v[46:49], v[134:137], v[200:203], v[46:49]
	v_mfma_f32_16x16x32_bf16 v[42:45], v[142:145], v[200:203], v[42:45]
	v_mfma_f32_16x16x32_bf16 v[30:33], v[134:137], v[210:213], v[30:33]
	v_mfma_f32_16x16x32_bf16 v[26:29], v[142:145], v[210:213], v[26:29]
	v_mfma_f32_16x16x32_bf16 v[14:17], v[134:137], v[218:221], v[14:17]
	v_mfma_f32_16x16x32_bf16 v[10:13], v[142:145], v[218:221], v[10:13]
	v_mfma_f32_16x16x32_bf16 v[54:57], v[164:167], v[188:191], v[54:57]
	v_mfma_f32_16x16x32_bf16 v[50:53], v[180:183], v[188:191], v[50:53]
	v_mfma_f32_16x16x32_bf16 v[38:41], v[164:167], v[196:199], v[38:41]
	v_mfma_f32_16x16x32_bf16 v[34:37], v[180:183], v[196:199], v[34:37]
	v_mfma_f32_16x16x32_bf16 v[22:25], v[164:167], v[206:209], v[22:25]
	v_mfma_f32_16x16x32_bf16 v[18:21], v[180:183], v[206:209], v[18:21]
	v_mfma_f32_16x16x32_bf16 v[6:9], v[164:167], v[214:217], v[6:9]
	v_mfma_f32_16x16x32_bf16 v[2:5], v[180:183], v[214:217], v[2:5]
	v_mfma_f32_16x16x32_bf16 v[54:57], v[176:179], v[192:195], v[54:57]
	v_mfma_f32_16x16x32_bf16 v[50:53], v[184:187], v[192:195], v[50:53]
	v_mfma_f32_16x16x32_bf16 v[38:41], v[176:179], v[200:203], v[38:41]
	v_mfma_f32_16x16x32_bf16 v[34:37], v[184:187], v[200:203], v[34:37]
	v_mfma_f32_16x16x32_bf16 v[22:25], v[176:179], v[210:213], v[22:25]
	v_mfma_f32_16x16x32_bf16 v[18:21], v[184:187], v[210:213], v[18:21]
	v_mfma_f32_16x16x32_bf16 v[6:9], v[176:179], v[218:221], v[6:9]
	v_mfma_f32_16x16x32_bf16 v[2:5], v[184:187], v[218:221], v[2:5]
	s_setprio 0
	s_barrier
	s_add_i32 s24, s24, 2
	s_add_u32 s64, s64, 0x100
	s_addc_u32 s65, s65, 0
	s_add_u32 s18, s18, 0x100
	s_addc_u32 s19, s19, 0
	s_cmp_gt_u32 s24, 13
.LBB0_1013:
	ds_read_b128 v[130:133], v172
	ds_read_b128 v[134:137], v172 offset:1024
	ds_read_b128 v[138:141], v172 offset:2048
	ds_read_b128 v[142:145], v172 offset:3072
	ds_read_b128 v[164:167], v173
	ds_read_b128 v[176:179], v173 offset:1024
	ds_read_b128 v[180:183], v173 offset:2048
	ds_read_b128 v[184:187], v173 offset:3072
	ds_read_b128 v[188:191], v174
	ds_read_b128 v[192:195], v174 offset:1024
	ds_read_b128 v[196:199], v174 offset:2048
	ds_read_b128 v[200:203], v174 offset:3072
	ds_read_b128 v[206:209], v174 offset:4096
	ds_read_b128 v[210:213], v174 offset:5120
	ds_read_b128 v[214:217], v174 offset:6144
	ds_read_b128 v[218:221], v174 offset:7168
	s_add_u32 s25, s64, 0xfffc0080
	s_addc_u32 s28, s65, -1
	s_cmp_eq_u32 s24, 12
	s_cselect_b32 s69, s6, s28
	s_cselect_b32 s68, s14, s25
	s_cselect_b32 s67, s15, s19
	s_cselect_b32 s66, s17, s18
	s_add_i32 m0, s73, 0xc000
	v_lshl_add_u64 v[168:169], s[64:65], 0, v[156:157]
	global_load_lds_dwordx4 v[168:169], off
	s_add_i32 m0, s73, 0xe000
	v_lshl_add_u64 v[168:169], s[64:65], 0, v[158:159]
	global_load_lds_dwordx4 v[168:169], off
	s_waitcnt vmcnt(8) lgkmcnt(0)
	s_setprio 1
	s_barrier
	v_mfma_f32_16x16x32_bf16 v[126:129], v[130:133], v[188:191], v[126:129]
	v_mfma_f32_16x16x32_bf16 v[122:125], v[138:141], v[188:191], v[122:125]
	v_mfma_f32_16x16x32_bf16 v[110:113], v[130:133], v[196:199], v[110:113]
	v_mfma_f32_16x16x32_bf16 v[106:109], v[138:141], v[196:199], v[106:109]
	v_mfma_f32_16x16x32_bf16 v[94:97], v[130:133], v[206:209], v[94:97]
	v_mfma_f32_16x16x32_bf16 v[90:93], v[138:141], v[206:209], v[90:93]
	v_mfma_f32_16x16x32_bf16 v[78:81], v[130:133], v[214:217], v[78:81]
	v_mfma_f32_16x16x32_bf16 v[74:77], v[138:141], v[214:217], v[74:77]
	v_mfma_f32_16x16x32_bf16 v[126:129], v[134:137], v[192:195], v[126:129]
	v_mfma_f32_16x16x32_bf16 v[122:125], v[142:145], v[192:195], v[122:125]
	v_mfma_f32_16x16x32_bf16 v[110:113], v[134:137], v[200:203], v[110:113]
	v_mfma_f32_16x16x32_bf16 v[106:109], v[142:145], v[200:203], v[106:109]
	v_mfma_f32_16x16x32_bf16 v[94:97], v[134:137], v[210:213], v[94:97]
	v_mfma_f32_16x16x32_bf16 v[90:93], v[142:145], v[210:213], v[90:93]
	v_mfma_f32_16x16x32_bf16 v[78:81], v[134:137], v[218:221], v[78:81]
	v_mfma_f32_16x16x32_bf16 v[74:77], v[142:145], v[218:221], v[74:77]
	v_mfma_f32_16x16x32_bf16 v[118:121], v[164:167], v[188:191], v[118:121]
	v_mfma_f32_16x16x32_bf16 v[114:117], v[180:183], v[188:191], v[114:117]
	v_mfma_f32_16x16x32_bf16 v[102:105], v[164:167], v[196:199], v[102:105]
	v_mfma_f32_16x16x32_bf16 v[98:101], v[180:183], v[196:199], v[98:101]
	v_mfma_f32_16x16x32_bf16 v[86:89], v[164:167], v[206:209], v[86:89]
	v_mfma_f32_16x16x32_bf16 v[82:85], v[180:183], v[206:209], v[82:85]
	v_mfma_f32_16x16x32_bf16 v[70:73], v[164:167], v[214:217], v[70:73]
	v_mfma_f32_16x16x32_bf16 v[66:69], v[180:183], v[214:217], v[66:69]
	v_mfma_f32_16x16x32_bf16 v[118:121], v[176:179], v[192:195], v[118:121]
	v_mfma_f32_16x16x32_bf16 v[114:117], v[184:187], v[192:195], v[114:117]
	v_mfma_f32_16x16x32_bf16 v[102:105], v[176:179], v[200:203], v[102:105]
	v_mfma_f32_16x16x32_bf16 v[98:101], v[184:187], v[200:203], v[98:101]
	v_mfma_f32_16x16x32_bf16 v[86:89], v[176:179], v[210:213], v[86:89]
	v_mfma_f32_16x16x32_bf16 v[82:85], v[184:187], v[210:213], v[82:85]
	v_mfma_f32_16x16x32_bf16 v[70:73], v[176:179], v[218:221], v[70:73]
	v_mfma_f32_16x16x32_bf16 v[66:69], v[184:187], v[218:221], v[66:69]
	s_setprio 0
	s_barrier
	ds_read_b128 v[188:191], v174 offset:16384
	ds_read_b128 v[192:195], v174 offset:17408
	ds_read_b128 v[196:199], v174 offset:18432
	ds_read_b128 v[200:203], v174 offset:19456
	ds_read_b128 v[206:209], v174 offset:20480
	ds_read_b128 v[210:213], v174 offset:21504
	ds_read_b128 v[214:217], v174 offset:22528
	ds_read_b128 v[218:221], v174 offset:23552
	s_add_i32 s25, s82, s70
	s_mov_b32 m0, s25
	v_lshl_add_u64 v[168:169], s[66:67], 0, v[150:151]
	global_load_lds_dwordx4 v[168:169], off
	s_add_i32 m0, s25, 0x2000
	s_add_u32 s28, s66, 0x40000
	v_lshl_add_u64 v[222:223], s[66:67], 0, v[146:147]
	s_addc_u32 s29, s67, 0
	s_add_i32 s25, s83, s70
	global_load_lds_dwordx4 v[222:223], off
	v_lshl_add_u64 v[224:225], s[28:29], 0, v[150:151]
	s_mov_b32 m0, s25
	v_lshl_add_u64 v[226:227], s[68:69], 0, v[148:149]
	global_load_lds_dwordx4 v[224:225], off
	s_add_i32 m0, s25, 0x2000
	v_lshl_add_u64 v[224:225], s[28:29], 0, v[146:147]
	global_load_lds_dwordx4 v[224:225], off
	s_mov_b32 m0, s73
	v_lshl_add_u64 v[224:225], s[68:69], 0, v[152:153]
	global_load_lds_dwordx4 v[224:225], off
	s_mov_b32 m0, s74
	s_nop 0
	global_load_lds_dwordx4 v[226:227], off
	s_waitcnt vmcnt(8) lgkmcnt(0)
	s_setprio 1
	s_barrier
	v_mfma_f32_16x16x32_bf16 v[62:65], v[130:133], v[188:191], v[62:65]
	v_mfma_f32_16x16x32_bf16 v[58:61], v[138:141], v[188:191], v[58:61]
	v_mfma_f32_16x16x32_bf16 v[46:49], v[130:133], v[196:199], v[46:49]
	v_mfma_f32_16x16x32_bf16 v[42:45], v[138:141], v[196:199], v[42:45]
	v_mfma_f32_16x16x32_bf16 v[30:33], v[130:133], v[206:209], v[30:33]
	v_mfma_f32_16x16x32_bf16 v[26:29], v[138:141], v[206:209], v[26:29]
	v_mfma_f32_16x16x32_bf16 v[14:17], v[130:133], v[214:217], v[14:17]
	v_mfma_f32_16x16x32_bf16 v[10:13], v[138:141], v[214:217], v[10:13]
	v_mfma_f32_16x16x32_bf16 v[62:65], v[134:137], v[192:195], v[62:65]
	v_mfma_f32_16x16x32_bf16 v[58:61], v[142:145], v[192:195], v[58:61]
	v_mfma_f32_16x16x32_bf16 v[46:49], v[134:137], v[200:203], v[46:49]
	v_mfma_f32_16x16x32_bf16 v[42:45], v[142:145], v[200:203], v[42:45]
	v_mfma_f32_16x16x32_bf16 v[30:33], v[134:137], v[210:213], v[30:33]
	v_mfma_f32_16x16x32_bf16 v[26:29], v[142:145], v[210:213], v[26:29]
	v_mfma_f32_16x16x32_bf16 v[14:17], v[134:137], v[218:221], v[14:17]
	v_mfma_f32_16x16x32_bf16 v[10:13], v[142:145], v[218:221], v[10:13]
	v_mfma_f32_16x16x32_bf16 v[54:57], v[164:167], v[188:191], v[54:57]
	v_mfma_f32_16x16x32_bf16 v[50:53], v[180:183], v[188:191], v[50:53]
	v_mfma_f32_16x16x32_bf16 v[38:41], v[164:167], v[196:199], v[38:41]
	v_mfma_f32_16x16x32_bf16 v[34:37], v[180:183], v[196:199], v[34:37]
	v_mfma_f32_16x16x32_bf16 v[22:25], v[164:167], v[206:209], v[22:25]
	v_mfma_f32_16x16x32_bf16 v[18:21], v[180:183], v[206:209], v[18:21]
	v_mfma_f32_16x16x32_bf16 v[6:9], v[164:167], v[214:217], v[6:9]
	v_mfma_f32_16x16x32_bf16 v[2:5], v[180:183], v[214:217], v[2:5]
	v_mfma_f32_16x16x32_bf16 v[54:57], v[176:179], v[192:195], v[54:57]
	v_mfma_f32_16x16x32_bf16 v[50:53], v[184:187], v[192:195], v[50:53]
	v_mfma_f32_16x16x32_bf16 v[38:41], v[176:179], v[200:203], v[38:41]
	v_mfma_f32_16x16x32_bf16 v[34:37], v[184:187], v[200:203], v[34:37]
	v_mfma_f32_16x16x32_bf16 v[22:25], v[176:179], v[210:213], v[22:25]
	v_mfma_f32_16x16x32_bf16 v[18:21], v[184:187], v[210:213], v[18:21]
	v_mfma_f32_16x16x32_bf16 v[6:9], v[176:179], v[218:221], v[6:9]
	v_mfma_f32_16x16x32_bf16 v[2:5], v[184:187], v[218:221], v[2:5]
	s_setprio 0
	s_barrier
	s_add_i32 s25, 0, 0x18000
	s_add_i32 s30, 0, 0x1c000
	v_add_u32_e32 v142, s25, v171
	v_add_u32_e32 v175, s30, v171
	ds_read_b128 v[130:133], v142
	ds_read_b128 v[134:137], v142 offset:1024
	ds_read_b128 v[138:141], v142 offset:2048
	ds_read_b128 v[142:145], v142 offset:3072
	ds_read_b128 v[164:167], v175
	ds_read_b128 v[176:179], v175 offset:1024
	ds_read_b128 v[180:183], v175 offset:2048
	ds_read_b128 v[184:187], v175 offset:3072
	s_add_u32 s28, s68, 0x40000
	s_addc_u32 s29, s69, 0
	s_mov_b32 m0, s75
	v_lshl_add_u64 v[228:229], s[28:29], 0, v[152:153]
	ds_read_b128 v[188:191], v174 offset:32768
	ds_read_b128 v[192:195], v174 offset:33792
	ds_read_b128 v[196:199], v174 offset:34816
	ds_read_b128 v[200:203], v174 offset:35840
	ds_read_b128 v[206:209], v174 offset:36864
	ds_read_b128 v[210:213], v174 offset:37888
	ds_read_b128 v[214:217], v174 offset:38912
	ds_read_b128 v[218:221], v174 offset:39936
	global_load_lds_dwordx4 v[228:229], off
	s_mov_b32 m0, s76
	v_lshl_add_u64 v[228:229], s[28:29], 0, v[148:149]
	global_load_lds_dwordx4 v[228:229], off
	s_waitcnt vmcnt(8) lgkmcnt(0)
	s_setprio 1
	s_barrier
	v_mfma_f32_16x16x32_bf16 v[126:129], v[130:133], v[188:191], v[126:129]
	v_mfma_f32_16x16x32_bf16 v[122:125], v[138:141], v[188:191], v[122:125]
	v_mfma_f32_16x16x32_bf16 v[110:113], v[130:133], v[196:199], v[110:113]
	v_mfma_f32_16x16x32_bf16 v[106:109], v[138:141], v[196:199], v[106:109]
	v_mfma_f32_16x16x32_bf16 v[94:97], v[130:133], v[206:209], v[94:97]
	v_mfma_f32_16x16x32_bf16 v[90:93], v[138:141], v[206:209], v[90:93]
	v_mfma_f32_16x16x32_bf16 v[78:81], v[130:133], v[214:217], v[78:81]
	v_mfma_f32_16x16x32_bf16 v[74:77], v[138:141], v[214:217], v[74:77]
	v_mfma_f32_16x16x32_bf16 v[126:129], v[134:137], v[192:195], v[126:129]
	v_mfma_f32_16x16x32_bf16 v[122:125], v[142:145], v[192:195], v[122:125]
	v_mfma_f32_16x16x32_bf16 v[110:113], v[134:137], v[200:203], v[110:113]
	v_mfma_f32_16x16x32_bf16 v[106:109], v[142:145], v[200:203], v[106:109]
	v_mfma_f32_16x16x32_bf16 v[94:97], v[134:137], v[210:213], v[94:97]
	v_mfma_f32_16x16x32_bf16 v[90:93], v[142:145], v[210:213], v[90:93]
	v_mfma_f32_16x16x32_bf16 v[78:81], v[134:137], v[218:221], v[78:81]
	v_mfma_f32_16x16x32_bf16 v[74:77], v[142:145], v[218:221], v[74:77]
	v_mfma_f32_16x16x32_bf16 v[118:121], v[164:167], v[188:191], v[118:121]
	v_mfma_f32_16x16x32_bf16 v[114:117], v[180:183], v[188:191], v[114:117]
	v_mfma_f32_16x16x32_bf16 v[102:105], v[164:167], v[196:199], v[102:105]
	v_mfma_f32_16x16x32_bf16 v[98:101], v[180:183], v[196:199], v[98:101]
	v_mfma_f32_16x16x32_bf16 v[86:89], v[164:167], v[206:209], v[86:89]
	v_mfma_f32_16x16x32_bf16 v[82:85], v[180:183], v[206:209], v[82:85]
	v_mfma_f32_16x16x32_bf16 v[70:73], v[164:167], v[214:217], v[70:73]
	v_mfma_f32_16x16x32_bf16 v[66:69], v[180:183], v[214:217], v[66:69]
	v_mfma_f32_16x16x32_bf16 v[118:121], v[176:179], v[192:195], v[118:121]
	v_mfma_f32_16x16x32_bf16 v[114:117], v[184:187], v[192:195], v[114:117]
	v_mfma_f32_16x16x32_bf16 v[102:105], v[176:179], v[200:203], v[102:105]
	v_mfma_f32_16x16x32_bf16 v[98:101], v[184:187], v[200:203], v[98:101]
	v_mfma_f32_16x16x32_bf16 v[86:89], v[176:179], v[210:213], v[86:89]
	v_mfma_f32_16x16x32_bf16 v[82:85], v[184:187], v[210:213], v[82:85]
	v_mfma_f32_16x16x32_bf16 v[70:73], v[176:179], v[218:221], v[70:73]
	v_mfma_f32_16x16x32_bf16 v[66:69], v[184:187], v[218:221], v[66:69]
	s_setprio 0
	s_barrier
	ds_read_b128 v[188:191], v174 offset:49152
	ds_read_b128 v[192:195], v174 offset:50176
	ds_read_b128 v[196:199], v174 offset:51200
	ds_read_b128 v[200:203], v174 offset:52224
	ds_read_b128 v[206:209], v174 offset:53248
	ds_read_b128 v[210:213], v174 offset:54272
	ds_read_b128 v[214:217], v174 offset:55296
	ds_read_b128 v[218:221], v174 offset:56320
	s_add_i32 s25, s25, s70
	s_mov_b32 m0, s25
	v_lshl_add_u64 v[168:169], v[168:169], 0, s[36:37]
	global_load_lds_dwordx4 v[168:169], off
	s_add_i32 m0, s25, 0x2000
	s_add_u32 s28, s66, 0x40080
	v_lshl_add_u64 v[168:169], v[222:223], 0, s[36:37]
	s_addc_u32 s29, s67, 0
	s_add_i32 s25, s30, s70
	global_load_lds_dwordx4 v[168:169], off
	s_mov_b32 m0, s25
	v_lshl_add_u64 v[168:169], s[28:29], 0, v[150:151]
	global_load_lds_dwordx4 v[168:169], off
	s_add_i32 m0, s25, 0x2000
	v_lshl_add_u64 v[168:169], s[28:29], 0, v[146:147]
	global_load_lds_dwordx4 v[168:169], off
	s_mov_b32 m0, s79
	v_lshl_add_u64 v[168:169], v[224:225], 0, s[36:37]
	global_load_lds_dwordx4 v[168:169], off
	s_mov_b32 m0, s80
	v_lshl_add_u64 v[168:169], v[226:227], 0, s[36:37]
	global_load_lds_dwordx4 v[168:169], off
	s_waitcnt vmcnt(8) lgkmcnt(0)
	s_setprio 1
	s_barrier
	v_mfma_f32_16x16x32_bf16 v[62:65], v[130:133], v[188:191], v[62:65]
	v_mfma_f32_16x16x32_bf16 v[58:61], v[138:141], v[188:191], v[58:61]
	v_mfma_f32_16x16x32_bf16 v[46:49], v[130:133], v[196:199], v[46:49]
	v_mfma_f32_16x16x32_bf16 v[42:45], v[138:141], v[196:199], v[42:45]
	v_mfma_f32_16x16x32_bf16 v[30:33], v[130:133], v[206:209], v[30:33]
	v_mfma_f32_16x16x32_bf16 v[26:29], v[138:141], v[206:209], v[26:29]
	v_mfma_f32_16x16x32_bf16 v[14:17], v[130:133], v[214:217], v[14:17]
	v_mfma_f32_16x16x32_bf16 v[10:13], v[138:141], v[214:217], v[10:13]
	v_mfma_f32_16x16x32_bf16 v[62:65], v[134:137], v[192:195], v[62:65]
	v_mfma_f32_16x16x32_bf16 v[58:61], v[142:145], v[192:195], v[58:61]
	v_mfma_f32_16x16x32_bf16 v[46:49], v[134:137], v[200:203], v[46:49]
	v_mfma_f32_16x16x32_bf16 v[42:45], v[142:145], v[200:203], v[42:45]
	v_mfma_f32_16x16x32_bf16 v[30:33], v[134:137], v[210:213], v[30:33]
	v_mfma_f32_16x16x32_bf16 v[26:29], v[142:145], v[210:213], v[26:29]
	v_mfma_f32_16x16x32_bf16 v[14:17], v[134:137], v[218:221], v[14:17]
	v_mfma_f32_16x16x32_bf16 v[10:13], v[142:145], v[218:221], v[10:13]
	v_mfma_f32_16x16x32_bf16 v[54:57], v[164:167], v[188:191], v[54:57]
	v_mfma_f32_16x16x32_bf16 v[50:53], v[180:183], v[188:191], v[50:53]
	v_mfma_f32_16x16x32_bf16 v[38:41], v[164:167], v[196:199], v[38:41]
	v_mfma_f32_16x16x32_bf16 v[34:37], v[180:183], v[196:199], v[34:37]
	v_mfma_f32_16x16x32_bf16 v[22:25], v[164:167], v[206:209], v[22:25]
	v_mfma_f32_16x16x32_bf16 v[18:21], v[180:183], v[206:209], v[18:21]
	v_mfma_f32_16x16x32_bf16 v[6:9], v[164:167], v[214:217], v[6:9]
	v_mfma_f32_16x16x32_bf16 v[2:5], v[180:183], v[214:217], v[2:5]
	v_mfma_f32_16x16x32_bf16 v[54:57], v[176:179], v[192:195], v[54:57]
	v_mfma_f32_16x16x32_bf16 v[50:53], v[184:187], v[192:195], v[50:53]
	v_mfma_f32_16x16x32_bf16 v[38:41], v[176:179], v[200:203], v[38:41]
	v_mfma_f32_16x16x32_bf16 v[34:37], v[184:187], v[200:203], v[34:37]
	v_mfma_f32_16x16x32_bf16 v[22:25], v[176:179], v[210:213], v[22:25]
	v_mfma_f32_16x16x32_bf16 v[18:21], v[184:187], v[210:213], v[18:21]
	v_mfma_f32_16x16x32_bf16 v[6:9], v[176:179], v[218:221], v[6:9]
	v_mfma_f32_16x16x32_bf16 v[2:5], v[184:187], v[218:221], v[2:5]
	s_setprio 0
	s_barrier
	s_add_i32 s24, s24, 2
	s_add_u32 s64, s64, 0x100
	s_addc_u32 s65, s65, 0
	s_add_u32 s18, s18, 0x100
	s_addc_u32 s19, s19, 0
	s_cmp_gt_u32 s24, 13
	s_cbranch_scc0 .LBB0_1013
	s_and_b64 vcc, exec, s[38:39]
	s_cbranch_vccz .LBB0_1016
	s_barrier

.LBB0_1427:
	s_add_u32 s90, s35, s86
	s_addc_u32 s91, s64, s87
	s_and_b64 s[14:15], s[88:89], exec
	s_cselect_b32 s14, s91, s11
	s_cselect_b32 s15, s90, s10
	s_add_u32 s92, s65, s74
	s_addc_u32 s93, s68, s75
	s_and_b64 s[66:67], s[88:89], exec
	s_cselect_b32 s51, s93, s95
	s_cselect_b32 s84, s92, s94
	s_add_i32 s85, s18, -2
	s_add_u32 s10, s10, 0x40080
	s_addc_u32 s11, s11, 0
	s_add_u32 vcc_lo, s94, 0x100
	s_addc_u32 vcc_hi, s95, 0
	s_mov_b32 s94, 0
	s_waitcnt vmcnt(0)
	s_add_i32 s66, s94, 2
	s_add_u32 s67, s10, 0xfffc0080
	s_addc_u32 s72, s11, -1
	s_cmp_eq_u32 s85, s94
	s_cselect_b32 s97, s14, s72
	s_cselect_b32 s96, s15, s67
	s_cselect_b32 s95, s51, vcc_hi
	s_cselect_b32 s94, s84, vcc_lo
	s_add_i32 s67, 0, 0x10000
	s_add_i32 s62, 0, 0x14000
	v_add_u32_e32 v126, s67, v199
	v_add_u32_e32 v158, s62, v199
	ds_read_b128 v[114:117], v126
	ds_read_b128 v[118:121], v126 offset:1024
	ds_read_b128 v[122:125], v126 offset:2048
	ds_read_b128 v[126:129], v126 offset:3072
	ds_read_b128 v[146:149], v158
	ds_read_b128 v[150:153], v158 offset:1024
	ds_read_b128 v[154:157], v158 offset:2048
	ds_read_b128 v[158:161], v158 offset:3072
	v_lshl_add_u64 v[202:203], s[10:11], 0, v[196:197]
	s_add_i32 m0, s28, 0xc000
	ds_read_b128 v[162:165], v214
	ds_read_b128 v[166:169], v214 offset:1024
	ds_read_b128 v[216:219], v214 offset:2048
	ds_read_b128 v[220:223], v214 offset:3072
	ds_read_b128 v[224:227], v214 offset:4096
	ds_read_b128 v[228:231], v214 offset:5120
	ds_read_b128 v[232:235], v214 offset:6144
	ds_read_b128 v[236:239], v214 offset:7168
	global_load_lds_dwordx4 v[202:203], off
	s_add_i32 m0, s28, 0xe000
	v_lshl_add_u64 v[202:203], s[10:11], 0, v[176:177]
	global_load_lds_dwordx4 v[202:203], off
	s_waitcnt vmcnt(8) lgkmcnt(0)
	s_setprio 1
	s_barrier
	v_mfma_f32_16x16x32_bf16 v[142:145], v[114:117], v[162:165], 0
	v_mfma_f32_16x16x32_bf16 v[138:141], v[122:125], v[162:165], 0
	v_mfma_f32_16x16x32_bf16 v[110:113], v[114:117], v[216:219], 0
	v_mfma_f32_16x16x32_bf16 v[106:109], v[122:125], v[216:219], 0
	v_mfma_f32_16x16x32_bf16 v[98:101], v[114:117], v[224:227], 0
	v_mfma_f32_16x16x32_bf16 v[90:93], v[122:125], v[224:227], 0
	v_mfma_f32_16x16x32_bf16 v[82:85], v[114:117], v[232:235], 0
	v_mfma_f32_16x16x32_bf16 v[74:77], v[122:125], v[232:235], 0
	v_mfma_f32_16x16x32_bf16 v[142:145], v[118:121], v[166:169], v[142:145]
	v_mfma_f32_16x16x32_bf16 v[138:141], v[126:129], v[166:169], v[138:141]
	v_mfma_f32_16x16x32_bf16 v[110:113], v[118:121], v[220:223], v[110:113]
	v_mfma_f32_16x16x32_bf16 v[106:109], v[126:129], v[220:223], v[106:109]
	v_mfma_f32_16x16x32_bf16 v[98:101], v[118:121], v[228:231], v[98:101]
	v_mfma_f32_16x16x32_bf16 v[90:93], v[126:129], v[228:231], v[90:93]
	v_mfma_f32_16x16x32_bf16 v[82:85], v[118:121], v[236:239], v[82:85]
	v_mfma_f32_16x16x32_bf16 v[74:77], v[126:129], v[236:239], v[74:77]
	v_mfma_f32_16x16x32_bf16 v[134:137], v[146:149], v[162:165], 0
	v_mfma_f32_16x16x32_bf16 v[130:133], v[154:157], v[162:165], 0
	v_mfma_f32_16x16x32_bf16 v[102:105], v[146:149], v[216:219], 0
	v_mfma_f32_16x16x32_bf16 v[94:97], v[154:157], v[216:219], 0
	v_mfma_f32_16x16x32_bf16 v[86:89], v[146:149], v[224:227], 0
	v_mfma_f32_16x16x32_bf16 v[78:81], v[154:157], v[224:227], 0
	v_mfma_f32_16x16x32_bf16 v[70:73], v[146:149], v[232:235], 0
	v_mfma_f32_16x16x32_bf16 v[66:69], v[154:157], v[232:235], 0
	v_mfma_f32_16x16x32_bf16 v[134:137], v[150:153], v[166:169], v[134:137]
	v_mfma_f32_16x16x32_bf16 v[130:133], v[158:161], v[166:169], v[130:133]
	v_mfma_f32_16x16x32_bf16 v[102:105], v[150:153], v[220:223], v[102:105]
	v_mfma_f32_16x16x32_bf16 v[94:97], v[158:161], v[220:223], v[94:97]
	v_mfma_f32_16x16x32_bf16 v[86:89], v[150:153], v[228:231], v[86:89]
	v_mfma_f32_16x16x32_bf16 v[78:81], v[158:161], v[228:231], v[78:81]
	v_mfma_f32_16x16x32_bf16 v[70:73], v[150:153], v[236:239], v[70:73]
	v_mfma_f32_16x16x32_bf16 v[66:69], v[158:161], v[236:239], v[66:69]
	s_setprio 0
	s_barrier
	ds_read_b128 v[162:165], v214 offset:16384
	ds_read_b128 v[166:169], v214 offset:17408
	ds_read_b128 v[216:219], v214 offset:18432
	ds_read_b128 v[220:223], v214 offset:19456
	ds_read_b128 v[224:227], v214 offset:20480
	ds_read_b128 v[228:231], v214 offset:21504
	ds_read_b128 v[232:235], v214 offset:22528
	ds_read_b128 v[236:239], v214 offset:23552
	s_add_i32 s63, s67, s17
	s_mov_b32 m0, s63
	v_lshl_add_u64 v[202:203], s[94:95], 0, v[174:175]
	global_load_lds_dwordx4 v[202:203], off
	s_add_i32 m0, s63, 0x2000
	s_add_u32 s72, s94, 0x40000
	v_lshl_add_u64 v[240:241], s[94:95], 0, v[178:179]
	s_addc_u32 s73, s95, 0
	s_add_i32 s62, s62, s17
	global_load_lds_dwordx4 v[240:241], off
	v_lshl_add_u64 v[242:243], s[72:73], 0, v[174:175]
	s_mov_b32 m0, s62
	v_lshl_add_u64 v[244:245], s[96:97], 0, v[176:177]
	global_load_lds_dwordx4 v[242:243], off
	s_add_i32 m0, s62, 0x2000
	v_lshl_add_u64 v[242:243], s[72:73], 0, v[178:179]
	global_load_lds_dwordx4 v[242:243], off
	s_mov_b32 m0, s28
	v_lshl_add_u64 v[242:243], s[96:97], 0, v[172:173]
	global_load_lds_dwordx4 v[242:243], off
	s_mov_b32 m0, s29
	s_nop 0
	global_load_lds_dwordx4 v[244:245], off
	s_waitcnt vmcnt(8) lgkmcnt(0)
	s_setprio 1
	s_barrier
	v_mfma_f32_16x16x32_bf16 v[62:65], v[114:117], v[162:165], 0
	v_mfma_f32_16x16x32_bf16 v[58:61], v[122:125], v[162:165], 0
	v_mfma_f32_16x16x32_bf16 v[50:53], v[114:117], v[216:219], 0
	v_mfma_f32_16x16x32_bf16 v[42:45], v[122:125], v[216:219], 0
	v_mfma_f32_16x16x32_bf16 v[34:37], v[114:117], v[224:227], 0
	v_mfma_f32_16x16x32_bf16 v[26:29], v[122:125], v[224:227], 0
	v_mfma_f32_16x16x32_bf16 v[18:21], v[114:117], v[232:235], 0
	v_mfma_f32_16x16x32_bf16 v[10:13], v[122:125], v[232:235], 0
	v_mfma_f32_16x16x32_bf16 v[62:65], v[118:121], v[166:169], v[62:65]
	v_mfma_f32_16x16x32_bf16 v[58:61], v[126:129], v[166:169], v[58:61]
	v_mfma_f32_16x16x32_bf16 v[50:53], v[118:121], v[220:223], v[50:53]
	v_mfma_f32_16x16x32_bf16 v[42:45], v[126:129], v[220:223], v[42:45]
	v_mfma_f32_16x16x32_bf16 v[34:37], v[118:121], v[228:231], v[34:37]
	v_mfma_f32_16x16x32_bf16 v[26:29], v[126:129], v[228:231], v[26:29]
	v_mfma_f32_16x16x32_bf16 v[18:21], v[118:121], v[236:239], v[18:21]
	v_mfma_f32_16x16x32_bf16 v[10:13], v[126:129], v[236:239], v[10:13]
	v_mfma_f32_16x16x32_bf16 v[54:57], v[146:149], v[162:165], 0
	v_mfma_f32_16x16x32_bf16 v[46:49], v[154:157], v[162:165], 0
	v_mfma_f32_16x16x32_bf16 v[38:41], v[146:149], v[216:219], 0
	v_mfma_f32_16x16x32_bf16 v[30:33], v[154:157], v[216:219], 0
	v_mfma_f32_16x16x32_bf16 v[22:25], v[146:149], v[224:227], 0
	v_mfma_f32_16x16x32_bf16 v[14:17], v[154:157], v[224:227], 0
	v_mfma_f32_16x16x32_bf16 v[6:9], v[146:149], v[232:235], 0
	v_mfma_f32_16x16x32_bf16 v[2:5], v[154:157], v[232:235], 0
	v_mfma_f32_16x16x32_bf16 v[54:57], v[150:153], v[166:169], v[54:57]
	v_mfma_f32_16x16x32_bf16 v[46:49], v[158:161], v[166:169], v[46:49]
	v_mfma_f32_16x16x32_bf16 v[38:41], v[150:153], v[220:223], v[38:41]
	v_mfma_f32_16x16x32_bf16 v[30:33], v[158:161], v[220:223], v[30:33]
	v_mfma_f32_16x16x32_bf16 v[22:25], v[150:153], v[228:231], v[22:25]
	v_mfma_f32_16x16x32_bf16 v[14:17], v[158:161], v[228:231], v[14:17]
	v_mfma_f32_16x16x32_bf16 v[6:9], v[150:153], v[236:239], v[6:9]
	v_mfma_f32_16x16x32_bf16 v[2:5], v[158:161], v[236:239], v[2:5]
	s_setprio 0
	s_barrier
	s_add_i32 s62, 0, 0x18000
	s_add_i32 s63, 0, 0x1c000
	v_add_u32_e32 v126, s62, v199
	v_add_u32_e32 v158, s63, v199
	ds_read_b128 v[114:117], v126
	ds_read_b128 v[118:121], v126 offset:1024
	ds_read_b128 v[122:125], v126 offset:2048
	ds_read_b128 v[126:129], v126 offset:3072
	ds_read_b128 v[146:149], v158
	ds_read_b128 v[150:153], v158 offset:1024
	ds_read_b128 v[154:157], v158 offset:2048
	ds_read_b128 v[158:161], v158 offset:3072
	s_add_u32 s72, s96, 0x40000
	s_addc_u32 s73, s97, 0
	s_mov_b32 m0, s30
	v_lshl_add_u64 v[246:247], s[72:73], 0, v[172:173]
	ds_read_b128 v[162:165], v214 offset:32768
	ds_read_b128 v[166:169], v214 offset:33792
	ds_read_b128 v[216:219], v214 offset:34816
	ds_read_b128 v[220:223], v214 offset:35840
	ds_read_b128 v[224:227], v214 offset:36864
	ds_read_b128 v[228:231], v214 offset:37888
	ds_read_b128 v[232:235], v214 offset:38912
	ds_read_b128 v[236:239], v214 offset:39936
	global_load_lds_dwordx4 v[246:247], off
	s_mov_b32 m0, s31
	v_lshl_add_u64 v[246:247], s[72:73], 0, v[176:177]
	global_load_lds_dwordx4 v[246:247], off
	s_waitcnt vmcnt(8) lgkmcnt(0)
	s_setprio 1
	s_barrier
	v_mfma_f32_16x16x32_bf16 v[142:145], v[114:117], v[162:165], v[142:145]
	v_mfma_f32_16x16x32_bf16 v[138:141], v[122:125], v[162:165], v[138:141]
	v_mfma_f32_16x16x32_bf16 v[110:113], v[114:117], v[216:219], v[110:113]
	v_mfma_f32_16x16x32_bf16 v[106:109], v[122:125], v[216:219], v[106:109]
	v_mfma_f32_16x16x32_bf16 v[98:101], v[114:117], v[224:227], v[98:101]
	v_mfma_f32_16x16x32_bf16 v[90:93], v[122:125], v[224:227], v[90:93]
	v_mfma_f32_16x16x32_bf16 v[82:85], v[114:117], v[232:235], v[82:85]
	v_mfma_f32_16x16x32_bf16 v[74:77], v[122:125], v[232:235], v[74:77]
	v_mfma_f32_16x16x32_bf16 v[142:145], v[118:121], v[166:169], v[142:145]
	v_mfma_f32_16x16x32_bf16 v[138:141], v[126:129], v[166:169], v[138:141]
	v_mfma_f32_16x16x32_bf16 v[110:113], v[118:121], v[220:223], v[110:113]
	v_mfma_f32_16x16x32_bf16 v[106:109], v[126:129], v[220:223], v[106:109]
	v_mfma_f32_16x16x32_bf16 v[98:101], v[118:121], v[228:231], v[98:101]
	v_mfma_f32_16x16x32_bf16 v[90:93], v[126:129], v[228:231], v[90:93]
	v_mfma_f32_16x16x32_bf16 v[82:85], v[118:121], v[236:239], v[82:85]
	v_mfma_f32_16x16x32_bf16 v[74:77], v[126:129], v[236:239], v[74:77]
	v_mfma_f32_16x16x32_bf16 v[134:137], v[146:149], v[162:165], v[134:137]
	v_mfma_f32_16x16x32_bf16 v[130:133], v[154:157], v[162:165], v[130:133]
	v_mfma_f32_16x16x32_bf16 v[102:105], v[146:149], v[216:219], v[102:105]
	v_mfma_f32_16x16x32_bf16 v[94:97], v[154:157], v[216:219], v[94:97]
	v_mfma_f32_16x16x32_bf16 v[86:89], v[146:149], v[224:227], v[86:89]
	v_mfma_f32_16x16x32_bf16 v[78:81], v[154:157], v[224:227], v[78:81]
	v_mfma_f32_16x16x32_bf16 v[70:73], v[146:149], v[232:235], v[70:73]
	v_mfma_f32_16x16x32_bf16 v[66:69], v[154:157], v[232:235], v[66:69]
	v_mfma_f32_16x16x32_bf16 v[134:137], v[150:153], v[166:169], v[134:137]
	v_mfma_f32_16x16x32_bf16 v[130:133], v[158:161], v[166:169], v[130:133]
	v_mfma_f32_16x16x32_bf16 v[102:105], v[150:153], v[220:223], v[102:105]
	v_mfma_f32_16x16x32_bf16 v[94:97], v[158:161], v[220:223], v[94:97]
	v_mfma_f32_16x16x32_bf16 v[86:89], v[150:153], v[228:231], v[86:89]
	v_mfma_f32_16x16x32_bf16 v[78:81], v[158:161], v[228:231], v[78:81]
	v_mfma_f32_16x16x32_bf16 v[70:73], v[150:153], v[236:239], v[70:73]
	v_mfma_f32_16x16x32_bf16 v[66:69], v[158:161], v[236:239], v[66:69]
	s_setprio 0
	s_barrier
	ds_read_b128 v[162:165], v214 offset:49152
	ds_read_b128 v[166:169], v214 offset:50176
	ds_read_b128 v[216:219], v214 offset:51200
	ds_read_b128 v[220:223], v214 offset:52224
	ds_read_b128 v[224:227], v214 offset:53248
	ds_read_b128 v[228:231], v214 offset:54272
	ds_read_b128 v[232:235], v214 offset:55296
	ds_read_b128 v[236:239], v214 offset:56320
	s_add_i32 s62, s62, s17
	s_mov_b32 m0, s62
	v_lshl_add_u64 v[202:203], v[202:203], 0, s[76:77]
	global_load_lds_dwordx4 v[202:203], off
	s_add_i32 m0, s62, 0x2000
	s_add_u32 s72, s94, 0x40080
	v_lshl_add_u64 v[202:203], v[240:241], 0, s[76:77]
	s_addc_u32 s73, s95, 0
	s_add_i32 s62, s63, s17
	global_load_lds_dwordx4 v[202:203], off
	s_mov_b32 m0, s62
	v_lshl_add_u64 v[202:203], s[72:73], 0, v[174:175]
	global_load_lds_dwordx4 v[202:203], off
	s_add_i32 m0, s62, 0x2000
	v_lshl_add_u64 v[202:203], s[72:73], 0, v[178:179]
	global_load_lds_dwordx4 v[202:203], off
	s_mov_b32 m0, s44
	v_lshl_add_u64 v[202:203], v[242:243], 0, s[76:77]
	global_load_lds_dwordx4 v[202:203], off
	s_mov_b32 m0, s36
	v_lshl_add_u64 v[202:203], v[244:245], 0, s[76:77]
	global_load_lds_dwordx4 v[202:203], off
	s_waitcnt vmcnt(8) lgkmcnt(0)
	s_setprio 1
	s_barrier
	v_mfma_f32_16x16x32_bf16 v[62:65], v[114:117], v[162:165], v[62:65]
	v_mfma_f32_16x16x32_bf16 v[58:61], v[122:125], v[162:165], v[58:61]
	v_mfma_f32_16x16x32_bf16 v[50:53], v[114:117], v[216:219], v[50:53]
	v_mfma_f32_16x16x32_bf16 v[42:45], v[122:125], v[216:219], v[42:45]
	v_mfma_f32_16x16x32_bf16 v[34:37], v[114:117], v[224:227], v[34:37]
	v_mfma_f32_16x16x32_bf16 v[26:29], v[122:125], v[224:227], v[26:29]
	v_mfma_f32_16x16x32_bf16 v[18:21], v[114:117], v[232:235], v[18:21]
	v_mfma_f32_16x16x32_bf16 v[10:13], v[122:125], v[232:235], v[10:13]
	v_mfma_f32_16x16x32_bf16 v[62:65], v[118:121], v[166:169], v[62:65]
	v_mfma_f32_16x16x32_bf16 v[58:61], v[126:129], v[166:169], v[58:61]
	v_mfma_f32_16x16x32_bf16 v[50:53], v[118:121], v[220:223], v[50:53]
	v_mfma_f32_16x16x32_bf16 v[42:45], v[126:129], v[220:223], v[42:45]
	v_mfma_f32_16x16x32_bf16 v[34:37], v[118:121], v[228:231], v[34:37]
	v_mfma_f32_16x16x32_bf16 v[26:29], v[126:129], v[228:231], v[26:29]
	v_mfma_f32_16x16x32_bf16 v[18:21], v[118:121], v[236:239], v[18:21]
	v_mfma_f32_16x16x32_bf16 v[10:13], v[126:129], v[236:239], v[10:13]
	v_mfma_f32_16x16x32_bf16 v[54:57], v[146:149], v[162:165], v[54:57]
	v_mfma_f32_16x16x32_bf16 v[46:49], v[154:157], v[162:165], v[46:49]
	v_mfma_f32_16x16x32_bf16 v[38:41], v[146:149], v[216:219], v[38:41]
	v_mfma_f32_16x16x32_bf16 v[30:33], v[154:157], v[216:219], v[30:33]
	v_mfma_f32_16x16x32_bf16 v[22:25], v[146:149], v[224:227], v[22:25]
	v_mfma_f32_16x16x32_bf16 v[14:17], v[154:157], v[224:227], v[14:17]
	v_mfma_f32_16x16x32_bf16 v[6:9], v[146:149], v[232:235], v[6:9]
	v_mfma_f32_16x16x32_bf16 v[2:5], v[154:157], v[232:235], v[2:5]
	v_mfma_f32_16x16x32_bf16 v[54:57], v[150:153], v[166:169], v[54:57]
	v_mfma_f32_16x16x32_bf16 v[46:49], v[158:161], v[166:169], v[46:49]
	v_mfma_f32_16x16x32_bf16 v[38:41], v[150:153], v[220:223], v[38:41]
	v_mfma_f32_16x16x32_bf16 v[30:33], v[158:161], v[220:223], v[30:33]
	v_mfma_f32_16x16x32_bf16 v[22:25], v[150:153], v[228:231], v[22:25]
	v_mfma_f32_16x16x32_bf16 v[14:17], v[158:161], v[228:231], v[14:17]
	v_mfma_f32_16x16x32_bf16 v[6:9], v[150:153], v[236:239], v[6:9]
	v_mfma_f32_16x16x32_bf16 v[2:5], v[158:161], v[236:239], v[2:5]
	s_setprio 0
	s_barrier
	s_add_u32 s10, s10, 0x100
	s_addc_u32 s11, s11, 0
	s_add_u32 vcc_lo, vcc_lo, 0x100
	s_addc_u32 vcc_hi, vcc_hi, 0
	s_cmp_ge_i32 s66, s18
	s_mov_b32 s94, s66
.LBB0_1428:
	s_add_i32 s66, s94, 2
	s_add_u32 s67, s10, 0xfffc0080
	s_addc_u32 s72, s11, -1
	s_cmp_eq_u32 s85, s94
	s_cselect_b32 s97, s14, s72
	s_cselect_b32 s96, s15, s67
	s_cselect_b32 s95, s51, vcc_hi
	s_cselect_b32 s94, s84, vcc_lo
	s_add_i32 s67, 0, 0x10000
	s_add_i32 s62, 0, 0x14000
	v_add_u32_e32 v126, s67, v199
	v_add_u32_e32 v158, s62, v199
	ds_read_b128 v[114:117], v126
	ds_read_b128 v[118:121], v126 offset:1024
	ds_read_b128 v[122:125], v126 offset:2048
	ds_read_b128 v[126:129], v126 offset:3072
	ds_read_b128 v[146:149], v158
	ds_read_b128 v[150:153], v158 offset:1024
	ds_read_b128 v[154:157], v158 offset:2048
	ds_read_b128 v[158:161], v158 offset:3072
	v_lshl_add_u64 v[202:203], s[10:11], 0, v[196:197]
	s_add_i32 m0, s28, 0xc000
	ds_read_b128 v[162:165], v214
	ds_read_b128 v[166:169], v214 offset:1024
	ds_read_b128 v[216:219], v214 offset:2048
	ds_read_b128 v[220:223], v214 offset:3072
	ds_read_b128 v[224:227], v214 offset:4096
	ds_read_b128 v[228:231], v214 offset:5120
	ds_read_b128 v[232:235], v214 offset:6144
	ds_read_b128 v[236:239], v214 offset:7168
	global_load_lds_dwordx4 v[202:203], off
	s_add_i32 m0, s28, 0xe000
	v_lshl_add_u64 v[202:203], s[10:11], 0, v[176:177]
	global_load_lds_dwordx4 v[202:203], off
	s_waitcnt vmcnt(8) lgkmcnt(0)
	s_setprio 1
	s_barrier
	v_mfma_f32_16x16x32_bf16 v[142:145], v[114:117], v[162:165], v[142:145]
	v_mfma_f32_16x16x32_bf16 v[138:141], v[122:125], v[162:165], v[138:141]
	v_mfma_f32_16x16x32_bf16 v[110:113], v[114:117], v[216:219], v[110:113]
	v_mfma_f32_16x16x32_bf16 v[106:109], v[122:125], v[216:219], v[106:109]
	v_mfma_f32_16x16x32_bf16 v[98:101], v[114:117], v[224:227], v[98:101]
	v_mfma_f32_16x16x32_bf16 v[90:93], v[122:125], v[224:227], v[90:93]
	v_mfma_f32_16x16x32_bf16 v[82:85], v[114:117], v[232:235], v[82:85]
	v_mfma_f32_16x16x32_bf16 v[74:77], v[122:125], v[232:235], v[74:77]
	v_mfma_f32_16x16x32_bf16 v[142:145], v[118:121], v[166:169], v[142:145]
	v_mfma_f32_16x16x32_bf16 v[138:141], v[126:129], v[166:169], v[138:141]
	v_mfma_f32_16x16x32_bf16 v[110:113], v[118:121], v[220:223], v[110:113]
	v_mfma_f32_16x16x32_bf16 v[106:109], v[126:129], v[220:223], v[106:109]
	v_mfma_f32_16x16x32_bf16 v[98:101], v[118:121], v[228:231], v[98:101]
	v_mfma_f32_16x16x32_bf16 v[90:93], v[126:129], v[228:231], v[90:93]
	v_mfma_f32_16x16x32_bf16 v[82:85], v[118:121], v[236:239], v[82:85]
	v_mfma_f32_16x16x32_bf16 v[74:77], v[126:129], v[236:239], v[74:77]
	v_mfma_f32_16x16x32_bf16 v[134:137], v[146:149], v[162:165], v[134:137]
	v_mfma_f32_16x16x32_bf16 v[130:133], v[154:157], v[162:165], v[130:133]
	v_mfma_f32_16x16x32_bf16 v[102:105], v[146:149], v[216:219], v[102:105]
	v_mfma_f32_16x16x32_bf16 v[94:97], v[154:157], v[216:219], v[94:97]
	v_mfma_f32_16x16x32_bf16 v[86:89], v[146:149], v[224:227], v[86:89]
	v_mfma_f32_16x16x32_bf16 v[78:81], v[154:157], v[224:227], v[78:81]
	v_mfma_f32_16x16x32_bf16 v[70:73], v[146:149], v[232:235], v[70:73]
	v_mfma_f32_16x16x32_bf16 v[66:69], v[154:157], v[232:235], v[66:69]
	v_mfma_f32_16x16x32_bf16 v[134:137], v[150:153], v[166:169], v[134:137]
	v_mfma_f32_16x16x32_bf16 v[130:133], v[158:161], v[166:169], v[130:133]
	v_mfma_f32_16x16x32_bf16 v[102:105], v[150:153], v[220:223], v[102:105]
	v_mfma_f32_16x16x32_bf16 v[94:97], v[158:161], v[220:223], v[94:97]
	v_mfma_f32_16x16x32_bf16 v[86:89], v[150:153], v[228:231], v[86:89]
	v_mfma_f32_16x16x32_bf16 v[78:81], v[158:161], v[228:231], v[78:81]
	v_mfma_f32_16x16x32_bf16 v[70:73], v[150:153], v[236:239], v[70:73]
	v_mfma_f32_16x16x32_bf16 v[66:69], v[158:161], v[236:239], v[66:69]
	s_setprio 0
	s_barrier
	ds_read_b128 v[162:165], v214 offset:16384
	ds_read_b128 v[166:169], v214 offset:17408
	ds_read_b128 v[216:219], v214 offset:18432
	ds_read_b128 v[220:223], v214 offset:19456
	ds_read_b128 v[224:227], v214 offset:20480
	ds_read_b128 v[228:231], v214 offset:21504
	ds_read_b128 v[232:235], v214 offset:22528
	ds_read_b128 v[236:239], v214 offset:23552
	s_add_i32 s63, s67, s17
	s_mov_b32 m0, s63
	v_lshl_add_u64 v[202:203], s[94:95], 0, v[174:175]
	global_load_lds_dwordx4 v[202:203], off
	s_add_i32 m0, s63, 0x2000
	s_add_u32 s72, s94, 0x40000
	v_lshl_add_u64 v[240:241], s[94:95], 0, v[178:179]
	s_addc_u32 s73, s95, 0
	s_add_i32 s62, s62, s17
	global_load_lds_dwordx4 v[240:241], off
	v_lshl_add_u64 v[242:243], s[72:73], 0, v[174:175]
	s_mov_b32 m0, s62
	v_lshl_add_u64 v[244:245], s[96:97], 0, v[176:177]
	global_load_lds_dwordx4 v[242:243], off
	s_add_i32 m0, s62, 0x2000
	v_lshl_add_u64 v[242:243], s[72:73], 0, v[178:179]
	global_load_lds_dwordx4 v[242:243], off
	s_mov_b32 m0, s28
	v_lshl_add_u64 v[242:243], s[96:97], 0, v[172:173]
	global_load_lds_dwordx4 v[242:243], off
	s_mov_b32 m0, s29
	s_nop 0
	global_load_lds_dwordx4 v[244:245], off
	s_waitcnt vmcnt(8) lgkmcnt(0)
	s_setprio 1
	s_barrier
	v_mfma_f32_16x16x32_bf16 v[62:65], v[114:117], v[162:165], v[62:65]
	v_mfma_f32_16x16x32_bf16 v[58:61], v[122:125], v[162:165], v[58:61]
	v_mfma_f32_16x16x32_bf16 v[50:53], v[114:117], v[216:219], v[50:53]
	v_mfma_f32_16x16x32_bf16 v[42:45], v[122:125], v[216:219], v[42:45]
	v_mfma_f32_16x16x32_bf16 v[34:37], v[114:117], v[224:227], v[34:37]
	v_mfma_f32_16x16x32_bf16 v[26:29], v[122:125], v[224:227], v[26:29]
	v_mfma_f32_16x16x32_bf16 v[18:21], v[114:117], v[232:235], v[18:21]
	v_mfma_f32_16x16x32_bf16 v[10:13], v[122:125], v[232:235], v[10:13]
	v_mfma_f32_16x16x32_bf16 v[62:65], v[118:121], v[166:169], v[62:65]
	v_mfma_f32_16x16x32_bf16 v[58:61], v[126:129], v[166:169], v[58:61]
	v_mfma_f32_16x16x32_bf16 v[50:53], v[118:121], v[220:223], v[50:53]
	v_mfma_f32_16x16x32_bf16 v[42:45], v[126:129], v[220:223], v[42:45]
	v_mfma_f32_16x16x32_bf16 v[34:37], v[118:121], v[228:231], v[34:37]
	v_mfma_f32_16x16x32_bf16 v[26:29], v[126:129], v[228:231], v[26:29]
	v_mfma_f32_16x16x32_bf16 v[18:21], v[118:121], v[236:239], v[18:21]
	v_mfma_f32_16x16x32_bf16 v[10:13], v[126:129], v[236:239], v[10:13]
	v_mfma_f32_16x16x32_bf16 v[54:57], v[146:149], v[162:165], v[54:57]
	v_mfma_f32_16x16x32_bf16 v[46:49], v[154:157], v[162:165], v[46:49]
	v_mfma_f32_16x16x32_bf16 v[38:41], v[146:149], v[216:219], v[38:41]
	v_mfma_f32_16x16x32_bf16 v[30:33], v[154:157], v[216:219], v[30:33]
	v_mfma_f32_16x16x32_bf16 v[22:25], v[146:149], v[224:227], v[22:25]
	v_mfma_f32_16x16x32_bf16 v[14:17], v[154:157], v[224:227], v[14:17]
	v_mfma_f32_16x16x32_bf16 v[6:9], v[146:149], v[232:235], v[6:9]
	v_mfma_f32_16x16x32_bf16 v[2:5], v[154:157], v[232:235], v[2:5]
	v_mfma_f32_16x16x32_bf16 v[54:57], v[150:153], v[166:169], v[54:57]
	v_mfma_f32_16x16x32_bf16 v[46:49], v[158:161], v[166:169], v[46:49]
	v_mfma_f32_16x16x32_bf16 v[38:41], v[150:153], v[220:223], v[38:41]
	v_mfma_f32_16x16x32_bf16 v[30:33], v[158:161], v[220:223], v[30:33]
	v_mfma_f32_16x16x32_bf16 v[22:25], v[150:153], v[228:231], v[22:25]
	v_mfma_f32_16x16x32_bf16 v[14:17], v[158:161], v[228:231], v[14:17]
	v_mfma_f32_16x16x32_bf16 v[6:9], v[150:153], v[236:239], v[6:9]
	v_mfma_f32_16x16x32_bf16 v[2:5], v[158:161], v[236:239], v[2:5]
	s_setprio 0
	s_barrier
	s_add_i32 s62, 0, 0x18000
	s_add_i32 s63, 0, 0x1c000
	v_add_u32_e32 v126, s62, v199
	v_add_u32_e32 v158, s63, v199
	ds_read_b128 v[114:117], v126
	ds_read_b128 v[118:121], v126 offset:1024
	ds_read_b128 v[122:125], v126 offset:2048
	ds_read_b128 v[126:129], v126 offset:3072
	ds_read_b128 v[146:149], v158
	ds_read_b128 v[150:153], v158 offset:1024
	ds_read_b128 v[154:157], v158 offset:2048
	ds_read_b128 v[158:161], v158 offset:3072
	s_add_u32 s72, s96, 0x40000
	s_addc_u32 s73, s97, 0
	s_mov_b32 m0, s30
	v_lshl_add_u64 v[246:247], s[72:73], 0, v[172:173]
	ds_read_b128 v[162:165], v214 offset:32768
	ds_read_b128 v[166:169], v214 offset:33792
	ds_read_b128 v[216:219], v214 offset:34816
	ds_read_b128 v[220:223], v214 offset:35840
	ds_read_b128 v[224:227], v214 offset:36864
	ds_read_b128 v[228:231], v214 offset:37888
	ds_read_b128 v[232:235], v214 offset:38912
	ds_read_b128 v[236:239], v214 offset:39936
	global_load_lds_dwordx4 v[246:247], off
	s_mov_b32 m0, s31
	v_lshl_add_u64 v[246:247], s[72:73], 0, v[176:177]
	global_load_lds_dwordx4 v[246:247], off
	s_waitcnt vmcnt(8) lgkmcnt(0)
	s_setprio 1
	s_barrier
	v_mfma_f32_16x16x32_bf16 v[142:145], v[114:117], v[162:165], v[142:145]
	v_mfma_f32_16x16x32_bf16 v[138:141], v[122:125], v[162:165], v[138:141]
	v_mfma_f32_16x16x32_bf16 v[110:113], v[114:117], v[216:219], v[110:113]
	v_mfma_f32_16x16x32_bf16 v[106:109], v[122:125], v[216:219], v[106:109]
	v_mfma_f32_16x16x32_bf16 v[98:101], v[114:117], v[224:227], v[98:101]
	v_mfma_f32_16x16x32_bf16 v[90:93], v[122:125], v[224:227], v[90:93]
	v_mfma_f32_16x16x32_bf16 v[82:85], v[114:117], v[232:235], v[82:85]
	v_mfma_f32_16x16x32_bf16 v[74:77], v[122:125], v[232:235], v[74:77]
	v_mfma_f32_16x16x32_bf16 v[142:145], v[118:121], v[166:169], v[142:145]
	v_mfma_f32_16x16x32_bf16 v[138:141], v[126:129], v[166:169], v[138:141]
	v_mfma_f32_16x16x32_bf16 v[110:113], v[118:121], v[220:223], v[110:113]
	v_mfma_f32_16x16x32_bf16 v[106:109], v[126:129], v[220:223], v[106:109]
	v_mfma_f32_16x16x32_bf16 v[98:101], v[118:121], v[228:231], v[98:101]
	v_mfma_f32_16x16x32_bf16 v[90:93], v[126:129], v[228:231], v[90:93]
	v_mfma_f32_16x16x32_bf16 v[82:85], v[118:121], v[236:239], v[82:85]
	v_mfma_f32_16x16x32_bf16 v[74:77], v[126:129], v[236:239], v[74:77]
	v_mfma_f32_16x16x32_bf16 v[134:137], v[146:149], v[162:165], v[134:137]
	v_mfma_f32_16x16x32_bf16 v[130:133], v[154:157], v[162:165], v[130:133]
	v_mfma_f32_16x16x32_bf16 v[102:105], v[146:149], v[216:219], v[102:105]
	v_mfma_f32_16x16x32_bf16 v[94:97], v[154:157], v[216:219], v[94:97]
	v_mfma_f32_16x16x32_bf16 v[86:89], v[146:149], v[224:227], v[86:89]
	v_mfma_f32_16x16x32_bf16 v[78:81], v[154:157], v[224:227], v[78:81]
	v_mfma_f32_16x16x32_bf16 v[70:73], v[146:149], v[232:235], v[70:73]
	v_mfma_f32_16x16x32_bf16 v[66:69], v[154:157], v[232:235], v[66:69]
	v_mfma_f32_16x16x32_bf16 v[134:137], v[150:153], v[166:169], v[134:137]
	v_mfma_f32_16x16x32_bf16 v[130:133], v[158:161], v[166:169], v[130:133]
	v_mfma_f32_16x16x32_bf16 v[102:105], v[150:153], v[220:223], v[102:105]
	v_mfma_f32_16x16x32_bf16 v[94:97], v[158:161], v[220:223], v[94:97]
	v_mfma_f32_16x16x32_bf16 v[86:89], v[150:153], v[228:231], v[86:89]
	v_mfma_f32_16x16x32_bf16 v[78:81], v[158:161], v[228:231], v[78:81]
	v_mfma_f32_16x16x32_bf16 v[70:73], v[150:153], v[236:239], v[70:73]
	v_mfma_f32_16x16x32_bf16 v[66:69], v[158:161], v[236:239], v[66:69]
	s_setprio 0
	s_barrier
	ds_read_b128 v[162:165], v214 offset:49152
	ds_read_b128 v[166:169], v214 offset:50176
	ds_read_b128 v[216:219], v214 offset:51200
	ds_read_b128 v[220:223], v214 offset:52224
	ds_read_b128 v[224:227], v214 offset:53248
	ds_read_b128 v[228:231], v214 offset:54272
	ds_read_b128 v[232:235], v214 offset:55296
	ds_read_b128 v[236:239], v214 offset:56320
	s_add_i32 s62, s62, s17
	s_mov_b32 m0, s62
	v_lshl_add_u64 v[202:203], v[202:203], 0, s[76:77]
	global_load_lds_dwordx4 v[202:203], off
	s_add_i32 m0, s62, 0x2000
	s_add_u32 s72, s94, 0x40080
	v_lshl_add_u64 v[202:203], v[240:241], 0, s[76:77]
	s_addc_u32 s73, s95, 0
	s_add_i32 s62, s63, s17
	global_load_lds_dwordx4 v[202:203], off
	s_mov_b32 m0, s62
	v_lshl_add_u64 v[202:203], s[72:73], 0, v[174:175]
	global_load_lds_dwordx4 v[202:203], off
	s_add_i32 m0, s62, 0x2000
	v_lshl_add_u64 v[202:203], s[72:73], 0, v[178:179]
	global_load_lds_dwordx4 v[202:203], off
	s_mov_b32 m0, s44
	v_lshl_add_u64 v[202:203], v[242:243], 0, s[76:77]
	global_load_lds_dwordx4 v[202:203], off
	s_mov_b32 m0, s36
	v_lshl_add_u64 v[202:203], v[244:245], 0, s[76:77]
	global_load_lds_dwordx4 v[202:203], off
	s_waitcnt vmcnt(8) lgkmcnt(0)
	s_setprio 1
	s_barrier
	v_mfma_f32_16x16x32_bf16 v[62:65], v[114:117], v[162:165], v[62:65]
	v_mfma_f32_16x16x32_bf16 v[58:61], v[122:125], v[162:165], v[58:61]
	v_mfma_f32_16x16x32_bf16 v[50:53], v[114:117], v[216:219], v[50:53]
	v_mfma_f32_16x16x32_bf16 v[42:45], v[122:125], v[216:219], v[42:45]
	v_mfma_f32_16x16x32_bf16 v[34:37], v[114:117], v[224:227], v[34:37]
	v_mfma_f32_16x16x32_bf16 v[26:29], v[122:125], v[224:227], v[26:29]
	v_mfma_f32_16x16x32_bf16 v[18:21], v[114:117], v[232:235], v[18:21]
	v_mfma_f32_16x16x32_bf16 v[10:13], v[122:125], v[232:235], v[10:13]
	v_mfma_f32_16x16x32_bf16 v[62:65], v[118:121], v[166:169], v[62:65]
	v_mfma_f32_16x16x32_bf16 v[58:61], v[126:129], v[166:169], v[58:61]
	v_mfma_f32_16x16x32_bf16 v[50:53], v[118:121], v[220:223], v[50:53]
	v_mfma_f32_16x16x32_bf16 v[42:45], v[126:129], v[220:223], v[42:45]
	v_mfma_f32_16x16x32_bf16 v[34:37], v[118:121], v[228:231], v[34:37]
	v_mfma_f32_16x16x32_bf16 v[26:29], v[126:129], v[228:231], v[26:29]
	v_mfma_f32_16x16x32_bf16 v[18:21], v[118:121], v[236:239], v[18:21]
	v_mfma_f32_16x16x32_bf16 v[10:13], v[126:129], v[236:239], v[10:13]
	v_mfma_f32_16x16x32_bf16 v[54:57], v[146:149], v[162:165], v[54:57]
	v_mfma_f32_16x16x32_bf16 v[46:49], v[154:157], v[162:165], v[46:49]
	v_mfma_f32_16x16x32_bf16 v[38:41], v[146:149], v[216:219], v[38:41]
	v_mfma_f32_16x16x32_bf16 v[30:33], v[154:157], v[216:219], v[30:33]
	v_mfma_f32_16x16x32_bf16 v[22:25], v[146:149], v[224:227], v[22:25]
	v_mfma_f32_16x16x32_bf16 v[14:17], v[154:157], v[224:227], v[14:17]
	v_mfma_f32_16x16x32_bf16 v[6:9], v[146:149], v[232:235], v[6:9]
	v_mfma_f32_16x16x32_bf16 v[2:5], v[154:157], v[232:235], v[2:5]
	v_mfma_f32_16x16x32_bf16 v[54:57], v[150:153], v[166:169], v[54:57]
	v_mfma_f32_16x16x32_bf16 v[46:49], v[158:161], v[166:169], v[46:49]
	v_mfma_f32_16x16x32_bf16 v[38:41], v[150:153], v[220:223], v[38:41]
	v_mfma_f32_16x16x32_bf16 v[30:33], v[158:161], v[220:223], v[30:33]
	v_mfma_f32_16x16x32_bf16 v[22:25], v[150:153], v[228:231], v[22:25]
	v_mfma_f32_16x16x32_bf16 v[14:17], v[158:161], v[228:231], v[14:17]
	v_mfma_f32_16x16x32_bf16 v[6:9], v[150:153], v[236:239], v[6:9]
	v_mfma_f32_16x16x32_bf16 v[2:5], v[158:161], v[236:239], v[2:5]
	s_setprio 0
	s_barrier
	s_add_u32 s10, s10, 0x100
	s_addc_u32 s11, s11, 0
	s_add_u32 vcc_lo, vcc_lo, 0x100
	s_addc_u32 vcc_hi, vcc_hi, 0
	s_cmp_ge_i32 s66, s18
	s_mov_b32 s94, s66
	s_cbranch_scc0 .LBB0_1428
	s_and_b64 vcc, exec, s[82:83]
	s_cbranch_vccz .LBB0_1431
	s_barrier

.LBB0_1618:
	s_add_u32 s24, s96, s20
	s_addc_u32 s25, s97, s21
	s_and_b64 s[14:15], s[4:5], exec
	s_cselect_b32 s14, s25, s29
	s_cselect_b32 s15, s24, s28
	s_add_u32 s26, s2, s22
	s_addc_u32 s27, s3, s23
	s_and_b64 s[36:37], s[4:5], exec
	s_cselect_b32 s17, s27, s31
	s_cselect_b32 s49, s26, s30
	s_add_u32 s28, s28, 0x40080
	s_addc_u32 s29, s29, 0
	s_add_u32 s50, s30, 0x100
	s_addc_u32 s51, s31, 0
	s_mov_b32 s62, -2
	ds_read_b128 v[154:157], v150
	ds_read_b128 v[158:161], v150 offset:1024
	ds_read_b128 v[162:165], v150 offset:2048
	ds_read_b128 v[166:169], v150 offset:3072
	ds_read_b128 v[170:173], v151
	ds_read_b128 v[174:177], v151 offset:1024
	ds_read_b128 v[178:181], v151 offset:2048
	ds_read_b128 v[182:185], v151 offset:3072
	ds_read_b128 v[186:189], v152
	ds_read_b128 v[190:193], v152 offset:1024
	ds_read_b128 v[194:197], v152 offset:2048
	ds_read_b128 v[198:201], v152 offset:3072
	ds_read_b128 v[206:209], v152 offset:4096
	ds_read_b128 v[210:213], v152 offset:5120
	ds_read_b128 v[214:217], v152 offset:6144
	ds_read_b128 v[218:221], v152 offset:7168
	s_add_u32 s30, s28, 0xfffc0080
	s_addc_u32 s31, s29, -1
	s_cmp_eq_u32 s62, 12
	s_cselect_b32 s37, s14, s31
	s_cselect_b32 s36, s15, s30
	s_cselect_b32 s31, s17, s51
	s_cselect_b32 s30, s49, s50
	s_add_i32 m0, s19, 0xc000
	v_lshl_add_u64 v[146:147], s[28:29], 0, v[138:139]
	global_load_lds_dwordx4 v[146:147], off
	s_add_i32 m0, s19, 0xe000
	v_lshl_add_u64 v[146:147], s[28:29], 0, v[140:141]
	global_load_lds_dwordx4 v[146:147], off
	s_waitcnt vmcnt(8) lgkmcnt(0)
	s_setprio 1
	s_barrier
	v_mfma_f32_16x16x32_bf16 v[126:129], v[154:157], v[186:189], 0
	v_mfma_f32_16x16x32_bf16 v[122:125], v[162:165], v[186:189], 0
	v_mfma_f32_16x16x32_bf16 v[110:113], v[154:157], v[194:197], 0
	v_mfma_f32_16x16x32_bf16 v[106:109], v[162:165], v[194:197], 0
	v_mfma_f32_16x16x32_bf16 v[94:97], v[154:157], v[206:209], 0
	v_mfma_f32_16x16x32_bf16 v[90:93], v[162:165], v[206:209], 0
	v_mfma_f32_16x16x32_bf16 v[78:81], v[154:157], v[214:217], 0
	v_mfma_f32_16x16x32_bf16 v[74:77], v[162:165], v[214:217], 0
	v_mfma_f32_16x16x32_bf16 v[126:129], v[158:161], v[190:193], v[126:129]
	v_mfma_f32_16x16x32_bf16 v[122:125], v[166:169], v[190:193], v[122:125]
	v_mfma_f32_16x16x32_bf16 v[110:113], v[158:161], v[198:201], v[110:113]
	v_mfma_f32_16x16x32_bf16 v[106:109], v[166:169], v[198:201], v[106:109]
	v_mfma_f32_16x16x32_bf16 v[94:97], v[158:161], v[210:213], v[94:97]
	v_mfma_f32_16x16x32_bf16 v[90:93], v[166:169], v[210:213], v[90:93]
	v_mfma_f32_16x16x32_bf16 v[78:81], v[158:161], v[218:221], v[78:81]
	v_mfma_f32_16x16x32_bf16 v[74:77], v[166:169], v[218:221], v[74:77]
	v_mfma_f32_16x16x32_bf16 v[118:121], v[170:173], v[186:189], 0
	v_mfma_f32_16x16x32_bf16 v[114:117], v[178:181], v[186:189], 0
	v_mfma_f32_16x16x32_bf16 v[102:105], v[170:173], v[194:197], 0
	v_mfma_f32_16x16x32_bf16 v[98:101], v[178:181], v[194:197], 0
	v_mfma_f32_16x16x32_bf16 v[86:89], v[170:173], v[206:209], 0
	v_mfma_f32_16x16x32_bf16 v[82:85], v[178:181], v[206:209], 0
	v_mfma_f32_16x16x32_bf16 v[70:73], v[170:173], v[214:217], 0
	v_mfma_f32_16x16x32_bf16 v[66:69], v[178:181], v[214:217], 0
	v_mfma_f32_16x16x32_bf16 v[118:121], v[174:177], v[190:193], v[118:121]
	v_mfma_f32_16x16x32_bf16 v[114:117], v[182:185], v[190:193], v[114:117]
	v_mfma_f32_16x16x32_bf16 v[102:105], v[174:177], v[198:201], v[102:105]
	v_mfma_f32_16x16x32_bf16 v[98:101], v[182:185], v[198:201], v[98:101]
	v_mfma_f32_16x16x32_bf16 v[86:89], v[174:177], v[210:213], v[86:89]
	v_mfma_f32_16x16x32_bf16 v[82:85], v[182:185], v[210:213], v[82:85]
	v_mfma_f32_16x16x32_bf16 v[70:73], v[174:177], v[218:221], v[70:73]
	v_mfma_f32_16x16x32_bf16 v[66:69], v[182:185], v[218:221], v[66:69]
	s_setprio 0
	s_barrier
	ds_read_b128 v[186:189], v152 offset:16384
	ds_read_b128 v[190:193], v152 offset:17408
	ds_read_b128 v[194:197], v152 offset:18432
	ds_read_b128 v[198:201], v152 offset:19456
	ds_read_b128 v[206:209], v152 offset:20480
	ds_read_b128 v[210:213], v152 offset:21504
	ds_read_b128 v[214:217], v152 offset:22528
	ds_read_b128 v[218:221], v152 offset:23552
	s_add_i32 s63, s45, s12
	s_mov_b32 m0, s63
	v_lshl_add_u64 v[146:147], s[30:31], 0, v[134:135]
	global_load_lds_dwordx4 v[146:147], off
	s_add_i32 m0, s63, 0x2000
	s_add_u32 s64, s30, 0x40000
	v_lshl_add_u64 v[202:203], s[30:31], 0, v[130:131]
	s_addc_u32 s65, s31, 0
	s_add_i32 s63, s46, s12
	global_load_lds_dwordx4 v[202:203], off
	v_lshl_add_u64 v[222:223], s[64:65], 0, v[134:135]
	s_mov_b32 m0, s63
	v_lshl_add_u64 v[224:225], s[36:37], 0, v[132:133]
	global_load_lds_dwordx4 v[222:223], off
	s_add_i32 m0, s63, 0x2000
	v_lshl_add_u64 v[222:223], s[64:65], 0, v[130:131]
	global_load_lds_dwordx4 v[222:223], off
	s_mov_b32 m0, s19
	v_lshl_add_u64 v[222:223], s[36:37], 0, v[136:137]
	global_load_lds_dwordx4 v[222:223], off
	s_mov_b32 m0, s33
	s_nop 0
	global_load_lds_dwordx4 v[224:225], off
	s_waitcnt vmcnt(8) lgkmcnt(0)
	s_setprio 1
	s_barrier
	v_mfma_f32_16x16x32_bf16 v[62:65], v[154:157], v[186:189], 0
	v_mfma_f32_16x16x32_bf16 v[58:61], v[162:165], v[186:189], 0
	v_mfma_f32_16x16x32_bf16 v[46:49], v[154:157], v[194:197], 0
	v_mfma_f32_16x16x32_bf16 v[42:45], v[162:165], v[194:197], 0
	v_mfma_f32_16x16x32_bf16 v[30:33], v[154:157], v[206:209], 0
	v_mfma_f32_16x16x32_bf16 v[26:29], v[162:165], v[206:209], 0
	v_mfma_f32_16x16x32_bf16 v[14:17], v[154:157], v[214:217], 0
	v_mfma_f32_16x16x32_bf16 v[10:13], v[162:165], v[214:217], 0
	v_mfma_f32_16x16x32_bf16 v[62:65], v[158:161], v[190:193], v[62:65]
	v_mfma_f32_16x16x32_bf16 v[58:61], v[166:169], v[190:193], v[58:61]
	v_mfma_f32_16x16x32_bf16 v[46:49], v[158:161], v[198:201], v[46:49]
	v_mfma_f32_16x16x32_bf16 v[42:45], v[166:169], v[198:201], v[42:45]
	v_mfma_f32_16x16x32_bf16 v[30:33], v[158:161], v[210:213], v[30:33]
	v_mfma_f32_16x16x32_bf16 v[26:29], v[166:169], v[210:213], v[26:29]
	v_mfma_f32_16x16x32_bf16 v[14:17], v[158:161], v[218:221], v[14:17]
	v_mfma_f32_16x16x32_bf16 v[10:13], v[166:169], v[218:221], v[10:13]
	v_mfma_f32_16x16x32_bf16 v[54:57], v[170:173], v[186:189], 0
	v_mfma_f32_16x16x32_bf16 v[50:53], v[178:181], v[186:189], 0
	v_mfma_f32_16x16x32_bf16 v[38:41], v[170:173], v[194:197], 0
	v_mfma_f32_16x16x32_bf16 v[34:37], v[178:181], v[194:197], 0
	v_mfma_f32_16x16x32_bf16 v[22:25], v[170:173], v[206:209], 0
	v_mfma_f32_16x16x32_bf16 v[18:21], v[178:181], v[206:209], 0
	v_mfma_f32_16x16x32_bf16 v[6:9], v[170:173], v[214:217], 0
	v_mfma_f32_16x16x32_bf16 v[2:5], v[178:181], v[214:217], 0
	v_mfma_f32_16x16x32_bf16 v[54:57], v[174:177], v[190:193], v[54:57]
	v_mfma_f32_16x16x32_bf16 v[50:53], v[182:185], v[190:193], v[50:53]
	v_mfma_f32_16x16x32_bf16 v[38:41], v[174:177], v[198:201], v[38:41]
	v_mfma_f32_16x16x32_bf16 v[34:37], v[182:185], v[198:201], v[34:37]
	v_mfma_f32_16x16x32_bf16 v[22:25], v[174:177], v[210:213], v[22:25]
	v_mfma_f32_16x16x32_bf16 v[18:21], v[182:185], v[210:213], v[18:21]
	v_mfma_f32_16x16x32_bf16 v[6:9], v[174:177], v[218:221], v[6:9]
	v_mfma_f32_16x16x32_bf16 v[2:5], v[182:185], v[218:221], v[2:5]
	s_setprio 0
	s_barrier
	s_add_i32 s63, 0, 0x18000
	v_add_u32_e32 v153, s63, v149
	s_add_i32 s64, 0, 0x1c000
	ds_read_b128 v[154:157], v153
	ds_read_b128 v[158:161], v153 offset:1024
	ds_read_b128 v[162:165], v153 offset:2048
	ds_read_b128 v[166:169], v153 offset:3072
	v_add_u32_e32 v153, s64, v149
	ds_read_b128 v[170:173], v153
	ds_read_b128 v[174:177], v153 offset:1024
	ds_read_b128 v[178:181], v153 offset:2048
	ds_read_b128 v[182:185], v153 offset:3072
	s_add_u32 s36, s36, 0x40000
	s_addc_u32 s37, s37, 0
	s_mov_b32 m0, s35
	v_lshl_add_u64 v[226:227], s[36:37], 0, v[136:137]
	ds_read_b128 v[186:189], v152 offset:32768
	ds_read_b128 v[190:193], v152 offset:33792
	ds_read_b128 v[194:197], v152 offset:34816
	ds_read_b128 v[198:201], v152 offset:35840
	ds_read_b128 v[206:209], v152 offset:36864
	ds_read_b128 v[210:213], v152 offset:37888
	ds_read_b128 v[214:217], v152 offset:38912
	ds_read_b128 v[218:221], v152 offset:39936
	global_load_lds_dwordx4 v[226:227], off
	s_mov_b32 m0, s38
	v_lshl_add_u64 v[226:227], s[36:37], 0, v[132:133]
	global_load_lds_dwordx4 v[226:227], off
	s_waitcnt vmcnt(8) lgkmcnt(0)
	s_setprio 1
	s_barrier
	v_mfma_f32_16x16x32_bf16 v[126:129], v[154:157], v[186:189], v[126:129]
	v_mfma_f32_16x16x32_bf16 v[122:125], v[162:165], v[186:189], v[122:125]
	v_mfma_f32_16x16x32_bf16 v[110:113], v[154:157], v[194:197], v[110:113]
	v_mfma_f32_16x16x32_bf16 v[106:109], v[162:165], v[194:197], v[106:109]
	v_mfma_f32_16x16x32_bf16 v[94:97], v[154:157], v[206:209], v[94:97]
	v_mfma_f32_16x16x32_bf16 v[90:93], v[162:165], v[206:209], v[90:93]
	v_mfma_f32_16x16x32_bf16 v[78:81], v[154:157], v[214:217], v[78:81]
	v_mfma_f32_16x16x32_bf16 v[74:77], v[162:165], v[214:217], v[74:77]
	v_mfma_f32_16x16x32_bf16 v[126:129], v[158:161], v[190:193], v[126:129]
	v_mfma_f32_16x16x32_bf16 v[122:125], v[166:169], v[190:193], v[122:125]
	v_mfma_f32_16x16x32_bf16 v[110:113], v[158:161], v[198:201], v[110:113]
	v_mfma_f32_16x16x32_bf16 v[106:109], v[166:169], v[198:201], v[106:109]
	v_mfma_f32_16x16x32_bf16 v[94:97], v[158:161], v[210:213], v[94:97]
	v_mfma_f32_16x16x32_bf16 v[90:93], v[166:169], v[210:213], v[90:93]
	v_mfma_f32_16x16x32_bf16 v[78:81], v[158:161], v[218:221], v[78:81]
	v_mfma_f32_16x16x32_bf16 v[74:77], v[166:169], v[218:221], v[74:77]
	v_mfma_f32_16x16x32_bf16 v[118:121], v[170:173], v[186:189], v[118:121]
	v_mfma_f32_16x16x32_bf16 v[114:117], v[178:181], v[186:189], v[114:117]
	v_mfma_f32_16x16x32_bf16 v[102:105], v[170:173], v[194:197], v[102:105]
	v_mfma_f32_16x16x32_bf16 v[98:101], v[178:181], v[194:197], v[98:101]
	v_mfma_f32_16x16x32_bf16 v[86:89], v[170:173], v[206:209], v[86:89]
	v_mfma_f32_16x16x32_bf16 v[82:85], v[178:181], v[206:209], v[82:85]
	v_mfma_f32_16x16x32_bf16 v[70:73], v[170:173], v[214:217], v[70:73]
	v_mfma_f32_16x16x32_bf16 v[66:69], v[178:181], v[214:217], v[66:69]
	v_mfma_f32_16x16x32_bf16 v[118:121], v[174:177], v[190:193], v[118:121]
	v_mfma_f32_16x16x32_bf16 v[114:117], v[182:185], v[190:193], v[114:117]
	v_mfma_f32_16x16x32_bf16 v[102:105], v[174:177], v[198:201], v[102:105]
	v_mfma_f32_16x16x32_bf16 v[98:101], v[182:185], v[198:201], v[98:101]
	v_mfma_f32_16x16x32_bf16 v[86:89], v[174:177], v[210:213], v[86:89]
	v_mfma_f32_16x16x32_bf16 v[82:85], v[182:185], v[210:213], v[82:85]
	v_mfma_f32_16x16x32_bf16 v[70:73], v[174:177], v[218:221], v[70:73]
	v_mfma_f32_16x16x32_bf16 v[66:69], v[182:185], v[218:221], v[66:69]
	s_setprio 0
	s_barrier
	ds_read_b128 v[186:189], v152 offset:49152
	ds_read_b128 v[190:193], v152 offset:50176
	ds_read_b128 v[194:197], v152 offset:51200
	ds_read_b128 v[198:201], v152 offset:52224
	ds_read_b128 v[206:209], v152 offset:53248
	ds_read_b128 v[210:213], v152 offset:54272
	ds_read_b128 v[214:217], v152 offset:55296
	ds_read_b128 v[218:221], v152 offset:56320
	s_add_i32 s36, s63, s12
	s_mov_b32 m0, s36
	v_lshl_add_u64 v[146:147], v[146:147], 0, s[8:9]
	global_load_lds_dwordx4 v[146:147], off
	s_add_i32 m0, s36, 0x2000
	s_add_u32 s30, s30, 0x40080
	v_lshl_add_u64 v[146:147], v[202:203], 0, s[8:9]
	s_addc_u32 s31, s31, 0
	s_add_i32 s36, s64, s12
	global_load_lds_dwordx4 v[146:147], off
	s_mov_b32 m0, s36
	v_lshl_add_u64 v[146:147], s[30:31], 0, v[134:135]
	global_load_lds_dwordx4 v[146:147], off
	s_add_i32 m0, s36, 0x2000
	v_lshl_add_u64 v[146:147], s[30:31], 0, v[130:131]
	global_load_lds_dwordx4 v[146:147], off
	s_mov_b32 m0, s42
	v_lshl_add_u64 v[146:147], v[222:223], 0, s[8:9]
	global_load_lds_dwordx4 v[146:147], off
	s_mov_b32 m0, s43
	v_lshl_add_u64 v[146:147], v[224:225], 0, s[8:9]
	global_load_lds_dwordx4 v[146:147], off
	s_waitcnt vmcnt(8) lgkmcnt(0)
	s_setprio 1
	s_barrier
	v_mfma_f32_16x16x32_bf16 v[62:65], v[154:157], v[186:189], v[62:65]
	v_mfma_f32_16x16x32_bf16 v[58:61], v[162:165], v[186:189], v[58:61]
	v_mfma_f32_16x16x32_bf16 v[46:49], v[154:157], v[194:197], v[46:49]
	v_mfma_f32_16x16x32_bf16 v[42:45], v[162:165], v[194:197], v[42:45]
	v_mfma_f32_16x16x32_bf16 v[30:33], v[154:157], v[206:209], v[30:33]
	v_mfma_f32_16x16x32_bf16 v[26:29], v[162:165], v[206:209], v[26:29]
	v_mfma_f32_16x16x32_bf16 v[14:17], v[154:157], v[214:217], v[14:17]
	v_mfma_f32_16x16x32_bf16 v[10:13], v[162:165], v[214:217], v[10:13]
	v_mfma_f32_16x16x32_bf16 v[62:65], v[158:161], v[190:193], v[62:65]
	v_mfma_f32_16x16x32_bf16 v[58:61], v[166:169], v[190:193], v[58:61]
	v_mfma_f32_16x16x32_bf16 v[46:49], v[158:161], v[198:201], v[46:49]
	v_mfma_f32_16x16x32_bf16 v[42:45], v[166:169], v[198:201], v[42:45]
	v_mfma_f32_16x16x32_bf16 v[30:33], v[158:161], v[210:213], v[30:33]
	v_mfma_f32_16x16x32_bf16 v[26:29], v[166:169], v[210:213], v[26:29]
	v_mfma_f32_16x16x32_bf16 v[14:17], v[158:161], v[218:221], v[14:17]
	v_mfma_f32_16x16x32_bf16 v[10:13], v[166:169], v[218:221], v[10:13]
	v_mfma_f32_16x16x32_bf16 v[54:57], v[170:173], v[186:189], v[54:57]
	v_mfma_f32_16x16x32_bf16 v[50:53], v[178:181], v[186:189], v[50:53]
	v_mfma_f32_16x16x32_bf16 v[38:41], v[170:173], v[194:197], v[38:41]
	v_mfma_f32_16x16x32_bf16 v[34:37], v[178:181], v[194:197], v[34:37]
	v_mfma_f32_16x16x32_bf16 v[22:25], v[170:173], v[206:209], v[22:25]
	v_mfma_f32_16x16x32_bf16 v[18:21], v[178:181], v[206:209], v[18:21]
	v_mfma_f32_16x16x32_bf16 v[6:9], v[170:173], v[214:217], v[6:9]
	v_mfma_f32_16x16x32_bf16 v[2:5], v[178:181], v[214:217], v[2:5]
	v_mfma_f32_16x16x32_bf16 v[54:57], v[174:177], v[190:193], v[54:57]
	v_mfma_f32_16x16x32_bf16 v[50:53], v[182:185], v[190:193], v[50:53]
	v_mfma_f32_16x16x32_bf16 v[38:41], v[174:177], v[198:201], v[38:41]
	v_mfma_f32_16x16x32_bf16 v[34:37], v[182:185], v[198:201], v[34:37]
	v_mfma_f32_16x16x32_bf16 v[22:25], v[174:177], v[210:213], v[22:25]
	v_mfma_f32_16x16x32_bf16 v[18:21], v[182:185], v[210:213], v[18:21]
	v_mfma_f32_16x16x32_bf16 v[6:9], v[174:177], v[218:221], v[6:9]
	v_mfma_f32_16x16x32_bf16 v[2:5], v[182:185], v[218:221], v[2:5]
	s_setprio 0
	s_barrier
	s_add_i32 s62, s62, 2
	s_add_u32 s28, s28, 0x100
	s_addc_u32 s29, s29, 0
	s_add_u32 s50, s50, 0x100
	s_addc_u32 s51, s51, 0
	s_cmp_gt_u32 s62, 13
.LBB0_1619:
	ds_read_b128 v[154:157], v150
	ds_read_b128 v[158:161], v150 offset:1024
	ds_read_b128 v[162:165], v150 offset:2048
	ds_read_b128 v[166:169], v150 offset:3072
	ds_read_b128 v[170:173], v151
	ds_read_b128 v[174:177], v151 offset:1024
	ds_read_b128 v[178:181], v151 offset:2048
	ds_read_b128 v[182:185], v151 offset:3072
	ds_read_b128 v[186:189], v152
	ds_read_b128 v[190:193], v152 offset:1024
	ds_read_b128 v[194:197], v152 offset:2048
	ds_read_b128 v[198:201], v152 offset:3072
	ds_read_b128 v[206:209], v152 offset:4096
	ds_read_b128 v[210:213], v152 offset:5120
	ds_read_b128 v[214:217], v152 offset:6144
	ds_read_b128 v[218:221], v152 offset:7168
	s_add_u32 s30, s28, 0xfffc0080
	s_addc_u32 s31, s29, -1
	s_cmp_eq_u32 s62, 12
	s_cselect_b32 s37, s14, s31
	s_cselect_b32 s36, s15, s30
	s_cselect_b32 s31, s17, s51
	s_cselect_b32 s30, s49, s50
	s_add_i32 m0, s19, 0xc000
	v_lshl_add_u64 v[146:147], s[28:29], 0, v[138:139]
	global_load_lds_dwordx4 v[146:147], off
	s_add_i32 m0, s19, 0xe000
	v_lshl_add_u64 v[146:147], s[28:29], 0, v[140:141]
	global_load_lds_dwordx4 v[146:147], off
	s_waitcnt vmcnt(8) lgkmcnt(0)
	s_setprio 1
	s_barrier
	v_mfma_f32_16x16x32_bf16 v[126:129], v[154:157], v[186:189], v[126:129]
	v_mfma_f32_16x16x32_bf16 v[122:125], v[162:165], v[186:189], v[122:125]
	v_mfma_f32_16x16x32_bf16 v[110:113], v[154:157], v[194:197], v[110:113]
	v_mfma_f32_16x16x32_bf16 v[106:109], v[162:165], v[194:197], v[106:109]
	v_mfma_f32_16x16x32_bf16 v[94:97], v[154:157], v[206:209], v[94:97]
	v_mfma_f32_16x16x32_bf16 v[90:93], v[162:165], v[206:209], v[90:93]
	v_mfma_f32_16x16x32_bf16 v[78:81], v[154:157], v[214:217], v[78:81]
	v_mfma_f32_16x16x32_bf16 v[74:77], v[162:165], v[214:217], v[74:77]
	v_mfma_f32_16x16x32_bf16 v[126:129], v[158:161], v[190:193], v[126:129]
	v_mfma_f32_16x16x32_bf16 v[122:125], v[166:169], v[190:193], v[122:125]
	v_mfma_f32_16x16x32_bf16 v[110:113], v[158:161], v[198:201], v[110:113]
	v_mfma_f32_16x16x32_bf16 v[106:109], v[166:169], v[198:201], v[106:109]
	v_mfma_f32_16x16x32_bf16 v[94:97], v[158:161], v[210:213], v[94:97]
	v_mfma_f32_16x16x32_bf16 v[90:93], v[166:169], v[210:213], v[90:93]
	v_mfma_f32_16x16x32_bf16 v[78:81], v[158:161], v[218:221], v[78:81]
	v_mfma_f32_16x16x32_bf16 v[74:77], v[166:169], v[218:221], v[74:77]
	v_mfma_f32_16x16x32_bf16 v[118:121], v[170:173], v[186:189], v[118:121]
	v_mfma_f32_16x16x32_bf16 v[114:117], v[178:181], v[186:189], v[114:117]
	v_mfma_f32_16x16x32_bf16 v[102:105], v[170:173], v[194:197], v[102:105]
	v_mfma_f32_16x16x32_bf16 v[98:101], v[178:181], v[194:197], v[98:101]
	v_mfma_f32_16x16x32_bf16 v[86:89], v[170:173], v[206:209], v[86:89]
	v_mfma_f32_16x16x32_bf16 v[82:85], v[178:181], v[206:209], v[82:85]
	v_mfma_f32_16x16x32_bf16 v[70:73], v[170:173], v[214:217], v[70:73]
	v_mfma_f32_16x16x32_bf16 v[66:69], v[178:181], v[214:217], v[66:69]
	v_mfma_f32_16x16x32_bf16 v[118:121], v[174:177], v[190:193], v[118:121]
	v_mfma_f32_16x16x32_bf16 v[114:117], v[182:185], v[190:193], v[114:117]
	v_mfma_f32_16x16x32_bf16 v[102:105], v[174:177], v[198:201], v[102:105]
	v_mfma_f32_16x16x32_bf16 v[98:101], v[182:185], v[198:201], v[98:101]
	v_mfma_f32_16x16x32_bf16 v[86:89], v[174:177], v[210:213], v[86:89]
	v_mfma_f32_16x16x32_bf16 v[82:85], v[182:185], v[210:213], v[82:85]
	v_mfma_f32_16x16x32_bf16 v[70:73], v[174:177], v[218:221], v[70:73]
	v_mfma_f32_16x16x32_bf16 v[66:69], v[182:185], v[218:221], v[66:69]
	s_setprio 0
	s_barrier
	ds_read_b128 v[186:189], v152 offset:16384
	ds_read_b128 v[190:193], v152 offset:17408
	ds_read_b128 v[194:197], v152 offset:18432
	ds_read_b128 v[198:201], v152 offset:19456
	ds_read_b128 v[206:209], v152 offset:20480
	ds_read_b128 v[210:213], v152 offset:21504
	ds_read_b128 v[214:217], v152 offset:22528
	ds_read_b128 v[218:221], v152 offset:23552
	s_add_i32 s63, s45, s12
	s_mov_b32 m0, s63
	v_lshl_add_u64 v[146:147], s[30:31], 0, v[134:135]
	global_load_lds_dwordx4 v[146:147], off
	s_add_i32 m0, s63, 0x2000
	s_add_u32 s64, s30, 0x40000
	v_lshl_add_u64 v[202:203], s[30:31], 0, v[130:131]
	s_addc_u32 s65, s31, 0
	s_add_i32 s63, s46, s12
	global_load_lds_dwordx4 v[202:203], off
	v_lshl_add_u64 v[222:223], s[64:65], 0, v[134:135]
	s_mov_b32 m0, s63
	v_lshl_add_u64 v[224:225], s[36:37], 0, v[132:133]
	global_load_lds_dwordx4 v[222:223], off
	s_add_i32 m0, s63, 0x2000
	v_lshl_add_u64 v[222:223], s[64:65], 0, v[130:131]
	global_load_lds_dwordx4 v[222:223], off
	s_mov_b32 m0, s19
	v_lshl_add_u64 v[222:223], s[36:37], 0, v[136:137]
	global_load_lds_dwordx4 v[222:223], off
	s_mov_b32 m0, s33
	s_nop 0
	global_load_lds_dwordx4 v[224:225], off
	s_waitcnt vmcnt(8) lgkmcnt(0)
	s_setprio 1
	s_barrier
	v_mfma_f32_16x16x32_bf16 v[62:65], v[154:157], v[186:189], v[62:65]
	v_mfma_f32_16x16x32_bf16 v[58:61], v[162:165], v[186:189], v[58:61]
	v_mfma_f32_16x16x32_bf16 v[46:49], v[154:157], v[194:197], v[46:49]
	v_mfma_f32_16x16x32_bf16 v[42:45], v[162:165], v[194:197], v[42:45]
	v_mfma_f32_16x16x32_bf16 v[30:33], v[154:157], v[206:209], v[30:33]
	v_mfma_f32_16x16x32_bf16 v[26:29], v[162:165], v[206:209], v[26:29]
	v_mfma_f32_16x16x32_bf16 v[14:17], v[154:157], v[214:217], v[14:17]
	v_mfma_f32_16x16x32_bf16 v[10:13], v[162:165], v[214:217], v[10:13]
	v_mfma_f32_16x16x32_bf16 v[62:65], v[158:161], v[190:193], v[62:65]
	v_mfma_f32_16x16x32_bf16 v[58:61], v[166:169], v[190:193], v[58:61]
	v_mfma_f32_16x16x32_bf16 v[46:49], v[158:161], v[198:201], v[46:49]
	v_mfma_f32_16x16x32_bf16 v[42:45], v[166:169], v[198:201], v[42:45]
	v_mfma_f32_16x16x32_bf16 v[30:33], v[158:161], v[210:213], v[30:33]
	v_mfma_f32_16x16x32_bf16 v[26:29], v[166:169], v[210:213], v[26:29]
	v_mfma_f32_16x16x32_bf16 v[14:17], v[158:161], v[218:221], v[14:17]
	v_mfma_f32_16x16x32_bf16 v[10:13], v[166:169], v[218:221], v[10:13]
	v_mfma_f32_16x16x32_bf16 v[54:57], v[170:173], v[186:189], v[54:57]
	v_mfma_f32_16x16x32_bf16 v[50:53], v[178:181], v[186:189], v[50:53]
	v_mfma_f32_16x16x32_bf16 v[38:41], v[170:173], v[194:197], v[38:41]
	v_mfma_f32_16x16x32_bf16 v[34:37], v[178:181], v[194:197], v[34:37]
	v_mfma_f32_16x16x32_bf16 v[22:25], v[170:173], v[206:209], v[22:25]
	v_mfma_f32_16x16x32_bf16 v[18:21], v[178:181], v[206:209], v[18:21]
	v_mfma_f32_16x16x32_bf16 v[6:9], v[170:173], v[214:217], v[6:9]
	v_mfma_f32_16x16x32_bf16 v[2:5], v[178:181], v[214:217], v[2:5]
	v_mfma_f32_16x16x32_bf16 v[54:57], v[174:177], v[190:193], v[54:57]
	v_mfma_f32_16x16x32_bf16 v[50:53], v[182:185], v[190:193], v[50:53]
	v_mfma_f32_16x16x32_bf16 v[38:41], v[174:177], v[198:201], v[38:41]
	v_mfma_f32_16x16x32_bf16 v[34:37], v[182:185], v[198:201], v[34:37]
	v_mfma_f32_16x16x32_bf16 v[22:25], v[174:177], v[210:213], v[22:25]
	v_mfma_f32_16x16x32_bf16 v[18:21], v[182:185], v[210:213], v[18:21]
	v_mfma_f32_16x16x32_bf16 v[6:9], v[174:177], v[218:221], v[6:9]
	v_mfma_f32_16x16x32_bf16 v[2:5], v[182:185], v[218:221], v[2:5]
	s_setprio 0
	s_barrier
	s_add_i32 s63, 0, 0x18000
	v_add_u32_e32 v153, s63, v149
	s_add_i32 s64, 0, 0x1c000
	ds_read_b128 v[154:157], v153
	ds_read_b128 v[158:161], v153 offset:1024
	ds_read_b128 v[162:165], v153 offset:2048
	ds_read_b128 v[166:169], v153 offset:3072
	v_add_u32_e32 v153, s64, v149
	ds_read_b128 v[170:173], v153
	ds_read_b128 v[174:177], v153 offset:1024
	ds_read_b128 v[178:181], v153 offset:2048
	ds_read_b128 v[182:185], v153 offset:3072
	s_add_u32 s36, s36, 0x40000
	s_addc_u32 s37, s37, 0
	s_mov_b32 m0, s35
	v_lshl_add_u64 v[226:227], s[36:37], 0, v[136:137]
	ds_read_b128 v[186:189], v152 offset:32768
	ds_read_b128 v[190:193], v152 offset:33792
	ds_read_b128 v[194:197], v152 offset:34816
	ds_read_b128 v[198:201], v152 offset:35840
	ds_read_b128 v[206:209], v152 offset:36864
	ds_read_b128 v[210:213], v152 offset:37888
	ds_read_b128 v[214:217], v152 offset:38912
	ds_read_b128 v[218:221], v152 offset:39936
	global_load_lds_dwordx4 v[226:227], off
	s_mov_b32 m0, s38
	v_lshl_add_u64 v[226:227], s[36:37], 0, v[132:133]
	global_load_lds_dwordx4 v[226:227], off
	s_waitcnt vmcnt(8) lgkmcnt(0)
	s_setprio 1
	s_barrier
	v_mfma_f32_16x16x32_bf16 v[126:129], v[154:157], v[186:189], v[126:129]
	v_mfma_f32_16x16x32_bf16 v[122:125], v[162:165], v[186:189], v[122:125]
	v_mfma_f32_16x16x32_bf16 v[110:113], v[154:157], v[194:197], v[110:113]
	v_mfma_f32_16x16x32_bf16 v[106:109], v[162:165], v[194:197], v[106:109]
	v_mfma_f32_16x16x32_bf16 v[94:97], v[154:157], v[206:209], v[94:97]
	v_mfma_f32_16x16x32_bf16 v[90:93], v[162:165], v[206:209], v[90:93]
	v_mfma_f32_16x16x32_bf16 v[78:81], v[154:157], v[214:217], v[78:81]
	v_mfma_f32_16x16x32_bf16 v[74:77], v[162:165], v[214:217], v[74:77]
	v_mfma_f32_16x16x32_bf16 v[126:129], v[158:161], v[190:193], v[126:129]
	v_mfma_f32_16x16x32_bf16 v[122:125], v[166:169], v[190:193], v[122:125]
	v_mfma_f32_16x16x32_bf16 v[110:113], v[158:161], v[198:201], v[110:113]
	v_mfma_f32_16x16x32_bf16 v[106:109], v[166:169], v[198:201], v[106:109]
	v_mfma_f32_16x16x32_bf16 v[94:97], v[158:161], v[210:213], v[94:97]
	v_mfma_f32_16x16x32_bf16 v[90:93], v[166:169], v[210:213], v[90:93]
	v_mfma_f32_16x16x32_bf16 v[78:81], v[158:161], v[218:221], v[78:81]
	v_mfma_f32_16x16x32_bf16 v[74:77], v[166:169], v[218:221], v[74:77]
	v_mfma_f32_16x16x32_bf16 v[118:121], v[170:173], v[186:189], v[118:121]
	v_mfma_f32_16x16x32_bf16 v[114:117], v[178:181], v[186:189], v[114:117]
	v_mfma_f32_16x16x32_bf16 v[102:105], v[170:173], v[194:197], v[102:105]
	v_mfma_f32_16x16x32_bf16 v[98:101], v[178:181], v[194:197], v[98:101]
	v_mfma_f32_16x16x32_bf16 v[86:89], v[170:173], v[206:209], v[86:89]
	v_mfma_f32_16x16x32_bf16 v[82:85], v[178:181], v[206:209], v[82:85]
	v_mfma_f32_16x16x32_bf16 v[70:73], v[170:173], v[214:217], v[70:73]
	v_mfma_f32_16x16x32_bf16 v[66:69], v[178:181], v[214:217], v[66:69]
	v_mfma_f32_16x16x32_bf16 v[118:121], v[174:177], v[190:193], v[118:121]
	v_mfma_f32_16x16x32_bf16 v[114:117], v[182:185], v[190:193], v[114:117]
	v_mfma_f32_16x16x32_bf16 v[102:105], v[174:177], v[198:201], v[102:105]
	v_mfma_f32_16x16x32_bf16 v[98:101], v[182:185], v[198:201], v[98:101]
	v_mfma_f32_16x16x32_bf16 v[86:89], v[174:177], v[210:213], v[86:89]
	v_mfma_f32_16x16x32_bf16 v[82:85], v[182:185], v[210:213], v[82:85]
	v_mfma_f32_16x16x32_bf16 v[70:73], v[174:177], v[218:221], v[70:73]
	v_mfma_f32_16x16x32_bf16 v[66:69], v[182:185], v[218:221], v[66:69]
	s_setprio 0
	s_barrier
	ds_read_b128 v[186:189], v152 offset:49152
	ds_read_b128 v[190:193], v152 offset:50176
	ds_read_b128 v[194:197], v152 offset:51200
	ds_read_b128 v[198:201], v152 offset:52224
	ds_read_b128 v[206:209], v152 offset:53248
	ds_read_b128 v[210:213], v152 offset:54272
	ds_read_b128 v[214:217], v152 offset:55296
	ds_read_b128 v[218:221], v152 offset:56320
	s_add_i32 s36, s63, s12
	s_mov_b32 m0, s36
	v_lshl_add_u64 v[146:147], v[146:147], 0, s[8:9]
	global_load_lds_dwordx4 v[146:147], off
	s_add_i32 m0, s36, 0x2000
	s_add_u32 s30, s30, 0x40080
	v_lshl_add_u64 v[146:147], v[202:203], 0, s[8:9]
	s_addc_u32 s31, s31, 0
	s_add_i32 s36, s64, s12
	global_load_lds_dwordx4 v[146:147], off
	s_mov_b32 m0, s36
	v_lshl_add_u64 v[146:147], s[30:31], 0, v[134:135]
	global_load_lds_dwordx4 v[146:147], off
	s_add_i32 m0, s36, 0x2000
	v_lshl_add_u64 v[146:147], s[30:31], 0, v[130:131]
	global_load_lds_dwordx4 v[146:147], off
	s_mov_b32 m0, s42
	v_lshl_add_u64 v[146:147], v[222:223], 0, s[8:9]
	global_load_lds_dwordx4 v[146:147], off
	s_mov_b32 m0, s43
	v_lshl_add_u64 v[146:147], v[224:225], 0, s[8:9]
	global_load_lds_dwordx4 v[146:147], off
	s_waitcnt vmcnt(8) lgkmcnt(0)
	s_setprio 1
	s_barrier
	v_mfma_f32_16x16x32_bf16 v[62:65], v[154:157], v[186:189], v[62:65]
	v_mfma_f32_16x16x32_bf16 v[58:61], v[162:165], v[186:189], v[58:61]
	v_mfma_f32_16x16x32_bf16 v[46:49], v[154:157], v[194:197], v[46:49]
	v_mfma_f32_16x16x32_bf16 v[42:45], v[162:165], v[194:197], v[42:45]
	v_mfma_f32_16x16x32_bf16 v[30:33], v[154:157], v[206:209], v[30:33]
	v_mfma_f32_16x16x32_bf16 v[26:29], v[162:165], v[206:209], v[26:29]
	v_mfma_f32_16x16x32_bf16 v[14:17], v[154:157], v[214:217], v[14:17]
	v_mfma_f32_16x16x32_bf16 v[10:13], v[162:165], v[214:217], v[10:13]
	v_mfma_f32_16x16x32_bf16 v[62:65], v[158:161], v[190:193], v[62:65]
	v_mfma_f32_16x16x32_bf16 v[58:61], v[166:169], v[190:193], v[58:61]
	v_mfma_f32_16x16x32_bf16 v[46:49], v[158:161], v[198:201], v[46:49]
	v_mfma_f32_16x16x32_bf16 v[42:45], v[166:169], v[198:201], v[42:45]
	v_mfma_f32_16x16x32_bf16 v[30:33], v[158:161], v[210:213], v[30:33]
	v_mfma_f32_16x16x32_bf16 v[26:29], v[166:169], v[210:213], v[26:29]
	v_mfma_f32_16x16x32_bf16 v[14:17], v[158:161], v[218:221], v[14:17]
	v_mfma_f32_16x16x32_bf16 v[10:13], v[166:169], v[218:221], v[10:13]
	v_mfma_f32_16x16x32_bf16 v[54:57], v[170:173], v[186:189], v[54:57]
	v_mfma_f32_16x16x32_bf16 v[50:53], v[178:181], v[186:189], v[50:53]
	v_mfma_f32_16x16x32_bf16 v[38:41], v[170:173], v[194:197], v[38:41]
	v_mfma_f32_16x16x32_bf16 v[34:37], v[178:181], v[194:197], v[34:37]
	v_mfma_f32_16x16x32_bf16 v[22:25], v[170:173], v[206:209], v[22:25]
	v_mfma_f32_16x16x32_bf16 v[18:21], v[178:181], v[206:209], v[18:21]
	v_mfma_f32_16x16x32_bf16 v[6:9], v[170:173], v[214:217], v[6:9]
	v_mfma_f32_16x16x32_bf16 v[2:5], v[178:181], v[214:217], v[2:5]
	v_mfma_f32_16x16x32_bf16 v[54:57], v[174:177], v[190:193], v[54:57]
	v_mfma_f32_16x16x32_bf16 v[50:53], v[182:185], v[190:193], v[50:53]
	v_mfma_f32_16x16x32_bf16 v[38:41], v[174:177], v[198:201], v[38:41]
	v_mfma_f32_16x16x32_bf16 v[34:37], v[182:185], v[198:201], v[34:37]
	v_mfma_f32_16x16x32_bf16 v[22:25], v[174:177], v[210:213], v[22:25]
	v_mfma_f32_16x16x32_bf16 v[18:21], v[182:185], v[210:213], v[18:21]
	v_mfma_f32_16x16x32_bf16 v[6:9], v[174:177], v[218:221], v[6:9]
	v_mfma_f32_16x16x32_bf16 v[2:5], v[182:185], v[218:221], v[2:5]
	s_setprio 0
	s_barrier
	s_add_i32 s62, s62, 2
	s_add_u32 s28, s28, 0x100
	s_addc_u32 s29, s29, 0
	s_add_u32 s50, s50, 0x100
	s_addc_u32 s51, s51, 0
	s_cmp_gt_u32 s62, 13
	s_cbranch_scc0 .LBB0_1619
	s_and_b64 vcc, exec, s[10:11]
	s_cbranch_vccz .LBB0_1622
	s_barrier

.LBB0_1707:
	v_readlane_b32 s46, v249, 32
	v_readlane_b32 s47, v249, 33
	s_add_u32 s46, s46, s42
	s_addc_u32 s47, s47, s43
	s_and_b64 s[48:49], s[44:45], exec
	s_cselect_b32 s34, s47, s51
	s_cselect_b32 s66, s46, s50
	s_add_u32 s48, s35, s40
	s_addc_u32 s49, s70, s41
	s_and_b64 s[64:65], s[44:45], exec
	s_cselect_b32 s67, s49, s63
	s_cselect_b32 s68, s48, s62
	s_add_i32 s69, s7, -2
	s_add_u32 s50, s50, 0x100080
	s_addc_u32 s51, s51, 0
	s_add_u32 s91, s62, 0x100
	s_addc_u32 s92, s63, 0
	s_mov_b32 s62, 0
	s_waitcnt vmcnt(0)
	ds_read_b128 v[130:133], v168
	ds_read_b128 v[134:137], v168 offset:1024
	ds_read_b128 v[138:141], v168 offset:2048
	ds_read_b128 v[142:145], v168 offset:3072
	ds_read_b128 v[162:165], v169
	ds_read_b128 v[172:175], v169 offset:1024
	ds_read_b128 v[176:179], v169 offset:2048
	ds_read_b128 v[180:183], v169 offset:3072
	ds_read_b128 v[184:187], v170
	ds_read_b128 v[188:191], v170 offset:1024
	ds_read_b128 v[192:195], v170 offset:2048
	ds_read_b128 v[196:199], v170 offset:3072
	ds_read_b128 v[200:203], v170 offset:4096
	ds_read_b128 v[206:209], v170 offset:5120
	ds_read_b128 v[210:213], v170 offset:6144
	ds_read_b128 v[214:217], v170 offset:7168
	s_add_i32 s93, s62, 2
	s_add_u32 s63, s50, 0xfff00080
	s_addc_u32 s64, s51, -1
	s_cmp_eq_u32 s69, s62
	s_cselect_b32 s62, s68, s91
	s_cselect_b32 s65, s34, s64
	s_cselect_b32 s64, s66, s63
	s_cselect_b32 s63, s67, s92
	s_add_i32 m0, s12, 0xc000
	v_lshl_add_u64 v[218:219], s[50:51], 0, v[156:157]
	global_load_lds_dwordx4 v[218:219], off
	s_add_i32 m0, s12, 0xe000
	v_lshl_add_u64 v[218:219], s[50:51], 0, v[158:159]
	global_load_lds_dwordx4 v[218:219], off
	s_waitcnt vmcnt(8) lgkmcnt(0)
	s_setprio 1
	s_barrier
	v_mfma_f32_16x16x32_bf16 v[126:129], v[130:133], v[184:187], 0
	v_mfma_f32_16x16x32_bf16 v[122:125], v[138:141], v[184:187], 0
	v_mfma_f32_16x16x32_bf16 v[110:113], v[130:133], v[192:195], 0
	v_mfma_f32_16x16x32_bf16 v[106:109], v[138:141], v[192:195], 0
	v_mfma_f32_16x16x32_bf16 v[98:101], v[130:133], v[200:203], 0
	v_mfma_f32_16x16x32_bf16 v[90:93], v[138:141], v[200:203], 0
	v_mfma_f32_16x16x32_bf16 v[82:85], v[130:133], v[210:213], 0
	v_mfma_f32_16x16x32_bf16 v[74:77], v[138:141], v[210:213], 0
	v_mfma_f32_16x16x32_bf16 v[126:129], v[134:137], v[188:191], v[126:129]
	v_mfma_f32_16x16x32_bf16 v[122:125], v[142:145], v[188:191], v[122:125]
	v_mfma_f32_16x16x32_bf16 v[110:113], v[134:137], v[196:199], v[110:113]
	v_mfma_f32_16x16x32_bf16 v[106:109], v[142:145], v[196:199], v[106:109]
	v_mfma_f32_16x16x32_bf16 v[98:101], v[134:137], v[206:209], v[98:101]
	v_mfma_f32_16x16x32_bf16 v[90:93], v[142:145], v[206:209], v[90:93]
	v_mfma_f32_16x16x32_bf16 v[82:85], v[134:137], v[214:217], v[82:85]
	v_mfma_f32_16x16x32_bf16 v[74:77], v[142:145], v[214:217], v[74:77]
	v_mfma_f32_16x16x32_bf16 v[118:121], v[162:165], v[184:187], 0
	v_mfma_f32_16x16x32_bf16 v[114:117], v[176:179], v[184:187], 0
	v_mfma_f32_16x16x32_bf16 v[102:105], v[162:165], v[192:195], 0
	v_mfma_f32_16x16x32_bf16 v[94:97], v[176:179], v[192:195], 0
	v_mfma_f32_16x16x32_bf16 v[86:89], v[162:165], v[200:203], 0
	v_mfma_f32_16x16x32_bf16 v[78:81], v[176:179], v[200:203], 0
	v_mfma_f32_16x16x32_bf16 v[70:73], v[162:165], v[210:213], 0
	v_mfma_f32_16x16x32_bf16 v[66:69], v[176:179], v[210:213], 0
	v_mfma_f32_16x16x32_bf16 v[118:121], v[172:175], v[188:191], v[118:121]
	v_mfma_f32_16x16x32_bf16 v[114:117], v[180:183], v[188:191], v[114:117]
	v_mfma_f32_16x16x32_bf16 v[102:105], v[172:175], v[196:199], v[102:105]
	v_mfma_f32_16x16x32_bf16 v[94:97], v[180:183], v[196:199], v[94:97]
	v_mfma_f32_16x16x32_bf16 v[86:89], v[172:175], v[206:209], v[86:89]
	v_mfma_f32_16x16x32_bf16 v[78:81], v[180:183], v[206:209], v[78:81]
	v_mfma_f32_16x16x32_bf16 v[70:73], v[172:175], v[214:217], v[70:73]
	v_mfma_f32_16x16x32_bf16 v[66:69], v[180:183], v[214:217], v[66:69]
	s_setprio 0
	s_barrier
	ds_read_b128 v[184:187], v170 offset:16384
	ds_read_b128 v[188:191], v170 offset:17408
	ds_read_b128 v[192:195], v170 offset:18432
	ds_read_b128 v[196:199], v170 offset:19456
	ds_read_b128 v[200:203], v170 offset:20480
	ds_read_b128 v[206:209], v170 offset:21504
	ds_read_b128 v[210:213], v170 offset:22528
	ds_read_b128 v[214:217], v170 offset:23552
	s_add_i32 s94, s31, s2
	s_mov_b32 m0, s94
	v_lshl_add_u64 v[218:219], s[62:63], 0, v[148:149]
	global_load_lds_dwordx4 v[218:219], off
	s_add_i32 m0, s94, 0x2000
	s_add_u32 s94, s62, 0x100000
	v_lshl_add_u64 v[220:221], s[62:63], 0, v[152:153]
	s_addc_u32 s95, s63, 0
	s_add_i32 s96, s82, s2
	global_load_lds_dwordx4 v[220:221], off
	v_lshl_add_u64 v[222:223], s[94:95], 0, v[148:149]
	s_mov_b32 m0, s96
	v_lshl_add_u64 v[224:225], s[64:65], 0, v[150:151]
	global_load_lds_dwordx4 v[222:223], off
	s_add_i32 m0, s96, 0x2000
	v_lshl_add_u64 v[222:223], s[94:95], 0, v[152:153]
	global_load_lds_dwordx4 v[222:223], off
	s_mov_b32 m0, s12
	v_lshl_add_u64 v[222:223], s[64:65], 0, v[146:147]
	global_load_lds_dwordx4 v[222:223], off
	s_mov_b32 m0, s13
	s_nop 0
	global_load_lds_dwordx4 v[224:225], off
	s_waitcnt vmcnt(8) lgkmcnt(0)
	s_setprio 1
	s_barrier
	v_mfma_f32_16x16x32_bf16 v[62:65], v[130:133], v[184:187], 0
	v_mfma_f32_16x16x32_bf16 v[58:61], v[138:141], v[184:187], 0
	v_mfma_f32_16x16x32_bf16 v[50:53], v[130:133], v[192:195], 0
	v_mfma_f32_16x16x32_bf16 v[42:45], v[138:141], v[192:195], 0
	v_mfma_f32_16x16x32_bf16 v[34:37], v[130:133], v[200:203], 0
	v_mfma_f32_16x16x32_bf16 v[26:29], v[138:141], v[200:203], 0
	v_mfma_f32_16x16x32_bf16 v[18:21], v[130:133], v[210:213], 0
	v_mfma_f32_16x16x32_bf16 v[10:13], v[138:141], v[210:213], 0
	v_mfma_f32_16x16x32_bf16 v[62:65], v[134:137], v[188:191], v[62:65]
	v_mfma_f32_16x16x32_bf16 v[58:61], v[142:145], v[188:191], v[58:61]
	v_mfma_f32_16x16x32_bf16 v[50:53], v[134:137], v[196:199], v[50:53]
	v_mfma_f32_16x16x32_bf16 v[42:45], v[142:145], v[196:199], v[42:45]
	v_mfma_f32_16x16x32_bf16 v[34:37], v[134:137], v[206:209], v[34:37]
	v_mfma_f32_16x16x32_bf16 v[26:29], v[142:145], v[206:209], v[26:29]
	v_mfma_f32_16x16x32_bf16 v[18:21], v[134:137], v[214:217], v[18:21]
	v_mfma_f32_16x16x32_bf16 v[10:13], v[142:145], v[214:217], v[10:13]
	v_mfma_f32_16x16x32_bf16 v[54:57], v[162:165], v[184:187], 0
	v_mfma_f32_16x16x32_bf16 v[46:49], v[176:179], v[184:187], 0
	v_mfma_f32_16x16x32_bf16 v[38:41], v[162:165], v[192:195], 0
	v_mfma_f32_16x16x32_bf16 v[30:33], v[176:179], v[192:195], 0
	v_mfma_f32_16x16x32_bf16 v[22:25], v[162:165], v[200:203], 0
	v_mfma_f32_16x16x32_bf16 v[14:17], v[176:179], v[200:203], 0
	v_mfma_f32_16x16x32_bf16 v[6:9], v[162:165], v[210:213], 0
	v_mfma_f32_16x16x32_bf16 v[2:5], v[176:179], v[210:213], 0
	v_mfma_f32_16x16x32_bf16 v[54:57], v[172:175], v[188:191], v[54:57]
	v_mfma_f32_16x16x32_bf16 v[46:49], v[180:183], v[188:191], v[46:49]
	v_mfma_f32_16x16x32_bf16 v[38:41], v[172:175], v[196:199], v[38:41]
	v_mfma_f32_16x16x32_bf16 v[30:33], v[180:183], v[196:199], v[30:33]
	v_mfma_f32_16x16x32_bf16 v[22:25], v[172:175], v[206:209], v[22:25]
	v_mfma_f32_16x16x32_bf16 v[14:17], v[180:183], v[206:209], v[14:17]
	v_mfma_f32_16x16x32_bf16 v[6:9], v[172:175], v[214:217], v[6:9]
	v_mfma_f32_16x16x32_bf16 v[2:5], v[180:183], v[214:217], v[2:5]
	s_setprio 0
	s_barrier
	s_add_i32 s94, 0, 0x18000
	s_add_i32 s95, 0, 0x1c000
	v_add_u32_e32 v142, s94, v167
	v_add_u32_e32 v154, s95, v167
	ds_read_b128 v[130:133], v142
	ds_read_b128 v[134:137], v142 offset:1024
	ds_read_b128 v[138:141], v142 offset:2048
	ds_read_b128 v[142:145], v142 offset:3072
	ds_read_b128 v[162:165], v154
	ds_read_b128 v[172:175], v154 offset:1024
	ds_read_b128 v[176:179], v154 offset:2048
	ds_read_b128 v[180:183], v154 offset:3072
	s_add_u32 s64, s64, 0x100000
	s_addc_u32 s65, s65, 0
	s_mov_b32 m0, s18
	v_lshl_add_u64 v[226:227], s[64:65], 0, v[146:147]
	ds_read_b128 v[184:187], v170 offset:32768
	ds_read_b128 v[188:191], v170 offset:33792
	ds_read_b128 v[192:195], v170 offset:34816
	ds_read_b128 v[196:199], v170 offset:35840
	ds_read_b128 v[200:203], v170 offset:36864
	ds_read_b128 v[206:209], v170 offset:37888
	ds_read_b128 v[210:213], v170 offset:38912
	ds_read_b128 v[214:217], v170 offset:39936
	global_load_lds_dwordx4 v[226:227], off
	s_mov_b32 m0, s19
	v_lshl_add_u64 v[226:227], s[64:65], 0, v[150:151]
	global_load_lds_dwordx4 v[226:227], off
	s_waitcnt vmcnt(8) lgkmcnt(0)
	s_setprio 1
	s_barrier
	v_mfma_f32_16x16x32_bf16 v[126:129], v[130:133], v[184:187], v[126:129]
	v_mfma_f32_16x16x32_bf16 v[122:125], v[138:141], v[184:187], v[122:125]
	v_mfma_f32_16x16x32_bf16 v[110:113], v[130:133], v[192:195], v[110:113]
	v_mfma_f32_16x16x32_bf16 v[106:109], v[138:141], v[192:195], v[106:109]
	v_mfma_f32_16x16x32_bf16 v[98:101], v[130:133], v[200:203], v[98:101]
	v_mfma_f32_16x16x32_bf16 v[90:93], v[138:141], v[200:203], v[90:93]
	v_mfma_f32_16x16x32_bf16 v[82:85], v[130:133], v[210:213], v[82:85]
	v_mfma_f32_16x16x32_bf16 v[74:77], v[138:141], v[210:213], v[74:77]
	v_mfma_f32_16x16x32_bf16 v[126:129], v[134:137], v[188:191], v[126:129]
	v_mfma_f32_16x16x32_bf16 v[122:125], v[142:145], v[188:191], v[122:125]
	v_mfma_f32_16x16x32_bf16 v[110:113], v[134:137], v[196:199], v[110:113]
	v_mfma_f32_16x16x32_bf16 v[106:109], v[142:145], v[196:199], v[106:109]
	v_mfma_f32_16x16x32_bf16 v[98:101], v[134:137], v[206:209], v[98:101]
	v_mfma_f32_16x16x32_bf16 v[90:93], v[142:145], v[206:209], v[90:93]
	v_mfma_f32_16x16x32_bf16 v[82:85], v[134:137], v[214:217], v[82:85]
	v_mfma_f32_16x16x32_bf16 v[74:77], v[142:145], v[214:217], v[74:77]
	v_mfma_f32_16x16x32_bf16 v[118:121], v[162:165], v[184:187], v[118:121]
	v_mfma_f32_16x16x32_bf16 v[114:117], v[176:179], v[184:187], v[114:117]
	v_mfma_f32_16x16x32_bf16 v[102:105], v[162:165], v[192:195], v[102:105]
	v_mfma_f32_16x16x32_bf16 v[94:97], v[176:179], v[192:195], v[94:97]
	v_mfma_f32_16x16x32_bf16 v[86:89], v[162:165], v[200:203], v[86:89]
	v_mfma_f32_16x16x32_bf16 v[78:81], v[176:179], v[200:203], v[78:81]
	v_mfma_f32_16x16x32_bf16 v[70:73], v[162:165], v[210:213], v[70:73]
	v_mfma_f32_16x16x32_bf16 v[66:69], v[176:179], v[210:213], v[66:69]
	v_mfma_f32_16x16x32_bf16 v[118:121], v[172:175], v[188:191], v[118:121]
	v_mfma_f32_16x16x32_bf16 v[114:117], v[180:183], v[188:191], v[114:117]
	v_mfma_f32_16x16x32_bf16 v[102:105], v[172:175], v[196:199], v[102:105]
	v_mfma_f32_16x16x32_bf16 v[94:97], v[180:183], v[196:199], v[94:97]
	v_mfma_f32_16x16x32_bf16 v[86:89], v[172:175], v[206:209], v[86:89]
	v_mfma_f32_16x16x32_bf16 v[78:81], v[180:183], v[206:209], v[78:81]
	v_mfma_f32_16x16x32_bf16 v[70:73], v[172:175], v[214:217], v[70:73]
	v_mfma_f32_16x16x32_bf16 v[66:69], v[180:183], v[214:217], v[66:69]
	s_setprio 0
	s_barrier
	ds_read_b128 v[184:187], v170 offset:49152
	ds_read_b128 v[188:191], v170 offset:50176
	ds_read_b128 v[192:195], v170 offset:51200
	ds_read_b128 v[196:199], v170 offset:52224
	ds_read_b128 v[200:203], v170 offset:53248
	ds_read_b128 v[206:209], v170 offset:54272
	ds_read_b128 v[210:213], v170 offset:55296
	ds_read_b128 v[214:217], v170 offset:56320
	s_add_i32 s64, s94, s2
	s_mov_b32 m0, s64
	v_lshl_add_u64 v[218:219], v[218:219], 0, s[16:17]
	global_load_lds_dwordx4 v[218:219], off
	s_add_i32 m0, s64, 0x2000
	s_add_u32 s62, s62, 0x100080
	v_lshl_add_u64 v[218:219], v[220:221], 0, s[16:17]
	s_addc_u32 s63, s63, 0
	s_add_i32 s64, s95, s2
	global_load_lds_dwordx4 v[218:219], off
	s_mov_b32 m0, s64
	v_lshl_add_u64 v[218:219], s[62:63], 0, v[148:149]
	global_load_lds_dwordx4 v[218:219], off
	s_add_i32 m0, s64, 0x2000
	v_lshl_add_u64 v[218:219], s[62:63], 0, v[152:153]
	global_load_lds_dwordx4 v[218:219], off
	s_mov_b32 m0, s74
	v_lshl_add_u64 v[218:219], v[222:223], 0, s[16:17]
	global_load_lds_dwordx4 v[218:219], off
	s_mov_b32 m0, s75
	v_lshl_add_u64 v[218:219], v[224:225], 0, s[16:17]
	global_load_lds_dwordx4 v[218:219], off
	s_waitcnt vmcnt(8) lgkmcnt(0)
	s_setprio 1
	s_barrier
	v_mfma_f32_16x16x32_bf16 v[62:65], v[130:133], v[184:187], v[62:65]
	v_mfma_f32_16x16x32_bf16 v[58:61], v[138:141], v[184:187], v[58:61]
	v_mfma_f32_16x16x32_bf16 v[50:53], v[130:133], v[192:195], v[50:53]
	v_mfma_f32_16x16x32_bf16 v[42:45], v[138:141], v[192:195], v[42:45]
	v_mfma_f32_16x16x32_bf16 v[34:37], v[130:133], v[200:203], v[34:37]
	v_mfma_f32_16x16x32_bf16 v[26:29], v[138:141], v[200:203], v[26:29]
	v_mfma_f32_16x16x32_bf16 v[18:21], v[130:133], v[210:213], v[18:21]
	v_mfma_f32_16x16x32_bf16 v[10:13], v[138:141], v[210:213], v[10:13]
	v_mfma_f32_16x16x32_bf16 v[62:65], v[134:137], v[188:191], v[62:65]
	v_mfma_f32_16x16x32_bf16 v[58:61], v[142:145], v[188:191], v[58:61]
	v_mfma_f32_16x16x32_bf16 v[50:53], v[134:137], v[196:199], v[50:53]
	v_mfma_f32_16x16x32_bf16 v[42:45], v[142:145], v[196:199], v[42:45]
	v_mfma_f32_16x16x32_bf16 v[34:37], v[134:137], v[206:209], v[34:37]
	v_mfma_f32_16x16x32_bf16 v[26:29], v[142:145], v[206:209], v[26:29]
	v_mfma_f32_16x16x32_bf16 v[18:21], v[134:137], v[214:217], v[18:21]
	v_mfma_f32_16x16x32_bf16 v[10:13], v[142:145], v[214:217], v[10:13]
	v_mfma_f32_16x16x32_bf16 v[54:57], v[162:165], v[184:187], v[54:57]
	v_mfma_f32_16x16x32_bf16 v[46:49], v[176:179], v[184:187], v[46:49]
	v_mfma_f32_16x16x32_bf16 v[38:41], v[162:165], v[192:195], v[38:41]
	v_mfma_f32_16x16x32_bf16 v[30:33], v[176:179], v[192:195], v[30:33]
	v_mfma_f32_16x16x32_bf16 v[22:25], v[162:165], v[200:203], v[22:25]
	v_mfma_f32_16x16x32_bf16 v[14:17], v[176:179], v[200:203], v[14:17]
	v_mfma_f32_16x16x32_bf16 v[6:9], v[162:165], v[210:213], v[6:9]
	v_mfma_f32_16x16x32_bf16 v[2:5], v[176:179], v[210:213], v[2:5]
	v_mfma_f32_16x16x32_bf16 v[54:57], v[172:175], v[188:191], v[54:57]
	v_mfma_f32_16x16x32_bf16 v[46:49], v[180:183], v[188:191], v[46:49]
	v_mfma_f32_16x16x32_bf16 v[38:41], v[172:175], v[196:199], v[38:41]
	v_mfma_f32_16x16x32_bf16 v[30:33], v[180:183], v[196:199], v[30:33]
	v_mfma_f32_16x16x32_bf16 v[22:25], v[172:175], v[206:209], v[22:25]
	v_mfma_f32_16x16x32_bf16 v[14:17], v[180:183], v[206:209], v[14:17]
	v_mfma_f32_16x16x32_bf16 v[6:9], v[172:175], v[214:217], v[6:9]
	v_mfma_f32_16x16x32_bf16 v[2:5], v[180:183], v[214:217], v[2:5]
	s_setprio 0
	s_barrier
	s_add_u32 s50, s50, 0x100
	s_addc_u32 s51, s51, 0
	s_add_u32 s91, s91, 0x100
	s_addc_u32 s92, s92, 0
	s_cmp_ge_i32 s93, s7
	s_mov_b32 s62, s93
.LBB0_1708:
	ds_read_b128 v[130:133], v168
	ds_read_b128 v[134:137], v168 offset:1024
	ds_read_b128 v[138:141], v168 offset:2048
	ds_read_b128 v[142:145], v168 offset:3072
	ds_read_b128 v[162:165], v169
	ds_read_b128 v[172:175], v169 offset:1024
	ds_read_b128 v[176:179], v169 offset:2048
	ds_read_b128 v[180:183], v169 offset:3072
	ds_read_b128 v[184:187], v170
	ds_read_b128 v[188:191], v170 offset:1024
	ds_read_b128 v[192:195], v170 offset:2048
	ds_read_b128 v[196:199], v170 offset:3072
	ds_read_b128 v[200:203], v170 offset:4096
	ds_read_b128 v[206:209], v170 offset:5120
	ds_read_b128 v[210:213], v170 offset:6144
	ds_read_b128 v[214:217], v170 offset:7168
	s_add_i32 s93, s62, 2
	s_add_u32 s63, s50, 0xfff00080
	s_addc_u32 s64, s51, -1
	s_cmp_eq_u32 s69, s62
	s_cselect_b32 s62, s68, s91
	s_cselect_b32 s65, s34, s64
	s_cselect_b32 s64, s66, s63
	s_cselect_b32 s63, s67, s92
	s_add_i32 m0, s12, 0xc000
	v_lshl_add_u64 v[218:219], s[50:51], 0, v[156:157]
	global_load_lds_dwordx4 v[218:219], off
	s_add_i32 m0, s12, 0xe000
	v_lshl_add_u64 v[218:219], s[50:51], 0, v[158:159]
	global_load_lds_dwordx4 v[218:219], off
	s_waitcnt vmcnt(8) lgkmcnt(0)
	s_setprio 1
	s_barrier
	v_mfma_f32_16x16x32_bf16 v[126:129], v[130:133], v[184:187], v[126:129]
	v_mfma_f32_16x16x32_bf16 v[122:125], v[138:141], v[184:187], v[122:125]
	v_mfma_f32_16x16x32_bf16 v[110:113], v[130:133], v[192:195], v[110:113]
	v_mfma_f32_16x16x32_bf16 v[106:109], v[138:141], v[192:195], v[106:109]
	v_mfma_f32_16x16x32_bf16 v[98:101], v[130:133], v[200:203], v[98:101]
	v_mfma_f32_16x16x32_bf16 v[90:93], v[138:141], v[200:203], v[90:93]
	v_mfma_f32_16x16x32_bf16 v[82:85], v[130:133], v[210:213], v[82:85]
	v_mfma_f32_16x16x32_bf16 v[74:77], v[138:141], v[210:213], v[74:77]
	v_mfma_f32_16x16x32_bf16 v[126:129], v[134:137], v[188:191], v[126:129]
	v_mfma_f32_16x16x32_bf16 v[122:125], v[142:145], v[188:191], v[122:125]
	v_mfma_f32_16x16x32_bf16 v[110:113], v[134:137], v[196:199], v[110:113]
	v_mfma_f32_16x16x32_bf16 v[106:109], v[142:145], v[196:199], v[106:109]
	v_mfma_f32_16x16x32_bf16 v[98:101], v[134:137], v[206:209], v[98:101]
	v_mfma_f32_16x16x32_bf16 v[90:93], v[142:145], v[206:209], v[90:93]
	v_mfma_f32_16x16x32_bf16 v[82:85], v[134:137], v[214:217], v[82:85]
	v_mfma_f32_16x16x32_bf16 v[74:77], v[142:145], v[214:217], v[74:77]
	v_mfma_f32_16x16x32_bf16 v[118:121], v[162:165], v[184:187], v[118:121]
	v_mfma_f32_16x16x32_bf16 v[114:117], v[176:179], v[184:187], v[114:117]
	v_mfma_f32_16x16x32_bf16 v[102:105], v[162:165], v[192:195], v[102:105]
	v_mfma_f32_16x16x32_bf16 v[94:97], v[176:179], v[192:195], v[94:97]
	v_mfma_f32_16x16x32_bf16 v[86:89], v[162:165], v[200:203], v[86:89]
	v_mfma_f32_16x16x32_bf16 v[78:81], v[176:179], v[200:203], v[78:81]
	v_mfma_f32_16x16x32_bf16 v[70:73], v[162:165], v[210:213], v[70:73]
	v_mfma_f32_16x16x32_bf16 v[66:69], v[176:179], v[210:213], v[66:69]
	v_mfma_f32_16x16x32_bf16 v[118:121], v[172:175], v[188:191], v[118:121]
	v_mfma_f32_16x16x32_bf16 v[114:117], v[180:183], v[188:191], v[114:117]
	v_mfma_f32_16x16x32_bf16 v[102:105], v[172:175], v[196:199], v[102:105]
	v_mfma_f32_16x16x32_bf16 v[94:97], v[180:183], v[196:199], v[94:97]
	v_mfma_f32_16x16x32_bf16 v[86:89], v[172:175], v[206:209], v[86:89]
	v_mfma_f32_16x16x32_bf16 v[78:81], v[180:183], v[206:209], v[78:81]
	v_mfma_f32_16x16x32_bf16 v[70:73], v[172:175], v[214:217], v[70:73]
	v_mfma_f32_16x16x32_bf16 v[66:69], v[180:183], v[214:217], v[66:69]
	s_setprio 0
	s_barrier
	ds_read_b128 v[184:187], v170 offset:16384
	ds_read_b128 v[188:191], v170 offset:17408
	ds_read_b128 v[192:195], v170 offset:18432
	ds_read_b128 v[196:199], v170 offset:19456
	ds_read_b128 v[200:203], v170 offset:20480
	ds_read_b128 v[206:209], v170 offset:21504
	ds_read_b128 v[210:213], v170 offset:22528
	ds_read_b128 v[214:217], v170 offset:23552
	s_add_i32 s94, s31, s2
	s_mov_b32 m0, s94
	v_lshl_add_u64 v[218:219], s[62:63], 0, v[148:149]
	global_load_lds_dwordx4 v[218:219], off
	s_add_i32 m0, s94, 0x2000
	s_add_u32 s94, s62, 0x100000
	v_lshl_add_u64 v[220:221], s[62:63], 0, v[152:153]
	s_addc_u32 s95, s63, 0
	s_add_i32 s96, s82, s2
	global_load_lds_dwordx4 v[220:221], off
	v_lshl_add_u64 v[222:223], s[94:95], 0, v[148:149]
	s_mov_b32 m0, s96
	v_lshl_add_u64 v[224:225], s[64:65], 0, v[150:151]
	global_load_lds_dwordx4 v[222:223], off
	s_add_i32 m0, s96, 0x2000
	v_lshl_add_u64 v[222:223], s[94:95], 0, v[152:153]
	global_load_lds_dwordx4 v[222:223], off
	s_mov_b32 m0, s12
	v_lshl_add_u64 v[222:223], s[64:65], 0, v[146:147]
	global_load_lds_dwordx4 v[222:223], off
	s_mov_b32 m0, s13
	s_nop 0
	global_load_lds_dwordx4 v[224:225], off
	s_waitcnt vmcnt(8) lgkmcnt(0)
	s_setprio 1
	s_barrier
	v_mfma_f32_16x16x32_bf16 v[62:65], v[130:133], v[184:187], v[62:65]
	v_mfma_f32_16x16x32_bf16 v[58:61], v[138:141], v[184:187], v[58:61]
	v_mfma_f32_16x16x32_bf16 v[50:53], v[130:133], v[192:195], v[50:53]
	v_mfma_f32_16x16x32_bf16 v[42:45], v[138:141], v[192:195], v[42:45]
	v_mfma_f32_16x16x32_bf16 v[34:37], v[130:133], v[200:203], v[34:37]
	v_mfma_f32_16x16x32_bf16 v[26:29], v[138:141], v[200:203], v[26:29]
	v_mfma_f32_16x16x32_bf16 v[18:21], v[130:133], v[210:213], v[18:21]
	v_mfma_f32_16x16x32_bf16 v[10:13], v[138:141], v[210:213], v[10:13]
	v_mfma_f32_16x16x32_bf16 v[62:65], v[134:137], v[188:191], v[62:65]
	v_mfma_f32_16x16x32_bf16 v[58:61], v[142:145], v[188:191], v[58:61]
	v_mfma_f32_16x16x32_bf16 v[50:53], v[134:137], v[196:199], v[50:53]
	v_mfma_f32_16x16x32_bf16 v[42:45], v[142:145], v[196:199], v[42:45]
	v_mfma_f32_16x16x32_bf16 v[34:37], v[134:137], v[206:209], v[34:37]
	v_mfma_f32_16x16x32_bf16 v[26:29], v[142:145], v[206:209], v[26:29]
	v_mfma_f32_16x16x32_bf16 v[18:21], v[134:137], v[214:217], v[18:21]
	v_mfma_f32_16x16x32_bf16 v[10:13], v[142:145], v[214:217], v[10:13]
	v_mfma_f32_16x16x32_bf16 v[54:57], v[162:165], v[184:187], v[54:57]
	v_mfma_f32_16x16x32_bf16 v[46:49], v[176:179], v[184:187], v[46:49]
	v_mfma_f32_16x16x32_bf16 v[38:41], v[162:165], v[192:195], v[38:41]
	v_mfma_f32_16x16x32_bf16 v[30:33], v[176:179], v[192:195], v[30:33]
	v_mfma_f32_16x16x32_bf16 v[22:25], v[162:165], v[200:203], v[22:25]
	v_mfma_f32_16x16x32_bf16 v[14:17], v[176:179], v[200:203], v[14:17]
	v_mfma_f32_16x16x32_bf16 v[6:9], v[162:165], v[210:213], v[6:9]
	v_mfma_f32_16x16x32_bf16 v[2:5], v[176:179], v[210:213], v[2:5]
	v_mfma_f32_16x16x32_bf16 v[54:57], v[172:175], v[188:191], v[54:57]
	v_mfma_f32_16x16x32_bf16 v[46:49], v[180:183], v[188:191], v[46:49]
	v_mfma_f32_16x16x32_bf16 v[38:41], v[172:175], v[196:199], v[38:41]
	v_mfma_f32_16x16x32_bf16 v[30:33], v[180:183], v[196:199], v[30:33]
	v_mfma_f32_16x16x32_bf16 v[22:25], v[172:175], v[206:209], v[22:25]
	v_mfma_f32_16x16x32_bf16 v[14:17], v[180:183], v[206:209], v[14:17]
	v_mfma_f32_16x16x32_bf16 v[6:9], v[172:175], v[214:217], v[6:9]
	v_mfma_f32_16x16x32_bf16 v[2:5], v[180:183], v[214:217], v[2:5]
	s_setprio 0
	s_barrier
	s_add_i32 s94, 0, 0x18000
	s_add_i32 s95, 0, 0x1c000
	v_add_u32_e32 v142, s94, v167
	v_add_u32_e32 v154, s95, v167
	ds_read_b128 v[130:133], v142
	ds_read_b128 v[134:137], v142 offset:1024
	ds_read_b128 v[138:141], v142 offset:2048
	ds_read_b128 v[142:145], v142 offset:3072
	ds_read_b128 v[162:165], v154
	ds_read_b128 v[172:175], v154 offset:1024
	ds_read_b128 v[176:179], v154 offset:2048
	ds_read_b128 v[180:183], v154 offset:3072
	s_add_u32 s64, s64, 0x100000
	s_addc_u32 s65, s65, 0
	s_mov_b32 m0, s18
	v_lshl_add_u64 v[226:227], s[64:65], 0, v[146:147]
	ds_read_b128 v[184:187], v170 offset:32768
	ds_read_b128 v[188:191], v170 offset:33792
	ds_read_b128 v[192:195], v170 offset:34816
	ds_read_b128 v[196:199], v170 offset:35840
	ds_read_b128 v[200:203], v170 offset:36864
	ds_read_b128 v[206:209], v170 offset:37888
	ds_read_b128 v[210:213], v170 offset:38912
	ds_read_b128 v[214:217], v170 offset:39936
	global_load_lds_dwordx4 v[226:227], off
	s_mov_b32 m0, s19
	v_lshl_add_u64 v[226:227], s[64:65], 0, v[150:151]
	global_load_lds_dwordx4 v[226:227], off
	s_waitcnt vmcnt(8) lgkmcnt(0)
	s_setprio 1
	s_barrier
	v_mfma_f32_16x16x32_bf16 v[126:129], v[130:133], v[184:187], v[126:129]
	v_mfma_f32_16x16x32_bf16 v[122:125], v[138:141], v[184:187], v[122:125]
	v_mfma_f32_16x16x32_bf16 v[110:113], v[130:133], v[192:195], v[110:113]
	v_mfma_f32_16x16x32_bf16 v[106:109], v[138:141], v[192:195], v[106:109]
	v_mfma_f32_16x16x32_bf16 v[98:101], v[130:133], v[200:203], v[98:101]
	v_mfma_f32_16x16x32_bf16 v[90:93], v[138:141], v[200:203], v[90:93]
	v_mfma_f32_16x16x32_bf16 v[82:85], v[130:133], v[210:213], v[82:85]
	v_mfma_f32_16x16x32_bf16 v[74:77], v[138:141], v[210:213], v[74:77]
	v_mfma_f32_16x16x32_bf16 v[126:129], v[134:137], v[188:191], v[126:129]
	v_mfma_f32_16x16x32_bf16 v[122:125], v[142:145], v[188:191], v[122:125]
	v_mfma_f32_16x16x32_bf16 v[110:113], v[134:137], v[196:199], v[110:113]
	v_mfma_f32_16x16x32_bf16 v[106:109], v[142:145], v[196:199], v[106:109]
	v_mfma_f32_16x16x32_bf16 v[98:101], v[134:137], v[206:209], v[98:101]
	v_mfma_f32_16x16x32_bf16 v[90:93], v[142:145], v[206:209], v[90:93]
	v_mfma_f32_16x16x32_bf16 v[82:85], v[134:137], v[214:217], v[82:85]
	v_mfma_f32_16x16x32_bf16 v[74:77], v[142:145], v[214:217], v[74:77]
	v_mfma_f32_16x16x32_bf16 v[118:121], v[162:165], v[184:187], v[118:121]
	v_mfma_f32_16x16x32_bf16 v[114:117], v[176:179], v[184:187], v[114:117]
	v_mfma_f32_16x16x32_bf16 v[102:105], v[162:165], v[192:195], v[102:105]
	v_mfma_f32_16x16x32_bf16 v[94:97], v[176:179], v[192:195], v[94:97]
	v_mfma_f32_16x16x32_bf16 v[86:89], v[162:165], v[200:203], v[86:89]
	v_mfma_f32_16x16x32_bf16 v[78:81], v[176:179], v[200:203], v[78:81]
	v_mfma_f32_16x16x32_bf16 v[70:73], v[162:165], v[210:213], v[70:73]
	v_mfma_f32_16x16x32_bf16 v[66:69], v[176:179], v[210:213], v[66:69]
	v_mfma_f32_16x16x32_bf16 v[118:121], v[172:175], v[188:191], v[118:121]
	v_mfma_f32_16x16x32_bf16 v[114:117], v[180:183], v[188:191], v[114:117]
	v_mfma_f32_16x16x32_bf16 v[102:105], v[172:175], v[196:199], v[102:105]
	v_mfma_f32_16x16x32_bf16 v[94:97], v[180:183], v[196:199], v[94:97]
	v_mfma_f32_16x16x32_bf16 v[86:89], v[172:175], v[206:209], v[86:89]
	v_mfma_f32_16x16x32_bf16 v[78:81], v[180:183], v[206:209], v[78:81]
	v_mfma_f32_16x16x32_bf16 v[70:73], v[172:175], v[214:217], v[70:73]
	v_mfma_f32_16x16x32_bf16 v[66:69], v[180:183], v[214:217], v[66:69]
	s_setprio 0
	s_barrier
	ds_read_b128 v[184:187], v170 offset:49152
	ds_read_b128 v[188:191], v170 offset:50176
	ds_read_b128 v[192:195], v170 offset:51200
	ds_read_b128 v[196:199], v170 offset:52224
	ds_read_b128 v[200:203], v170 offset:53248
	ds_read_b128 v[206:209], v170 offset:54272
	ds_read_b128 v[210:213], v170 offset:55296
	ds_read_b128 v[214:217], v170 offset:56320
	s_add_i32 s64, s94, s2
	s_mov_b32 m0, s64
	v_lshl_add_u64 v[218:219], v[218:219], 0, s[16:17]
	global_load_lds_dwordx4 v[218:219], off
	s_add_i32 m0, s64, 0x2000
	s_add_u32 s62, s62, 0x100080
	v_lshl_add_u64 v[218:219], v[220:221], 0, s[16:17]
	s_addc_u32 s63, s63, 0
	s_add_i32 s64, s95, s2
	global_load_lds_dwordx4 v[218:219], off
	s_mov_b32 m0, s64
	v_lshl_add_u64 v[218:219], s[62:63], 0, v[148:149]
	global_load_lds_dwordx4 v[218:219], off
	s_add_i32 m0, s64, 0x2000
	v_lshl_add_u64 v[218:219], s[62:63], 0, v[152:153]
	global_load_lds_dwordx4 v[218:219], off
	s_mov_b32 m0, s74
	v_lshl_add_u64 v[218:219], v[222:223], 0, s[16:17]
	global_load_lds_dwordx4 v[218:219], off
	s_mov_b32 m0, s75
	v_lshl_add_u64 v[218:219], v[224:225], 0, s[16:17]
	global_load_lds_dwordx4 v[218:219], off
	s_waitcnt vmcnt(8) lgkmcnt(0)
	s_setprio 1
	s_barrier
	v_mfma_f32_16x16x32_bf16 v[62:65], v[130:133], v[184:187], v[62:65]
	v_mfma_f32_16x16x32_bf16 v[58:61], v[138:141], v[184:187], v[58:61]
	v_mfma_f32_16x16x32_bf16 v[50:53], v[130:133], v[192:195], v[50:53]
	v_mfma_f32_16x16x32_bf16 v[42:45], v[138:141], v[192:195], v[42:45]
	v_mfma_f32_16x16x32_bf16 v[34:37], v[130:133], v[200:203], v[34:37]
	v_mfma_f32_16x16x32_bf16 v[26:29], v[138:141], v[200:203], v[26:29]
	v_mfma_f32_16x16x32_bf16 v[18:21], v[130:133], v[210:213], v[18:21]
	v_mfma_f32_16x16x32_bf16 v[10:13], v[138:141], v[210:213], v[10:13]
	v_mfma_f32_16x16x32_bf16 v[62:65], v[134:137], v[188:191], v[62:65]
	v_mfma_f32_16x16x32_bf16 v[58:61], v[142:145], v[188:191], v[58:61]
	v_mfma_f32_16x16x32_bf16 v[50:53], v[134:137], v[196:199], v[50:53]
	v_mfma_f32_16x16x32_bf16 v[42:45], v[142:145], v[196:199], v[42:45]
	v_mfma_f32_16x16x32_bf16 v[34:37], v[134:137], v[206:209], v[34:37]
	v_mfma_f32_16x16x32_bf16 v[26:29], v[142:145], v[206:209], v[26:29]
	v_mfma_f32_16x16x32_bf16 v[18:21], v[134:137], v[214:217], v[18:21]
	v_mfma_f32_16x16x32_bf16 v[10:13], v[142:145], v[214:217], v[10:13]
	v_mfma_f32_16x16x32_bf16 v[54:57], v[162:165], v[184:187], v[54:57]
	v_mfma_f32_16x16x32_bf16 v[46:49], v[176:179], v[184:187], v[46:49]
	v_mfma_f32_16x16x32_bf16 v[38:41], v[162:165], v[192:195], v[38:41]
	v_mfma_f32_16x16x32_bf16 v[30:33], v[176:179], v[192:195], v[30:33]
	v_mfma_f32_16x16x32_bf16 v[22:25], v[162:165], v[200:203], v[22:25]
	v_mfma_f32_16x16x32_bf16 v[14:17], v[176:179], v[200:203], v[14:17]
	v_mfma_f32_16x16x32_bf16 v[6:9], v[162:165], v[210:213], v[6:9]
	v_mfma_f32_16x16x32_bf16 v[2:5], v[176:179], v[210:213], v[2:5]
	v_mfma_f32_16x16x32_bf16 v[54:57], v[172:175], v[188:191], v[54:57]
	v_mfma_f32_16x16x32_bf16 v[46:49], v[180:183], v[188:191], v[46:49]
	v_mfma_f32_16x16x32_bf16 v[38:41], v[172:175], v[196:199], v[38:41]
	v_mfma_f32_16x16x32_bf16 v[30:33], v[180:183], v[196:199], v[30:33]
	v_mfma_f32_16x16x32_bf16 v[22:25], v[172:175], v[206:209], v[22:25]
	v_mfma_f32_16x16x32_bf16 v[14:17], v[180:183], v[206:209], v[14:17]
	v_mfma_f32_16x16x32_bf16 v[6:9], v[172:175], v[214:217], v[6:9]
	v_mfma_f32_16x16x32_bf16 v[2:5], v[180:183], v[214:217], v[2:5]
	s_setprio 0
	s_barrier
	s_add_u32 s50, s50, 0x100
	s_addc_u32 s51, s51, 0
	s_add_u32 s91, s91, 0x100
	s_addc_u32 s92, s92, 0
	s_cmp_ge_i32 s93, s7
	s_mov_b32 s62, s93
	s_cbranch_scc0 .LBB0_1708
	s_and_b64 vcc, exec, s[20:21]
	s_cbranch_vccz .LBB0_1711
	s_barrier
